# s_setprio 1 of each MFMA segment issued before the segment's barrier instead of after it (64 sites)
# speedup vs baseline: 1.0102x; 1.0102x over previous
; #define PG8_STAGE(bufoff, gbase, voff) do { _Pragma("unroll") for (int _i = 0; _i < 2; ++_i) \
;         __builtin_amdgcn_global_load_lds((const unsigned*)((const char*)(gbase) + (voff)[_i]), (LAS unsigned*)(lds + (bufoff) + ldsw + _i * 8192), 16, 0, 0); } while (0)
; #define PG8_LDA(dst, b, h) do { _Pragma("unroll") for (int m = 0; m < 4; ++m) _Pragma("unroll") for (int k = 0; k < 2; ++k) dst[m][k] = *(const LAS bf16x8*)(lds + PG8_SA(b, h) + aoff + m * 2048 + k * 1024); } while (0)
; #define PG8_LDB(dst, b, h) do { _Pragma("unroll") for (int n = 0; n < 2; ++n) _Pragma("unroll") for (int k = 0; k < 2; ++k) dst[n][k] = *(const LAS bf16x8*)(lds + PG8_SB(b, h) + boff + n * 2048 + k * 1024); } while (0)
; #define PG8_MMA(ai, bj, At, Bt) do { __builtin_amdgcn_s_setprio(1); _Pragma("unroll") for (int k = 0; k < 2; ++k) _Pragma("unroll") for (int m = 0; m < 4; ++m) _Pragma("unroll") for (int n = 0; n < 2; ++n) \
;         acc[ai][bj][m][n] = __builtin_amdgcn_mfma_f32_16x16x32_bf16(Bt[n][k], At[m][k], acc[ai][bj][m][n], 0, 0, 0); __builtin_amdgcn_s_setprio(0); } while (0)
; template <class Epi, bool ALIGN_EPI>
; __device__ __forceinline__ void gemm_phase(LAS unsigned char* lds, const Gemm g, const StaticOrder& S, const Epi& E, const int tid) {
;     ...
;     for (;;) {
;         const bool has_next = S.next(ui + 1, nxt);
;         const char* nA = has_next ? (const char*)g.A + (size_t)nxt.pm * tA + (size_t)nxt.pn * g.apn * 2 : cA; const char* nB = has_next ? (const char*)g.Bt + (size_t)nxt.pn * tB : cB;
;         for (int t = 0; t < nt; t += 2) {
;             const bool last = (t == nt - 2);
;             const char* a1 = cA + (size_t)(t + 1) * kstep;
;             const char* a2 = last ? nA : cA + (size_t)(t + 2) * kstep; const char* b2 = last ? nB : cB + (size_t)(t + 2) * kstep;
;             const char* a3 = a2 + kstep; const char* b3 = b2 + kstep;
;             PG8_LDB(B0, 0, 0); PG8_LDB(B1, 0, 1); PG8_SCHED; PG8_LDA(At, 0, 0); PG8_STAGE(PG8_SA(1, 1), a1 + hA, voffA);
;             PG8_WAIT_V(8); PG8_WAIT_L(0); PG8_BAR; PG8_MMA(0, 0, At, B0); PG8_MMA(0, 1, At, B1); PG8_BAR; PG8_SCHED;
;             PG8_LDA(At, 0, 1); PG8_STAGE(PG8_SB(0, 0), b2, voffB); PG8_STAGE(PG8_SB(0, 1), b2 + hB, voffB); PG8_STAGE(PG8_SA(0, 0), a2, voffA);
;             PG8_WAIT_V(8); PG8_WAIT_L(0); PG8_BAR; PG8_MMA(1, 0, At, B0); PG8_MMA(1, 1, At, B1); PG8_BAR; PG8_SCHED;
.LBB0_234:
	s_andn2_b64 vcc, exec, s[36:37]
	s_waitcnt lgkmcnt(0)
	s_cbranch_vccnz .LBB0_238
	s_add_u32 s12, s46, 0x100
	v_lshl_add_u64 v[128:129], v[128:129], 0, s[92:93]
	s_addc_u32 s13, s47, 0
	s_mov_b32 s46, 0
	s_add_i32 s47, s46, 2
	s_cmp_eq_u32 s60, s46
	s_cselect_b64 vcc, -1, 0
	s_cselect_b32 s71, s15, s13
	s_cselect_b32 s70, s14, s12
	s_add_i32 s46, 0, 0x14000
	v_lshl_add_u64 v[130:131], v[128:129], 0, s[92:93]
	v_add_u32_e32 v142, s33, v218
	v_add_u32_e32 v166, s46, v218
	v_cndmask_b32_e32 v159, v131, v165, vcc
	v_cndmask_b32_e32 v158, v130, v164, vcc
	ds_read_b128 v[130:133], v142
	ds_read_b128 v[134:137], v142 offset:1024
	ds_read_b128 v[138:141], v142 offset:2048
	ds_read_b128 v[142:145], v142 offset:3072
	ds_read_b128 v[146:149], v166
	ds_read_b128 v[150:153], v166 offset:1024
	ds_read_b128 v[154:157], v166 offset:2048
	ds_read_b128 v[186:189], v166 offset:3072
	v_lshl_add_u64 v[166:167], v[128:129], 0, v[160:161]
	s_add_i32 m0, s53, 0xc000
	ds_read_b128 v[190:193], v219
	ds_read_b128 v[194:197], v219 offset:1024
	ds_read_b128 v[198:201], v219 offset:2048
	ds_read_b128 v[202:205], v219 offset:3072
	ds_read_b128 v[206:209], v219 offset:4096
	ds_read_b128 v[210:213], v219 offset:5120
	ds_read_b128 v[240:243], v219 offset:6144
	ds_read_b128 v[244:247], v219 offset:7168
	global_load_lds_dwordx4 v[166:167], off
	v_lshl_add_u64 v[166:167], v[128:129], 0, v[162:163]
	s_add_i32 m0, s53, 0xe000
	s_nop 0
	global_load_lds_dwordx4 v[166:167], off
	s_waitcnt vmcnt(8)
	s_waitcnt lgkmcnt(0)
	s_setprio 1
	s_barrier
	s_waitcnt lgkmcnt(0)
	v_mfma_f32_16x16x32_bf16 v[120:123], v[130:133], v[190:193], 0
	v_mfma_f32_16x16x32_bf16 v[124:127], v[138:141], v[190:193], 0
	v_mfma_f32_16x16x32_bf16 v[108:111], v[130:133], v[198:201], 0
	v_mfma_f32_16x16x32_bf16 v[104:107], v[138:141], v[198:201], 0
	v_mfma_f32_16x16x32_bf16 v[92:95], v[130:133], v[206:209], 0
	v_mfma_f32_16x16x32_bf16 v[88:91], v[138:141], v[206:209], 0
	v_mfma_f32_16x16x32_bf16 v[76:79], v[130:133], v[240:243], 0
	v_mfma_f32_16x16x32_bf16 v[72:75], v[138:141], v[240:243], 0
	v_mfma_f32_16x16x32_bf16 v[120:123], v[134:137], v[194:197], v[120:123]
	v_mfma_f32_16x16x32_bf16 v[124:127], v[142:145], v[194:197], v[124:127]
	v_mfma_f32_16x16x32_bf16 v[108:111], v[134:137], v[202:205], v[108:111]
	v_mfma_f32_16x16x32_bf16 v[104:107], v[142:145], v[202:205], v[104:107]
	v_mfma_f32_16x16x32_bf16 v[92:95], v[134:137], v[210:213], v[92:95]
	v_mfma_f32_16x16x32_bf16 v[88:91], v[142:145], v[210:213], v[88:91]
	v_mfma_f32_16x16x32_bf16 v[76:79], v[134:137], v[244:247], v[76:79]
	v_mfma_f32_16x16x32_bf16 v[72:75], v[142:145], v[244:247], v[72:75]
	s_setprio 0
	s_setprio 1
	v_mfma_f32_16x16x32_bf16 v[116:119], v[146:149], v[190:193], 0
	v_mfma_f32_16x16x32_bf16 v[112:115], v[154:157], v[190:193], 0
	v_mfma_f32_16x16x32_bf16 v[100:103], v[146:149], v[198:201], 0
	v_mfma_f32_16x16x32_bf16 v[96:99], v[154:157], v[198:201], 0
	v_mfma_f32_16x16x32_bf16 v[84:87], v[146:149], v[206:209], 0
	v_mfma_f32_16x16x32_bf16 v[80:83], v[154:157], v[206:209], 0
	v_mfma_f32_16x16x32_bf16 v[68:71], v[146:149], v[240:243], 0
	v_mfma_f32_16x16x32_bf16 v[64:67], v[154:157], v[240:243], 0
	v_mfma_f32_16x16x32_bf16 v[116:119], v[150:153], v[194:197], v[116:119]
	v_mfma_f32_16x16x32_bf16 v[112:115], v[186:189], v[194:197], v[112:115]
	v_mfma_f32_16x16x32_bf16 v[100:103], v[150:153], v[202:205], v[100:103]
	v_mfma_f32_16x16x32_bf16 v[96:99], v[186:189], v[202:205], v[96:99]
	v_mfma_f32_16x16x32_bf16 v[84:87], v[150:153], v[210:213], v[84:87]
	v_mfma_f32_16x16x32_bf16 v[80:83], v[186:189], v[210:213], v[80:83]
	v_mfma_f32_16x16x32_bf16 v[68:71], v[150:153], v[244:247], v[68:71]
	v_mfma_f32_16x16x32_bf16 v[64:67], v[186:189], v[244:247], v[64:67]
	s_setprio 0
	s_barrier
	s_add_i32 s72, s33, s52
	v_lshl_add_u64 v[166:167], s[70:71], 0, v[180:181]
	s_mov_b32 m0, s72
	ds_read_b128 v[190:193], v219 offset:16384
	ds_read_b128 v[194:197], v219 offset:17408
	ds_read_b128 v[198:201], v219 offset:18432
	ds_read_b128 v[202:205], v219 offset:19456
	ds_read_b128 v[206:209], v219 offset:20480
	ds_read_b128 v[210:213], v219 offset:21504
	ds_read_b128 v[240:243], v219 offset:22528
	ds_read_b128 v[244:247], v219 offset:23552
	global_load_lds_dwordx4 v[166:167], off
	s_add_i32 m0, s72, 0x2000
	v_lshl_add_u64 v[214:215], s[70:71], 0, v[184:185]
	s_add_u32 s70, s70, s49
	s_addc_u32 s71, s71, 0
	s_add_i32 s46, s46, s52
	global_load_lds_dwordx4 v[214:215], off
	v_lshl_add_u64 v[220:221], s[70:71], 0, v[180:181]
	s_mov_b32 m0, s46
	v_lshl_add_u64 v[226:227], s[70:71], 0, v[184:185]
	global_load_lds_dwordx4 v[220:221], off
	s_add_i32 m0, s46, 0x2000
	v_lshl_add_u64 v[248:249], v[158:159], 0, v[178:179]
	global_load_lds_dwordx4 v[226:227], off
	s_mov_b32 m0, s53
	v_lshl_add_u64 v[250:251], v[158:159], 0, v[182:183]
	global_load_lds_dwordx4 v[248:249], off
	s_mov_b32 m0, s54
	s_nop 0
	global_load_lds_dwordx4 v[250:251], off
	s_waitcnt vmcnt(8)
	s_waitcnt lgkmcnt(0)
	s_setprio 1
	s_barrier
; #define PG8_STAGE(bufoff, gbase, voff) do { _Pragma("unroll") for (int _i = 0; _i < 2; ++_i) \
;         __builtin_amdgcn_global_load_lds((const unsigned*)((const char*)(gbase) + (voff)[_i]), (LAS unsigned*)(lds + (bufoff) + ldsw + _i * 8192), 16, 0, 0); } while (0)
; #define PG8_LDA(dst, b, h) do { _Pragma("unroll") for (int m = 0; m < 4; ++m) _Pragma("unroll") for (int k = 0; k < 2; ++k) dst[m][k] = *(const LAS bf16x8*)(lds + PG8_SA(b, h) + aoff + m * 2048 + k * 1024); } while (0)
; #define PG8_LDB(dst, b, h) do { _Pragma("unroll") for (int n = 0; n < 2; ++n) _Pragma("unroll") for (int k = 0; k < 2; ++k) dst[n][k] = *(const LAS bf16x8*)(lds + PG8_SB(b, h) + boff + n * 2048 + k * 1024); } while (0)
; #define PG8_MMA(ai, bj, At, Bt) do { __builtin_amdgcn_s_setprio(1); _Pragma("unroll") for (int k = 0; k < 2; ++k) _Pragma("unroll") for (int m = 0; m < 4; ++m) _Pragma("unroll") for (int n = 0; n < 2; ++n) \
;         acc[ai][bj][m][n] = __builtin_amdgcn_mfma_f32_16x16x32_bf16(Bt[n][k], At[m][k], acc[ai][bj][m][n], 0, 0, 0); __builtin_amdgcn_s_setprio(0); } while (0)
; #define PG8_WAIT_V(n) asm volatile("s_waitcnt vmcnt(" #n ")" ::: "memory")
; #define PG8_WAIT_L(n) asm volatile("s_waitcnt lgkmcnt(" #n ")" ::: "memory")
; #define PG8_BAR __builtin_amdgcn_s_barrier()
; #define PG8_SCHED __builtin_amdgcn_sched_barrier(0)
; template <class Epi, bool ALIGN_EPI>
; __device__ __forceinline__ void gemm_phase(LAS unsigned char* lds, const Gemm g, const StaticOrder& S, const Epi& E, const int tid) {
;     ...
;             PG8_WAIT_V(8); PG8_WAIT_L(0); PG8_BAR; PG8_MMA(1, 0, At, B0); PG8_MMA(1, 1, At, B1); PG8_BAR; PG8_SCHED;
;             PG8_LDB(B0, 1, 0); PG8_LDB(B1, 1, 1); PG8_SCHED; PG8_LDA(At, 1, 0); PG8_STAGE(PG8_SA(0, 1), a2 + hA, voffA);
;             PG8_WAIT_V(8); PG8_WAIT_L(0); PG8_BAR; PG8_MMA(0, 0, At, B0); PG8_MMA(0, 1, At, B1); PG8_BAR; PG8_SCHED;
	s_waitcnt lgkmcnt(0)
	v_mfma_f32_16x16x32_bf16 v[60:63], v[130:133], v[190:193], 0
	v_mfma_f32_16x16x32_bf16 v[56:59], v[138:141], v[190:193], 0
	v_mfma_f32_16x16x32_bf16 v[44:47], v[130:133], v[198:201], 0
	v_mfma_f32_16x16x32_bf16 v[40:43], v[138:141], v[198:201], 0
	v_mfma_f32_16x16x32_bf16 v[28:31], v[130:133], v[206:209], 0
	v_mfma_f32_16x16x32_bf16 v[24:27], v[138:141], v[206:209], 0
	v_mfma_f32_16x16x32_bf16 v[12:15], v[130:133], v[240:243], 0
	v_mfma_f32_16x16x32_bf16 v[8:11], v[138:141], v[240:243], 0
	v_mfma_f32_16x16x32_bf16 v[60:63], v[134:137], v[194:197], v[60:63]
	v_mfma_f32_16x16x32_bf16 v[56:59], v[142:145], v[194:197], v[56:59]
	v_mfma_f32_16x16x32_bf16 v[44:47], v[134:137], v[202:205], v[44:47]
	v_mfma_f32_16x16x32_bf16 v[40:43], v[142:145], v[202:205], v[40:43]
	v_mfma_f32_16x16x32_bf16 v[28:31], v[134:137], v[210:213], v[28:31]
	v_mfma_f32_16x16x32_bf16 v[24:27], v[142:145], v[210:213], v[24:27]
	v_mfma_f32_16x16x32_bf16 v[12:15], v[134:137], v[244:247], v[12:15]
	v_mfma_f32_16x16x32_bf16 v[8:11], v[142:145], v[244:247], v[8:11]
	s_setprio 0
	s_setprio 1
	v_mfma_f32_16x16x32_bf16 v[52:55], v[146:149], v[190:193], 0
	v_mfma_f32_16x16x32_bf16 v[48:51], v[154:157], v[190:193], 0
	v_mfma_f32_16x16x32_bf16 v[36:39], v[146:149], v[198:201], 0
	v_mfma_f32_16x16x32_bf16 v[32:35], v[154:157], v[198:201], 0
	v_mfma_f32_16x16x32_bf16 v[20:23], v[146:149], v[206:209], 0
	v_mfma_f32_16x16x32_bf16 v[16:19], v[154:157], v[206:209], 0
	v_mfma_f32_16x16x32_bf16 v[4:7], v[146:149], v[240:243], 0
	v_mfma_f32_16x16x32_bf16 v[0:3], v[154:157], v[240:243], 0
	v_mfma_f32_16x16x32_bf16 v[52:55], v[150:153], v[194:197], v[52:55]
	v_mfma_f32_16x16x32_bf16 v[48:51], v[186:189], v[194:197], v[48:51]
	v_mfma_f32_16x16x32_bf16 v[36:39], v[150:153], v[202:205], v[36:39]
	v_mfma_f32_16x16x32_bf16 v[32:35], v[186:189], v[202:205], v[32:35]
	v_mfma_f32_16x16x32_bf16 v[20:23], v[150:153], v[210:213], v[20:23]
	v_mfma_f32_16x16x32_bf16 v[16:19], v[186:189], v[210:213], v[16:19]
	v_mfma_f32_16x16x32_bf16 v[4:7], v[150:153], v[244:247], v[4:7]
	v_mfma_f32_16x16x32_bf16 v[0:3], v[186:189], v[244:247], v[0:3]
	s_setprio 0
	s_barrier
	s_add_i32 s46, 0, 0x18000
	s_add_i32 s70, 0, 0x1c000
	v_add_u32_e32 v142, s46, v218
	v_add_u32_e32 v168, s70, v218
	ds_read_b128 v[130:133], v142
	ds_read_b128 v[134:137], v142 offset:1024
	ds_read_b128 v[138:141], v142 offset:2048
	ds_read_b128 v[142:145], v142 offset:3072
	ds_read_b128 v[146:149], v168
	ds_read_b128 v[150:153], v168 offset:1024
	ds_read_b128 v[154:157], v168 offset:2048
	ds_read_b128 v[186:189], v168 offset:3072
	v_lshl_add_u64 v[158:159], v[158:159], 0, s[94:95]
	s_mov_b32 m0, s55
	v_lshl_add_u64 v[252:253], v[158:159], 0, v[178:179]
	ds_read_b128 v[190:193], v219 offset:32768
	ds_read_b128 v[194:197], v219 offset:33792
	ds_read_b128 v[198:201], v219 offset:34816
	ds_read_b128 v[202:205], v219 offset:35840
	ds_read_b128 v[206:209], v219 offset:36864
	ds_read_b128 v[210:213], v219 offset:37888
	ds_read_b128 v[240:243], v219 offset:38912
	ds_read_b128 v[244:247], v219 offset:39936
	global_load_lds_dwordx4 v[252:253], off
	v_lshl_add_u64 v[158:159], v[158:159], 0, v[182:183]
	s_mov_b32 m0, s56
	s_nop 0
	global_load_lds_dwordx4 v[158:159], off
	s_waitcnt vmcnt(8)
	s_waitcnt lgkmcnt(0)
	s_setprio 1
	s_barrier
	s_waitcnt lgkmcnt(0)
	v_mfma_f32_16x16x32_bf16 v[120:123], v[130:133], v[190:193], v[120:123]
	v_mfma_f32_16x16x32_bf16 v[124:127], v[138:141], v[190:193], v[124:127]
	v_mfma_f32_16x16x32_bf16 v[108:111], v[130:133], v[198:201], v[108:111]
	v_mfma_f32_16x16x32_bf16 v[104:107], v[138:141], v[198:201], v[104:107]
	v_mfma_f32_16x16x32_bf16 v[92:95], v[130:133], v[206:209], v[92:95]
	v_mfma_f32_16x16x32_bf16 v[88:91], v[138:141], v[206:209], v[88:91]
	v_mfma_f32_16x16x32_bf16 v[76:79], v[130:133], v[240:243], v[76:79]
	v_mfma_f32_16x16x32_bf16 v[72:75], v[138:141], v[240:243], v[72:75]
	v_mfma_f32_16x16x32_bf16 v[120:123], v[134:137], v[194:197], v[120:123]
	v_mfma_f32_16x16x32_bf16 v[124:127], v[142:145], v[194:197], v[124:127]
	v_mfma_f32_16x16x32_bf16 v[108:111], v[134:137], v[202:205], v[108:111]
	v_mfma_f32_16x16x32_bf16 v[104:107], v[142:145], v[202:205], v[104:107]
	v_mfma_f32_16x16x32_bf16 v[92:95], v[134:137], v[210:213], v[92:95]
	v_mfma_f32_16x16x32_bf16 v[88:91], v[142:145], v[210:213], v[88:91]
	v_mfma_f32_16x16x32_bf16 v[76:79], v[134:137], v[244:247], v[76:79]
	v_mfma_f32_16x16x32_bf16 v[72:75], v[142:145], v[244:247], v[72:75]
	s_setprio 0
	s_setprio 1
	v_mfma_f32_16x16x32_bf16 v[116:119], v[146:149], v[190:193], v[116:119]
	v_mfma_f32_16x16x32_bf16 v[112:115], v[154:157], v[190:193], v[112:115]
	v_mfma_f32_16x16x32_bf16 v[100:103], v[146:149], v[198:201], v[100:103]
	v_mfma_f32_16x16x32_bf16 v[96:99], v[154:157], v[198:201], v[96:99]
	v_mfma_f32_16x16x32_bf16 v[84:87], v[146:149], v[206:209], v[84:87]
	v_mfma_f32_16x16x32_bf16 v[80:83], v[154:157], v[206:209], v[80:83]
	v_mfma_f32_16x16x32_bf16 v[68:71], v[146:149], v[240:243], v[68:71]
	v_mfma_f32_16x16x32_bf16 v[64:67], v[154:157], v[240:243], v[64:67]
	v_mfma_f32_16x16x32_bf16 v[116:119], v[150:153], v[194:197], v[116:119]
	v_mfma_f32_16x16x32_bf16 v[112:115], v[186:189], v[194:197], v[112:115]
	v_mfma_f32_16x16x32_bf16 v[100:103], v[150:153], v[202:205], v[100:103]
	v_mfma_f32_16x16x32_bf16 v[96:99], v[186:189], v[202:205], v[96:99]
	v_mfma_f32_16x16x32_bf16 v[84:87], v[150:153], v[210:213], v[84:87]
	v_mfma_f32_16x16x32_bf16 v[80:83], v[186:189], v[210:213], v[80:83]
	v_mfma_f32_16x16x32_bf16 v[68:71], v[150:153], v[244:247], v[68:71]
	v_mfma_f32_16x16x32_bf16 v[64:67], v[186:189], v[244:247], v[64:67]
	s_setprio 0
	s_barrier
; #define PG8_STAGE(bufoff, gbase, voff) do { _Pragma("unroll") for (int _i = 0; _i < 2; ++_i) \
;         __builtin_amdgcn_global_load_lds((const unsigned*)((const char*)(gbase) + (voff)[_i]), (LAS unsigned*)(lds + (bufoff) + ldsw + _i * 8192), 16, 0, 0); } while (0)
; #define PG8_LDA(dst, b, h) do { _Pragma("unroll") for (int m = 0; m < 4; ++m) _Pragma("unroll") for (int k = 0; k < 2; ++k) dst[m][k] = *(const LAS bf16x8*)(lds + PG8_SA(b, h) + aoff + m * 2048 + k * 1024); } while (0)
; #define PG8_LDB(dst, b, h) do { _Pragma("unroll") for (int n = 0; n < 2; ++n) _Pragma("unroll") for (int k = 0; k < 2; ++k) dst[n][k] = *(const LAS bf16x8*)(lds + PG8_SB(b, h) + boff + n * 2048 + k * 1024); } while (0)
; #define PG8_WAIT_V(n) asm volatile("s_waitcnt vmcnt(" #n ")" ::: "memory")
; #define PG8_BAR __builtin_amdgcn_s_barrier()
; template <class Epi, bool ALIGN_EPI>
; __device__ __forceinline__ void gemm_phase(LAS unsigned char* lds, const Gemm g, const StaticOrder& S, const Epi& E, const int tid) {
;     ...
;         for (int t = 0; t < nt; t += 2) {
;             const bool last = (t == nt - 2);
;             const char* a1 = cA + (size_t)(t + 1) * kstep;
;             const char* a2 = last ? nA : cA + (size_t)(t + 2) * kstep; const char* b2 = last ? nB : cB + (size_t)(t + 2) * kstep;
;             const char* a3 = a2 + kstep; const char* b3 = b2 + kstep;
;             PG8_LDB(B0, 0, 0); PG8_LDB(B1, 0, 1); PG8_SCHED; PG8_LDA(At, 0, 0); PG8_STAGE(PG8_SA(1, 1), a1 + hA, voffA);
;             PG8_WAIT_V(8); PG8_WAIT_L(0); PG8_BAR; PG8_MMA(0, 0, At, B0); PG8_MMA(0, 1, At, B1); PG8_BAR; PG8_SCHED;
;             PG8_LDA(At, 0, 1); PG8_STAGE(PG8_SB(0, 0), b2, voffB); PG8_STAGE(PG8_SB(0, 1), b2 + hB, voffB); PG8_STAGE(PG8_SA(0, 0), a2, voffA);
;             PG8_WAIT_V(8); PG8_WAIT_L(0); PG8_BAR; PG8_MMA(1, 0, At, B0); PG8_MMA(1, 1, At, B1); PG8_BAR; PG8_SCHED;
;             PG8_LDB(B0, 1, 0); PG8_LDB(B1, 1, 1); PG8_SCHED; PG8_LDA(At, 1, 0); PG8_STAGE(PG8_SA(0, 1), a2 + hA, voffA);
;             PG8_WAIT_V(8); PG8_WAIT_L(0); PG8_BAR; PG8_MMA(0, 0, At, B0); PG8_MMA(0, 1, At, B1); PG8_BAR; PG8_SCHED;
;             PG8_LDA(At, 1, 1); PG8_STAGE(PG8_SB(1, 0), b3, voffB); PG8_STAGE(PG8_SB(1, 1), b3 + hB, voffB); PG8_STAGE(PG8_SA(1, 0), a3, voffA);
;             PG8_WAIT_V(8); PG8_WAIT_L(0); PG8_BAR; PG8_MMA(1, 0, At, B0); PG8_MMA(1, 1, At, B1); PG8_BAR; PG8_SCHED;
	s_add_i32 s46, s46, s52
	v_lshl_add_u64 v[158:159], v[166:167], 0, s[92:93]
	s_mov_b32 m0, s46
	ds_read_b128 v[190:193], v219 offset:49152
	ds_read_b128 v[194:197], v219 offset:50176
	ds_read_b128 v[198:201], v219 offset:51200
	ds_read_b128 v[202:205], v219 offset:52224
	ds_read_b128 v[206:209], v219 offset:53248
	ds_read_b128 v[210:213], v219 offset:54272
	ds_read_b128 v[240:243], v219 offset:55296
	ds_read_b128 v[244:247], v219 offset:56320
	global_load_lds_dwordx4 v[158:159], off
	v_lshl_add_u64 v[158:159], v[214:215], 0, s[92:93]
	s_add_i32 m0, s46, 0x2000
	s_add_i32 s46, s70, s52
	global_load_lds_dwordx4 v[158:159], off
	v_lshl_add_u64 v[158:159], v[220:221], 0, s[92:93]
	s_mov_b32 m0, s46
	s_nop 0
	global_load_lds_dwordx4 v[158:159], off
	v_lshl_add_u64 v[158:159], v[226:227], 0, s[92:93]
	s_add_i32 m0, s46, 0x2000
	s_nop 0
	global_load_lds_dwordx4 v[158:159], off
	v_lshl_add_u64 v[158:159], v[248:249], 0, s[92:93]
	s_mov_b32 m0, s57
	s_nop 0
	global_load_lds_dwordx4 v[158:159], off
	v_lshl_add_u64 v[158:159], v[250:251], 0, s[92:93]
	s_mov_b32 m0, s58
	s_nop 0
	global_load_lds_dwordx4 v[158:159], off
	s_waitcnt vmcnt(8)
	s_waitcnt lgkmcnt(0)
	s_setprio 1
	s_barrier
	s_waitcnt lgkmcnt(0)
	v_mfma_f32_16x16x32_bf16 v[60:63], v[130:133], v[190:193], v[60:63]
	v_mfma_f32_16x16x32_bf16 v[56:59], v[138:141], v[190:193], v[56:59]
	v_mfma_f32_16x16x32_bf16 v[44:47], v[130:133], v[198:201], v[44:47]
	v_mfma_f32_16x16x32_bf16 v[40:43], v[138:141], v[198:201], v[40:43]
	v_mfma_f32_16x16x32_bf16 v[28:31], v[130:133], v[206:209], v[28:31]
	v_mfma_f32_16x16x32_bf16 v[24:27], v[138:141], v[206:209], v[24:27]
	v_mfma_f32_16x16x32_bf16 v[12:15], v[130:133], v[240:243], v[12:15]
	v_mfma_f32_16x16x32_bf16 v[8:11], v[138:141], v[240:243], v[8:11]
	v_mfma_f32_16x16x32_bf16 v[60:63], v[134:137], v[194:197], v[60:63]
	v_mfma_f32_16x16x32_bf16 v[56:59], v[142:145], v[194:197], v[56:59]
	v_mfma_f32_16x16x32_bf16 v[44:47], v[134:137], v[202:205], v[44:47]
	v_mfma_f32_16x16x32_bf16 v[40:43], v[142:145], v[202:205], v[40:43]
	v_mfma_f32_16x16x32_bf16 v[28:31], v[134:137], v[210:213], v[28:31]
	v_mfma_f32_16x16x32_bf16 v[24:27], v[142:145], v[210:213], v[24:27]
	v_mfma_f32_16x16x32_bf16 v[12:15], v[134:137], v[244:247], v[12:15]
	v_mfma_f32_16x16x32_bf16 v[8:11], v[142:145], v[244:247], v[8:11]
	s_setprio 0
	s_setprio 1
	v_mfma_f32_16x16x32_bf16 v[52:55], v[146:149], v[190:193], v[52:55]
	v_mfma_f32_16x16x32_bf16 v[48:51], v[154:157], v[190:193], v[48:51]
	v_mfma_f32_16x16x32_bf16 v[36:39], v[146:149], v[198:201], v[36:39]
	v_mfma_f32_16x16x32_bf16 v[32:35], v[154:157], v[198:201], v[32:35]
	v_mfma_f32_16x16x32_bf16 v[20:23], v[146:149], v[206:209], v[20:23]
	v_mfma_f32_16x16x32_bf16 v[16:19], v[154:157], v[206:209], v[16:19]
	v_mfma_f32_16x16x32_bf16 v[4:7], v[146:149], v[240:243], v[4:7]
	v_mfma_f32_16x16x32_bf16 v[0:3], v[154:157], v[240:243], v[0:3]
	v_mfma_f32_16x16x32_bf16 v[52:55], v[150:153], v[194:197], v[52:55]
	v_mfma_f32_16x16x32_bf16 v[48:51], v[186:189], v[194:197], v[48:51]
	v_mfma_f32_16x16x32_bf16 v[36:39], v[150:153], v[202:205], v[36:39]
	v_mfma_f32_16x16x32_bf16 v[32:35], v[186:189], v[202:205], v[32:35]
	v_mfma_f32_16x16x32_bf16 v[20:23], v[150:153], v[210:213], v[20:23]
	v_mfma_f32_16x16x32_bf16 v[16:19], v[186:189], v[210:213], v[16:19]
	v_mfma_f32_16x16x32_bf16 v[4:7], v[150:153], v[244:247], v[4:7]
	v_mfma_f32_16x16x32_bf16 v[0:3], v[186:189], v[244:247], v[0:3]
	s_setprio 0
	s_barrier
	s_add_u32 s12, s12, 0x100
	s_addc_u32 s13, s13, 0
	v_lshl_add_u64 v[128:129], v[128:129], 0, s[80:81]
	s_cmp_ge_u32 s47, s48
	s_mov_b32 s46, s47
	s_cbranch_scc1 .Lpl1_after
.LBB0_236:
	s_add_i32 s47, s46, 2
	s_cmp_eq_u32 s60, s46
	s_cselect_b64 vcc, -1, 0
	s_cselect_b32 s71, s15, s13
	s_cselect_b32 s70, s14, s12
	s_add_i32 s46, 0, 0x14000
	v_lshl_add_u64 v[130:131], v[128:129], 0, s[92:93]
	v_add_u32_e32 v142, s33, v218
	v_add_u32_e32 v166, s46, v218
	v_cndmask_b32_e32 v159, v131, v165, vcc
	v_cndmask_b32_e32 v158, v130, v164, vcc
	ds_read_b128 v[130:133], v142
	ds_read_b128 v[134:137], v142 offset:1024
	ds_read_b128 v[138:141], v142 offset:2048
	ds_read_b128 v[142:145], v142 offset:3072
	ds_read_b128 v[146:149], v166
	ds_read_b128 v[150:153], v166 offset:1024
	ds_read_b128 v[154:157], v166 offset:2048
	ds_read_b128 v[186:189], v166 offset:3072
	v_lshl_add_u64 v[166:167], v[128:129], 0, v[160:161]
	s_add_i32 m0, s53, 0xc000
	ds_read_b128 v[190:193], v219
	ds_read_b128 v[194:197], v219 offset:1024
	ds_read_b128 v[198:201], v219 offset:2048
	ds_read_b128 v[202:205], v219 offset:3072
	ds_read_b128 v[206:209], v219 offset:4096
	ds_read_b128 v[210:213], v219 offset:5120
	ds_read_b128 v[240:243], v219 offset:6144
	ds_read_b128 v[244:247], v219 offset:7168
	global_load_lds_dwordx4 v[166:167], off
	v_lshl_add_u64 v[166:167], v[128:129], 0, v[162:163]
	s_add_i32 m0, s53, 0xe000
	s_nop 0
	global_load_lds_dwordx4 v[166:167], off
	s_waitcnt vmcnt(8)
	s_waitcnt lgkmcnt(0)
	s_setprio 1
	s_barrier
; #define PG8_STAGE(bufoff, gbase, voff) do { _Pragma("unroll") for (int _i = 0; _i < 2; ++_i) \
;         __builtin_amdgcn_global_load_lds((const unsigned*)((const char*)(gbase) + (voff)[_i]), (LAS unsigned*)(lds + (bufoff) + ldsw + _i * 8192), 16, 0, 0); } while (0)
; #define PG8_LDA(dst, b, h) do { _Pragma("unroll") for (int m = 0; m < 4; ++m) _Pragma("unroll") for (int k = 0; k < 2; ++k) dst[m][k] = *(const LAS bf16x8*)(lds + PG8_SA(b, h) + aoff + m * 2048 + k * 1024); } while (0)
; #define PG8_LDB(dst, b, h) do { _Pragma("unroll") for (int n = 0; n < 2; ++n) _Pragma("unroll") for (int k = 0; k < 2; ++k) dst[n][k] = *(const LAS bf16x8*)(lds + PG8_SB(b, h) + boff + n * 2048 + k * 1024); } while (0)
; #define PG8_MMA(ai, bj, At, Bt) do { __builtin_amdgcn_s_setprio(1); _Pragma("unroll") for (int k = 0; k < 2; ++k) _Pragma("unroll") for (int m = 0; m < 4; ++m) _Pragma("unroll") for (int n = 0; n < 2; ++n) \
;         acc[ai][bj][m][n] = __builtin_amdgcn_mfma_f32_16x16x32_bf16(Bt[n][k], At[m][k], acc[ai][bj][m][n], 0, 0, 0); __builtin_amdgcn_s_setprio(0); } while (0)
; #define PG8_WAIT_V(n) asm volatile("s_waitcnt vmcnt(" #n ")" ::: "memory")
; #define PG8_WAIT_L(n) asm volatile("s_waitcnt lgkmcnt(" #n ")" ::: "memory")
; #define PG8_BAR __builtin_amdgcn_s_barrier()
; #define PG8_SCHED __builtin_amdgcn_sched_barrier(0)
; template <class Epi, bool ALIGN_EPI>
; __device__ __forceinline__ void gemm_phase(LAS unsigned char* lds, const Gemm g, const StaticOrder& S, const Epi& E, const int tid) {
;     ...
;             PG8_LDB(B0, 0, 0); PG8_LDB(B1, 0, 1); PG8_SCHED; PG8_LDA(At, 0, 0); PG8_STAGE(PG8_SA(1, 1), a1 + hA, voffA);
;             PG8_WAIT_V(8); PG8_WAIT_L(0); PG8_BAR; PG8_MMA(0, 0, At, B0); PG8_MMA(0, 1, At, B1); PG8_BAR; PG8_SCHED;
;             PG8_LDA(At, 0, 1); PG8_STAGE(PG8_SB(0, 0), b2, voffB); PG8_STAGE(PG8_SB(0, 1), b2 + hB, voffB); PG8_STAGE(PG8_SA(0, 0), a2, voffA);
;             PG8_WAIT_V(8); PG8_WAIT_L(0); PG8_BAR; PG8_MMA(1, 0, At, B0); PG8_MMA(1, 1, At, B1); PG8_BAR; PG8_SCHED;
	s_waitcnt lgkmcnt(0)
	v_mfma_f32_16x16x32_bf16 v[120:123], v[130:133], v[190:193], v[120:123]
	v_mfma_f32_16x16x32_bf16 v[124:127], v[138:141], v[190:193], v[124:127]
	v_mfma_f32_16x16x32_bf16 v[108:111], v[130:133], v[198:201], v[108:111]
	v_mfma_f32_16x16x32_bf16 v[104:107], v[138:141], v[198:201], v[104:107]
	v_mfma_f32_16x16x32_bf16 v[92:95], v[130:133], v[206:209], v[92:95]
	v_mfma_f32_16x16x32_bf16 v[88:91], v[138:141], v[206:209], v[88:91]
	v_mfma_f32_16x16x32_bf16 v[76:79], v[130:133], v[240:243], v[76:79]
	v_mfma_f32_16x16x32_bf16 v[72:75], v[138:141], v[240:243], v[72:75]
	v_mfma_f32_16x16x32_bf16 v[120:123], v[134:137], v[194:197], v[120:123]
	v_mfma_f32_16x16x32_bf16 v[124:127], v[142:145], v[194:197], v[124:127]
	v_mfma_f32_16x16x32_bf16 v[108:111], v[134:137], v[202:205], v[108:111]
	v_mfma_f32_16x16x32_bf16 v[104:107], v[142:145], v[202:205], v[104:107]
	v_mfma_f32_16x16x32_bf16 v[92:95], v[134:137], v[210:213], v[92:95]
	v_mfma_f32_16x16x32_bf16 v[88:91], v[142:145], v[210:213], v[88:91]
	v_mfma_f32_16x16x32_bf16 v[76:79], v[134:137], v[244:247], v[76:79]
	v_mfma_f32_16x16x32_bf16 v[72:75], v[142:145], v[244:247], v[72:75]
	s_setprio 0
	s_setprio 1
	v_mfma_f32_16x16x32_bf16 v[116:119], v[146:149], v[190:193], v[116:119]
	v_mfma_f32_16x16x32_bf16 v[112:115], v[154:157], v[190:193], v[112:115]
	v_mfma_f32_16x16x32_bf16 v[100:103], v[146:149], v[198:201], v[100:103]
	v_mfma_f32_16x16x32_bf16 v[96:99], v[154:157], v[198:201], v[96:99]
	v_mfma_f32_16x16x32_bf16 v[84:87], v[146:149], v[206:209], v[84:87]
	v_mfma_f32_16x16x32_bf16 v[80:83], v[154:157], v[206:209], v[80:83]
	v_mfma_f32_16x16x32_bf16 v[68:71], v[146:149], v[240:243], v[68:71]
	v_mfma_f32_16x16x32_bf16 v[64:67], v[154:157], v[240:243], v[64:67]
	v_mfma_f32_16x16x32_bf16 v[116:119], v[150:153], v[194:197], v[116:119]
	v_mfma_f32_16x16x32_bf16 v[112:115], v[186:189], v[194:197], v[112:115]
	v_mfma_f32_16x16x32_bf16 v[100:103], v[150:153], v[202:205], v[100:103]
	v_mfma_f32_16x16x32_bf16 v[96:99], v[186:189], v[202:205], v[96:99]
	v_mfma_f32_16x16x32_bf16 v[84:87], v[150:153], v[210:213], v[84:87]
	v_mfma_f32_16x16x32_bf16 v[80:83], v[186:189], v[210:213], v[80:83]
	v_mfma_f32_16x16x32_bf16 v[68:71], v[150:153], v[244:247], v[68:71]
	v_mfma_f32_16x16x32_bf16 v[64:67], v[186:189], v[244:247], v[64:67]
	s_setprio 0
	s_barrier
	s_add_i32 s72, s33, s52
	v_lshl_add_u64 v[166:167], s[70:71], 0, v[180:181]
	s_mov_b32 m0, s72
	ds_read_b128 v[190:193], v219 offset:16384
	ds_read_b128 v[194:197], v219 offset:17408
	ds_read_b128 v[198:201], v219 offset:18432
	ds_read_b128 v[202:205], v219 offset:19456
	ds_read_b128 v[206:209], v219 offset:20480
	ds_read_b128 v[210:213], v219 offset:21504
	ds_read_b128 v[240:243], v219 offset:22528
	ds_read_b128 v[244:247], v219 offset:23552
	global_load_lds_dwordx4 v[166:167], off
	s_add_i32 m0, s72, 0x2000
	v_lshl_add_u64 v[214:215], s[70:71], 0, v[184:185]
	s_add_u32 s70, s70, s49
	s_addc_u32 s71, s71, 0
	s_add_i32 s46, s46, s52
	global_load_lds_dwordx4 v[214:215], off
	v_lshl_add_u64 v[220:221], s[70:71], 0, v[180:181]
	s_mov_b32 m0, s46
	v_lshl_add_u64 v[226:227], s[70:71], 0, v[184:185]
	global_load_lds_dwordx4 v[220:221], off
	s_add_i32 m0, s46, 0x2000
	v_lshl_add_u64 v[248:249], v[158:159], 0, v[178:179]
	global_load_lds_dwordx4 v[226:227], off
	s_mov_b32 m0, s53
	v_lshl_add_u64 v[250:251], v[158:159], 0, v[182:183]
	global_load_lds_dwordx4 v[248:249], off
	s_mov_b32 m0, s54
	s_nop 0
	global_load_lds_dwordx4 v[250:251], off
	s_waitcnt vmcnt(8)
	s_waitcnt lgkmcnt(0)
	s_setprio 1
	s_barrier
	s_waitcnt lgkmcnt(0)
	v_mfma_f32_16x16x32_bf16 v[60:63], v[130:133], v[190:193], v[60:63]
	v_mfma_f32_16x16x32_bf16 v[56:59], v[138:141], v[190:193], v[56:59]
	v_mfma_f32_16x16x32_bf16 v[44:47], v[130:133], v[198:201], v[44:47]
	v_mfma_f32_16x16x32_bf16 v[40:43], v[138:141], v[198:201], v[40:43]
	v_mfma_f32_16x16x32_bf16 v[28:31], v[130:133], v[206:209], v[28:31]
	v_mfma_f32_16x16x32_bf16 v[24:27], v[138:141], v[206:209], v[24:27]
	v_mfma_f32_16x16x32_bf16 v[12:15], v[130:133], v[240:243], v[12:15]
	v_mfma_f32_16x16x32_bf16 v[8:11], v[138:141], v[240:243], v[8:11]
	v_mfma_f32_16x16x32_bf16 v[60:63], v[134:137], v[194:197], v[60:63]
	v_mfma_f32_16x16x32_bf16 v[56:59], v[142:145], v[194:197], v[56:59]
	v_mfma_f32_16x16x32_bf16 v[44:47], v[134:137], v[202:205], v[44:47]
	v_mfma_f32_16x16x32_bf16 v[40:43], v[142:145], v[202:205], v[40:43]
	v_mfma_f32_16x16x32_bf16 v[28:31], v[134:137], v[210:213], v[28:31]
	v_mfma_f32_16x16x32_bf16 v[24:27], v[142:145], v[210:213], v[24:27]
	v_mfma_f32_16x16x32_bf16 v[12:15], v[134:137], v[244:247], v[12:15]
	v_mfma_f32_16x16x32_bf16 v[8:11], v[142:145], v[244:247], v[8:11]
	s_setprio 0
	s_setprio 1
	v_mfma_f32_16x16x32_bf16 v[52:55], v[146:149], v[190:193], v[52:55]
	v_mfma_f32_16x16x32_bf16 v[48:51], v[154:157], v[190:193], v[48:51]
	v_mfma_f32_16x16x32_bf16 v[36:39], v[146:149], v[198:201], v[36:39]
	v_mfma_f32_16x16x32_bf16 v[32:35], v[154:157], v[198:201], v[32:35]
	v_mfma_f32_16x16x32_bf16 v[20:23], v[146:149], v[206:209], v[20:23]
	v_mfma_f32_16x16x32_bf16 v[16:19], v[154:157], v[206:209], v[16:19]
	v_mfma_f32_16x16x32_bf16 v[4:7], v[146:149], v[240:243], v[4:7]
	v_mfma_f32_16x16x32_bf16 v[0:3], v[154:157], v[240:243], v[0:3]
	v_mfma_f32_16x16x32_bf16 v[52:55], v[150:153], v[194:197], v[52:55]
	v_mfma_f32_16x16x32_bf16 v[48:51], v[186:189], v[194:197], v[48:51]
	v_mfma_f32_16x16x32_bf16 v[36:39], v[150:153], v[202:205], v[36:39]
	v_mfma_f32_16x16x32_bf16 v[32:35], v[186:189], v[202:205], v[32:35]
	v_mfma_f32_16x16x32_bf16 v[20:23], v[150:153], v[210:213], v[20:23]
	v_mfma_f32_16x16x32_bf16 v[16:19], v[186:189], v[210:213], v[16:19]
	v_mfma_f32_16x16x32_bf16 v[4:7], v[150:153], v[244:247], v[4:7]
	v_mfma_f32_16x16x32_bf16 v[0:3], v[186:189], v[244:247], v[0:3]
	s_setprio 0
	s_barrier
; #define PG8_STAGE(bufoff, gbase, voff) do { _Pragma("unroll") for (int _i = 0; _i < 2; ++_i) \
;         __builtin_amdgcn_global_load_lds((const unsigned*)((const char*)(gbase) + (voff)[_i]), (LAS unsigned*)(lds + (bufoff) + ldsw + _i * 8192), 16, 0, 0); } while (0)
; #define PG8_LDA(dst, b, h) do { _Pragma("unroll") for (int m = 0; m < 4; ++m) _Pragma("unroll") for (int k = 0; k < 2; ++k) dst[m][k] = *(const LAS bf16x8*)(lds + PG8_SA(b, h) + aoff + m * 2048 + k * 1024); } while (0)
; #define PG8_LDB(dst, b, h) do { _Pragma("unroll") for (int n = 0; n < 2; ++n) _Pragma("unroll") for (int k = 0; k < 2; ++k) dst[n][k] = *(const LAS bf16x8*)(lds + PG8_SB(b, h) + boff + n * 2048 + k * 1024); } while (0)
; #define PG8_MMA(ai, bj, At, Bt) do { __builtin_amdgcn_s_setprio(1); _Pragma("unroll") for (int k = 0; k < 2; ++k) _Pragma("unroll") for (int m = 0; m < 4; ++m) _Pragma("unroll") for (int n = 0; n < 2; ++n) \
;         acc[ai][bj][m][n] = __builtin_amdgcn_mfma_f32_16x16x32_bf16(Bt[n][k], At[m][k], acc[ai][bj][m][n], 0, 0, 0); __builtin_amdgcn_s_setprio(0); } while (0)
; #define PG8_WAIT_V(n) asm volatile("s_waitcnt vmcnt(" #n ")" ::: "memory")
; #define PG8_WAIT_L(n) asm volatile("s_waitcnt lgkmcnt(" #n ")" ::: "memory")
; #define PG8_BAR __builtin_amdgcn_s_barrier()
; #define PG8_SCHED __builtin_amdgcn_sched_barrier(0)
; template <class Epi, bool ALIGN_EPI>
; __device__ __forceinline__ void gemm_phase(LAS unsigned char* lds, const Gemm g, const StaticOrder& S, const Epi& E, const int tid) {
;     ...
;             PG8_LDB(B0, 1, 0); PG8_LDB(B1, 1, 1); PG8_SCHED; PG8_LDA(At, 1, 0); PG8_STAGE(PG8_SA(0, 1), a2 + hA, voffA);
;             PG8_WAIT_V(8); PG8_WAIT_L(0); PG8_BAR; PG8_MMA(0, 0, At, B0); PG8_MMA(0, 1, At, B1); PG8_BAR; PG8_SCHED;
	s_add_i32 s46, 0, 0x18000
	s_add_i32 s70, 0, 0x1c000
	v_add_u32_e32 v142, s46, v218
	v_add_u32_e32 v168, s70, v218
	ds_read_b128 v[130:133], v142
	ds_read_b128 v[134:137], v142 offset:1024
	ds_read_b128 v[138:141], v142 offset:2048
	ds_read_b128 v[142:145], v142 offset:3072
	ds_read_b128 v[146:149], v168
	ds_read_b128 v[150:153], v168 offset:1024
	ds_read_b128 v[154:157], v168 offset:2048
	ds_read_b128 v[186:189], v168 offset:3072
	v_lshl_add_u64 v[158:159], v[158:159], 0, s[94:95]
	s_mov_b32 m0, s55
	v_lshl_add_u64 v[252:253], v[158:159], 0, v[178:179]
	ds_read_b128 v[190:193], v219 offset:32768
	ds_read_b128 v[194:197], v219 offset:33792
	ds_read_b128 v[198:201], v219 offset:34816
	ds_read_b128 v[202:205], v219 offset:35840
	ds_read_b128 v[206:209], v219 offset:36864
	ds_read_b128 v[210:213], v219 offset:37888
	ds_read_b128 v[240:243], v219 offset:38912
	ds_read_b128 v[244:247], v219 offset:39936
	global_load_lds_dwordx4 v[252:253], off
	v_lshl_add_u64 v[158:159], v[158:159], 0, v[182:183]
	s_mov_b32 m0, s56
	s_nop 0
	global_load_lds_dwordx4 v[158:159], off
	s_waitcnt vmcnt(8)
	s_waitcnt lgkmcnt(0)
	s_setprio 1
	s_barrier
	s_waitcnt lgkmcnt(0)
	v_mfma_f32_16x16x32_bf16 v[120:123], v[130:133], v[190:193], v[120:123]
	v_mfma_f32_16x16x32_bf16 v[124:127], v[138:141], v[190:193], v[124:127]
	v_mfma_f32_16x16x32_bf16 v[108:111], v[130:133], v[198:201], v[108:111]
	v_mfma_f32_16x16x32_bf16 v[104:107], v[138:141], v[198:201], v[104:107]
	v_mfma_f32_16x16x32_bf16 v[92:95], v[130:133], v[206:209], v[92:95]
	v_mfma_f32_16x16x32_bf16 v[88:91], v[138:141], v[206:209], v[88:91]
	v_mfma_f32_16x16x32_bf16 v[76:79], v[130:133], v[240:243], v[76:79]
	v_mfma_f32_16x16x32_bf16 v[72:75], v[138:141], v[240:243], v[72:75]
	v_mfma_f32_16x16x32_bf16 v[120:123], v[134:137], v[194:197], v[120:123]
	v_mfma_f32_16x16x32_bf16 v[124:127], v[142:145], v[194:197], v[124:127]
	v_mfma_f32_16x16x32_bf16 v[108:111], v[134:137], v[202:205], v[108:111]
	v_mfma_f32_16x16x32_bf16 v[104:107], v[142:145], v[202:205], v[104:107]
	v_mfma_f32_16x16x32_bf16 v[92:95], v[134:137], v[210:213], v[92:95]
	v_mfma_f32_16x16x32_bf16 v[88:91], v[142:145], v[210:213], v[88:91]
	v_mfma_f32_16x16x32_bf16 v[76:79], v[134:137], v[244:247], v[76:79]
	v_mfma_f32_16x16x32_bf16 v[72:75], v[142:145], v[244:247], v[72:75]
	s_setprio 0
	s_setprio 1
	v_mfma_f32_16x16x32_bf16 v[116:119], v[146:149], v[190:193], v[116:119]
	v_mfma_f32_16x16x32_bf16 v[112:115], v[154:157], v[190:193], v[112:115]
	v_mfma_f32_16x16x32_bf16 v[100:103], v[146:149], v[198:201], v[100:103]
	v_mfma_f32_16x16x32_bf16 v[96:99], v[154:157], v[198:201], v[96:99]
	v_mfma_f32_16x16x32_bf16 v[84:87], v[146:149], v[206:209], v[84:87]
	v_mfma_f32_16x16x32_bf16 v[80:83], v[154:157], v[206:209], v[80:83]
	v_mfma_f32_16x16x32_bf16 v[68:71], v[146:149], v[240:243], v[68:71]
	v_mfma_f32_16x16x32_bf16 v[64:67], v[154:157], v[240:243], v[64:67]
	v_mfma_f32_16x16x32_bf16 v[116:119], v[150:153], v[194:197], v[116:119]
	v_mfma_f32_16x16x32_bf16 v[112:115], v[186:189], v[194:197], v[112:115]
	v_mfma_f32_16x16x32_bf16 v[100:103], v[150:153], v[202:205], v[100:103]
	v_mfma_f32_16x16x32_bf16 v[96:99], v[186:189], v[202:205], v[96:99]
	v_mfma_f32_16x16x32_bf16 v[84:87], v[150:153], v[210:213], v[84:87]
	v_mfma_f32_16x16x32_bf16 v[80:83], v[186:189], v[210:213], v[80:83]
	v_mfma_f32_16x16x32_bf16 v[68:71], v[150:153], v[244:247], v[68:71]
	v_mfma_f32_16x16x32_bf16 v[64:67], v[186:189], v[244:247], v[64:67]
	s_setprio 0
	s_barrier
; #define PG8_STAGE(bufoff, gbase, voff) do { _Pragma("unroll") for (int _i = 0; _i < 2; ++_i) \
;         __builtin_amdgcn_global_load_lds((const unsigned*)((const char*)(gbase) + (voff)[_i]), (LAS unsigned*)(lds + (bufoff) + ldsw + _i * 8192), 16, 0, 0); } while (0)
; #define PG8_LDA(dst, b, h) do { _Pragma("unroll") for (int m = 0; m < 4; ++m) _Pragma("unroll") for (int k = 0; k < 2; ++k) dst[m][k] = *(const LAS bf16x8*)(lds + PG8_SA(b, h) + aoff + m * 2048 + k * 1024); } while (0)
; #define PG8_MMA(ai, bj, At, Bt) do { __builtin_amdgcn_s_setprio(1); _Pragma("unroll") for (int k = 0; k < 2; ++k) _Pragma("unroll") for (int m = 0; m < 4; ++m) _Pragma("unroll") for (int n = 0; n < 2; ++n) \
;         acc[ai][bj][m][n] = __builtin_amdgcn_mfma_f32_16x16x32_bf16(Bt[n][k], At[m][k], acc[ai][bj][m][n], 0, 0, 0); __builtin_amdgcn_s_setprio(0); } while (0)
; #define PG8_WAIT_V(n) asm volatile("s_waitcnt vmcnt(" #n ")" ::: "memory")
; #define PG8_WAIT_L(n) asm volatile("s_waitcnt lgkmcnt(" #n ")" ::: "memory")
; #define PG8_BAR __builtin_amdgcn_s_barrier()
; #define PG8_SCHED __builtin_amdgcn_sched_barrier(0)
; template <class Epi, bool ALIGN_EPI>
; __device__ __forceinline__ void gemm_phase(LAS unsigned char* lds, const Gemm g, const StaticOrder& S, const Epi& E, const int tid) {
;     ...
;         for (int t = 0; t < nt; t += 2) {
;     ...
;             PG8_LDA(At, 1, 1); PG8_STAGE(PG8_SB(1, 0), b3, voffB); PG8_STAGE(PG8_SB(1, 1), b3 + hB, voffB); PG8_STAGE(PG8_SA(1, 0), a3, voffA);
;             PG8_WAIT_V(8); PG8_WAIT_L(0); PG8_BAR; PG8_MMA(1, 0, At, B0); PG8_MMA(1, 1, At, B1); PG8_BAR; PG8_SCHED;
;         }
	s_add_i32 s46, s46, s52
	v_lshl_add_u64 v[158:159], v[166:167], 0, s[92:93]
	s_mov_b32 m0, s46
	ds_read_b128 v[190:193], v219 offset:49152
	ds_read_b128 v[194:197], v219 offset:50176
	ds_read_b128 v[198:201], v219 offset:51200
	ds_read_b128 v[202:205], v219 offset:52224
	ds_read_b128 v[206:209], v219 offset:53248
	ds_read_b128 v[210:213], v219 offset:54272
	ds_read_b128 v[240:243], v219 offset:55296
	ds_read_b128 v[244:247], v219 offset:56320
	global_load_lds_dwordx4 v[158:159], off
	v_lshl_add_u64 v[158:159], v[214:215], 0, s[92:93]
	s_add_i32 m0, s46, 0x2000
	s_add_i32 s46, s70, s52
	global_load_lds_dwordx4 v[158:159], off
	v_lshl_add_u64 v[158:159], v[220:221], 0, s[92:93]
	s_mov_b32 m0, s46
	s_nop 0
	global_load_lds_dwordx4 v[158:159], off
	v_lshl_add_u64 v[158:159], v[226:227], 0, s[92:93]
	s_add_i32 m0, s46, 0x2000
	s_nop 0
	global_load_lds_dwordx4 v[158:159], off
	v_lshl_add_u64 v[158:159], v[248:249], 0, s[92:93]
	s_mov_b32 m0, s57
	s_nop 0
	global_load_lds_dwordx4 v[158:159], off
	v_lshl_add_u64 v[158:159], v[250:251], 0, s[92:93]
	s_mov_b32 m0, s58
	s_nop 0
	global_load_lds_dwordx4 v[158:159], off
	s_waitcnt vmcnt(8)
	s_waitcnt lgkmcnt(0)
	s_setprio 1
	s_barrier
	s_waitcnt lgkmcnt(0)
	v_mfma_f32_16x16x32_bf16 v[60:63], v[130:133], v[190:193], v[60:63]
	v_mfma_f32_16x16x32_bf16 v[56:59], v[138:141], v[190:193], v[56:59]
	v_mfma_f32_16x16x32_bf16 v[44:47], v[130:133], v[198:201], v[44:47]
	v_mfma_f32_16x16x32_bf16 v[40:43], v[138:141], v[198:201], v[40:43]
	v_mfma_f32_16x16x32_bf16 v[28:31], v[130:133], v[206:209], v[28:31]
	v_mfma_f32_16x16x32_bf16 v[24:27], v[138:141], v[206:209], v[24:27]
	v_mfma_f32_16x16x32_bf16 v[12:15], v[130:133], v[240:243], v[12:15]
	v_mfma_f32_16x16x32_bf16 v[8:11], v[138:141], v[240:243], v[8:11]
	v_mfma_f32_16x16x32_bf16 v[60:63], v[134:137], v[194:197], v[60:63]
	v_mfma_f32_16x16x32_bf16 v[56:59], v[142:145], v[194:197], v[56:59]
	v_mfma_f32_16x16x32_bf16 v[44:47], v[134:137], v[202:205], v[44:47]
	v_mfma_f32_16x16x32_bf16 v[40:43], v[142:145], v[202:205], v[40:43]
	v_mfma_f32_16x16x32_bf16 v[28:31], v[134:137], v[210:213], v[28:31]
	v_mfma_f32_16x16x32_bf16 v[24:27], v[142:145], v[210:213], v[24:27]
	v_mfma_f32_16x16x32_bf16 v[12:15], v[134:137], v[244:247], v[12:15]
	v_mfma_f32_16x16x32_bf16 v[8:11], v[142:145], v[244:247], v[8:11]
	s_setprio 0
	s_setprio 1
	v_mfma_f32_16x16x32_bf16 v[52:55], v[146:149], v[190:193], v[52:55]
	v_mfma_f32_16x16x32_bf16 v[48:51], v[154:157], v[190:193], v[48:51]
	v_mfma_f32_16x16x32_bf16 v[36:39], v[146:149], v[198:201], v[36:39]
	v_mfma_f32_16x16x32_bf16 v[32:35], v[154:157], v[198:201], v[32:35]
	v_mfma_f32_16x16x32_bf16 v[20:23], v[146:149], v[206:209], v[20:23]
	v_mfma_f32_16x16x32_bf16 v[16:19], v[154:157], v[206:209], v[16:19]
	v_mfma_f32_16x16x32_bf16 v[4:7], v[146:149], v[240:243], v[4:7]
	v_mfma_f32_16x16x32_bf16 v[0:3], v[154:157], v[240:243], v[0:3]
	v_mfma_f32_16x16x32_bf16 v[52:55], v[150:153], v[194:197], v[52:55]
	v_mfma_f32_16x16x32_bf16 v[48:51], v[186:189], v[194:197], v[48:51]
	v_mfma_f32_16x16x32_bf16 v[36:39], v[150:153], v[202:205], v[36:39]
	v_mfma_f32_16x16x32_bf16 v[32:35], v[186:189], v[202:205], v[32:35]
	v_mfma_f32_16x16x32_bf16 v[20:23], v[150:153], v[210:213], v[20:23]
	v_mfma_f32_16x16x32_bf16 v[16:19], v[186:189], v[210:213], v[16:19]
	v_mfma_f32_16x16x32_bf16 v[4:7], v[150:153], v[244:247], v[4:7]
	v_mfma_f32_16x16x32_bf16 v[0:3], v[186:189], v[244:247], v[0:3]
	s_setprio 0
	s_barrier
	s_add_u32 s12, s12, 0x100
	s_addc_u32 s13, s13, 0
	v_lshl_add_u64 v[128:129], v[128:129], 0, s[80:81]
	s_cmp_ge_u32 s47, s48
	s_mov_b32 s46, s47
	s_cbranch_scc0 .LBB0_236

; #define PG8_STAGE(bufoff, gbase, voff) do { _Pragma("unroll") for (int _i = 0; _i < 2; ++_i) \
;         __builtin_amdgcn_global_load_lds((const unsigned*)((const char*)(gbase) + (voff)[_i]), (LAS unsigned*)(lds + (bufoff) + ldsw + _i * 8192), 16, 0, 0); } while (0)
; #define PG8_LDA(dst, b, h) do { _Pragma("unroll") for (int m = 0; m < 4; ++m) _Pragma("unroll") for (int k = 0; k < 2; ++k) dst[m][k] = *(const LAS bf16x8*)(lds + PG8_SA(b, h) + aoff + m * 2048 + k * 1024); } while (0)
; #define PG8_LDB(dst, b, h) do { _Pragma("unroll") for (int n = 0; n < 2; ++n) _Pragma("unroll") for (int k = 0; k < 2; ++k) dst[n][k] = *(const LAS bf16x8*)(lds + PG8_SB(b, h) + boff + n * 2048 + k * 1024); } while (0)
; #define PG8_MMA(ai, bj, At, Bt) do { __builtin_amdgcn_s_setprio(1); _Pragma("unroll") for (int k = 0; k < 2; ++k) _Pragma("unroll") for (int m = 0; m < 4; ++m) _Pragma("unroll") for (int n = 0; n < 2; ++n) \
;         acc[ai][bj][m][n] = __builtin_amdgcn_mfma_f32_16x16x32_bf16(Bt[n][k], At[m][k], acc[ai][bj][m][n], 0, 0, 0); __builtin_amdgcn_s_setprio(0); } while (0)
; template <class Epi, bool ALIGN_EPI>
; __device__ __forceinline__ void gemm_phase(LAS unsigned char* lds, const Gemm g, const StaticOrder& S, const Epi& E, const int tid) {
;     ...
;     for (;;) {
;         const bool has_next = S.next(ui + 1, nxt);
;         const char* nA = has_next ? (const char*)g.A + (size_t)nxt.pm * tA + (size_t)nxt.pn * g.apn * 2 : cA; const char* nB = has_next ? (const char*)g.Bt + (size_t)nxt.pn * tB : cB;
;         for (int t = 0; t < nt; t += 2) {
;             const bool last = (t == nt - 2);
;             const char* a1 = cA + (size_t)(t + 1) * kstep;
;             const char* a2 = last ? nA : cA + (size_t)(t + 2) * kstep; const char* b2 = last ? nB : cB + (size_t)(t + 2) * kstep;
;             const char* a3 = a2 + kstep; const char* b3 = b2 + kstep;
;             PG8_LDB(B0, 0, 0); PG8_LDB(B1, 0, 1); PG8_SCHED; PG8_LDA(At, 0, 0); PG8_STAGE(PG8_SA(1, 1), a1 + hA, voffA);
;             PG8_WAIT_V(8); PG8_WAIT_L(0); PG8_BAR; PG8_MMA(0, 0, At, B0); PG8_MMA(0, 1, At, B1); PG8_BAR; PG8_SCHED;
;             PG8_LDA(At, 0, 1); PG8_STAGE(PG8_SB(0, 0), b2, voffB); PG8_STAGE(PG8_SB(0, 1), b2 + hB, voffB); PG8_STAGE(PG8_SA(0, 0), a2, voffA);
;             PG8_WAIT_V(8); PG8_WAIT_L(0); PG8_BAR; PG8_MMA(1, 0, At, B0); PG8_MMA(1, 1, At, B1); PG8_BAR; PG8_SCHED;
.LBB0_272:
	s_andn2_b64 vcc, exec, s[36:37]
	s_cbranch_vccnz .LBB0_276
	s_add_u32 s10, s14, 0x100
	v_lshl_add_u64 v[128:129], v[128:129], 0, s[92:93]
	s_addc_u32 s11, s15, 0
	s_mov_b32 s14, 0
	s_add_i32 s15, s14, 2
	s_cmp_eq_u32 s57, s14
	s_cselect_b64 vcc, -1, 0
	s_cselect_b32 s69, s13, s11
	s_cselect_b32 s68, s12, s10
	s_add_i32 s14, 0, 0x14000
	v_lshl_add_u64 v[130:131], v[128:129], 0, s[92:93]
	v_add_u32_e32 v142, s33, v239
	v_add_u32_e32 v158, s14, v239
	v_cndmask_b32_e32 v167, v131, v191, vcc
	v_cndmask_b32_e32 v166, v130, v190, vcc
	ds_read_b128 v[130:133], v142
	ds_read_b128 v[134:137], v142 offset:1024
	ds_read_b128 v[138:141], v142 offset:2048
	ds_read_b128 v[142:145], v142 offset:3072
	ds_read_b128 v[146:149], v158
	ds_read_b128 v[150:153], v158 offset:1024
	ds_read_b128 v[154:157], v158 offset:2048
	ds_read_b128 v[158:161], v158 offset:3072
	v_lshl_add_u64 v[220:221], v[128:129], 0, v[186:187]
	s_add_i32 m0, s51, 0xc000
	ds_read_b128 v[162:165], v171
	ds_read_b128 v[192:195], v171 offset:1024
	ds_read_b128 v[196:199], v171 offset:2048
	ds_read_b128 v[200:203], v171 offset:3072
	ds_read_b128 v[204:207], v171 offset:4096
	ds_read_b128 v[208:211], v171 offset:5120
	ds_read_b128 v[212:215], v171 offset:6144
	ds_read_b128 v[216:219], v171 offset:7168
	global_load_lds_dwordx4 v[220:221], off
	v_lshl_add_u64 v[220:221], v[128:129], 0, v[188:189]
	s_add_i32 m0, s51, 0xe000
	s_nop 0
	global_load_lds_dwordx4 v[220:221], off
	s_waitcnt vmcnt(8)
	s_waitcnt lgkmcnt(0)
	s_setprio 1
	s_barrier
	s_waitcnt lgkmcnt(0)
	v_mfma_f32_16x16x32_bf16 v[124:127], v[130:133], v[162:165], 0
	v_mfma_f32_16x16x32_bf16 v[120:123], v[138:141], v[162:165], 0
	v_mfma_f32_16x16x32_bf16 v[108:111], v[130:133], v[196:199], 0
	v_mfma_f32_16x16x32_bf16 v[104:107], v[138:141], v[196:199], 0
	v_mfma_f32_16x16x32_bf16 v[92:95], v[130:133], v[204:207], 0
	v_mfma_f32_16x16x32_bf16 v[88:91], v[138:141], v[204:207], 0
	v_mfma_f32_16x16x32_bf16 v[76:79], v[130:133], v[212:215], 0
	v_mfma_f32_16x16x32_bf16 v[72:75], v[138:141], v[212:215], 0
	v_mfma_f32_16x16x32_bf16 v[124:127], v[134:137], v[192:195], v[124:127]
	v_mfma_f32_16x16x32_bf16 v[120:123], v[142:145], v[192:195], v[120:123]
	v_mfma_f32_16x16x32_bf16 v[108:111], v[134:137], v[200:203], v[108:111]
	v_mfma_f32_16x16x32_bf16 v[104:107], v[142:145], v[200:203], v[104:107]
	v_mfma_f32_16x16x32_bf16 v[92:95], v[134:137], v[208:211], v[92:95]
	v_mfma_f32_16x16x32_bf16 v[88:91], v[142:145], v[208:211], v[88:91]
	v_mfma_f32_16x16x32_bf16 v[76:79], v[134:137], v[216:219], v[76:79]
	v_mfma_f32_16x16x32_bf16 v[72:75], v[142:145], v[216:219], v[72:75]
	s_setprio 0
	s_setprio 1
	v_mfma_f32_16x16x32_bf16 v[116:119], v[146:149], v[162:165], 0
	v_mfma_f32_16x16x32_bf16 v[112:115], v[154:157], v[162:165], 0
	v_mfma_f32_16x16x32_bf16 v[100:103], v[146:149], v[196:199], 0
	v_mfma_f32_16x16x32_bf16 v[96:99], v[154:157], v[196:199], 0
	v_mfma_f32_16x16x32_bf16 v[84:87], v[146:149], v[204:207], 0
	v_mfma_f32_16x16x32_bf16 v[80:83], v[154:157], v[204:207], 0
	v_mfma_f32_16x16x32_bf16 v[68:71], v[146:149], v[212:215], 0
	v_mfma_f32_16x16x32_bf16 v[64:67], v[154:157], v[212:215], 0
	v_mfma_f32_16x16x32_bf16 v[116:119], v[150:153], v[192:195], v[116:119]
	v_mfma_f32_16x16x32_bf16 v[112:115], v[158:161], v[192:195], v[112:115]
	v_mfma_f32_16x16x32_bf16 v[100:103], v[150:153], v[200:203], v[100:103]
	v_mfma_f32_16x16x32_bf16 v[96:99], v[158:161], v[200:203], v[96:99]
	v_mfma_f32_16x16x32_bf16 v[84:87], v[150:153], v[208:211], v[84:87]
	v_mfma_f32_16x16x32_bf16 v[80:83], v[158:161], v[208:211], v[80:83]
	v_mfma_f32_16x16x32_bf16 v[68:71], v[150:153], v[216:219], v[68:71]
	v_mfma_f32_16x16x32_bf16 v[64:67], v[158:161], v[216:219], v[64:67]
	s_setprio 0
	s_barrier
	s_add_i32 s70, s33, s47
	v_lshl_add_u64 v[220:221], s[68:69], 0, v[180:181]
	s_mov_b32 m0, s70
	ds_read_b128 v[162:165], v171 offset:16384
	ds_read_b128 v[192:195], v171 offset:17408
	ds_read_b128 v[196:199], v171 offset:18432
	ds_read_b128 v[200:203], v171 offset:19456
	ds_read_b128 v[204:207], v171 offset:20480
	ds_read_b128 v[208:211], v171 offset:21504
	ds_read_b128 v[212:215], v171 offset:22528
	ds_read_b128 v[216:219], v171 offset:23552
	global_load_lds_dwordx4 v[220:221], off
	s_add_i32 m0, s70, 0x2000
	v_lshl_add_u64 v[226:227], s[68:69], 0, v[184:185]
	s_add_u32 s68, s68, s49
	s_addc_u32 s69, s69, 0
	s_add_i32 s14, s14, s47
	global_load_lds_dwordx4 v[226:227], off
	v_lshl_add_u64 v[240:241], s[68:69], 0, v[180:181]
	s_mov_b32 m0, s14
	v_lshl_add_u64 v[242:243], s[68:69], 0, v[184:185]
	global_load_lds_dwordx4 v[240:241], off
	s_add_i32 m0, s14, 0x2000
	v_lshl_add_u64 v[244:245], v[166:167], 0, v[178:179]
	global_load_lds_dwordx4 v[242:243], off
	s_mov_b32 m0, s51
	v_lshl_add_u64 v[246:247], v[166:167], 0, v[182:183]
	global_load_lds_dwordx4 v[244:245], off
	s_mov_b32 m0, s52
	s_nop 0
	global_load_lds_dwordx4 v[246:247], off
	s_waitcnt vmcnt(8)
	s_waitcnt lgkmcnt(0)
	s_setprio 1
	s_barrier
; #define PG8_STAGE(bufoff, gbase, voff) do { _Pragma("unroll") for (int _i = 0; _i < 2; ++_i) \
;         __builtin_amdgcn_global_load_lds((const unsigned*)((const char*)(gbase) + (voff)[_i]), (LAS unsigned*)(lds + (bufoff) + ldsw + _i * 8192), 16, 0, 0); } while (0)
; #define PG8_LDA(dst, b, h) do { _Pragma("unroll") for (int m = 0; m < 4; ++m) _Pragma("unroll") for (int k = 0; k < 2; ++k) dst[m][k] = *(const LAS bf16x8*)(lds + PG8_SA(b, h) + aoff + m * 2048 + k * 1024); } while (0)
; #define PG8_LDB(dst, b, h) do { _Pragma("unroll") for (int n = 0; n < 2; ++n) _Pragma("unroll") for (int k = 0; k < 2; ++k) dst[n][k] = *(const LAS bf16x8*)(lds + PG8_SB(b, h) + boff + n * 2048 + k * 1024); } while (0)
; #define PG8_MMA(ai, bj, At, Bt) do { __builtin_amdgcn_s_setprio(1); _Pragma("unroll") for (int k = 0; k < 2; ++k) _Pragma("unroll") for (int m = 0; m < 4; ++m) _Pragma("unroll") for (int n = 0; n < 2; ++n) \
;         acc[ai][bj][m][n] = __builtin_amdgcn_mfma_f32_16x16x32_bf16(Bt[n][k], At[m][k], acc[ai][bj][m][n], 0, 0, 0); __builtin_amdgcn_s_setprio(0); } while (0)
; #define PG8_WAIT_V(n) asm volatile("s_waitcnt vmcnt(" #n ")" ::: "memory")
; #define PG8_WAIT_L(n) asm volatile("s_waitcnt lgkmcnt(" #n ")" ::: "memory")
; #define PG8_BAR __builtin_amdgcn_s_barrier()
; #define PG8_SCHED __builtin_amdgcn_sched_barrier(0)
; template <class Epi, bool ALIGN_EPI>
; __device__ __forceinline__ void gemm_phase(LAS unsigned char* lds, const Gemm g, const StaticOrder& S, const Epi& E, const int tid) {
;     ...
;             PG8_WAIT_V(8); PG8_WAIT_L(0); PG8_BAR; PG8_MMA(1, 0, At, B0); PG8_MMA(1, 1, At, B1); PG8_BAR; PG8_SCHED;
;             PG8_LDB(B0, 1, 0); PG8_LDB(B1, 1, 1); PG8_SCHED; PG8_LDA(At, 1, 0); PG8_STAGE(PG8_SA(0, 1), a2 + hA, voffA);
;             PG8_WAIT_V(8); PG8_WAIT_L(0); PG8_BAR; PG8_MMA(0, 0, At, B0); PG8_MMA(0, 1, At, B1); PG8_BAR; PG8_SCHED;
	s_waitcnt lgkmcnt(0)
	v_mfma_f32_16x16x32_bf16 v[60:63], v[130:133], v[162:165], 0
	v_mfma_f32_16x16x32_bf16 v[56:59], v[138:141], v[162:165], 0
	v_mfma_f32_16x16x32_bf16 v[44:47], v[130:133], v[196:199], 0
	v_mfma_f32_16x16x32_bf16 v[40:43], v[138:141], v[196:199], 0
	v_mfma_f32_16x16x32_bf16 v[28:31], v[130:133], v[204:207], 0
	v_mfma_f32_16x16x32_bf16 v[24:27], v[138:141], v[204:207], 0
	v_mfma_f32_16x16x32_bf16 v[12:15], v[130:133], v[212:215], 0
	v_mfma_f32_16x16x32_bf16 v[8:11], v[138:141], v[212:215], 0
	v_mfma_f32_16x16x32_bf16 v[60:63], v[134:137], v[192:195], v[60:63]
	v_mfma_f32_16x16x32_bf16 v[56:59], v[142:145], v[192:195], v[56:59]
	v_mfma_f32_16x16x32_bf16 v[44:47], v[134:137], v[200:203], v[44:47]
	v_mfma_f32_16x16x32_bf16 v[40:43], v[142:145], v[200:203], v[40:43]
	v_mfma_f32_16x16x32_bf16 v[28:31], v[134:137], v[208:211], v[28:31]
	v_mfma_f32_16x16x32_bf16 v[24:27], v[142:145], v[208:211], v[24:27]
	v_mfma_f32_16x16x32_bf16 v[12:15], v[134:137], v[216:219], v[12:15]
	v_mfma_f32_16x16x32_bf16 v[8:11], v[142:145], v[216:219], v[8:11]
	s_setprio 0
	s_setprio 1
	v_mfma_f32_16x16x32_bf16 v[52:55], v[146:149], v[162:165], 0
	v_mfma_f32_16x16x32_bf16 v[48:51], v[154:157], v[162:165], 0
	v_mfma_f32_16x16x32_bf16 v[36:39], v[146:149], v[196:199], 0
	v_mfma_f32_16x16x32_bf16 v[32:35], v[154:157], v[196:199], 0
	v_mfma_f32_16x16x32_bf16 v[20:23], v[146:149], v[204:207], 0
	v_mfma_f32_16x16x32_bf16 v[16:19], v[154:157], v[204:207], 0
	v_mfma_f32_16x16x32_bf16 v[4:7], v[146:149], v[212:215], 0
	v_mfma_f32_16x16x32_bf16 v[0:3], v[154:157], v[212:215], 0
	v_mfma_f32_16x16x32_bf16 v[52:55], v[150:153], v[192:195], v[52:55]
	v_mfma_f32_16x16x32_bf16 v[48:51], v[158:161], v[192:195], v[48:51]
	v_mfma_f32_16x16x32_bf16 v[36:39], v[150:153], v[200:203], v[36:39]
	v_mfma_f32_16x16x32_bf16 v[32:35], v[158:161], v[200:203], v[32:35]
	v_mfma_f32_16x16x32_bf16 v[20:23], v[150:153], v[208:211], v[20:23]
	v_mfma_f32_16x16x32_bf16 v[16:19], v[158:161], v[208:211], v[16:19]
	v_mfma_f32_16x16x32_bf16 v[4:7], v[150:153], v[216:219], v[4:7]
	v_mfma_f32_16x16x32_bf16 v[0:3], v[158:161], v[216:219], v[0:3]
	s_setprio 0
	s_barrier
	s_add_i32 s14, 0, 0x18000
	s_add_i32 s68, 0, 0x1c000
	v_add_u32_e32 v142, s14, v239
	v_add_u32_e32 v158, s68, v239
	ds_read_b128 v[130:133], v142
	ds_read_b128 v[134:137], v142 offset:1024
	ds_read_b128 v[138:141], v142 offset:2048
	ds_read_b128 v[142:145], v142 offset:3072
	ds_read_b128 v[146:149], v158
	ds_read_b128 v[150:153], v158 offset:1024
	ds_read_b128 v[154:157], v158 offset:2048
	ds_read_b128 v[158:161], v158 offset:3072
	v_lshl_add_u64 v[166:167], v[166:167], 0, s[94:95]
	s_mov_b32 m0, s53
	v_lshl_add_u64 v[248:249], v[166:167], 0, v[178:179]
	ds_read_b128 v[162:165], v171 offset:32768
	ds_read_b128 v[192:195], v171 offset:33792
	ds_read_b128 v[196:199], v171 offset:34816
	ds_read_b128 v[200:203], v171 offset:35840
	ds_read_b128 v[204:207], v171 offset:36864
	ds_read_b128 v[208:211], v171 offset:37888
	ds_read_b128 v[212:215], v171 offset:38912
	ds_read_b128 v[216:219], v171 offset:39936
	global_load_lds_dwordx4 v[248:249], off
	v_lshl_add_u64 v[166:167], v[166:167], 0, v[182:183]
	s_mov_b32 m0, s54
	s_nop 0
	global_load_lds_dwordx4 v[166:167], off
	s_waitcnt vmcnt(8)
	s_waitcnt lgkmcnt(0)
	s_setprio 1
	s_barrier
	s_waitcnt lgkmcnt(0)
	v_mfma_f32_16x16x32_bf16 v[124:127], v[130:133], v[162:165], v[124:127]
	v_mfma_f32_16x16x32_bf16 v[120:123], v[138:141], v[162:165], v[120:123]
	v_mfma_f32_16x16x32_bf16 v[108:111], v[130:133], v[196:199], v[108:111]
	v_mfma_f32_16x16x32_bf16 v[104:107], v[138:141], v[196:199], v[104:107]
	v_mfma_f32_16x16x32_bf16 v[92:95], v[130:133], v[204:207], v[92:95]
	v_mfma_f32_16x16x32_bf16 v[88:91], v[138:141], v[204:207], v[88:91]
	v_mfma_f32_16x16x32_bf16 v[76:79], v[130:133], v[212:215], v[76:79]
	v_mfma_f32_16x16x32_bf16 v[72:75], v[138:141], v[212:215], v[72:75]
	v_mfma_f32_16x16x32_bf16 v[124:127], v[134:137], v[192:195], v[124:127]
	v_mfma_f32_16x16x32_bf16 v[120:123], v[142:145], v[192:195], v[120:123]
	v_mfma_f32_16x16x32_bf16 v[108:111], v[134:137], v[200:203], v[108:111]
	v_mfma_f32_16x16x32_bf16 v[104:107], v[142:145], v[200:203], v[104:107]
	v_mfma_f32_16x16x32_bf16 v[92:95], v[134:137], v[208:211], v[92:95]
	v_mfma_f32_16x16x32_bf16 v[88:91], v[142:145], v[208:211], v[88:91]
	v_mfma_f32_16x16x32_bf16 v[76:79], v[134:137], v[216:219], v[76:79]
	v_mfma_f32_16x16x32_bf16 v[72:75], v[142:145], v[216:219], v[72:75]
	s_setprio 0
	s_setprio 1
	v_mfma_f32_16x16x32_bf16 v[116:119], v[146:149], v[162:165], v[116:119]
	v_mfma_f32_16x16x32_bf16 v[112:115], v[154:157], v[162:165], v[112:115]
	v_mfma_f32_16x16x32_bf16 v[100:103], v[146:149], v[196:199], v[100:103]
	v_mfma_f32_16x16x32_bf16 v[96:99], v[154:157], v[196:199], v[96:99]
	v_mfma_f32_16x16x32_bf16 v[84:87], v[146:149], v[204:207], v[84:87]
	v_mfma_f32_16x16x32_bf16 v[80:83], v[154:157], v[204:207], v[80:83]
	v_mfma_f32_16x16x32_bf16 v[68:71], v[146:149], v[212:215], v[68:71]
	v_mfma_f32_16x16x32_bf16 v[64:67], v[154:157], v[212:215], v[64:67]
	v_mfma_f32_16x16x32_bf16 v[116:119], v[150:153], v[192:195], v[116:119]
	v_mfma_f32_16x16x32_bf16 v[112:115], v[158:161], v[192:195], v[112:115]
	v_mfma_f32_16x16x32_bf16 v[100:103], v[150:153], v[200:203], v[100:103]
	v_mfma_f32_16x16x32_bf16 v[96:99], v[158:161], v[200:203], v[96:99]
	v_mfma_f32_16x16x32_bf16 v[84:87], v[150:153], v[208:211], v[84:87]
	v_mfma_f32_16x16x32_bf16 v[80:83], v[158:161], v[208:211], v[80:83]
	v_mfma_f32_16x16x32_bf16 v[68:71], v[150:153], v[216:219], v[68:71]
	v_mfma_f32_16x16x32_bf16 v[64:67], v[158:161], v[216:219], v[64:67]
	s_setprio 0
	s_barrier
; #define PG8_STAGE(bufoff, gbase, voff) do { _Pragma("unroll") for (int _i = 0; _i < 2; ++_i) \
;         __builtin_amdgcn_global_load_lds((const unsigned*)((const char*)(gbase) + (voff)[_i]), (LAS unsigned*)(lds + (bufoff) + ldsw + _i * 8192), 16, 0, 0); } while (0)
; #define PG8_LDA(dst, b, h) do { _Pragma("unroll") for (int m = 0; m < 4; ++m) _Pragma("unroll") for (int k = 0; k < 2; ++k) dst[m][k] = *(const LAS bf16x8*)(lds + PG8_SA(b, h) + aoff + m * 2048 + k * 1024); } while (0)
; #define PG8_LDB(dst, b, h) do { _Pragma("unroll") for (int n = 0; n < 2; ++n) _Pragma("unroll") for (int k = 0; k < 2; ++k) dst[n][k] = *(const LAS bf16x8*)(lds + PG8_SB(b, h) + boff + n * 2048 + k * 1024); } while (0)
; #define PG8_WAIT_V(n) asm volatile("s_waitcnt vmcnt(" #n ")" ::: "memory")
; #define PG8_BAR __builtin_amdgcn_s_barrier()
; template <class Epi, bool ALIGN_EPI>
; __device__ __forceinline__ void gemm_phase(LAS unsigned char* lds, const Gemm g, const StaticOrder& S, const Epi& E, const int tid) {
;     ...
;         for (int t = 0; t < nt; t += 2) {
;             const bool last = (t == nt - 2);
;             const char* a1 = cA + (size_t)(t + 1) * kstep;
;             const char* a2 = last ? nA : cA + (size_t)(t + 2) * kstep; const char* b2 = last ? nB : cB + (size_t)(t + 2) * kstep;
;             const char* a3 = a2 + kstep; const char* b3 = b2 + kstep;
;             PG8_LDB(B0, 0, 0); PG8_LDB(B1, 0, 1); PG8_SCHED; PG8_LDA(At, 0, 0); PG8_STAGE(PG8_SA(1, 1), a1 + hA, voffA);
;             PG8_WAIT_V(8); PG8_WAIT_L(0); PG8_BAR; PG8_MMA(0, 0, At, B0); PG8_MMA(0, 1, At, B1); PG8_BAR; PG8_SCHED;
;             PG8_LDA(At, 0, 1); PG8_STAGE(PG8_SB(0, 0), b2, voffB); PG8_STAGE(PG8_SB(0, 1), b2 + hB, voffB); PG8_STAGE(PG8_SA(0, 0), a2, voffA);
;             PG8_WAIT_V(8); PG8_WAIT_L(0); PG8_BAR; PG8_MMA(1, 0, At, B0); PG8_MMA(1, 1, At, B1); PG8_BAR; PG8_SCHED;
;             PG8_LDB(B0, 1, 0); PG8_LDB(B1, 1, 1); PG8_SCHED; PG8_LDA(At, 1, 0); PG8_STAGE(PG8_SA(0, 1), a2 + hA, voffA);
;             PG8_WAIT_V(8); PG8_WAIT_L(0); PG8_BAR; PG8_MMA(0, 0, At, B0); PG8_MMA(0, 1, At, B1); PG8_BAR; PG8_SCHED;
;             PG8_LDA(At, 1, 1); PG8_STAGE(PG8_SB(1, 0), b3, voffB); PG8_STAGE(PG8_SB(1, 1), b3 + hB, voffB); PG8_STAGE(PG8_SA(1, 0), a3, voffA);
;             PG8_WAIT_V(8); PG8_WAIT_L(0); PG8_BAR; PG8_MMA(1, 0, At, B0); PG8_MMA(1, 1, At, B1); PG8_BAR; PG8_SCHED;
	s_add_i32 s14, s14, s47
	v_lshl_add_u64 v[166:167], v[220:221], 0, s[92:93]
	s_mov_b32 m0, s14
	ds_read_b128 v[162:165], v171 offset:49152
	ds_read_b128 v[192:195], v171 offset:50176
	ds_read_b128 v[196:199], v171 offset:51200
	ds_read_b128 v[200:203], v171 offset:52224
	ds_read_b128 v[204:207], v171 offset:53248
	ds_read_b128 v[208:211], v171 offset:54272
	ds_read_b128 v[212:215], v171 offset:55296
	ds_read_b128 v[216:219], v171 offset:56320
	global_load_lds_dwordx4 v[166:167], off
	v_lshl_add_u64 v[166:167], v[226:227], 0, s[92:93]
	s_add_i32 m0, s14, 0x2000
	s_add_i32 s14, s68, s47
	global_load_lds_dwordx4 v[166:167], off
	v_lshl_add_u64 v[166:167], v[240:241], 0, s[92:93]
	s_mov_b32 m0, s14
	s_nop 0
	global_load_lds_dwordx4 v[166:167], off
	v_lshl_add_u64 v[166:167], v[242:243], 0, s[92:93]
	s_add_i32 m0, s14, 0x2000
	s_nop 0
	global_load_lds_dwordx4 v[166:167], off
	v_lshl_add_u64 v[166:167], v[244:245], 0, s[92:93]
	s_mov_b32 m0, s55
	s_nop 0
	global_load_lds_dwordx4 v[166:167], off
	v_lshl_add_u64 v[166:167], v[246:247], 0, s[92:93]
	s_mov_b32 m0, s56
	s_nop 0
	global_load_lds_dwordx4 v[166:167], off
	s_waitcnt vmcnt(8)
	s_waitcnt lgkmcnt(0)
	s_setprio 1
	s_barrier
	s_waitcnt lgkmcnt(0)
	v_mfma_f32_16x16x32_bf16 v[60:63], v[130:133], v[162:165], v[60:63]
	v_mfma_f32_16x16x32_bf16 v[56:59], v[138:141], v[162:165], v[56:59]
	v_mfma_f32_16x16x32_bf16 v[44:47], v[130:133], v[196:199], v[44:47]
	v_mfma_f32_16x16x32_bf16 v[40:43], v[138:141], v[196:199], v[40:43]
	v_mfma_f32_16x16x32_bf16 v[28:31], v[130:133], v[204:207], v[28:31]
	v_mfma_f32_16x16x32_bf16 v[24:27], v[138:141], v[204:207], v[24:27]
	v_mfma_f32_16x16x32_bf16 v[12:15], v[130:133], v[212:215], v[12:15]
	v_mfma_f32_16x16x32_bf16 v[8:11], v[138:141], v[212:215], v[8:11]
	v_mfma_f32_16x16x32_bf16 v[60:63], v[134:137], v[192:195], v[60:63]
	v_mfma_f32_16x16x32_bf16 v[56:59], v[142:145], v[192:195], v[56:59]
	v_mfma_f32_16x16x32_bf16 v[44:47], v[134:137], v[200:203], v[44:47]
	v_mfma_f32_16x16x32_bf16 v[40:43], v[142:145], v[200:203], v[40:43]
	v_mfma_f32_16x16x32_bf16 v[28:31], v[134:137], v[208:211], v[28:31]
	v_mfma_f32_16x16x32_bf16 v[24:27], v[142:145], v[208:211], v[24:27]
	v_mfma_f32_16x16x32_bf16 v[12:15], v[134:137], v[216:219], v[12:15]
	v_mfma_f32_16x16x32_bf16 v[8:11], v[142:145], v[216:219], v[8:11]
	s_setprio 0
	s_setprio 1
	v_mfma_f32_16x16x32_bf16 v[52:55], v[146:149], v[162:165], v[52:55]
	v_mfma_f32_16x16x32_bf16 v[48:51], v[154:157], v[162:165], v[48:51]
	v_mfma_f32_16x16x32_bf16 v[36:39], v[146:149], v[196:199], v[36:39]
	v_mfma_f32_16x16x32_bf16 v[32:35], v[154:157], v[196:199], v[32:35]
	v_mfma_f32_16x16x32_bf16 v[20:23], v[146:149], v[204:207], v[20:23]
	v_mfma_f32_16x16x32_bf16 v[16:19], v[154:157], v[204:207], v[16:19]
	v_mfma_f32_16x16x32_bf16 v[4:7], v[146:149], v[212:215], v[4:7]
	v_mfma_f32_16x16x32_bf16 v[0:3], v[154:157], v[212:215], v[0:3]
	v_mfma_f32_16x16x32_bf16 v[52:55], v[150:153], v[192:195], v[52:55]
	v_mfma_f32_16x16x32_bf16 v[48:51], v[158:161], v[192:195], v[48:51]
	v_mfma_f32_16x16x32_bf16 v[36:39], v[150:153], v[200:203], v[36:39]
	v_mfma_f32_16x16x32_bf16 v[32:35], v[158:161], v[200:203], v[32:35]
	v_mfma_f32_16x16x32_bf16 v[20:23], v[150:153], v[208:211], v[20:23]
	v_mfma_f32_16x16x32_bf16 v[16:19], v[158:161], v[208:211], v[16:19]
	v_mfma_f32_16x16x32_bf16 v[4:7], v[150:153], v[216:219], v[4:7]
	v_mfma_f32_16x16x32_bf16 v[0:3], v[158:161], v[216:219], v[0:3]
	s_setprio 0
	s_barrier
	s_add_u32 s10, s10, 0x100
	s_addc_u32 s11, s11, 0
	v_lshl_add_u64 v[128:129], v[128:129], 0, s[80:81]
	s_cmp_ge_u32 s15, s48
	s_mov_b32 s14, s15
	s_cbranch_scc1 .Lpl2_after
.LBB0_274:
	s_add_i32 s15, s14, 2
	s_cmp_eq_u32 s57, s14
	s_cselect_b64 vcc, -1, 0
	s_cselect_b32 s69, s13, s11
	s_cselect_b32 s68, s12, s10
	s_add_i32 s14, 0, 0x14000
	v_lshl_add_u64 v[130:131], v[128:129], 0, s[92:93]
	v_add_u32_e32 v142, s33, v239
	v_add_u32_e32 v158, s14, v239
	v_cndmask_b32_e32 v167, v131, v191, vcc
	v_cndmask_b32_e32 v166, v130, v190, vcc
	ds_read_b128 v[130:133], v142
	ds_read_b128 v[134:137], v142 offset:1024
	ds_read_b128 v[138:141], v142 offset:2048
	ds_read_b128 v[142:145], v142 offset:3072
	ds_read_b128 v[146:149], v158
	ds_read_b128 v[150:153], v158 offset:1024
	ds_read_b128 v[154:157], v158 offset:2048
	ds_read_b128 v[158:161], v158 offset:3072
	v_lshl_add_u64 v[220:221], v[128:129], 0, v[186:187]
	s_add_i32 m0, s51, 0xc000
	ds_read_b128 v[162:165], v171
	ds_read_b128 v[192:195], v171 offset:1024
	ds_read_b128 v[196:199], v171 offset:2048
	ds_read_b128 v[200:203], v171 offset:3072
	ds_read_b128 v[204:207], v171 offset:4096
	ds_read_b128 v[208:211], v171 offset:5120
	ds_read_b128 v[212:215], v171 offset:6144
	ds_read_b128 v[216:219], v171 offset:7168
	global_load_lds_dwordx4 v[220:221], off
	v_lshl_add_u64 v[220:221], v[128:129], 0, v[188:189]
	s_add_i32 m0, s51, 0xe000
	s_nop 0
	global_load_lds_dwordx4 v[220:221], off
	s_waitcnt vmcnt(8)
	s_waitcnt lgkmcnt(0)
	s_setprio 1
	s_barrier
; #define PG8_STAGE(bufoff, gbase, voff) do { _Pragma("unroll") for (int _i = 0; _i < 2; ++_i) \
;         __builtin_amdgcn_global_load_lds((const unsigned*)((const char*)(gbase) + (voff)[_i]), (LAS unsigned*)(lds + (bufoff) + ldsw + _i * 8192), 16, 0, 0); } while (0)
; #define PG8_LDA(dst, b, h) do { _Pragma("unroll") for (int m = 0; m < 4; ++m) _Pragma("unroll") for (int k = 0; k < 2; ++k) dst[m][k] = *(const LAS bf16x8*)(lds + PG8_SA(b, h) + aoff + m * 2048 + k * 1024); } while (0)
; #define PG8_MMA(ai, bj, At, Bt) do { __builtin_amdgcn_s_setprio(1); _Pragma("unroll") for (int k = 0; k < 2; ++k) _Pragma("unroll") for (int m = 0; m < 4; ++m) _Pragma("unroll") for (int n = 0; n < 2; ++n) \
;         acc[ai][bj][m][n] = __builtin_amdgcn_mfma_f32_16x16x32_bf16(Bt[n][k], At[m][k], acc[ai][bj][m][n], 0, 0, 0); __builtin_amdgcn_s_setprio(0); } while (0)
; #define PG8_WAIT_V(n) asm volatile("s_waitcnt vmcnt(" #n ")" ::: "memory")
; #define PG8_WAIT_L(n) asm volatile("s_waitcnt lgkmcnt(" #n ")" ::: "memory")
; #define PG8_BAR __builtin_amdgcn_s_barrier()
; #define PG8_SCHED __builtin_amdgcn_sched_barrier(0)
; template <class Epi, bool ALIGN_EPI>
; __device__ __forceinline__ void gemm_phase(LAS unsigned char* lds, const Gemm g, const StaticOrder& S, const Epi& E, const int tid) {
;     ...
;             PG8_WAIT_V(8); PG8_WAIT_L(0); PG8_BAR; PG8_MMA(0, 0, At, B0); PG8_MMA(0, 1, At, B1); PG8_BAR; PG8_SCHED;
;             PG8_LDA(At, 0, 1); PG8_STAGE(PG8_SB(0, 0), b2, voffB); PG8_STAGE(PG8_SB(0, 1), b2 + hB, voffB); PG8_STAGE(PG8_SA(0, 0), a2, voffA);
;             PG8_WAIT_V(8); PG8_WAIT_L(0); PG8_BAR; PG8_MMA(1, 0, At, B0); PG8_MMA(1, 1, At, B1); PG8_BAR; PG8_SCHED;
	s_waitcnt lgkmcnt(0)
	v_mfma_f32_16x16x32_bf16 v[124:127], v[130:133], v[162:165], v[124:127]
	v_mfma_f32_16x16x32_bf16 v[120:123], v[138:141], v[162:165], v[120:123]
	v_mfma_f32_16x16x32_bf16 v[108:111], v[130:133], v[196:199], v[108:111]
	v_mfma_f32_16x16x32_bf16 v[104:107], v[138:141], v[196:199], v[104:107]
	v_mfma_f32_16x16x32_bf16 v[92:95], v[130:133], v[204:207], v[92:95]
	v_mfma_f32_16x16x32_bf16 v[88:91], v[138:141], v[204:207], v[88:91]
	v_mfma_f32_16x16x32_bf16 v[76:79], v[130:133], v[212:215], v[76:79]
	v_mfma_f32_16x16x32_bf16 v[72:75], v[138:141], v[212:215], v[72:75]
	v_mfma_f32_16x16x32_bf16 v[124:127], v[134:137], v[192:195], v[124:127]
	v_mfma_f32_16x16x32_bf16 v[120:123], v[142:145], v[192:195], v[120:123]
	v_mfma_f32_16x16x32_bf16 v[108:111], v[134:137], v[200:203], v[108:111]
	v_mfma_f32_16x16x32_bf16 v[104:107], v[142:145], v[200:203], v[104:107]
	v_mfma_f32_16x16x32_bf16 v[92:95], v[134:137], v[208:211], v[92:95]
	v_mfma_f32_16x16x32_bf16 v[88:91], v[142:145], v[208:211], v[88:91]
	v_mfma_f32_16x16x32_bf16 v[76:79], v[134:137], v[216:219], v[76:79]
	v_mfma_f32_16x16x32_bf16 v[72:75], v[142:145], v[216:219], v[72:75]
	s_setprio 0
	s_setprio 1
	v_mfma_f32_16x16x32_bf16 v[116:119], v[146:149], v[162:165], v[116:119]
	v_mfma_f32_16x16x32_bf16 v[112:115], v[154:157], v[162:165], v[112:115]
	v_mfma_f32_16x16x32_bf16 v[100:103], v[146:149], v[196:199], v[100:103]
	v_mfma_f32_16x16x32_bf16 v[96:99], v[154:157], v[196:199], v[96:99]
	v_mfma_f32_16x16x32_bf16 v[84:87], v[146:149], v[204:207], v[84:87]
	v_mfma_f32_16x16x32_bf16 v[80:83], v[154:157], v[204:207], v[80:83]
	v_mfma_f32_16x16x32_bf16 v[68:71], v[146:149], v[212:215], v[68:71]
	v_mfma_f32_16x16x32_bf16 v[64:67], v[154:157], v[212:215], v[64:67]
	v_mfma_f32_16x16x32_bf16 v[116:119], v[150:153], v[192:195], v[116:119]
	v_mfma_f32_16x16x32_bf16 v[112:115], v[158:161], v[192:195], v[112:115]
	v_mfma_f32_16x16x32_bf16 v[100:103], v[150:153], v[200:203], v[100:103]
	v_mfma_f32_16x16x32_bf16 v[96:99], v[158:161], v[200:203], v[96:99]
	v_mfma_f32_16x16x32_bf16 v[84:87], v[150:153], v[208:211], v[84:87]
	v_mfma_f32_16x16x32_bf16 v[80:83], v[158:161], v[208:211], v[80:83]
	v_mfma_f32_16x16x32_bf16 v[68:71], v[150:153], v[216:219], v[68:71]
	v_mfma_f32_16x16x32_bf16 v[64:67], v[158:161], v[216:219], v[64:67]
	s_setprio 0
	s_barrier
	s_add_i32 s70, s33, s47
	v_lshl_add_u64 v[220:221], s[68:69], 0, v[180:181]
	s_mov_b32 m0, s70
	ds_read_b128 v[162:165], v171 offset:16384
	ds_read_b128 v[192:195], v171 offset:17408
	ds_read_b128 v[196:199], v171 offset:18432
	ds_read_b128 v[200:203], v171 offset:19456
	ds_read_b128 v[204:207], v171 offset:20480
	ds_read_b128 v[208:211], v171 offset:21504
	ds_read_b128 v[212:215], v171 offset:22528
	ds_read_b128 v[216:219], v171 offset:23552
	global_load_lds_dwordx4 v[220:221], off
	s_add_i32 m0, s70, 0x2000
	v_lshl_add_u64 v[226:227], s[68:69], 0, v[184:185]
	s_add_u32 s68, s68, s49
	s_addc_u32 s69, s69, 0
	s_add_i32 s14, s14, s47
	global_load_lds_dwordx4 v[226:227], off
	v_lshl_add_u64 v[240:241], s[68:69], 0, v[180:181]
	s_mov_b32 m0, s14
	v_lshl_add_u64 v[242:243], s[68:69], 0, v[184:185]
	global_load_lds_dwordx4 v[240:241], off
	s_add_i32 m0, s14, 0x2000
	v_lshl_add_u64 v[244:245], v[166:167], 0, v[178:179]
	global_load_lds_dwordx4 v[242:243], off
	s_mov_b32 m0, s51
	v_lshl_add_u64 v[246:247], v[166:167], 0, v[182:183]
	global_load_lds_dwordx4 v[244:245], off
	s_mov_b32 m0, s52
	s_nop 0
	global_load_lds_dwordx4 v[246:247], off
	s_waitcnt vmcnt(8)
	s_waitcnt lgkmcnt(0)
	s_setprio 1
	s_barrier
	s_waitcnt lgkmcnt(0)
	v_mfma_f32_16x16x32_bf16 v[60:63], v[130:133], v[162:165], v[60:63]
	v_mfma_f32_16x16x32_bf16 v[56:59], v[138:141], v[162:165], v[56:59]
	v_mfma_f32_16x16x32_bf16 v[44:47], v[130:133], v[196:199], v[44:47]
	v_mfma_f32_16x16x32_bf16 v[40:43], v[138:141], v[196:199], v[40:43]
	v_mfma_f32_16x16x32_bf16 v[28:31], v[130:133], v[204:207], v[28:31]
	v_mfma_f32_16x16x32_bf16 v[24:27], v[138:141], v[204:207], v[24:27]
	v_mfma_f32_16x16x32_bf16 v[12:15], v[130:133], v[212:215], v[12:15]
	v_mfma_f32_16x16x32_bf16 v[8:11], v[138:141], v[212:215], v[8:11]
	v_mfma_f32_16x16x32_bf16 v[60:63], v[134:137], v[192:195], v[60:63]
	v_mfma_f32_16x16x32_bf16 v[56:59], v[142:145], v[192:195], v[56:59]
	v_mfma_f32_16x16x32_bf16 v[44:47], v[134:137], v[200:203], v[44:47]
	v_mfma_f32_16x16x32_bf16 v[40:43], v[142:145], v[200:203], v[40:43]
	v_mfma_f32_16x16x32_bf16 v[28:31], v[134:137], v[208:211], v[28:31]
	v_mfma_f32_16x16x32_bf16 v[24:27], v[142:145], v[208:211], v[24:27]
	v_mfma_f32_16x16x32_bf16 v[12:15], v[134:137], v[216:219], v[12:15]
	v_mfma_f32_16x16x32_bf16 v[8:11], v[142:145], v[216:219], v[8:11]
	s_setprio 0
	s_setprio 1
	v_mfma_f32_16x16x32_bf16 v[52:55], v[146:149], v[162:165], v[52:55]
	v_mfma_f32_16x16x32_bf16 v[48:51], v[154:157], v[162:165], v[48:51]
	v_mfma_f32_16x16x32_bf16 v[36:39], v[146:149], v[196:199], v[36:39]
	v_mfma_f32_16x16x32_bf16 v[32:35], v[154:157], v[196:199], v[32:35]
	v_mfma_f32_16x16x32_bf16 v[20:23], v[146:149], v[204:207], v[20:23]
	v_mfma_f32_16x16x32_bf16 v[16:19], v[154:157], v[204:207], v[16:19]
	v_mfma_f32_16x16x32_bf16 v[4:7], v[146:149], v[212:215], v[4:7]
	v_mfma_f32_16x16x32_bf16 v[0:3], v[154:157], v[212:215], v[0:3]
	v_mfma_f32_16x16x32_bf16 v[52:55], v[150:153], v[192:195], v[52:55]
	v_mfma_f32_16x16x32_bf16 v[48:51], v[158:161], v[192:195], v[48:51]
	v_mfma_f32_16x16x32_bf16 v[36:39], v[150:153], v[200:203], v[36:39]
	v_mfma_f32_16x16x32_bf16 v[32:35], v[158:161], v[200:203], v[32:35]
	v_mfma_f32_16x16x32_bf16 v[20:23], v[150:153], v[208:211], v[20:23]
	v_mfma_f32_16x16x32_bf16 v[16:19], v[158:161], v[208:211], v[16:19]
	v_mfma_f32_16x16x32_bf16 v[4:7], v[150:153], v[216:219], v[4:7]
	v_mfma_f32_16x16x32_bf16 v[0:3], v[158:161], v[216:219], v[0:3]
	s_setprio 0
	s_barrier
; #define PG8_STAGE(bufoff, gbase, voff) do { _Pragma("unroll") for (int _i = 0; _i < 2; ++_i) \
;         __builtin_amdgcn_global_load_lds((const unsigned*)((const char*)(gbase) + (voff)[_i]), (LAS unsigned*)(lds + (bufoff) + ldsw + _i * 8192), 16, 0, 0); } while (0)
; #define PG8_LDA(dst, b, h) do { _Pragma("unroll") for (int m = 0; m < 4; ++m) _Pragma("unroll") for (int k = 0; k < 2; ++k) dst[m][k] = *(const LAS bf16x8*)(lds + PG8_SA(b, h) + aoff + m * 2048 + k * 1024); } while (0)
; #define PG8_LDB(dst, b, h) do { _Pragma("unroll") for (int n = 0; n < 2; ++n) _Pragma("unroll") for (int k = 0; k < 2; ++k) dst[n][k] = *(const LAS bf16x8*)(lds + PG8_SB(b, h) + boff + n * 2048 + k * 1024); } while (0)
; #define PG8_MMA(ai, bj, At, Bt) do { __builtin_amdgcn_s_setprio(1); _Pragma("unroll") for (int k = 0; k < 2; ++k) _Pragma("unroll") for (int m = 0; m < 4; ++m) _Pragma("unroll") for (int n = 0; n < 2; ++n) \
;         acc[ai][bj][m][n] = __builtin_amdgcn_mfma_f32_16x16x32_bf16(Bt[n][k], At[m][k], acc[ai][bj][m][n], 0, 0, 0); __builtin_amdgcn_s_setprio(0); } while (0)
; #define PG8_WAIT_V(n) asm volatile("s_waitcnt vmcnt(" #n ")" ::: "memory")
; #define PG8_WAIT_L(n) asm volatile("s_waitcnt lgkmcnt(" #n ")" ::: "memory")
; #define PG8_BAR __builtin_amdgcn_s_barrier()
; #define PG8_SCHED __builtin_amdgcn_sched_barrier(0)
; template <class Epi, bool ALIGN_EPI>
; __device__ __forceinline__ void gemm_phase(LAS unsigned char* lds, const Gemm g, const StaticOrder& S, const Epi& E, const int tid) {
;     ...
;             PG8_LDB(B0, 1, 0); PG8_LDB(B1, 1, 1); PG8_SCHED; PG8_LDA(At, 1, 0); PG8_STAGE(PG8_SA(0, 1), a2 + hA, voffA);
;             PG8_WAIT_V(8); PG8_WAIT_L(0); PG8_BAR; PG8_MMA(0, 0, At, B0); PG8_MMA(0, 1, At, B1); PG8_BAR; PG8_SCHED;
	s_add_i32 s14, 0, 0x18000
	s_add_i32 s68, 0, 0x1c000
	v_add_u32_e32 v142, s14, v239
	v_add_u32_e32 v158, s68, v239
	ds_read_b128 v[130:133], v142
	ds_read_b128 v[134:137], v142 offset:1024
	ds_read_b128 v[138:141], v142 offset:2048
	ds_read_b128 v[142:145], v142 offset:3072
	ds_read_b128 v[146:149], v158
	ds_read_b128 v[150:153], v158 offset:1024
	ds_read_b128 v[154:157], v158 offset:2048
	ds_read_b128 v[158:161], v158 offset:3072
	v_lshl_add_u64 v[166:167], v[166:167], 0, s[94:95]
	s_mov_b32 m0, s53
	v_lshl_add_u64 v[248:249], v[166:167], 0, v[178:179]
	ds_read_b128 v[162:165], v171 offset:32768
	ds_read_b128 v[192:195], v171 offset:33792
	ds_read_b128 v[196:199], v171 offset:34816
	ds_read_b128 v[200:203], v171 offset:35840
	ds_read_b128 v[204:207], v171 offset:36864
	ds_read_b128 v[208:211], v171 offset:37888
	ds_read_b128 v[212:215], v171 offset:38912
	ds_read_b128 v[216:219], v171 offset:39936
	global_load_lds_dwordx4 v[248:249], off
	v_lshl_add_u64 v[166:167], v[166:167], 0, v[182:183]
	s_mov_b32 m0, s54
	s_nop 0
	global_load_lds_dwordx4 v[166:167], off
	s_waitcnt vmcnt(8)
	s_waitcnt lgkmcnt(0)
	s_setprio 1
	s_barrier
	s_waitcnt lgkmcnt(0)
	v_mfma_f32_16x16x32_bf16 v[124:127], v[130:133], v[162:165], v[124:127]
	v_mfma_f32_16x16x32_bf16 v[120:123], v[138:141], v[162:165], v[120:123]
	v_mfma_f32_16x16x32_bf16 v[108:111], v[130:133], v[196:199], v[108:111]
	v_mfma_f32_16x16x32_bf16 v[104:107], v[138:141], v[196:199], v[104:107]
	v_mfma_f32_16x16x32_bf16 v[92:95], v[130:133], v[204:207], v[92:95]
	v_mfma_f32_16x16x32_bf16 v[88:91], v[138:141], v[204:207], v[88:91]
	v_mfma_f32_16x16x32_bf16 v[76:79], v[130:133], v[212:215], v[76:79]
	v_mfma_f32_16x16x32_bf16 v[72:75], v[138:141], v[212:215], v[72:75]
	v_mfma_f32_16x16x32_bf16 v[124:127], v[134:137], v[192:195], v[124:127]
	v_mfma_f32_16x16x32_bf16 v[120:123], v[142:145], v[192:195], v[120:123]
	v_mfma_f32_16x16x32_bf16 v[108:111], v[134:137], v[200:203], v[108:111]
	v_mfma_f32_16x16x32_bf16 v[104:107], v[142:145], v[200:203], v[104:107]
	v_mfma_f32_16x16x32_bf16 v[92:95], v[134:137], v[208:211], v[92:95]
	v_mfma_f32_16x16x32_bf16 v[88:91], v[142:145], v[208:211], v[88:91]
	v_mfma_f32_16x16x32_bf16 v[76:79], v[134:137], v[216:219], v[76:79]
	v_mfma_f32_16x16x32_bf16 v[72:75], v[142:145], v[216:219], v[72:75]
	s_setprio 0
	s_setprio 1
	v_mfma_f32_16x16x32_bf16 v[116:119], v[146:149], v[162:165], v[116:119]
	v_mfma_f32_16x16x32_bf16 v[112:115], v[154:157], v[162:165], v[112:115]
	v_mfma_f32_16x16x32_bf16 v[100:103], v[146:149], v[196:199], v[100:103]
	v_mfma_f32_16x16x32_bf16 v[96:99], v[154:157], v[196:199], v[96:99]
	v_mfma_f32_16x16x32_bf16 v[84:87], v[146:149], v[204:207], v[84:87]
	v_mfma_f32_16x16x32_bf16 v[80:83], v[154:157], v[204:207], v[80:83]
	v_mfma_f32_16x16x32_bf16 v[68:71], v[146:149], v[212:215], v[68:71]
	v_mfma_f32_16x16x32_bf16 v[64:67], v[154:157], v[212:215], v[64:67]
	v_mfma_f32_16x16x32_bf16 v[116:119], v[150:153], v[192:195], v[116:119]
	v_mfma_f32_16x16x32_bf16 v[112:115], v[158:161], v[192:195], v[112:115]
	v_mfma_f32_16x16x32_bf16 v[100:103], v[150:153], v[200:203], v[100:103]
	v_mfma_f32_16x16x32_bf16 v[96:99], v[158:161], v[200:203], v[96:99]
	v_mfma_f32_16x16x32_bf16 v[84:87], v[150:153], v[208:211], v[84:87]
	v_mfma_f32_16x16x32_bf16 v[80:83], v[158:161], v[208:211], v[80:83]
	v_mfma_f32_16x16x32_bf16 v[68:71], v[150:153], v[216:219], v[68:71]
	v_mfma_f32_16x16x32_bf16 v[64:67], v[158:161], v[216:219], v[64:67]
	s_setprio 0
	s_barrier
; #define PG8_STAGE(bufoff, gbase, voff) do { _Pragma("unroll") for (int _i = 0; _i < 2; ++_i) \
;         __builtin_amdgcn_global_load_lds((const unsigned*)((const char*)(gbase) + (voff)[_i]), (LAS unsigned*)(lds + (bufoff) + ldsw + _i * 8192), 16, 0, 0); } while (0)
; #define PG8_LDA(dst, b, h) do { _Pragma("unroll") for (int m = 0; m < 4; ++m) _Pragma("unroll") for (int k = 0; k < 2; ++k) dst[m][k] = *(const LAS bf16x8*)(lds + PG8_SA(b, h) + aoff + m * 2048 + k * 1024); } while (0)
; #define PG8_MMA(ai, bj, At, Bt) do { __builtin_amdgcn_s_setprio(1); _Pragma("unroll") for (int k = 0; k < 2; ++k) _Pragma("unroll") for (int m = 0; m < 4; ++m) _Pragma("unroll") for (int n = 0; n < 2; ++n) \
;         acc[ai][bj][m][n] = __builtin_amdgcn_mfma_f32_16x16x32_bf16(Bt[n][k], At[m][k], acc[ai][bj][m][n], 0, 0, 0); __builtin_amdgcn_s_setprio(0); } while (0)
; #define PG8_WAIT_V(n) asm volatile("s_waitcnt vmcnt(" #n ")" ::: "memory")
; #define PG8_WAIT_L(n) asm volatile("s_waitcnt lgkmcnt(" #n ")" ::: "memory")
; #define PG8_BAR __builtin_amdgcn_s_barrier()
; #define PG8_SCHED __builtin_amdgcn_sched_barrier(0)
; template <class Epi, bool ALIGN_EPI>
; __device__ __forceinline__ void gemm_phase(LAS unsigned char* lds, const Gemm g, const StaticOrder& S, const Epi& E, const int tid) {
;     ...
;             PG8_LDA(At, 1, 1); PG8_STAGE(PG8_SB(1, 0), b3, voffB); PG8_STAGE(PG8_SB(1, 1), b3 + hB, voffB); PG8_STAGE(PG8_SA(1, 0), a3, voffA);
;             PG8_WAIT_V(8); PG8_WAIT_L(0); PG8_BAR; PG8_MMA(1, 0, At, B0); PG8_MMA(1, 1, At, B1); PG8_BAR; PG8_SCHED;
;         }
	s_add_i32 s14, s14, s47
	v_lshl_add_u64 v[166:167], v[220:221], 0, s[92:93]
	s_mov_b32 m0, s14
	ds_read_b128 v[162:165], v171 offset:49152
	ds_read_b128 v[192:195], v171 offset:50176
	ds_read_b128 v[196:199], v171 offset:51200
	ds_read_b128 v[200:203], v171 offset:52224
	ds_read_b128 v[204:207], v171 offset:53248
	ds_read_b128 v[208:211], v171 offset:54272
	ds_read_b128 v[212:215], v171 offset:55296
	ds_read_b128 v[216:219], v171 offset:56320
	global_load_lds_dwordx4 v[166:167], off
	v_lshl_add_u64 v[166:167], v[226:227], 0, s[92:93]
	s_add_i32 m0, s14, 0x2000
	s_add_i32 s14, s68, s47
	global_load_lds_dwordx4 v[166:167], off
	v_lshl_add_u64 v[166:167], v[240:241], 0, s[92:93]
	s_mov_b32 m0, s14
	s_nop 0
	global_load_lds_dwordx4 v[166:167], off
	v_lshl_add_u64 v[166:167], v[242:243], 0, s[92:93]
	s_add_i32 m0, s14, 0x2000
	s_nop 0
	global_load_lds_dwordx4 v[166:167], off
	v_lshl_add_u64 v[166:167], v[244:245], 0, s[92:93]
	s_mov_b32 m0, s55
	s_nop 0
	global_load_lds_dwordx4 v[166:167], off
	v_lshl_add_u64 v[166:167], v[246:247], 0, s[92:93]
	s_mov_b32 m0, s56
	s_nop 0
	global_load_lds_dwordx4 v[166:167], off
	s_waitcnt vmcnt(8)
	s_waitcnt lgkmcnt(0)
	s_setprio 1
	s_barrier
	s_waitcnt lgkmcnt(0)
	v_mfma_f32_16x16x32_bf16 v[60:63], v[130:133], v[162:165], v[60:63]
	v_mfma_f32_16x16x32_bf16 v[56:59], v[138:141], v[162:165], v[56:59]
	v_mfma_f32_16x16x32_bf16 v[44:47], v[130:133], v[196:199], v[44:47]
	v_mfma_f32_16x16x32_bf16 v[40:43], v[138:141], v[196:199], v[40:43]
	v_mfma_f32_16x16x32_bf16 v[28:31], v[130:133], v[204:207], v[28:31]
	v_mfma_f32_16x16x32_bf16 v[24:27], v[138:141], v[204:207], v[24:27]
	v_mfma_f32_16x16x32_bf16 v[12:15], v[130:133], v[212:215], v[12:15]
	v_mfma_f32_16x16x32_bf16 v[8:11], v[138:141], v[212:215], v[8:11]
	v_mfma_f32_16x16x32_bf16 v[60:63], v[134:137], v[192:195], v[60:63]
	v_mfma_f32_16x16x32_bf16 v[56:59], v[142:145], v[192:195], v[56:59]
	v_mfma_f32_16x16x32_bf16 v[44:47], v[134:137], v[200:203], v[44:47]
	v_mfma_f32_16x16x32_bf16 v[40:43], v[142:145], v[200:203], v[40:43]
	v_mfma_f32_16x16x32_bf16 v[28:31], v[134:137], v[208:211], v[28:31]
	v_mfma_f32_16x16x32_bf16 v[24:27], v[142:145], v[208:211], v[24:27]
	v_mfma_f32_16x16x32_bf16 v[12:15], v[134:137], v[216:219], v[12:15]
	v_mfma_f32_16x16x32_bf16 v[8:11], v[142:145], v[216:219], v[8:11]
	s_setprio 0
	s_setprio 1
	v_mfma_f32_16x16x32_bf16 v[52:55], v[146:149], v[162:165], v[52:55]
	v_mfma_f32_16x16x32_bf16 v[48:51], v[154:157], v[162:165], v[48:51]
	v_mfma_f32_16x16x32_bf16 v[36:39], v[146:149], v[196:199], v[36:39]
	v_mfma_f32_16x16x32_bf16 v[32:35], v[154:157], v[196:199], v[32:35]
	v_mfma_f32_16x16x32_bf16 v[20:23], v[146:149], v[204:207], v[20:23]
	v_mfma_f32_16x16x32_bf16 v[16:19], v[154:157], v[204:207], v[16:19]
	v_mfma_f32_16x16x32_bf16 v[4:7], v[146:149], v[212:215], v[4:7]
	v_mfma_f32_16x16x32_bf16 v[0:3], v[154:157], v[212:215], v[0:3]
	v_mfma_f32_16x16x32_bf16 v[52:55], v[150:153], v[192:195], v[52:55]
	v_mfma_f32_16x16x32_bf16 v[48:51], v[158:161], v[192:195], v[48:51]
	v_mfma_f32_16x16x32_bf16 v[36:39], v[150:153], v[200:203], v[36:39]
	v_mfma_f32_16x16x32_bf16 v[32:35], v[158:161], v[200:203], v[32:35]
	v_mfma_f32_16x16x32_bf16 v[20:23], v[150:153], v[208:211], v[20:23]
	v_mfma_f32_16x16x32_bf16 v[16:19], v[158:161], v[208:211], v[16:19]
	v_mfma_f32_16x16x32_bf16 v[4:7], v[150:153], v[216:219], v[4:7]
	v_mfma_f32_16x16x32_bf16 v[0:3], v[158:161], v[216:219], v[0:3]
	s_setprio 0
	s_barrier
	s_add_u32 s10, s10, 0x100
	s_addc_u32 s11, s11, 0
	v_lshl_add_u64 v[128:129], v[128:129], 0, s[80:81]
	s_cmp_ge_u32 s15, s48
	s_mov_b32 s14, s15
	s_cbranch_scc0 .LBB0_274

; __device__ __forceinline__ unsigned cvt_pk_bf16(float lo, float hi) { unsigned r; asm volatile("v_cvt_pk_bf16_f32 %0, %1, %2" : "=v"(r) : "v"(lo), "v"(hi)); return r; }
; __device__ __forceinline__ float siluf_(float x) { return x * sigmoidf_(x); }
; #define PG8_STAGE(bufoff, gbase, voff) do { _Pragma("unroll") for (int _i = 0; _i < 2; ++_i) \
;         __builtin_amdgcn_global_load_lds((const unsigned*)((const char*)(gbase) + (voff)[_i]), (LAS unsigned*)(lds + (bufoff) + ldsw + _i * 8192), 16, 0, 0); } while (0)
; #define PG8_LDA(dst, b, h) do { _Pragma("unroll") for (int m = 0; m < 4; ++m) _Pragma("unroll") for (int k = 0; k < 2; ++k) dst[m][k] = *(const LAS bf16x8*)(lds + PG8_SA(b, h) + aoff + m * 2048 + k * 1024); } while (0)
; #define PG8_LDB(dst, b, h) do { _Pragma("unroll") for (int n = 0; n < 2; ++n) _Pragma("unroll") for (int k = 0; k < 2; ++k) dst[n][k] = *(const LAS bf16x8*)(lds + PG8_SB(b, h) + boff + n * 2048 + k * 1024); } while (0)
; #define PG8_WAIT_V(n) asm volatile("s_waitcnt vmcnt(" #n ")" ::: "memory")
; #define PG8_WAIT_L(n) asm volatile("s_waitcnt lgkmcnt(" #n ")" ::: "memory")
; #define PG8_BAR __builtin_amdgcn_s_barrier()
;     __device__ __forceinline__ void operator()(const f32x4 (&acc)[2][2][4][2], const Unit& u, int wr, int wc, int fr, int fq) const {
;     ...
;         for (int ai = 0; ai < 2; ++ai)
; #pragma unroll
;             for (int m = 0; m < 4; ++m) { const int row = row0 + ai * HALF + m * 16; bf16_t* rowp = O + (size_t)row * ldc + col0; const float rs = rsv[ai][m];
;                 f32x4 v0, v1;
; #pragma unroll
;                 for (int j = 0; j < 4; ++j) { v0[j] = siluf_(acc[ai][0][m][0][j] * rs) * (acc[ai][1][m][0][j] * rs); v1[j] = siluf_(acc[ai][0][m][1][j] * rs) * (acc[ai][1][m][1][j] * rs); }
;                 u32x4 w; w.x = cvt_pk_bf16(v0[0], v0[1]); w.y = cvt_pk_bf16(v0[2], v0[3]); w.z = cvt_pk_bf16(v1[0], v1[1]); w.w = cvt_pk_bf16(v1[2], v1[3]);
;                 *(u32x4*)rowp = w; }
; template <class Epi, bool ALIGN_EPI>
; __device__ __forceinline__ void gemm_phase(LAS unsigned char* lds, const Gemm g, const StaticOrder& S, const Epi& E, const int tid) {
;     ...
;             PG8_LDB(B0, 0, 0); PG8_LDB(B1, 0, 1); PG8_SCHED; PG8_LDA(At, 0, 0); PG8_STAGE(PG8_SA(1, 1), a1 + hA, voffA);
;             PG8_WAIT_V(8); PG8_WAIT_L(0); PG8_BAR; PG8_MMA(0, 0, At, B0); PG8_MMA(0, 1, At, B1); PG8_BAR; PG8_SCHED;
.Lgu_first_epi:
	s_add_i32 s11, s10, 2
	s_cmp_eq_u32 s58, s10
	v_lshl_add_u64 v[146:147], v[142:143], 0, s[92:93]
	s_cselect_b64 vcc, -1, 0
	v_add_u32_e32 v150, s33, v151
	s_add_i32 s10, 0, 0x14000
	v_cndmask_b32_e32 v167, v147, v139, vcc
	v_cndmask_b32_e32 v166, v146, v138, vcc
	ds_read_b128 v[146:149], v150
	ds_read_b128 v[154:157], v150 offset:1024
	ds_read_b128 v[158:161], v150 offset:2048
	ds_read_b128 v[162:165], v150 offset:3072
	v_add_u32_e32 v150, s10, v151
	ds_read_b128 v[176:179], v150
	ds_read_b128 v[180:183], v150 offset:1024
	ds_read_b128 v[184:187], v150 offset:2048
	ds_read_b128 v[188:191], v150 offset:3072
	v_cndmask_b32_e32 v221, v145, v141, vcc
	v_cndmask_b32_e32 v220, v144, v140, vcc
	v_lshl_add_u64 v[226:227], v[142:143], 0, v[134:135]
	s_add_i32 m0, s51, 0xc000
	ds_read_b128 v[192:195], v153
	ds_read_b128 v[196:199], v153 offset:1024
	ds_read_b128 v[200:203], v153 offset:2048
	ds_read_b128 v[204:207], v153 offset:3072
	ds_read_b128 v[208:211], v153 offset:4096
	ds_read_b128 v[212:215], v153 offset:5120
	ds_read_b128 v[216:219], v153 offset:6144
	ds_read_b128 v[240:243], v153 offset:7168
	global_load_lds_dwordx4 v[226:227], off
	v_lshl_add_u64 v[226:227], v[142:143], 0, v[136:137]
	s_add_i32 m0, s51, 0xe000
	s_nop 0
	global_load_lds_dwordx4 v[226:227], off
	s_waitcnt vmcnt(12)
	s_waitcnt lgkmcnt(0)
	s_setprio 1
	s_barrier
	s_waitcnt lgkmcnt(0)
	v_mfma_f32_16x16x32_bf16 v[120:123], v[146:149], v[192:195], 0
	s_lshl_b32 s98, s28, 5
	s_mov_b32 s99, 0
	s_mov_b32 s100, 0xbfb8aa3b
	s_mov_b32 s101, 0xbfb8aa3b
	v_mul_f32_e32 v56, v238, v56
	v_mul_f32_e32 v57, v238, v57
	v_mul_f32_e32 v58, v238, v58
	v_mul_f32_e32 v59, v238, v59
	v_mul_f32_e32 v60, v238, v60
	v_mul_f32_e32 v61, v238, v61
	v_mfma_f32_16x16x32_bf16 v[112:115], v[158:161], v[192:195], 0
	v_mul_f32_e32 v62, v238, v62
	v_mul_f32_e32 v63, v238, v63
	v_mul_f32_e32 v224, s100, v56
	v_mul_f32_e32 v225, s101, v57
	v_mul_f32_e32 v228, s100, v58
	v_mul_f32_e32 v229, s101, v59
	v_exp_f32_e32 v224, v224
	v_exp_f32_e32 v225, v225
	v_exp_f32_e32 v228, v228
	v_exp_f32_e32 v229, v229
	v_mfma_f32_16x16x32_bf16 v[104:107], v[146:149], v[200:203], 0
	v_add_f32_e32 v224, 1.0, v224
	v_add_f32_e32 v225, 1.0, v225
	v_add_f32_e32 v228, 1.0, v228
	v_add_f32_e32 v229, 1.0, v229
	v_rcp_f32_e32 v224, v224
	v_rcp_f32_e32 v225, v225
	v_rcp_f32_e32 v228, v228
	v_rcp_f32_e32 v229, v229
	v_nop
	v_mul_f32_e32 v56, v224, v56
	v_mfma_f32_16x16x32_bf16 v[96:99], v[158:161], v[200:203], 0
	v_mul_f32_e32 v57, v225, v57
	v_mul_f32_e32 v58, v228, v58
	v_mul_f32_e32 v59, v229, v59
	v_mul_f32_e32 v56, v60, v56
	v_mul_f32_e32 v57, v61, v57
	v_mul_f32_e32 v58, v62, v58
	v_mul_f32_e32 v59, v63, v59
	v_mul_f32_e32 v48, v238, v48
	v_mul_f32_e32 v49, v238, v49
	v_mul_f32_e32 v50, v238, v50
	v_mfma_f32_16x16x32_bf16 v[88:91], v[146:149], v[208:211], 0
	v_mul_f32_e32 v51, v238, v51
	v_mul_f32_e32 v52, v238, v52
	v_mul_f32_e32 v53, v238, v53
	v_mul_f32_e32 v54, v238, v54
	v_mul_f32_e32 v55, v238, v55
	v_mul_f32_e32 v224, s100, v48
	v_mul_f32_e32 v225, s101, v49
	v_mul_f32_e32 v228, s100, v50
	v_mul_f32_e32 v229, s101, v51
	v_exp_f32_e32 v224, v224
	v_mfma_f32_16x16x32_bf16 v[80:83], v[158:161], v[208:211], 0
	v_exp_f32_e32 v225, v225
	v_exp_f32_e32 v228, v228
	v_exp_f32_e32 v229, v229
	v_add_f32_e32 v224, 1.0, v224
	v_add_f32_e32 v225, 1.0, v225
	v_add_f32_e32 v228, 1.0, v228
	v_add_f32_e32 v229, 1.0, v229
	v_rcp_f32_e32 v224, v224
	v_rcp_f32_e32 v225, v225
	v_rcp_f32_e32 v228, v228
	v_mfma_f32_16x16x32_bf16 v[72:75], v[146:149], v[216:219], 0
	v_rcp_f32_e32 v229, v229
	v_nop
	v_mul_f32_e32 v48, v224, v48
	v_mul_f32_e32 v49, v225, v49
	v_mul_f32_e32 v50, v228, v50
	v_mul_f32_e32 v51, v229, v51
	v_mul_f32_e32 v48, v52, v48
	v_mul_f32_e32 v49, v53, v49
	v_mul_f32_e32 v50, v54, v50
	v_mul_f32_e32 v51, v55, v51
	v_mfma_f32_16x16x32_bf16 v[64:67], v[158:161], v[216:219], 0
	v_cvt_pk_bf16_f32 v56, v56, v57
	v_cvt_pk_bf16_f32 v57, v58, v59
	v_cvt_pk_bf16_f32 v58, v48, v49
	v_cvt_pk_bf16_f32 v59, v50, v51
	global_store_dwordx4 v[232:233], v[56:59], off
	v_lshl_add_u64 v[232:233], v[232:233], 0, s[98:99]
	v_mul_f32_e32 v40, v239, v40
	v_mul_f32_e32 v41, v239, v41
	v_mul_f32_e32 v42, v239, v42
	v_mul_f32_e32 v43, v239, v43
	v_mfma_f32_16x16x32_bf16 v[120:123], v[154:157], v[196:199], v[120:123]
	v_mul_f32_e32 v44, v239, v44
	v_mul_f32_e32 v45, v239, v45
	v_mul_f32_e32 v46, v239, v46
	v_mul_f32_e32 v47, v239, v47
	v_mul_f32_e32 v224, s100, v40
	v_mul_f32_e32 v225, s101, v41
	v_mul_f32_e32 v228, s100, v42
	v_mul_f32_e32 v229, s101, v43
	v_exp_f32_e32 v224, v224
	v_exp_f32_e32 v225, v225
	v_mfma_f32_16x16x32_bf16 v[112:115], v[162:165], v[196:199], v[112:115]
	v_exp_f32_e32 v228, v228
	v_exp_f32_e32 v229, v229
	v_add_f32_e32 v224, 1.0, v224
	v_add_f32_e32 v225, 1.0, v225
	v_add_f32_e32 v228, 1.0, v228
	v_add_f32_e32 v229, 1.0, v229
	v_rcp_f32_e32 v224, v224
	v_rcp_f32_e32 v225, v225
	v_rcp_f32_e32 v228, v228
	v_rcp_f32_e32 v229, v229
	v_mfma_f32_16x16x32_bf16 v[104:107], v[154:157], v[204:207], v[104:107]
	v_nop
	v_mul_f32_e32 v40, v224, v40
	v_mul_f32_e32 v41, v225, v41
	v_mul_f32_e32 v42, v228, v42
	v_mul_f32_e32 v43, v229, v43
	v_mul_f32_e32 v40, v44, v40
	v_mul_f32_e32 v41, v45, v41
	v_mul_f32_e32 v42, v46, v42
	v_mul_f32_e32 v43, v47, v43
	v_mul_f32_e32 v32, v239, v32
	v_mfma_f32_16x16x32_bf16 v[96:99], v[162:165], v[204:207], v[96:99]
	v_mul_f32_e32 v33, v239, v33
	v_mul_f32_e32 v34, v239, v34
	v_mul_f32_e32 v35, v239, v35
	v_mul_f32_e32 v36, v239, v36
	v_mul_f32_e32 v37, v239, v37
	v_mul_f32_e32 v38, v239, v38
	v_mul_f32_e32 v39, v239, v39
	v_mul_f32_e32 v224, s100, v32
	v_mul_f32_e32 v225, s101, v33
; __device__ __forceinline__ unsigned cvt_pk_bf16(float lo, float hi) { unsigned r; asm volatile("v_cvt_pk_bf16_f32 %0, %1, %2" : "=v"(r) : "v"(lo), "v"(hi)); return r; }
; __device__ __forceinline__ float siluf_(float x) { return x * sigmoidf_(x); }
; #define PG8_MMA(ai, bj, At, Bt) do { __builtin_amdgcn_s_setprio(1); _Pragma("unroll") for (int k = 0; k < 2; ++k) _Pragma("unroll") for (int m = 0; m < 4; ++m) _Pragma("unroll") for (int n = 0; n < 2; ++n) \
;         acc[ai][bj][m][n] = __builtin_amdgcn_mfma_f32_16x16x32_bf16(Bt[n][k], At[m][k], acc[ai][bj][m][n], 0, 0, 0); __builtin_amdgcn_s_setprio(0); } while (0)
; #define PG8_WAIT_V(n) asm volatile("s_waitcnt vmcnt(" #n ")" ::: "memory")
; #define PG8_WAIT_L(n) asm volatile("s_waitcnt lgkmcnt(" #n ")" ::: "memory")
; #define PG8_BAR __builtin_amdgcn_s_barrier()
; #define PG8_SCHED __builtin_amdgcn_sched_barrier(0)
;     __device__ __forceinline__ void operator()(const f32x4 (&acc)[2][2][4][2], const Unit& u, int wr, int wc, int fr, int fq) const {
;     ...
;         for (int ai = 0; ai < 2; ++ai)
; #pragma unroll
;             for (int m = 0; m < 4; ++m) { const int row = row0 + ai * HALF + m * 16; bf16_t* rowp = O + (size_t)row * ldc + col0; const float rs = rsv[ai][m];
;                 f32x4 v0, v1;
; #pragma unroll
;                 for (int j = 0; j < 4; ++j) { v0[j] = siluf_(acc[ai][0][m][0][j] * rs) * (acc[ai][1][m][0][j] * rs); v1[j] = siluf_(acc[ai][0][m][1][j] * rs) * (acc[ai][1][m][1][j] * rs); }
;                 u32x4 w; w.x = cvt_pk_bf16(v0[0], v0[1]); w.y = cvt_pk_bf16(v0[2], v0[3]); w.z = cvt_pk_bf16(v1[0], v1[1]); w.w = cvt_pk_bf16(v1[2], v1[3]);
;                 *(u32x4*)rowp = w; }
; template <class Epi, bool ALIGN_EPI>
; __device__ __forceinline__ void gemm_phase(LAS unsigned char* lds, const Gemm g, const StaticOrder& S, const Epi& E, const int tid) {
;     ...
;             PG8_WAIT_V(8); PG8_WAIT_L(0); PG8_BAR; PG8_MMA(0, 0, At, B0); PG8_MMA(0, 1, At, B1); PG8_BAR; PG8_SCHED;
	v_mul_f32_e32 v228, s100, v34
	v_mfma_f32_16x16x32_bf16 v[88:91], v[154:157], v[212:215], v[88:91]
	v_mul_f32_e32 v229, s101, v35
	v_exp_f32_e32 v224, v224
	v_exp_f32_e32 v225, v225
	v_exp_f32_e32 v228, v228
	v_exp_f32_e32 v229, v229
	v_add_f32_e32 v224, 1.0, v224
	v_add_f32_e32 v225, 1.0, v225
	v_add_f32_e32 v228, 1.0, v228
	v_add_f32_e32 v229, 1.0, v229
	v_rcp_f32_e32 v224, v224
	v_mfma_f32_16x16x32_bf16 v[80:83], v[162:165], v[212:215], v[80:83]
	v_rcp_f32_e32 v225, v225
	v_rcp_f32_e32 v228, v228
	v_rcp_f32_e32 v229, v229
	v_nop
	v_mul_f32_e32 v32, v224, v32
	v_mul_f32_e32 v33, v225, v33
	v_mul_f32_e32 v34, v228, v34
	v_mul_f32_e32 v35, v229, v35
	v_mul_f32_e32 v32, v36, v32
	v_mul_f32_e32 v33, v37, v33
	v_mfma_f32_16x16x32_bf16 v[72:75], v[154:157], v[240:243], v[72:75]
	v_mul_f32_e32 v34, v38, v34
	v_mul_f32_e32 v35, v39, v35
	v_cvt_pk_bf16_f32 v40, v40, v41
	v_cvt_pk_bf16_f32 v41, v42, v43
	v_cvt_pk_bf16_f32 v42, v32, v33
	v_cvt_pk_bf16_f32 v43, v34, v35
	global_store_dwordx4 v[232:233], v[40:43], off
	v_lshl_add_u64 v[232:233], v[232:233], 0, s[98:99]
	v_mul_f32_e32 v24, v230, v24
	v_mul_f32_e32 v25, v230, v25
	v_mfma_f32_16x16x32_bf16 v[64:67], v[162:165], v[240:243], v[64:67]
	v_mul_f32_e32 v26, v230, v26
	v_mul_f32_e32 v27, v230, v27
	v_mul_f32_e32 v28, v230, v28
	v_mul_f32_e32 v29, v230, v29
	v_mul_f32_e32 v30, v230, v30
	v_mul_f32_e32 v31, v230, v31
	v_mul_f32_e32 v224, s100, v24
	v_mul_f32_e32 v225, s101, v25
	v_mul_f32_e32 v228, s100, v26
	v_mul_f32_e32 v229, s101, v27
	s_setprio 0
	s_setprio 1
	v_mfma_f32_16x16x32_bf16 v[124:127], v[176:179], v[192:195], 0
	v_exp_f32_e32 v224, v224
	v_exp_f32_e32 v225, v225
	v_exp_f32_e32 v228, v228
	v_exp_f32_e32 v229, v229
	v_add_f32_e32 v224, 1.0, v224
	v_add_f32_e32 v225, 1.0, v225
	v_add_f32_e32 v228, 1.0, v228
	v_add_f32_e32 v229, 1.0, v229
	v_rcp_f32_e32 v224, v224
	v_rcp_f32_e32 v225, v225
	v_mfma_f32_16x16x32_bf16 v[116:119], v[184:187], v[192:195], 0
	v_rcp_f32_e32 v228, v228
	v_rcp_f32_e32 v229, v229
	v_nop
	v_mul_f32_e32 v24, v224, v24
	v_mul_f32_e32 v25, v225, v25
	v_mul_f32_e32 v26, v228, v26
	v_mul_f32_e32 v27, v229, v27
	v_mul_f32_e32 v24, v28, v24
	v_mul_f32_e32 v25, v29, v25
	v_mul_f32_e32 v26, v30, v26
	v_mfma_f32_16x16x32_bf16 v[108:111], v[176:179], v[200:203], 0
	v_mul_f32_e32 v27, v31, v27
	v_mul_f32_e32 v16, v230, v16
	v_mul_f32_e32 v17, v230, v17
	v_mul_f32_e32 v18, v230, v18
	v_mul_f32_e32 v19, v230, v19
	v_mul_f32_e32 v20, v230, v20
	v_mul_f32_e32 v21, v230, v21
	v_mul_f32_e32 v22, v230, v22
	v_mul_f32_e32 v23, v230, v23
	v_mul_f32_e32 v224, s100, v16
	v_mfma_f32_16x16x32_bf16 v[100:103], v[184:187], v[200:203], 0
	v_mul_f32_e32 v225, s101, v17
	v_mul_f32_e32 v228, s100, v18
	v_mul_f32_e32 v229, s101, v19
	v_exp_f32_e32 v224, v224
	v_exp_f32_e32 v225, v225
	v_exp_f32_e32 v228, v228
	v_exp_f32_e32 v229, v229
	v_add_f32_e32 v224, 1.0, v224
	v_add_f32_e32 v225, 1.0, v225
	v_add_f32_e32 v228, 1.0, v228
	v_mfma_f32_16x16x32_bf16 v[92:95], v[176:179], v[208:211], 0
	v_add_f32_e32 v229, 1.0, v229
	v_rcp_f32_e32 v224, v224
	v_rcp_f32_e32 v225, v225
	v_rcp_f32_e32 v228, v228
	v_rcp_f32_e32 v229, v229
	v_nop
	v_mul_f32_e32 v16, v224, v16
	v_mul_f32_e32 v17, v225, v17
	v_mul_f32_e32 v18, v228, v18
	v_mul_f32_e32 v19, v229, v19
	v_mfma_f32_16x16x32_bf16 v[84:87], v[184:187], v[208:211], 0
	v_mul_f32_e32 v16, v20, v16
	v_mul_f32_e32 v17, v21, v17
	v_mul_f32_e32 v18, v22, v18
	v_mul_f32_e32 v19, v23, v19
	v_cvt_pk_bf16_f32 v24, v24, v25
	v_cvt_pk_bf16_f32 v25, v26, v27
	v_cvt_pk_bf16_f32 v26, v16, v17
	v_cvt_pk_bf16_f32 v27, v18, v19
	global_store_dwordx4 v[232:233], v[24:27], off
	v_lshl_add_u64 v[232:233], v[232:233], 0, s[98:99]
	v_mfma_f32_16x16x32_bf16 v[76:79], v[176:179], v[216:219], 0
	v_mul_f32_e32 v8, v231, v8
	v_mul_f32_e32 v9, v231, v9
	v_mul_f32_e32 v10, v231, v10
	v_mul_f32_e32 v11, v231, v11
	v_mul_f32_e32 v12, v231, v12
	v_mul_f32_e32 v13, v231, v13
	v_mul_f32_e32 v14, v231, v14
	v_mul_f32_e32 v15, v231, v15
	v_mul_f32_e32 v224, s100, v8
	v_mul_f32_e32 v225, s101, v9
	v_mfma_f32_16x16x32_bf16 v[68:71], v[184:187], v[216:219], 0
	v_mul_f32_e32 v228, s100, v10
	v_mul_f32_e32 v229, s101, v11
	v_exp_f32_e32 v224, v224
	v_exp_f32_e32 v225, v225
	v_exp_f32_e32 v228, v228
	v_exp_f32_e32 v229, v229
	v_add_f32_e32 v224, 1.0, v224
	v_add_f32_e32 v225, 1.0, v225
	v_add_f32_e32 v228, 1.0, v228
	v_add_f32_e32 v229, 1.0, v229
	v_mfma_f32_16x16x32_bf16 v[124:127], v[180:183], v[196:199], v[124:127]
	v_rcp_f32_e32 v224, v224
	v_rcp_f32_e32 v225, v225
	v_rcp_f32_e32 v228, v228
	v_rcp_f32_e32 v229, v229
	v_nop
	v_mul_f32_e32 v8, v224, v8
	v_mul_f32_e32 v9, v225, v9
	v_mul_f32_e32 v10, v228, v10
	v_mul_f32_e32 v11, v229, v11
	v_mul_f32_e32 v8, v12, v8
	v_mfma_f32_16x16x32_bf16 v[116:119], v[188:191], v[196:199], v[116:119]
	v_mul_f32_e32 v9, v13, v9
	v_mul_f32_e32 v10, v14, v10
	v_mul_f32_e32 v11, v15, v11
	v_mul_f32_e32 v4, v231, v4
	v_mul_f32_e32 v5, v231, v5
	v_mul_f32_e32 v6, v231, v6
	v_mul_f32_e32 v7, v231, v7
	v_mul_f32_e32 v0, v231, v0
	v_mul_f32_e32 v1, v231, v1
	v_mul_f32_e32 v2, v231, v2
	v_mfma_f32_16x16x32_bf16 v[108:111], v[180:183], v[204:207], v[108:111]
	v_mul_f32_e32 v3, v231, v3
	v_mul_f32_e32 v224, s100, v4
	v_mul_f32_e32 v225, s101, v5
	v_mul_f32_e32 v228, s100, v6
	v_mul_f32_e32 v229, s101, v7
	v_exp_f32_e32 v224, v224
	v_exp_f32_e32 v225, v225
	v_exp_f32_e32 v228, v228
	v_exp_f32_e32 v229, v229
	v_add_f32_e32 v224, 1.0, v224
	v_mfma_f32_16x16x32_bf16 v[100:103], v[188:191], v[204:207], v[100:103]
	v_add_f32_e32 v225, 1.0, v225
	v_add_f32_e32 v228, 1.0, v228
	v_add_f32_e32 v229, 1.0, v229
	v_rcp_f32_e32 v224, v224
	v_rcp_f32_e32 v225, v225
	v_rcp_f32_e32 v228, v228
	v_rcp_f32_e32 v229, v229
	v_nop
	v_mul_f32_e32 v4, v224, v4
	v_mul_f32_e32 v5, v225, v5
	v_mfma_f32_16x16x32_bf16 v[92:95], v[180:183], v[212:215], v[92:95]
	v_mul_f32_e32 v6, v228, v6
	v_mul_f32_e32 v7, v229, v7
	v_mul_f32_e32 v4, v0, v4
	v_mul_f32_e32 v5, v1, v5
	v_mul_f32_e32 v6, v2, v6
	v_mul_f32_e32 v7, v3, v7
	v_cvt_pk_bf16_f32 v8, v8, v9
	v_cvt_pk_bf16_f32 v9, v10, v11
	v_cvt_pk_bf16_f32 v10, v4, v5
	v_cvt_pk_bf16_f32 v11, v6, v7
	v_mfma_f32_16x16x32_bf16 v[84:87], v[188:191], v[212:215], v[84:87]
	global_store_dwordx4 v[232:233], v[8:11], off
	v_mfma_f32_16x16x32_bf16 v[76:79], v[180:183], v[240:243], v[76:79]
	v_mfma_f32_16x16x32_bf16 v[68:71], v[188:191], v[240:243], v[68:71]
	s_setprio 0
	s_barrier
; #define PG8_STAGE(bufoff, gbase, voff) do { _Pragma("unroll") for (int _i = 0; _i < 2; ++_i) \
;         __builtin_amdgcn_global_load_lds((const unsigned*)((const char*)(gbase) + (voff)[_i]), (LAS unsigned*)(lds + (bufoff) + ldsw + _i * 8192), 16, 0, 0); } while (0)
; #define PG8_LDA(dst, b, h) do { _Pragma("unroll") for (int m = 0; m < 4; ++m) _Pragma("unroll") for (int k = 0; k < 2; ++k) dst[m][k] = *(const LAS bf16x8*)(lds + PG8_SA(b, h) + aoff + m * 2048 + k * 1024); } while (0)
; #define PG8_LDB(dst, b, h) do { _Pragma("unroll") for (int n = 0; n < 2; ++n) _Pragma("unroll") for (int k = 0; k < 2; ++k) dst[n][k] = *(const LAS bf16x8*)(lds + PG8_SB(b, h) + boff + n * 2048 + k * 1024); } while (0)
; #define PG8_MMA(ai, bj, At, Bt) do { __builtin_amdgcn_s_setprio(1); _Pragma("unroll") for (int k = 0; k < 2; ++k) _Pragma("unroll") for (int m = 0; m < 4; ++m) _Pragma("unroll") for (int n = 0; n < 2; ++n) \
;         acc[ai][bj][m][n] = __builtin_amdgcn_mfma_f32_16x16x32_bf16(Bt[n][k], At[m][k], acc[ai][bj][m][n], 0, 0, 0); __builtin_amdgcn_s_setprio(0); } while (0)
; #define PG8_WAIT_V(n) asm volatile("s_waitcnt vmcnt(" #n ")" ::: "memory")
; #define PG8_WAIT_L(n) asm volatile("s_waitcnt lgkmcnt(" #n ")" ::: "memory")
; #define PG8_BAR __builtin_amdgcn_s_barrier()
; #define PG8_SCHED __builtin_amdgcn_sched_barrier(0)
; template <class Epi, bool ALIGN_EPI>
; __device__ __forceinline__ void gemm_phase(LAS unsigned char* lds, const Gemm g, const StaticOrder& S, const Epi& E, const int tid) {
;     ...
;             PG8_LDA(At, 0, 1); PG8_STAGE(PG8_SB(0, 0), b2, voffB); PG8_STAGE(PG8_SB(0, 1), b2 + hB, voffB); PG8_STAGE(PG8_SA(0, 0), a2, voffA);
;             PG8_WAIT_V(8); PG8_WAIT_L(0); PG8_BAR; PG8_MMA(1, 0, At, B0); PG8_MMA(1, 1, At, B1); PG8_BAR; PG8_SCHED;
;             PG8_LDB(B0, 1, 0); PG8_LDB(B1, 1, 1); PG8_SCHED; PG8_LDA(At, 1, 0); PG8_STAGE(PG8_SA(0, 1), a2 + hA, voffA);
;             PG8_WAIT_V(8); PG8_WAIT_L(0); PG8_BAR; PG8_MMA(0, 0, At, B0); PG8_MMA(0, 1, At, B1); PG8_BAR; PG8_SCHED;
	s_add_i32 s65, s33, s45
	v_lshl_add_u64 v[226:227], v[220:221], 0, v[168:169]
	s_mov_b32 m0, s65
	ds_read_b128 v[192:195], v153 offset:16384
	ds_read_b128 v[196:199], v153 offset:17408
	ds_read_b128 v[200:203], v153 offset:18432
	ds_read_b128 v[204:207], v153 offset:19456
	ds_read_b128 v[208:211], v153 offset:20480
	ds_read_b128 v[212:215], v153 offset:21504
	ds_read_b128 v[216:219], v153 offset:22528
	ds_read_b128 v[240:243], v153 offset:23552
	global_load_lds_dwordx4 v[226:227], off
	v_lshl_add_u64 v[244:245], v[220:221], 0, v[128:129]
	s_add_i32 m0, s65, 0x2000
	v_lshl_add_u64 v[220:221], v[220:221], 0, s[12:13]
	s_add_i32 s10, s10, s45
	global_load_lds_dwordx4 v[244:245], off
	v_lshl_add_u64 v[246:247], v[220:221], 0, v[168:169]
	s_mov_b32 m0, s10
	v_lshl_add_u64 v[220:221], v[220:221], 0, v[128:129]
	global_load_lds_dwordx4 v[246:247], off
	s_add_i32 m0, s10, 0x2000
	v_lshl_add_u64 v[248:249], v[166:167], 0, v[132:133]
	global_load_lds_dwordx4 v[220:221], off
	s_mov_b32 m0, s51
	v_lshl_add_u64 v[250:251], v[166:167], 0, v[130:131]
	global_load_lds_dwordx4 v[248:249], off
	s_mov_b32 m0, s52
	s_nop 0
	global_load_lds_dwordx4 v[250:251], off
	s_waitcnt vmcnt(16)
	s_waitcnt lgkmcnt(0)
	s_setprio 1
	s_barrier
	s_waitcnt lgkmcnt(0)
	v_mfma_f32_16x16x32_bf16 v[56:59], v[146:149], v[192:195], 0
	v_mfma_f32_16x16x32_bf16 v[48:51], v[158:161], v[192:195], 0
	v_mfma_f32_16x16x32_bf16 v[40:43], v[146:149], v[200:203], 0
	v_mfma_f32_16x16x32_bf16 v[32:35], v[158:161], v[200:203], 0
	v_mfma_f32_16x16x32_bf16 v[24:27], v[146:149], v[208:211], 0
	v_mfma_f32_16x16x32_bf16 v[16:19], v[158:161], v[208:211], 0
	v_mfma_f32_16x16x32_bf16 v[8:11], v[146:149], v[216:219], 0
	v_mfma_f32_16x16x32_bf16 v[4:7], v[158:161], v[216:219], 0
	v_mfma_f32_16x16x32_bf16 v[56:59], v[154:157], v[196:199], v[56:59]
	v_mfma_f32_16x16x32_bf16 v[48:51], v[162:165], v[196:199], v[48:51]
	v_mfma_f32_16x16x32_bf16 v[40:43], v[154:157], v[204:207], v[40:43]
	v_mfma_f32_16x16x32_bf16 v[32:35], v[162:165], v[204:207], v[32:35]
	v_mfma_f32_16x16x32_bf16 v[24:27], v[154:157], v[212:215], v[24:27]
	v_mfma_f32_16x16x32_bf16 v[16:19], v[162:165], v[212:215], v[16:19]
	v_mfma_f32_16x16x32_bf16 v[8:11], v[154:157], v[240:243], v[8:11]
	v_mfma_f32_16x16x32_bf16 v[4:7], v[162:165], v[240:243], v[4:7]
	s_setprio 0
	s_setprio 1
	v_mfma_f32_16x16x32_bf16 v[60:63], v[176:179], v[192:195], 0
	v_mfma_f32_16x16x32_bf16 v[52:55], v[184:187], v[192:195], 0
	v_mfma_f32_16x16x32_bf16 v[44:47], v[176:179], v[200:203], 0
	v_mfma_f32_16x16x32_bf16 v[36:39], v[184:187], v[200:203], 0
	v_mfma_f32_16x16x32_bf16 v[28:31], v[176:179], v[208:211], 0
	v_mfma_f32_16x16x32_bf16 v[20:23], v[184:187], v[208:211], 0
	v_mfma_f32_16x16x32_bf16 v[12:15], v[176:179], v[216:219], 0
	v_mfma_f32_16x16x32_bf16 v[0:3], v[184:187], v[216:219], 0
	v_mfma_f32_16x16x32_bf16 v[60:63], v[180:183], v[196:199], v[60:63]
	v_mfma_f32_16x16x32_bf16 v[52:55], v[188:191], v[196:199], v[52:55]
	v_mfma_f32_16x16x32_bf16 v[44:47], v[180:183], v[204:207], v[44:47]
	v_mfma_f32_16x16x32_bf16 v[36:39], v[188:191], v[204:207], v[36:39]
	v_mfma_f32_16x16x32_bf16 v[28:31], v[180:183], v[212:215], v[28:31]
	v_mfma_f32_16x16x32_bf16 v[20:23], v[188:191], v[212:215], v[20:23]
	v_mfma_f32_16x16x32_bf16 v[12:15], v[180:183], v[240:243], v[12:15]
	v_mfma_f32_16x16x32_bf16 v[0:3], v[188:191], v[240:243], v[0:3]
	s_setprio 0
	s_barrier
	s_add_i32 s10, 0, 0x18000
	v_add_u32_e32 v150, s10, v151
	s_add_i32 s65, 0, 0x1c000
	ds_read_b128 v[146:149], v150
	ds_read_b128 v[154:157], v150 offset:1024
	ds_read_b128 v[158:161], v150 offset:2048
	ds_read_b128 v[162:165], v150 offset:3072
	v_add_u32_e32 v150, s65, v151
	ds_read_b128 v[176:179], v150
	ds_read_b128 v[180:183], v150 offset:1024
	ds_read_b128 v[184:187], v150 offset:2048
	ds_read_b128 v[188:191], v150 offset:3072
	v_lshl_add_u64 v[166:167], v[166:167], 0, s[94:95]
	s_mov_b32 m0, s53
	v_lshl_add_u64 v[252:253], v[166:167], 0, v[132:133]
	ds_read_b128 v[192:195], v153 offset:32768
	ds_read_b128 v[196:199], v153 offset:33792
	ds_read_b128 v[200:203], v153 offset:34816
	ds_read_b128 v[204:207], v153 offset:35840
	ds_read_b128 v[208:211], v153 offset:36864
	ds_read_b128 v[212:215], v153 offset:37888
	ds_read_b128 v[216:219], v153 offset:38912
	ds_read_b128 v[240:243], v153 offset:39936
	global_load_lds_dwordx4 v[252:253], off
	v_lshl_add_u64 v[166:167], v[166:167], 0, v[130:131]
	s_mov_b32 m0, s54
	s_nop 0
	global_load_lds_dwordx4 v[166:167], off
	s_waitcnt vmcnt(12)
	s_waitcnt lgkmcnt(0)
	s_setprio 1
	s_barrier
; #define PG8_STAGE(bufoff, gbase, voff) do { _Pragma("unroll") for (int _i = 0; _i < 2; ++_i) \
;         __builtin_amdgcn_global_load_lds((const unsigned*)((const char*)(gbase) + (voff)[_i]), (LAS unsigned*)(lds + (bufoff) + ldsw + _i * 8192), 16, 0, 0); } while (0)
; #define PG8_LDA(dst, b, h) do { _Pragma("unroll") for (int m = 0; m < 4; ++m) _Pragma("unroll") for (int k = 0; k < 2; ++k) dst[m][k] = *(const LAS bf16x8*)(lds + PG8_SA(b, h) + aoff + m * 2048 + k * 1024); } while (0)
; #define PG8_MMA(ai, bj, At, Bt) do { __builtin_amdgcn_s_setprio(1); _Pragma("unroll") for (int k = 0; k < 2; ++k) _Pragma("unroll") for (int m = 0; m < 4; ++m) _Pragma("unroll") for (int n = 0; n < 2; ++n) \
;         acc[ai][bj][m][n] = __builtin_amdgcn_mfma_f32_16x16x32_bf16(Bt[n][k], At[m][k], acc[ai][bj][m][n], 0, 0, 0); __builtin_amdgcn_s_setprio(0); } while (0)
; #define PG8_WAIT_V(n) asm volatile("s_waitcnt vmcnt(" #n ")" ::: "memory")
; #define PG8_WAIT_L(n) asm volatile("s_waitcnt lgkmcnt(" #n ")" ::: "memory")
; #define PG8_BAR __builtin_amdgcn_s_barrier()
; #define PG8_SCHED __builtin_amdgcn_sched_barrier(0)
; template <class Epi, bool ALIGN_EPI>
; __device__ __forceinline__ void gemm_phase(LAS unsigned char* lds, const Gemm g, const StaticOrder& S, const Epi& E, const int tid) {
;     ...
;             PG8_WAIT_V(8); PG8_WAIT_L(0); PG8_BAR; PG8_MMA(0, 0, At, B0); PG8_MMA(0, 1, At, B1); PG8_BAR; PG8_SCHED;
;             PG8_LDA(At, 1, 1); PG8_STAGE(PG8_SB(1, 0), b3, voffB); PG8_STAGE(PG8_SB(1, 1), b3 + hB, voffB); PG8_STAGE(PG8_SA(1, 0), a3, voffA);
;             PG8_WAIT_V(8); PG8_WAIT_L(0); PG8_BAR; PG8_MMA(1, 0, At, B0); PG8_MMA(1, 1, At, B1); PG8_BAR; PG8_SCHED;
	s_waitcnt lgkmcnt(0)
	v_mfma_f32_16x16x32_bf16 v[120:123], v[146:149], v[192:195], v[120:123]
	v_mfma_f32_16x16x32_bf16 v[112:115], v[158:161], v[192:195], v[112:115]
	v_mfma_f32_16x16x32_bf16 v[104:107], v[146:149], v[200:203], v[104:107]
	v_mfma_f32_16x16x32_bf16 v[96:99], v[158:161], v[200:203], v[96:99]
	v_mfma_f32_16x16x32_bf16 v[88:91], v[146:149], v[208:211], v[88:91]
	v_mfma_f32_16x16x32_bf16 v[80:83], v[158:161], v[208:211], v[80:83]
	v_mfma_f32_16x16x32_bf16 v[72:75], v[146:149], v[216:219], v[72:75]
	v_mfma_f32_16x16x32_bf16 v[64:67], v[158:161], v[216:219], v[64:67]
	v_mfma_f32_16x16x32_bf16 v[120:123], v[154:157], v[196:199], v[120:123]
	v_mfma_f32_16x16x32_bf16 v[112:115], v[162:165], v[196:199], v[112:115]
	v_mfma_f32_16x16x32_bf16 v[104:107], v[154:157], v[204:207], v[104:107]
	v_mfma_f32_16x16x32_bf16 v[96:99], v[162:165], v[204:207], v[96:99]
	v_mfma_f32_16x16x32_bf16 v[88:91], v[154:157], v[212:215], v[88:91]
	v_mfma_f32_16x16x32_bf16 v[80:83], v[162:165], v[212:215], v[80:83]
	v_mfma_f32_16x16x32_bf16 v[72:75], v[154:157], v[240:243], v[72:75]
	v_mfma_f32_16x16x32_bf16 v[64:67], v[162:165], v[240:243], v[64:67]
	s_setprio 0
	s_setprio 1
	v_mfma_f32_16x16x32_bf16 v[124:127], v[176:179], v[192:195], v[124:127]
	v_mfma_f32_16x16x32_bf16 v[116:119], v[184:187], v[192:195], v[116:119]
	v_mfma_f32_16x16x32_bf16 v[108:111], v[176:179], v[200:203], v[108:111]
	v_mfma_f32_16x16x32_bf16 v[100:103], v[184:187], v[200:203], v[100:103]
	v_mfma_f32_16x16x32_bf16 v[92:95], v[176:179], v[208:211], v[92:95]
	v_mfma_f32_16x16x32_bf16 v[84:87], v[184:187], v[208:211], v[84:87]
	v_mfma_f32_16x16x32_bf16 v[76:79], v[176:179], v[216:219], v[76:79]
	v_mfma_f32_16x16x32_bf16 v[68:71], v[184:187], v[216:219], v[68:71]
	v_mfma_f32_16x16x32_bf16 v[124:127], v[180:183], v[196:199], v[124:127]
	v_mfma_f32_16x16x32_bf16 v[116:119], v[188:191], v[196:199], v[116:119]
	v_mfma_f32_16x16x32_bf16 v[108:111], v[180:183], v[204:207], v[108:111]
	v_mfma_f32_16x16x32_bf16 v[100:103], v[188:191], v[204:207], v[100:103]
	v_mfma_f32_16x16x32_bf16 v[92:95], v[180:183], v[212:215], v[92:95]
	v_mfma_f32_16x16x32_bf16 v[84:87], v[188:191], v[212:215], v[84:87]
	v_mfma_f32_16x16x32_bf16 v[76:79], v[180:183], v[240:243], v[76:79]
	v_mfma_f32_16x16x32_bf16 v[68:71], v[188:191], v[240:243], v[68:71]
	s_setprio 0
	s_barrier
	s_add_i32 s10, s10, s45
	v_lshl_add_u64 v[166:167], v[226:227], 0, s[92:93]
	s_mov_b32 m0, s10
	ds_read_b128 v[192:195], v153 offset:49152
	ds_read_b128 v[196:199], v153 offset:50176
	ds_read_b128 v[200:203], v153 offset:51200
	ds_read_b128 v[204:207], v153 offset:52224
	ds_read_b128 v[208:211], v153 offset:53248
	ds_read_b128 v[212:215], v153 offset:54272
	ds_read_b128 v[216:219], v153 offset:55296
	ds_read_b128 v[240:243], v153 offset:56320
	global_load_lds_dwordx4 v[166:167], off
	v_lshl_add_u64 v[166:167], v[244:245], 0, s[92:93]
	s_add_i32 m0, s10, 0x2000
	s_add_i32 s10, s65, s45
	global_load_lds_dwordx4 v[166:167], off
	v_lshl_add_u64 v[166:167], v[246:247], 0, s[92:93]
	s_mov_b32 m0, s10
	s_nop 0
	global_load_lds_dwordx4 v[166:167], off
	v_lshl_add_u64 v[166:167], v[220:221], 0, s[92:93]
	s_add_i32 m0, s10, 0x2000
	s_nop 0
	global_load_lds_dwordx4 v[166:167], off
	v_lshl_add_u64 v[166:167], v[248:249], 0, s[92:93]
	s_mov_b32 m0, s56
	s_nop 0
	global_load_lds_dwordx4 v[166:167], off
	v_lshl_add_u64 v[166:167], v[250:251], 0, s[92:93]
	s_mov_b32 m0, s57
	s_nop 0
	global_load_lds_dwordx4 v[166:167], off
	s_waitcnt vmcnt(8)
	s_waitcnt lgkmcnt(0)
	s_setprio 1
	s_barrier
	s_waitcnt lgkmcnt(0)
	v_mfma_f32_16x16x32_bf16 v[56:59], v[146:149], v[192:195], v[56:59]
	v_mfma_f32_16x16x32_bf16 v[48:51], v[158:161], v[192:195], v[48:51]
	v_mfma_f32_16x16x32_bf16 v[40:43], v[146:149], v[200:203], v[40:43]
	v_mfma_f32_16x16x32_bf16 v[32:35], v[158:161], v[200:203], v[32:35]
	v_mfma_f32_16x16x32_bf16 v[24:27], v[146:149], v[208:211], v[24:27]
	v_mfma_f32_16x16x32_bf16 v[16:19], v[158:161], v[208:211], v[16:19]
	v_mfma_f32_16x16x32_bf16 v[8:11], v[146:149], v[216:219], v[8:11]
	v_mfma_f32_16x16x32_bf16 v[4:7], v[158:161], v[216:219], v[4:7]
	v_mfma_f32_16x16x32_bf16 v[56:59], v[154:157], v[196:199], v[56:59]
	v_mfma_f32_16x16x32_bf16 v[48:51], v[162:165], v[196:199], v[48:51]
	v_mfma_f32_16x16x32_bf16 v[40:43], v[154:157], v[204:207], v[40:43]
	v_mfma_f32_16x16x32_bf16 v[32:35], v[162:165], v[204:207], v[32:35]
	v_mfma_f32_16x16x32_bf16 v[24:27], v[154:157], v[212:215], v[24:27]
	v_mfma_f32_16x16x32_bf16 v[16:19], v[162:165], v[212:215], v[16:19]
	v_mfma_f32_16x16x32_bf16 v[8:11], v[154:157], v[240:243], v[8:11]
	v_mfma_f32_16x16x32_bf16 v[4:7], v[162:165], v[240:243], v[4:7]
	s_setprio 0
	s_setprio 1
	v_mfma_f32_16x16x32_bf16 v[60:63], v[176:179], v[192:195], v[60:63]
	v_mfma_f32_16x16x32_bf16 v[52:55], v[184:187], v[192:195], v[52:55]
	v_mfma_f32_16x16x32_bf16 v[44:47], v[176:179], v[200:203], v[44:47]
	v_mfma_f32_16x16x32_bf16 v[36:39], v[184:187], v[200:203], v[36:39]
	v_mfma_f32_16x16x32_bf16 v[28:31], v[176:179], v[208:211], v[28:31]
	v_mfma_f32_16x16x32_bf16 v[20:23], v[184:187], v[208:211], v[20:23]
	v_mfma_f32_16x16x32_bf16 v[12:15], v[176:179], v[216:219], v[12:15]
	v_mfma_f32_16x16x32_bf16 v[0:3], v[184:187], v[216:219], v[0:3]
	v_mfma_f32_16x16x32_bf16 v[60:63], v[180:183], v[196:199], v[60:63]
	v_mfma_f32_16x16x32_bf16 v[52:55], v[188:191], v[196:199], v[52:55]
	v_mfma_f32_16x16x32_bf16 v[44:47], v[180:183], v[204:207], v[44:47]
	v_mfma_f32_16x16x32_bf16 v[36:39], v[188:191], v[204:207], v[36:39]
	v_mfma_f32_16x16x32_bf16 v[28:31], v[180:183], v[212:215], v[28:31]
	v_mfma_f32_16x16x32_bf16 v[20:23], v[188:191], v[212:215], v[20:23]
	v_mfma_f32_16x16x32_bf16 v[12:15], v[180:183], v[240:243], v[12:15]
	v_mfma_f32_16x16x32_bf16 v[0:3], v[188:191], v[240:243], v[0:3]
	s_setprio 0
	s_barrier
	v_lshl_add_u64 v[142:143], v[142:143], 0, s[80:81]
	v_lshl_add_u64 v[144:145], v[144:145], 0, s[80:81]
	s_mov_b32 s10, s11
	s_cmp_eq_u32 s10, s58
	s_cbranch_scc1 .Lgu_last
	s_branch .LBB0_308
; #define PG8_STAGE(bufoff, gbase, voff) do { _Pragma("unroll") for (int _i = 0; _i < 2; ++_i) \
;         __builtin_amdgcn_global_load_lds((const unsigned*)((const char*)(gbase) + (voff)[_i]), (LAS unsigned*)(lds + (bufoff) + ldsw + _i * 8192), 16, 0, 0); } while (0)
; #define PG8_LDA(dst, b, h) do { _Pragma("unroll") for (int m = 0; m < 4; ++m) _Pragma("unroll") for (int k = 0; k < 2; ++k) dst[m][k] = *(const LAS bf16x8*)(lds + PG8_SA(b, h) + aoff + m * 2048 + k * 1024); } while (0)
; #define PG8_LDB(dst, b, h) do { _Pragma("unroll") for (int n = 0; n < 2; ++n) _Pragma("unroll") for (int k = 0; k < 2; ++k) dst[n][k] = *(const LAS bf16x8*)(lds + PG8_SB(b, h) + boff + n * 2048 + k * 1024); } while (0)
; #define PG8_MMA(ai, bj, At, Bt) do { __builtin_amdgcn_s_setprio(1); _Pragma("unroll") for (int k = 0; k < 2; ++k) _Pragma("unroll") for (int m = 0; m < 4; ++m) _Pragma("unroll") for (int n = 0; n < 2; ++n) \
;         acc[ai][bj][m][n] = __builtin_amdgcn_mfma_f32_16x16x32_bf16(Bt[n][k], At[m][k], acc[ai][bj][m][n], 0, 0, 0); __builtin_amdgcn_s_setprio(0); } while (0)
; #define PG8_WAIT_V(n) asm volatile("s_waitcnt vmcnt(" #n ")" ::: "memory")
; #define PG8_WAIT_L(n) asm volatile("s_waitcnt lgkmcnt(" #n ")" ::: "memory")
; #define PG8_BAR __builtin_amdgcn_s_barrier()
; #define PG8_SCHED __builtin_amdgcn_sched_barrier(0)
; template <class Epi, bool ALIGN_EPI>
; __device__ __forceinline__ void gemm_phase(LAS unsigned char* lds, const Gemm g, const StaticOrder& S, const Epi& E, const int tid) {
;     ...
;             PG8_LDB(B0, 0, 0); PG8_LDB(B1, 0, 1); PG8_SCHED; PG8_LDA(At, 0, 0); PG8_STAGE(PG8_SA(1, 1), a1 + hA, voffA);
;             PG8_WAIT_V(8); PG8_WAIT_L(0); PG8_BAR; PG8_MMA(0, 0, At, B0); PG8_MMA(0, 1, At, B1); PG8_BAR; PG8_SCHED;
;             PG8_LDA(At, 0, 1); PG8_STAGE(PG8_SB(0, 0), b2, voffB); PG8_STAGE(PG8_SB(0, 1), b2 + hB, voffB); PG8_STAGE(PG8_SA(0, 0), a2, voffA);
.Lgu_first:
	s_add_i32 s11, s10, 2
	s_cmp_eq_u32 s58, s10
	v_lshl_add_u64 v[146:147], v[142:143], 0, s[92:93]
	s_cselect_b64 vcc, -1, 0
	v_add_u32_e32 v150, s33, v151
	s_add_i32 s10, 0, 0x14000
	v_cndmask_b32_e32 v167, v147, v139, vcc
	v_cndmask_b32_e32 v166, v146, v138, vcc
	ds_read_b128 v[146:149], v150
	ds_read_b128 v[154:157], v150 offset:1024
	ds_read_b128 v[158:161], v150 offset:2048
	ds_read_b128 v[162:165], v150 offset:3072
	v_add_u32_e32 v150, s10, v151
	ds_read_b128 v[176:179], v150
	ds_read_b128 v[180:183], v150 offset:1024
	ds_read_b128 v[184:187], v150 offset:2048
	ds_read_b128 v[188:191], v150 offset:3072
	v_cndmask_b32_e32 v221, v145, v141, vcc
	v_cndmask_b32_e32 v220, v144, v140, vcc
	v_lshl_add_u64 v[226:227], v[142:143], 0, v[134:135]
	s_add_i32 m0, s51, 0xc000
	ds_read_b128 v[192:195], v153
	ds_read_b128 v[196:199], v153 offset:1024
	ds_read_b128 v[200:203], v153 offset:2048
	ds_read_b128 v[204:207], v153 offset:3072
	ds_read_b128 v[208:211], v153 offset:4096
	ds_read_b128 v[212:215], v153 offset:5120
	ds_read_b128 v[216:219], v153 offset:6144
	ds_read_b128 v[240:243], v153 offset:7168
	global_load_lds_dwordx4 v[226:227], off
	v_lshl_add_u64 v[226:227], v[142:143], 0, v[136:137]
	s_add_i32 m0, s51, 0xe000
	s_nop 0
	global_load_lds_dwordx4 v[226:227], off
	s_waitcnt vmcnt(8)
	s_waitcnt lgkmcnt(0)
	s_setprio 1
	s_barrier
	s_waitcnt lgkmcnt(0)
	v_mfma_f32_16x16x32_bf16 v[120:123], v[146:149], v[192:195], 0
	v_mfma_f32_16x16x32_bf16 v[112:115], v[158:161], v[192:195], 0
	v_mfma_f32_16x16x32_bf16 v[104:107], v[146:149], v[200:203], 0
	v_mfma_f32_16x16x32_bf16 v[96:99], v[158:161], v[200:203], 0
	v_mfma_f32_16x16x32_bf16 v[88:91], v[146:149], v[208:211], 0
	v_mfma_f32_16x16x32_bf16 v[80:83], v[158:161], v[208:211], 0
	v_mfma_f32_16x16x32_bf16 v[72:75], v[146:149], v[216:219], 0
	v_mfma_f32_16x16x32_bf16 v[64:67], v[158:161], v[216:219], 0
	v_mfma_f32_16x16x32_bf16 v[120:123], v[154:157], v[196:199], v[120:123]
	v_mfma_f32_16x16x32_bf16 v[112:115], v[162:165], v[196:199], v[112:115]
	v_mfma_f32_16x16x32_bf16 v[104:107], v[154:157], v[204:207], v[104:107]
	v_mfma_f32_16x16x32_bf16 v[96:99], v[162:165], v[204:207], v[96:99]
	v_mfma_f32_16x16x32_bf16 v[88:91], v[154:157], v[212:215], v[88:91]
	v_mfma_f32_16x16x32_bf16 v[80:83], v[162:165], v[212:215], v[80:83]
	v_mfma_f32_16x16x32_bf16 v[72:75], v[154:157], v[240:243], v[72:75]
	v_mfma_f32_16x16x32_bf16 v[64:67], v[162:165], v[240:243], v[64:67]
	s_setprio 0
	s_setprio 1
	v_mfma_f32_16x16x32_bf16 v[124:127], v[176:179], v[192:195], 0
	v_mfma_f32_16x16x32_bf16 v[116:119], v[184:187], v[192:195], 0
	v_mfma_f32_16x16x32_bf16 v[108:111], v[176:179], v[200:203], 0
	v_mfma_f32_16x16x32_bf16 v[100:103], v[184:187], v[200:203], 0
	v_mfma_f32_16x16x32_bf16 v[92:95], v[176:179], v[208:211], 0
	v_mfma_f32_16x16x32_bf16 v[84:87], v[184:187], v[208:211], 0
	v_mfma_f32_16x16x32_bf16 v[76:79], v[176:179], v[216:219], 0
	v_mfma_f32_16x16x32_bf16 v[68:71], v[184:187], v[216:219], 0
	v_mfma_f32_16x16x32_bf16 v[124:127], v[180:183], v[196:199], v[124:127]
	v_mfma_f32_16x16x32_bf16 v[116:119], v[188:191], v[196:199], v[116:119]
	v_mfma_f32_16x16x32_bf16 v[108:111], v[180:183], v[204:207], v[108:111]
	v_mfma_f32_16x16x32_bf16 v[100:103], v[188:191], v[204:207], v[100:103]
	v_mfma_f32_16x16x32_bf16 v[92:95], v[180:183], v[212:215], v[92:95]
	v_mfma_f32_16x16x32_bf16 v[84:87], v[188:191], v[212:215], v[84:87]
	v_mfma_f32_16x16x32_bf16 v[76:79], v[180:183], v[240:243], v[76:79]
	v_mfma_f32_16x16x32_bf16 v[68:71], v[188:191], v[240:243], v[68:71]
	s_setprio 0
	s_barrier
	s_add_i32 s65, s33, s45
	v_lshl_add_u64 v[226:227], v[220:221], 0, v[168:169]
	s_mov_b32 m0, s65
	ds_read_b128 v[192:195], v153 offset:16384
	ds_read_b128 v[196:199], v153 offset:17408
	ds_read_b128 v[200:203], v153 offset:18432
	ds_read_b128 v[204:207], v153 offset:19456
	ds_read_b128 v[208:211], v153 offset:20480
	ds_read_b128 v[212:215], v153 offset:21504
	ds_read_b128 v[216:219], v153 offset:22528
	ds_read_b128 v[240:243], v153 offset:23552
	global_load_lds_dwordx4 v[226:227], off
	v_lshl_add_u64 v[244:245], v[220:221], 0, v[128:129]
	s_add_i32 m0, s65, 0x2000
	v_lshl_add_u64 v[220:221], v[220:221], 0, s[12:13]
	s_add_i32 s10, s10, s45
	global_load_lds_dwordx4 v[244:245], off
	v_lshl_add_u64 v[246:247], v[220:221], 0, v[168:169]
	s_mov_b32 m0, s10
	v_lshl_add_u64 v[220:221], v[220:221], 0, v[128:129]
	global_load_lds_dwordx4 v[246:247], off
	s_add_i32 m0, s10, 0x2000
	v_lshl_add_u64 v[248:249], v[166:167], 0, v[132:133]
	global_load_lds_dwordx4 v[220:221], off
	s_mov_b32 m0, s51
	v_lshl_add_u64 v[250:251], v[166:167], 0, v[130:131]
	global_load_lds_dwordx4 v[248:249], off
	s_mov_b32 m0, s52
	s_nop 0
	global_load_lds_dwordx4 v[250:251], off
	s_waitcnt vmcnt(8)
	s_waitcnt lgkmcnt(0)
	s_setprio 1
	s_barrier
; #define PG8_STAGE(bufoff, gbase, voff) do { _Pragma("unroll") for (int _i = 0; _i < 2; ++_i) \
;         __builtin_amdgcn_global_load_lds((const unsigned*)((const char*)(gbase) + (voff)[_i]), (LAS unsigned*)(lds + (bufoff) + ldsw + _i * 8192), 16, 0, 0); } while (0)
; #define PG8_LDA(dst, b, h) do { _Pragma("unroll") for (int m = 0; m < 4; ++m) _Pragma("unroll") for (int k = 0; k < 2; ++k) dst[m][k] = *(const LAS bf16x8*)(lds + PG8_SA(b, h) + aoff + m * 2048 + k * 1024); } while (0)
; #define PG8_LDB(dst, b, h) do { _Pragma("unroll") for (int n = 0; n < 2; ++n) _Pragma("unroll") for (int k = 0; k < 2; ++k) dst[n][k] = *(const LAS bf16x8*)(lds + PG8_SB(b, h) + boff + n * 2048 + k * 1024); } while (0)
; #define PG8_MMA(ai, bj, At, Bt) do { __builtin_amdgcn_s_setprio(1); _Pragma("unroll") for (int k = 0; k < 2; ++k) _Pragma("unroll") for (int m = 0; m < 4; ++m) _Pragma("unroll") for (int n = 0; n < 2; ++n) \
;         acc[ai][bj][m][n] = __builtin_amdgcn_mfma_f32_16x16x32_bf16(Bt[n][k], At[m][k], acc[ai][bj][m][n], 0, 0, 0); __builtin_amdgcn_s_setprio(0); } while (0)
; #define PG8_WAIT_V(n) asm volatile("s_waitcnt vmcnt(" #n ")" ::: "memory")
; #define PG8_WAIT_L(n) asm volatile("s_waitcnt lgkmcnt(" #n ")" ::: "memory")
; #define PG8_BAR __builtin_amdgcn_s_barrier()
; #define PG8_SCHED __builtin_amdgcn_sched_barrier(0)
; template <class Epi, bool ALIGN_EPI>
; __device__ __forceinline__ void gemm_phase(LAS unsigned char* lds, const Gemm g, const StaticOrder& S, const Epi& E, const int tid) {
;     ...
;             PG8_WAIT_V(8); PG8_WAIT_L(0); PG8_BAR; PG8_MMA(1, 0, At, B0); PG8_MMA(1, 1, At, B1); PG8_BAR; PG8_SCHED;
;             PG8_LDB(B0, 1, 0); PG8_LDB(B1, 1, 1); PG8_SCHED; PG8_LDA(At, 1, 0); PG8_STAGE(PG8_SA(0, 1), a2 + hA, voffA);
;             PG8_WAIT_V(8); PG8_WAIT_L(0); PG8_BAR; PG8_MMA(0, 0, At, B0); PG8_MMA(0, 1, At, B1); PG8_BAR; PG8_SCHED;
	s_waitcnt lgkmcnt(0)
	v_mfma_f32_16x16x32_bf16 v[56:59], v[146:149], v[192:195], 0
	v_mfma_f32_16x16x32_bf16 v[48:51], v[158:161], v[192:195], 0
	v_mfma_f32_16x16x32_bf16 v[40:43], v[146:149], v[200:203], 0
	v_mfma_f32_16x16x32_bf16 v[32:35], v[158:161], v[200:203], 0
	v_mfma_f32_16x16x32_bf16 v[24:27], v[146:149], v[208:211], 0
	v_mfma_f32_16x16x32_bf16 v[16:19], v[158:161], v[208:211], 0
	v_mfma_f32_16x16x32_bf16 v[8:11], v[146:149], v[216:219], 0
	v_mfma_f32_16x16x32_bf16 v[4:7], v[158:161], v[216:219], 0
	v_mfma_f32_16x16x32_bf16 v[56:59], v[154:157], v[196:199], v[56:59]
	v_mfma_f32_16x16x32_bf16 v[48:51], v[162:165], v[196:199], v[48:51]
	v_mfma_f32_16x16x32_bf16 v[40:43], v[154:157], v[204:207], v[40:43]
	v_mfma_f32_16x16x32_bf16 v[32:35], v[162:165], v[204:207], v[32:35]
	v_mfma_f32_16x16x32_bf16 v[24:27], v[154:157], v[212:215], v[24:27]
	v_mfma_f32_16x16x32_bf16 v[16:19], v[162:165], v[212:215], v[16:19]
	v_mfma_f32_16x16x32_bf16 v[8:11], v[154:157], v[240:243], v[8:11]
	v_mfma_f32_16x16x32_bf16 v[4:7], v[162:165], v[240:243], v[4:7]
	s_setprio 0
	s_setprio 1
	v_mfma_f32_16x16x32_bf16 v[60:63], v[176:179], v[192:195], 0
	v_mfma_f32_16x16x32_bf16 v[52:55], v[184:187], v[192:195], 0
	v_mfma_f32_16x16x32_bf16 v[44:47], v[176:179], v[200:203], 0
	v_mfma_f32_16x16x32_bf16 v[36:39], v[184:187], v[200:203], 0
	v_mfma_f32_16x16x32_bf16 v[28:31], v[176:179], v[208:211], 0
	v_mfma_f32_16x16x32_bf16 v[20:23], v[184:187], v[208:211], 0
	v_mfma_f32_16x16x32_bf16 v[12:15], v[176:179], v[216:219], 0
	v_mfma_f32_16x16x32_bf16 v[0:3], v[184:187], v[216:219], 0
	v_mfma_f32_16x16x32_bf16 v[60:63], v[180:183], v[196:199], v[60:63]
	v_mfma_f32_16x16x32_bf16 v[52:55], v[188:191], v[196:199], v[52:55]
	v_mfma_f32_16x16x32_bf16 v[44:47], v[180:183], v[204:207], v[44:47]
	v_mfma_f32_16x16x32_bf16 v[36:39], v[188:191], v[204:207], v[36:39]
	v_mfma_f32_16x16x32_bf16 v[28:31], v[180:183], v[212:215], v[28:31]
	v_mfma_f32_16x16x32_bf16 v[20:23], v[188:191], v[212:215], v[20:23]
	v_mfma_f32_16x16x32_bf16 v[12:15], v[180:183], v[240:243], v[12:15]
	v_mfma_f32_16x16x32_bf16 v[0:3], v[188:191], v[240:243], v[0:3]
	s_setprio 0
	s_barrier
	s_add_i32 s10, 0, 0x18000
	v_add_u32_e32 v150, s10, v151
	s_add_i32 s65, 0, 0x1c000
	ds_read_b128 v[146:149], v150
	ds_read_b128 v[154:157], v150 offset:1024
	ds_read_b128 v[158:161], v150 offset:2048
	ds_read_b128 v[162:165], v150 offset:3072
	v_add_u32_e32 v150, s65, v151
	ds_read_b128 v[176:179], v150
	ds_read_b128 v[180:183], v150 offset:1024
	ds_read_b128 v[184:187], v150 offset:2048
	ds_read_b128 v[188:191], v150 offset:3072
	v_lshl_add_u64 v[166:167], v[166:167], 0, s[94:95]
	s_mov_b32 m0, s53
	v_lshl_add_u64 v[252:253], v[166:167], 0, v[132:133]
	ds_read_b128 v[192:195], v153 offset:32768
	ds_read_b128 v[196:199], v153 offset:33792
	ds_read_b128 v[200:203], v153 offset:34816
	ds_read_b128 v[204:207], v153 offset:35840
	ds_read_b128 v[208:211], v153 offset:36864
	ds_read_b128 v[212:215], v153 offset:37888
	ds_read_b128 v[216:219], v153 offset:38912
	ds_read_b128 v[240:243], v153 offset:39936
	global_load_lds_dwordx4 v[252:253], off
	v_lshl_add_u64 v[166:167], v[166:167], 0, v[130:131]
	s_mov_b32 m0, s54
	s_nop 0
	global_load_lds_dwordx4 v[166:167], off
	s_waitcnt vmcnt(8)
	s_waitcnt lgkmcnt(0)
	s_setprio 1
	s_barrier
	s_waitcnt lgkmcnt(0)
	v_mfma_f32_16x16x32_bf16 v[120:123], v[146:149], v[192:195], v[120:123]
	v_mfma_f32_16x16x32_bf16 v[112:115], v[158:161], v[192:195], v[112:115]
	v_mfma_f32_16x16x32_bf16 v[104:107], v[146:149], v[200:203], v[104:107]
	v_mfma_f32_16x16x32_bf16 v[96:99], v[158:161], v[200:203], v[96:99]
	v_mfma_f32_16x16x32_bf16 v[88:91], v[146:149], v[208:211], v[88:91]
	v_mfma_f32_16x16x32_bf16 v[80:83], v[158:161], v[208:211], v[80:83]
	v_mfma_f32_16x16x32_bf16 v[72:75], v[146:149], v[216:219], v[72:75]
	v_mfma_f32_16x16x32_bf16 v[64:67], v[158:161], v[216:219], v[64:67]
	v_mfma_f32_16x16x32_bf16 v[120:123], v[154:157], v[196:199], v[120:123]
	v_mfma_f32_16x16x32_bf16 v[112:115], v[162:165], v[196:199], v[112:115]
	v_mfma_f32_16x16x32_bf16 v[104:107], v[154:157], v[204:207], v[104:107]
	v_mfma_f32_16x16x32_bf16 v[96:99], v[162:165], v[204:207], v[96:99]
	v_mfma_f32_16x16x32_bf16 v[88:91], v[154:157], v[212:215], v[88:91]
	v_mfma_f32_16x16x32_bf16 v[80:83], v[162:165], v[212:215], v[80:83]
	v_mfma_f32_16x16x32_bf16 v[72:75], v[154:157], v[240:243], v[72:75]
	v_mfma_f32_16x16x32_bf16 v[64:67], v[162:165], v[240:243], v[64:67]
	s_setprio 0
	s_setprio 1
	v_mfma_f32_16x16x32_bf16 v[124:127], v[176:179], v[192:195], v[124:127]
	v_mfma_f32_16x16x32_bf16 v[116:119], v[184:187], v[192:195], v[116:119]
	v_mfma_f32_16x16x32_bf16 v[108:111], v[176:179], v[200:203], v[108:111]
	v_mfma_f32_16x16x32_bf16 v[100:103], v[184:187], v[200:203], v[100:103]
	v_mfma_f32_16x16x32_bf16 v[92:95], v[176:179], v[208:211], v[92:95]
	v_mfma_f32_16x16x32_bf16 v[84:87], v[184:187], v[208:211], v[84:87]
	v_mfma_f32_16x16x32_bf16 v[76:79], v[176:179], v[216:219], v[76:79]
	v_mfma_f32_16x16x32_bf16 v[68:71], v[184:187], v[216:219], v[68:71]
	v_mfma_f32_16x16x32_bf16 v[124:127], v[180:183], v[196:199], v[124:127]
	v_mfma_f32_16x16x32_bf16 v[116:119], v[188:191], v[196:199], v[116:119]
	v_mfma_f32_16x16x32_bf16 v[108:111], v[180:183], v[204:207], v[108:111]
	v_mfma_f32_16x16x32_bf16 v[100:103], v[188:191], v[204:207], v[100:103]
	v_mfma_f32_16x16x32_bf16 v[92:95], v[180:183], v[212:215], v[92:95]
	v_mfma_f32_16x16x32_bf16 v[84:87], v[188:191], v[212:215], v[84:87]
	v_mfma_f32_16x16x32_bf16 v[76:79], v[180:183], v[240:243], v[76:79]
	v_mfma_f32_16x16x32_bf16 v[68:71], v[188:191], v[240:243], v[68:71]
	s_setprio 0
	s_barrier
; #define PG8_STAGE(bufoff, gbase, voff) do { _Pragma("unroll") for (int _i = 0; _i < 2; ++_i) \
;         __builtin_amdgcn_global_load_lds((const unsigned*)((const char*)(gbase) + (voff)[_i]), (LAS unsigned*)(lds + (bufoff) + ldsw + _i * 8192), 16, 0, 0); } while (0)
; #define PG8_LDA(dst, b, h) do { _Pragma("unroll") for (int m = 0; m < 4; ++m) _Pragma("unroll") for (int k = 0; k < 2; ++k) dst[m][k] = *(const LAS bf16x8*)(lds + PG8_SA(b, h) + aoff + m * 2048 + k * 1024); } while (0)
; #define PG8_LDB(dst, b, h) do { _Pragma("unroll") for (int n = 0; n < 2; ++n) _Pragma("unroll") for (int k = 0; k < 2; ++k) dst[n][k] = *(const LAS bf16x8*)(lds + PG8_SB(b, h) + boff + n * 2048 + k * 1024); } while (0)
; #define PG8_MMA(ai, bj, At, Bt) do { __builtin_amdgcn_s_setprio(1); _Pragma("unroll") for (int k = 0; k < 2; ++k) _Pragma("unroll") for (int m = 0; m < 4; ++m) _Pragma("unroll") for (int n = 0; n < 2; ++n) \
;         acc[ai][bj][m][n] = __builtin_amdgcn_mfma_f32_16x16x32_bf16(Bt[n][k], At[m][k], acc[ai][bj][m][n], 0, 0, 0); __builtin_amdgcn_s_setprio(0); } while (0)
; #define PG8_WAIT_V(n) asm volatile("s_waitcnt vmcnt(" #n ")" ::: "memory")
; #define PG8_BAR __builtin_amdgcn_s_barrier()
; template <class Epi, bool ALIGN_EPI>
; __device__ __forceinline__ void gemm_phase(LAS unsigned char* lds, const Gemm g, const StaticOrder& S, const Epi& E, const int tid) {
;     ...
;             PG8_LDB(B0, 0, 0); PG8_LDB(B1, 0, 1); PG8_SCHED; PG8_LDA(At, 0, 0); PG8_STAGE(PG8_SA(1, 1), a1 + hA, voffA);
;             PG8_WAIT_V(8); PG8_WAIT_L(0); PG8_BAR; PG8_MMA(0, 0, At, B0); PG8_MMA(0, 1, At, B1); PG8_BAR; PG8_SCHED;
;             PG8_LDA(At, 0, 1); PG8_STAGE(PG8_SB(0, 0), b2, voffB); PG8_STAGE(PG8_SB(0, 1), b2 + hB, voffB); PG8_STAGE(PG8_SA(0, 0), a2, voffA);
;             PG8_WAIT_V(8); PG8_WAIT_L(0); PG8_BAR; PG8_MMA(1, 0, At, B0); PG8_MMA(1, 1, At, B1); PG8_BAR; PG8_SCHED;
;             PG8_LDB(B0, 1, 0); PG8_LDB(B1, 1, 1); PG8_SCHED; PG8_LDA(At, 1, 0); PG8_STAGE(PG8_SA(0, 1), a2 + hA, voffA);
;             PG8_WAIT_V(8); PG8_WAIT_L(0); PG8_BAR; PG8_MMA(0, 0, At, B0); PG8_MMA(0, 1, At, B1); PG8_BAR; PG8_SCHED;
;             PG8_LDA(At, 1, 1); PG8_STAGE(PG8_SB(1, 0), b3, voffB); PG8_STAGE(PG8_SB(1, 1), b3 + hB, voffB); PG8_STAGE(PG8_SA(1, 0), a3, voffA);
;             PG8_WAIT_V(8); PG8_WAIT_L(0); PG8_BAR; PG8_MMA(1, 0, At, B0); PG8_MMA(1, 1, At, B1); PG8_BAR; PG8_SCHED;
	s_add_i32 s10, s10, s45
	v_lshl_add_u64 v[166:167], v[226:227], 0, s[92:93]
	s_mov_b32 m0, s10
	ds_read_b128 v[192:195], v153 offset:49152
	ds_read_b128 v[196:199], v153 offset:50176
	ds_read_b128 v[200:203], v153 offset:51200
	ds_read_b128 v[204:207], v153 offset:52224
	ds_read_b128 v[208:211], v153 offset:53248
	ds_read_b128 v[212:215], v153 offset:54272
	ds_read_b128 v[216:219], v153 offset:55296
	ds_read_b128 v[240:243], v153 offset:56320
	global_load_lds_dwordx4 v[166:167], off
	v_lshl_add_u64 v[166:167], v[244:245], 0, s[92:93]
	s_add_i32 m0, s10, 0x2000
	s_add_i32 s10, s65, s45
	global_load_lds_dwordx4 v[166:167], off
	v_lshl_add_u64 v[166:167], v[246:247], 0, s[92:93]
	s_mov_b32 m0, s10
	s_nop 0
	global_load_lds_dwordx4 v[166:167], off
	v_lshl_add_u64 v[166:167], v[220:221], 0, s[92:93]
	s_add_i32 m0, s10, 0x2000
	s_nop 0
	global_load_lds_dwordx4 v[166:167], off
	v_lshl_add_u64 v[166:167], v[248:249], 0, s[92:93]
	s_mov_b32 m0, s56
	s_nop 0
	global_load_lds_dwordx4 v[166:167], off
	v_lshl_add_u64 v[166:167], v[250:251], 0, s[92:93]
	s_mov_b32 m0, s57
	s_nop 0
	global_load_lds_dwordx4 v[166:167], off
	s_waitcnt vmcnt(8)
	s_waitcnt lgkmcnt(0)
	s_setprio 1
	s_barrier
	s_waitcnt lgkmcnt(0)
	v_mfma_f32_16x16x32_bf16 v[56:59], v[146:149], v[192:195], v[56:59]
	v_mfma_f32_16x16x32_bf16 v[48:51], v[158:161], v[192:195], v[48:51]
	v_mfma_f32_16x16x32_bf16 v[40:43], v[146:149], v[200:203], v[40:43]
	v_mfma_f32_16x16x32_bf16 v[32:35], v[158:161], v[200:203], v[32:35]
	v_mfma_f32_16x16x32_bf16 v[24:27], v[146:149], v[208:211], v[24:27]
	v_mfma_f32_16x16x32_bf16 v[16:19], v[158:161], v[208:211], v[16:19]
	v_mfma_f32_16x16x32_bf16 v[8:11], v[146:149], v[216:219], v[8:11]
	v_mfma_f32_16x16x32_bf16 v[4:7], v[158:161], v[216:219], v[4:7]
	v_mfma_f32_16x16x32_bf16 v[56:59], v[154:157], v[196:199], v[56:59]
	v_mfma_f32_16x16x32_bf16 v[48:51], v[162:165], v[196:199], v[48:51]
	v_mfma_f32_16x16x32_bf16 v[40:43], v[154:157], v[204:207], v[40:43]
	v_mfma_f32_16x16x32_bf16 v[32:35], v[162:165], v[204:207], v[32:35]
	v_mfma_f32_16x16x32_bf16 v[24:27], v[154:157], v[212:215], v[24:27]
	v_mfma_f32_16x16x32_bf16 v[16:19], v[162:165], v[212:215], v[16:19]
	v_mfma_f32_16x16x32_bf16 v[8:11], v[154:157], v[240:243], v[8:11]
	v_mfma_f32_16x16x32_bf16 v[4:7], v[162:165], v[240:243], v[4:7]
	s_setprio 0
	s_setprio 1
	v_mfma_f32_16x16x32_bf16 v[60:63], v[176:179], v[192:195], v[60:63]
	v_mfma_f32_16x16x32_bf16 v[52:55], v[184:187], v[192:195], v[52:55]
	v_mfma_f32_16x16x32_bf16 v[44:47], v[176:179], v[200:203], v[44:47]
	v_mfma_f32_16x16x32_bf16 v[36:39], v[184:187], v[200:203], v[36:39]
	v_mfma_f32_16x16x32_bf16 v[28:31], v[176:179], v[208:211], v[28:31]
	v_mfma_f32_16x16x32_bf16 v[20:23], v[184:187], v[208:211], v[20:23]
	v_mfma_f32_16x16x32_bf16 v[12:15], v[176:179], v[216:219], v[12:15]
	v_mfma_f32_16x16x32_bf16 v[0:3], v[184:187], v[216:219], v[0:3]
	v_mfma_f32_16x16x32_bf16 v[60:63], v[180:183], v[196:199], v[60:63]
	v_mfma_f32_16x16x32_bf16 v[52:55], v[188:191], v[196:199], v[52:55]
	v_mfma_f32_16x16x32_bf16 v[44:47], v[180:183], v[204:207], v[44:47]
	v_mfma_f32_16x16x32_bf16 v[36:39], v[188:191], v[204:207], v[36:39]
	v_mfma_f32_16x16x32_bf16 v[28:31], v[180:183], v[212:215], v[28:31]
	v_mfma_f32_16x16x32_bf16 v[20:23], v[188:191], v[212:215], v[20:23]
	v_mfma_f32_16x16x32_bf16 v[12:15], v[180:183], v[240:243], v[12:15]
	v_mfma_f32_16x16x32_bf16 v[0:3], v[188:191], v[240:243], v[0:3]
	s_setprio 0
	s_barrier
	v_lshl_add_u64 v[142:143], v[142:143], 0, s[80:81]
	v_lshl_add_u64 v[144:145], v[144:145], 0, s[80:81]
	s_mov_b32 s10, s11
	s_cmp_eq_u32 s10, s58
	s_cbranch_scc1 .Lgu_last
.LBB0_308:
	s_add_i32 s11, s10, 2
	s_cmp_eq_u32 s58, s10
	v_lshl_add_u64 v[146:147], v[142:143], 0, s[92:93]
	s_cselect_b64 vcc, -1, 0
	v_add_u32_e32 v150, s33, v151
	s_add_i32 s10, 0, 0x14000
	v_cndmask_b32_e32 v167, v147, v139, vcc
	v_cndmask_b32_e32 v166, v146, v138, vcc
	ds_read_b128 v[146:149], v150
	ds_read_b128 v[154:157], v150 offset:1024
	ds_read_b128 v[158:161], v150 offset:2048
	ds_read_b128 v[162:165], v150 offset:3072
	v_add_u32_e32 v150, s10, v151
	ds_read_b128 v[176:179], v150
	ds_read_b128 v[180:183], v150 offset:1024
	ds_read_b128 v[184:187], v150 offset:2048
	ds_read_b128 v[188:191], v150 offset:3072
	v_cndmask_b32_e32 v221, v145, v141, vcc
	v_cndmask_b32_e32 v220, v144, v140, vcc
	v_lshl_add_u64 v[226:227], v[142:143], 0, v[134:135]
	s_add_i32 m0, s51, 0xc000
	ds_read_b128 v[192:195], v153
	ds_read_b128 v[196:199], v153 offset:1024
	ds_read_b128 v[200:203], v153 offset:2048
	ds_read_b128 v[204:207], v153 offset:3072
	ds_read_b128 v[208:211], v153 offset:4096
	ds_read_b128 v[212:215], v153 offset:5120
	ds_read_b128 v[216:219], v153 offset:6144
	ds_read_b128 v[240:243], v153 offset:7168
	global_load_lds_dwordx4 v[226:227], off
	v_lshl_add_u64 v[226:227], v[142:143], 0, v[136:137]
	s_add_i32 m0, s51, 0xe000
	s_nop 0
	global_load_lds_dwordx4 v[226:227], off
	s_waitcnt vmcnt(8)
	s_waitcnt lgkmcnt(0)
	s_setprio 1
	s_barrier
; #define PG8_STAGE(bufoff, gbase, voff) do { _Pragma("unroll") for (int _i = 0; _i < 2; ++_i) \
;         __builtin_amdgcn_global_load_lds((const unsigned*)((const char*)(gbase) + (voff)[_i]), (LAS unsigned*)(lds + (bufoff) + ldsw + _i * 8192), 16, 0, 0); } while (0)
; #define PG8_LDA(dst, b, h) do { _Pragma("unroll") for (int m = 0; m < 4; ++m) _Pragma("unroll") for (int k = 0; k < 2; ++k) dst[m][k] = *(const LAS bf16x8*)(lds + PG8_SA(b, h) + aoff + m * 2048 + k * 1024); } while (0)
; #define PG8_MMA(ai, bj, At, Bt) do { __builtin_amdgcn_s_setprio(1); _Pragma("unroll") for (int k = 0; k < 2; ++k) _Pragma("unroll") for (int m = 0; m < 4; ++m) _Pragma("unroll") for (int n = 0; n < 2; ++n) \
;         acc[ai][bj][m][n] = __builtin_amdgcn_mfma_f32_16x16x32_bf16(Bt[n][k], At[m][k], acc[ai][bj][m][n], 0, 0, 0); __builtin_amdgcn_s_setprio(0); } while (0)
; #define PG8_WAIT_V(n) asm volatile("s_waitcnt vmcnt(" #n ")" ::: "memory")
; #define PG8_WAIT_L(n) asm volatile("s_waitcnt lgkmcnt(" #n ")" ::: "memory")
; #define PG8_BAR __builtin_amdgcn_s_barrier()
; #define PG8_SCHED __builtin_amdgcn_sched_barrier(0)
; template <class Epi, bool ALIGN_EPI>
; __device__ __forceinline__ void gemm_phase(LAS unsigned char* lds, const Gemm g, const StaticOrder& S, const Epi& E, const int tid) {
;     ...
;             PG8_WAIT_V(8); PG8_WAIT_L(0); PG8_BAR; PG8_MMA(0, 0, At, B0); PG8_MMA(0, 1, At, B1); PG8_BAR; PG8_SCHED;
;             PG8_LDA(At, 0, 1); PG8_STAGE(PG8_SB(0, 0), b2, voffB); PG8_STAGE(PG8_SB(0, 1), b2 + hB, voffB); PG8_STAGE(PG8_SA(0, 0), a2, voffA);
;             PG8_WAIT_V(8); PG8_WAIT_L(0); PG8_BAR; PG8_MMA(1, 0, At, B0); PG8_MMA(1, 1, At, B1); PG8_BAR; PG8_SCHED;
	s_waitcnt lgkmcnt(0)
	v_mfma_f32_16x16x32_bf16 v[120:123], v[146:149], v[192:195], v[120:123]
	v_mfma_f32_16x16x32_bf16 v[112:115], v[158:161], v[192:195], v[112:115]
	v_mfma_f32_16x16x32_bf16 v[104:107], v[146:149], v[200:203], v[104:107]
	v_mfma_f32_16x16x32_bf16 v[96:99], v[158:161], v[200:203], v[96:99]
	v_mfma_f32_16x16x32_bf16 v[88:91], v[146:149], v[208:211], v[88:91]
	v_mfma_f32_16x16x32_bf16 v[80:83], v[158:161], v[208:211], v[80:83]
	v_mfma_f32_16x16x32_bf16 v[72:75], v[146:149], v[216:219], v[72:75]
	v_mfma_f32_16x16x32_bf16 v[64:67], v[158:161], v[216:219], v[64:67]
	v_mfma_f32_16x16x32_bf16 v[120:123], v[154:157], v[196:199], v[120:123]
	v_mfma_f32_16x16x32_bf16 v[112:115], v[162:165], v[196:199], v[112:115]
	v_mfma_f32_16x16x32_bf16 v[104:107], v[154:157], v[204:207], v[104:107]
	v_mfma_f32_16x16x32_bf16 v[96:99], v[162:165], v[204:207], v[96:99]
	v_mfma_f32_16x16x32_bf16 v[88:91], v[154:157], v[212:215], v[88:91]
	v_mfma_f32_16x16x32_bf16 v[80:83], v[162:165], v[212:215], v[80:83]
	v_mfma_f32_16x16x32_bf16 v[72:75], v[154:157], v[240:243], v[72:75]
	v_mfma_f32_16x16x32_bf16 v[64:67], v[162:165], v[240:243], v[64:67]
	s_setprio 0
	s_setprio 1
	v_mfma_f32_16x16x32_bf16 v[124:127], v[176:179], v[192:195], v[124:127]
	v_mfma_f32_16x16x32_bf16 v[116:119], v[184:187], v[192:195], v[116:119]
	v_mfma_f32_16x16x32_bf16 v[108:111], v[176:179], v[200:203], v[108:111]
	v_mfma_f32_16x16x32_bf16 v[100:103], v[184:187], v[200:203], v[100:103]
	v_mfma_f32_16x16x32_bf16 v[92:95], v[176:179], v[208:211], v[92:95]
	v_mfma_f32_16x16x32_bf16 v[84:87], v[184:187], v[208:211], v[84:87]
	v_mfma_f32_16x16x32_bf16 v[76:79], v[176:179], v[216:219], v[76:79]
	v_mfma_f32_16x16x32_bf16 v[68:71], v[184:187], v[216:219], v[68:71]
	v_mfma_f32_16x16x32_bf16 v[124:127], v[180:183], v[196:199], v[124:127]
	v_mfma_f32_16x16x32_bf16 v[116:119], v[188:191], v[196:199], v[116:119]
	v_mfma_f32_16x16x32_bf16 v[108:111], v[180:183], v[204:207], v[108:111]
	v_mfma_f32_16x16x32_bf16 v[100:103], v[188:191], v[204:207], v[100:103]
	v_mfma_f32_16x16x32_bf16 v[92:95], v[180:183], v[212:215], v[92:95]
	v_mfma_f32_16x16x32_bf16 v[84:87], v[188:191], v[212:215], v[84:87]
	v_mfma_f32_16x16x32_bf16 v[76:79], v[180:183], v[240:243], v[76:79]
	v_mfma_f32_16x16x32_bf16 v[68:71], v[188:191], v[240:243], v[68:71]
	s_setprio 0
	s_barrier
	s_add_i32 s65, s33, s45
	v_lshl_add_u64 v[226:227], v[220:221], 0, v[168:169]
	s_mov_b32 m0, s65
	ds_read_b128 v[192:195], v153 offset:16384
	ds_read_b128 v[196:199], v153 offset:17408
	ds_read_b128 v[200:203], v153 offset:18432
	ds_read_b128 v[204:207], v153 offset:19456
	ds_read_b128 v[208:211], v153 offset:20480
	ds_read_b128 v[212:215], v153 offset:21504
	ds_read_b128 v[216:219], v153 offset:22528
	ds_read_b128 v[240:243], v153 offset:23552
	global_load_lds_dwordx4 v[226:227], off
	v_lshl_add_u64 v[244:245], v[220:221], 0, v[128:129]
	s_add_i32 m0, s65, 0x2000
	v_lshl_add_u64 v[220:221], v[220:221], 0, s[12:13]
	s_add_i32 s10, s10, s45
	global_load_lds_dwordx4 v[244:245], off
	v_lshl_add_u64 v[246:247], v[220:221], 0, v[168:169]
	s_mov_b32 m0, s10
	v_lshl_add_u64 v[220:221], v[220:221], 0, v[128:129]
	global_load_lds_dwordx4 v[246:247], off
	s_add_i32 m0, s10, 0x2000
	v_lshl_add_u64 v[248:249], v[166:167], 0, v[132:133]
	global_load_lds_dwordx4 v[220:221], off
	s_mov_b32 m0, s51
	v_lshl_add_u64 v[250:251], v[166:167], 0, v[130:131]
	global_load_lds_dwordx4 v[248:249], off
	s_mov_b32 m0, s52
	s_nop 0
	global_load_lds_dwordx4 v[250:251], off
	s_waitcnt vmcnt(8)
	s_waitcnt lgkmcnt(0)
	s_setprio 1
	s_barrier
	s_waitcnt lgkmcnt(0)
	v_mfma_f32_16x16x32_bf16 v[56:59], v[146:149], v[192:195], v[56:59]
	v_mfma_f32_16x16x32_bf16 v[48:51], v[158:161], v[192:195], v[48:51]
	v_mfma_f32_16x16x32_bf16 v[40:43], v[146:149], v[200:203], v[40:43]
	v_mfma_f32_16x16x32_bf16 v[32:35], v[158:161], v[200:203], v[32:35]
	v_mfma_f32_16x16x32_bf16 v[24:27], v[146:149], v[208:211], v[24:27]
	v_mfma_f32_16x16x32_bf16 v[16:19], v[158:161], v[208:211], v[16:19]
	v_mfma_f32_16x16x32_bf16 v[8:11], v[146:149], v[216:219], v[8:11]
	v_mfma_f32_16x16x32_bf16 v[4:7], v[158:161], v[216:219], v[4:7]
	v_mfma_f32_16x16x32_bf16 v[56:59], v[154:157], v[196:199], v[56:59]
	v_mfma_f32_16x16x32_bf16 v[48:51], v[162:165], v[196:199], v[48:51]
	v_mfma_f32_16x16x32_bf16 v[40:43], v[154:157], v[204:207], v[40:43]
	v_mfma_f32_16x16x32_bf16 v[32:35], v[162:165], v[204:207], v[32:35]
	v_mfma_f32_16x16x32_bf16 v[24:27], v[154:157], v[212:215], v[24:27]
	v_mfma_f32_16x16x32_bf16 v[16:19], v[162:165], v[212:215], v[16:19]
	v_mfma_f32_16x16x32_bf16 v[8:11], v[154:157], v[240:243], v[8:11]
	v_mfma_f32_16x16x32_bf16 v[4:7], v[162:165], v[240:243], v[4:7]
	s_setprio 0
	s_setprio 1
	v_mfma_f32_16x16x32_bf16 v[60:63], v[176:179], v[192:195], v[60:63]
	v_mfma_f32_16x16x32_bf16 v[52:55], v[184:187], v[192:195], v[52:55]
	v_mfma_f32_16x16x32_bf16 v[44:47], v[176:179], v[200:203], v[44:47]
	v_mfma_f32_16x16x32_bf16 v[36:39], v[184:187], v[200:203], v[36:39]
	v_mfma_f32_16x16x32_bf16 v[28:31], v[176:179], v[208:211], v[28:31]
	v_mfma_f32_16x16x32_bf16 v[20:23], v[184:187], v[208:211], v[20:23]
	v_mfma_f32_16x16x32_bf16 v[12:15], v[176:179], v[216:219], v[12:15]
	v_mfma_f32_16x16x32_bf16 v[0:3], v[184:187], v[216:219], v[0:3]
	v_mfma_f32_16x16x32_bf16 v[60:63], v[180:183], v[196:199], v[60:63]
	v_mfma_f32_16x16x32_bf16 v[52:55], v[188:191], v[196:199], v[52:55]
	v_mfma_f32_16x16x32_bf16 v[44:47], v[180:183], v[204:207], v[44:47]
	v_mfma_f32_16x16x32_bf16 v[36:39], v[188:191], v[204:207], v[36:39]
	v_mfma_f32_16x16x32_bf16 v[28:31], v[180:183], v[212:215], v[28:31]
	v_mfma_f32_16x16x32_bf16 v[20:23], v[188:191], v[212:215], v[20:23]
	v_mfma_f32_16x16x32_bf16 v[12:15], v[180:183], v[240:243], v[12:15]
	v_mfma_f32_16x16x32_bf16 v[0:3], v[188:191], v[240:243], v[0:3]
	s_setprio 0
	s_barrier
; #define PG8_STAGE(bufoff, gbase, voff) do { _Pragma("unroll") for (int _i = 0; _i < 2; ++_i) \
;         __builtin_amdgcn_global_load_lds((const unsigned*)((const char*)(gbase) + (voff)[_i]), (LAS unsigned*)(lds + (bufoff) + ldsw + _i * 8192), 16, 0, 0); } while (0)
; #define PG8_LDA(dst, b, h) do { _Pragma("unroll") for (int m = 0; m < 4; ++m) _Pragma("unroll") for (int k = 0; k < 2; ++k) dst[m][k] = *(const LAS bf16x8*)(lds + PG8_SA(b, h) + aoff + m * 2048 + k * 1024); } while (0)
; #define PG8_LDB(dst, b, h) do { _Pragma("unroll") for (int n = 0; n < 2; ++n) _Pragma("unroll") for (int k = 0; k < 2; ++k) dst[n][k] = *(const LAS bf16x8*)(lds + PG8_SB(b, h) + boff + n * 2048 + k * 1024); } while (0)
; #define PG8_MMA(ai, bj, At, Bt) do { __builtin_amdgcn_s_setprio(1); _Pragma("unroll") for (int k = 0; k < 2; ++k) _Pragma("unroll") for (int m = 0; m < 4; ++m) _Pragma("unroll") for (int n = 0; n < 2; ++n) \
;         acc[ai][bj][m][n] = __builtin_amdgcn_mfma_f32_16x16x32_bf16(Bt[n][k], At[m][k], acc[ai][bj][m][n], 0, 0, 0); __builtin_amdgcn_s_setprio(0); } while (0)
; #define PG8_WAIT_V(n) asm volatile("s_waitcnt vmcnt(" #n ")" ::: "memory")
; #define PG8_WAIT_L(n) asm volatile("s_waitcnt lgkmcnt(" #n ")" ::: "memory")
; #define PG8_BAR __builtin_amdgcn_s_barrier()
; #define PG8_SCHED __builtin_amdgcn_sched_barrier(0)
; template <class Epi, bool ALIGN_EPI>
; __device__ __forceinline__ void gemm_phase(LAS unsigned char* lds, const Gemm g, const StaticOrder& S, const Epi& E, const int tid) {
;     ...
;             PG8_LDB(B0, 1, 0); PG8_LDB(B1, 1, 1); PG8_SCHED; PG8_LDA(At, 1, 0); PG8_STAGE(PG8_SA(0, 1), a2 + hA, voffA);
;             PG8_WAIT_V(8); PG8_WAIT_L(0); PG8_BAR; PG8_MMA(0, 0, At, B0); PG8_MMA(0, 1, At, B1); PG8_BAR; PG8_SCHED;
;             PG8_LDA(At, 1, 1); PG8_STAGE(PG8_SB(1, 0), b3, voffB); PG8_STAGE(PG8_SB(1, 1), b3 + hB, voffB); PG8_STAGE(PG8_SA(1, 0), a3, voffA);
;             PG8_WAIT_V(8); PG8_WAIT_L(0); PG8_BAR; PG8_MMA(1, 0, At, B0); PG8_MMA(1, 1, At, B1); PG8_BAR; PG8_SCHED;
	s_add_i32 s10, 0, 0x18000
	v_add_u32_e32 v150, s10, v151
	s_add_i32 s65, 0, 0x1c000
	ds_read_b128 v[146:149], v150
	ds_read_b128 v[154:157], v150 offset:1024
	ds_read_b128 v[158:161], v150 offset:2048
	ds_read_b128 v[162:165], v150 offset:3072
	v_add_u32_e32 v150, s65, v151
	ds_read_b128 v[176:179], v150
	ds_read_b128 v[180:183], v150 offset:1024
	ds_read_b128 v[184:187], v150 offset:2048
	ds_read_b128 v[188:191], v150 offset:3072
	v_lshl_add_u64 v[166:167], v[166:167], 0, s[94:95]
	s_mov_b32 m0, s53
	v_lshl_add_u64 v[252:253], v[166:167], 0, v[132:133]
	ds_read_b128 v[192:195], v153 offset:32768
	ds_read_b128 v[196:199], v153 offset:33792
	ds_read_b128 v[200:203], v153 offset:34816
	ds_read_b128 v[204:207], v153 offset:35840
	ds_read_b128 v[208:211], v153 offset:36864
	ds_read_b128 v[212:215], v153 offset:37888
	ds_read_b128 v[216:219], v153 offset:38912
	ds_read_b128 v[240:243], v153 offset:39936
	global_load_lds_dwordx4 v[252:253], off
	v_lshl_add_u64 v[166:167], v[166:167], 0, v[130:131]
	s_mov_b32 m0, s54
	s_nop 0
	global_load_lds_dwordx4 v[166:167], off
	s_waitcnt vmcnt(8)
	s_waitcnt lgkmcnt(0)
	s_setprio 1
	s_barrier
	s_waitcnt lgkmcnt(0)
	v_mfma_f32_16x16x32_bf16 v[120:123], v[146:149], v[192:195], v[120:123]
	v_mfma_f32_16x16x32_bf16 v[112:115], v[158:161], v[192:195], v[112:115]
	v_mfma_f32_16x16x32_bf16 v[104:107], v[146:149], v[200:203], v[104:107]
	v_mfma_f32_16x16x32_bf16 v[96:99], v[158:161], v[200:203], v[96:99]
	v_mfma_f32_16x16x32_bf16 v[88:91], v[146:149], v[208:211], v[88:91]
	v_mfma_f32_16x16x32_bf16 v[80:83], v[158:161], v[208:211], v[80:83]
	v_mfma_f32_16x16x32_bf16 v[72:75], v[146:149], v[216:219], v[72:75]
	v_mfma_f32_16x16x32_bf16 v[64:67], v[158:161], v[216:219], v[64:67]
	v_mfma_f32_16x16x32_bf16 v[120:123], v[154:157], v[196:199], v[120:123]
	v_mfma_f32_16x16x32_bf16 v[112:115], v[162:165], v[196:199], v[112:115]
	v_mfma_f32_16x16x32_bf16 v[104:107], v[154:157], v[204:207], v[104:107]
	v_mfma_f32_16x16x32_bf16 v[96:99], v[162:165], v[204:207], v[96:99]
	v_mfma_f32_16x16x32_bf16 v[88:91], v[154:157], v[212:215], v[88:91]
	v_mfma_f32_16x16x32_bf16 v[80:83], v[162:165], v[212:215], v[80:83]
	v_mfma_f32_16x16x32_bf16 v[72:75], v[154:157], v[240:243], v[72:75]
	v_mfma_f32_16x16x32_bf16 v[64:67], v[162:165], v[240:243], v[64:67]
	s_setprio 0
	s_setprio 1
	v_mfma_f32_16x16x32_bf16 v[124:127], v[176:179], v[192:195], v[124:127]
	v_mfma_f32_16x16x32_bf16 v[116:119], v[184:187], v[192:195], v[116:119]
	v_mfma_f32_16x16x32_bf16 v[108:111], v[176:179], v[200:203], v[108:111]
	v_mfma_f32_16x16x32_bf16 v[100:103], v[184:187], v[200:203], v[100:103]
	v_mfma_f32_16x16x32_bf16 v[92:95], v[176:179], v[208:211], v[92:95]
	v_mfma_f32_16x16x32_bf16 v[84:87], v[184:187], v[208:211], v[84:87]
	v_mfma_f32_16x16x32_bf16 v[76:79], v[176:179], v[216:219], v[76:79]
	v_mfma_f32_16x16x32_bf16 v[68:71], v[184:187], v[216:219], v[68:71]
	v_mfma_f32_16x16x32_bf16 v[124:127], v[180:183], v[196:199], v[124:127]
	v_mfma_f32_16x16x32_bf16 v[116:119], v[188:191], v[196:199], v[116:119]
	v_mfma_f32_16x16x32_bf16 v[108:111], v[180:183], v[204:207], v[108:111]
	v_mfma_f32_16x16x32_bf16 v[100:103], v[188:191], v[204:207], v[100:103]
	v_mfma_f32_16x16x32_bf16 v[92:95], v[180:183], v[212:215], v[92:95]
	v_mfma_f32_16x16x32_bf16 v[84:87], v[188:191], v[212:215], v[84:87]
	v_mfma_f32_16x16x32_bf16 v[76:79], v[180:183], v[240:243], v[76:79]
	v_mfma_f32_16x16x32_bf16 v[68:71], v[188:191], v[240:243], v[68:71]
	s_setprio 0
	s_barrier
	s_add_i32 s10, s10, s45
	v_lshl_add_u64 v[166:167], v[226:227], 0, s[92:93]
	s_mov_b32 m0, s10
	ds_read_b128 v[192:195], v153 offset:49152
	ds_read_b128 v[196:199], v153 offset:50176
	ds_read_b128 v[200:203], v153 offset:51200
	ds_read_b128 v[204:207], v153 offset:52224
	ds_read_b128 v[208:211], v153 offset:53248
	ds_read_b128 v[212:215], v153 offset:54272
	ds_read_b128 v[216:219], v153 offset:55296
	ds_read_b128 v[240:243], v153 offset:56320
	global_load_lds_dwordx4 v[166:167], off
	v_lshl_add_u64 v[166:167], v[244:245], 0, s[92:93]
	s_add_i32 m0, s10, 0x2000
	s_add_i32 s10, s65, s45
	global_load_lds_dwordx4 v[166:167], off
	v_lshl_add_u64 v[166:167], v[246:247], 0, s[92:93]
	s_mov_b32 m0, s10
	s_nop 0
	global_load_lds_dwordx4 v[166:167], off
	v_lshl_add_u64 v[166:167], v[220:221], 0, s[92:93]
	s_add_i32 m0, s10, 0x2000
	s_nop 0
	global_load_lds_dwordx4 v[166:167], off
	v_lshl_add_u64 v[166:167], v[248:249], 0, s[92:93]
	s_mov_b32 m0, s56
	s_nop 0
	global_load_lds_dwordx4 v[166:167], off
	v_lshl_add_u64 v[166:167], v[250:251], 0, s[92:93]
	s_mov_b32 m0, s57
	s_nop 0
	global_load_lds_dwordx4 v[166:167], off
	s_waitcnt vmcnt(8)
	s_waitcnt lgkmcnt(0)
	s_setprio 1
	s_barrier
; #define PG8_STAGE(bufoff, gbase, voff) do { _Pragma("unroll") for (int _i = 0; _i < 2; ++_i) \
;         __builtin_amdgcn_global_load_lds((const unsigned*)((const char*)(gbase) + (voff)[_i]), (LAS unsigned*)(lds + (bufoff) + ldsw + _i * 8192), 16, 0, 0); } while (0)
; #define PG8_LDA(dst, b, h) do { _Pragma("unroll") for (int m = 0; m < 4; ++m) _Pragma("unroll") for (int k = 0; k < 2; ++k) dst[m][k] = *(const LAS bf16x8*)(lds + PG8_SA(b, h) + aoff + m * 2048 + k * 1024); } while (0)
; #define PG8_LDB(dst, b, h) do { _Pragma("unroll") for (int n = 0; n < 2; ++n) _Pragma("unroll") for (int k = 0; k < 2; ++k) dst[n][k] = *(const LAS bf16x8*)(lds + PG8_SB(b, h) + boff + n * 2048 + k * 1024); } while (0)
; #define PG8_MMA(ai, bj, At, Bt) do { __builtin_amdgcn_s_setprio(1); _Pragma("unroll") for (int k = 0; k < 2; ++k) _Pragma("unroll") for (int m = 0; m < 4; ++m) _Pragma("unroll") for (int n = 0; n < 2; ++n) \
;         acc[ai][bj][m][n] = __builtin_amdgcn_mfma_f32_16x16x32_bf16(Bt[n][k], At[m][k], acc[ai][bj][m][n], 0, 0, 0); __builtin_amdgcn_s_setprio(0); } while (0)
; #define PG8_WAIT_V(n) asm volatile("s_waitcnt vmcnt(" #n ")" ::: "memory")
; #define PG8_BAR __builtin_amdgcn_s_barrier()
; template <class Epi, bool ALIGN_EPI>
; __device__ __forceinline__ void gemm_phase(LAS unsigned char* lds, const Gemm g, const StaticOrder& S, const Epi& E, const int tid) {
;     ...
;             PG8_LDB(B0, 0, 0); PG8_LDB(B1, 0, 1); PG8_SCHED; PG8_LDA(At, 0, 0); PG8_STAGE(PG8_SA(1, 1), a1 + hA, voffA);
;             PG8_WAIT_V(8); PG8_WAIT_L(0); PG8_BAR; PG8_MMA(0, 0, At, B0); PG8_MMA(0, 1, At, B1); PG8_BAR; PG8_SCHED;
;             PG8_LDA(At, 0, 1); PG8_STAGE(PG8_SB(0, 0), b2, voffB); PG8_STAGE(PG8_SB(0, 1), b2 + hB, voffB); PG8_STAGE(PG8_SA(0, 0), a2, voffA);
;             PG8_WAIT_V(8); PG8_WAIT_L(0); PG8_BAR; PG8_MMA(1, 0, At, B0); PG8_MMA(1, 1, At, B1); PG8_BAR; PG8_SCHED;
;             PG8_LDB(B0, 1, 0); PG8_LDB(B1, 1, 1); PG8_SCHED; PG8_LDA(At, 1, 0); PG8_STAGE(PG8_SA(0, 1), a2 + hA, voffA);
;             PG8_WAIT_V(8); PG8_WAIT_L(0); PG8_BAR; PG8_MMA(0, 0, At, B0); PG8_MMA(0, 1, At, B1); PG8_BAR; PG8_SCHED;
;             PG8_LDA(At, 1, 1); PG8_STAGE(PG8_SB(1, 0), b3, voffB); PG8_STAGE(PG8_SB(1, 1), b3 + hB, voffB); PG8_STAGE(PG8_SA(1, 0), a3, voffA);
;             PG8_WAIT_V(8); PG8_WAIT_L(0); PG8_BAR; PG8_MMA(1, 0, At, B0); PG8_MMA(1, 1, At, B1); PG8_BAR; PG8_SCHED;
	s_waitcnt lgkmcnt(0)
	v_mfma_f32_16x16x32_bf16 v[56:59], v[146:149], v[192:195], v[56:59]
	v_mfma_f32_16x16x32_bf16 v[48:51], v[158:161], v[192:195], v[48:51]
	v_mfma_f32_16x16x32_bf16 v[40:43], v[146:149], v[200:203], v[40:43]
	v_mfma_f32_16x16x32_bf16 v[32:35], v[158:161], v[200:203], v[32:35]
	v_mfma_f32_16x16x32_bf16 v[24:27], v[146:149], v[208:211], v[24:27]
	v_mfma_f32_16x16x32_bf16 v[16:19], v[158:161], v[208:211], v[16:19]
	v_mfma_f32_16x16x32_bf16 v[8:11], v[146:149], v[216:219], v[8:11]
	v_mfma_f32_16x16x32_bf16 v[4:7], v[158:161], v[216:219], v[4:7]
	v_mfma_f32_16x16x32_bf16 v[56:59], v[154:157], v[196:199], v[56:59]
	v_mfma_f32_16x16x32_bf16 v[48:51], v[162:165], v[196:199], v[48:51]
	v_mfma_f32_16x16x32_bf16 v[40:43], v[154:157], v[204:207], v[40:43]
	v_mfma_f32_16x16x32_bf16 v[32:35], v[162:165], v[204:207], v[32:35]
	v_mfma_f32_16x16x32_bf16 v[24:27], v[154:157], v[212:215], v[24:27]
	v_mfma_f32_16x16x32_bf16 v[16:19], v[162:165], v[212:215], v[16:19]
	v_mfma_f32_16x16x32_bf16 v[8:11], v[154:157], v[240:243], v[8:11]
	v_mfma_f32_16x16x32_bf16 v[4:7], v[162:165], v[240:243], v[4:7]
	s_setprio 0
	s_setprio 1
	v_mfma_f32_16x16x32_bf16 v[60:63], v[176:179], v[192:195], v[60:63]
	v_mfma_f32_16x16x32_bf16 v[52:55], v[184:187], v[192:195], v[52:55]
	v_mfma_f32_16x16x32_bf16 v[44:47], v[176:179], v[200:203], v[44:47]
	v_mfma_f32_16x16x32_bf16 v[36:39], v[184:187], v[200:203], v[36:39]
	v_mfma_f32_16x16x32_bf16 v[28:31], v[176:179], v[208:211], v[28:31]
	v_mfma_f32_16x16x32_bf16 v[20:23], v[184:187], v[208:211], v[20:23]
	v_mfma_f32_16x16x32_bf16 v[12:15], v[176:179], v[216:219], v[12:15]
	v_mfma_f32_16x16x32_bf16 v[0:3], v[184:187], v[216:219], v[0:3]
	v_mfma_f32_16x16x32_bf16 v[60:63], v[180:183], v[196:199], v[60:63]
	v_mfma_f32_16x16x32_bf16 v[52:55], v[188:191], v[196:199], v[52:55]
	v_mfma_f32_16x16x32_bf16 v[44:47], v[180:183], v[204:207], v[44:47]
	v_mfma_f32_16x16x32_bf16 v[36:39], v[188:191], v[204:207], v[36:39]
	v_mfma_f32_16x16x32_bf16 v[28:31], v[180:183], v[212:215], v[28:31]
	v_mfma_f32_16x16x32_bf16 v[20:23], v[188:191], v[212:215], v[20:23]
	v_mfma_f32_16x16x32_bf16 v[12:15], v[180:183], v[240:243], v[12:15]
	v_mfma_f32_16x16x32_bf16 v[0:3], v[188:191], v[240:243], v[0:3]
	s_setprio 0
	s_barrier
	v_lshl_add_u64 v[142:143], v[142:143], 0, s[80:81]
	v_lshl_add_u64 v[144:145], v[144:145], 0, s[80:81]
	s_mov_b32 s10, s11
	s_cmp_lg_u32 s10, s58
	s_cbranch_scc1 .LBB0_308
.Lgu_last:
	s_add_i32 s11, s10, 2
	s_cmp_eq_u32 s58, s10
	v_lshl_add_u64 v[146:147], v[142:143], 0, s[92:93]
	s_cselect_b64 vcc, -1, 0
	v_add_u32_e32 v150, s33, v151
	s_add_i32 s10, 0, 0x14000
	v_cndmask_b32_e32 v167, v147, v139, vcc
	v_cndmask_b32_e32 v166, v146, v138, vcc
	ds_read_b128 v[146:149], v150
	ds_read_b128 v[154:157], v150 offset:1024
	ds_read_b128 v[158:161], v150 offset:2048
	ds_read_b128 v[162:165], v150 offset:3072
	v_add_u32_e32 v150, s10, v151
	ds_read_b128 v[176:179], v150
	ds_read_b128 v[180:183], v150 offset:1024
	ds_read_b128 v[184:187], v150 offset:2048
	ds_read_b128 v[188:191], v150 offset:3072
	v_cndmask_b32_e32 v221, v145, v141, vcc
	v_cndmask_b32_e32 v220, v144, v140, vcc
	v_lshl_add_u64 v[226:227], v[142:143], 0, v[134:135]
	s_add_i32 m0, s51, 0xc000
	ds_read_b128 v[192:195], v153
	ds_read_b128 v[196:199], v153 offset:1024
	ds_read_b128 v[200:203], v153 offset:2048
	ds_read_b128 v[204:207], v153 offset:3072
	ds_read_b128 v[208:211], v153 offset:4096
	ds_read_b128 v[212:215], v153 offset:5120
	ds_read_b128 v[216:219], v153 offset:6144
	ds_read_b128 v[240:243], v153 offset:7168
	global_load_lds_dwordx4 v[226:227], off
	v_lshl_add_u64 v[226:227], v[142:143], 0, v[136:137]
	s_add_i32 m0, s51, 0xe000
	s_nop 0
	global_load_lds_dwordx4 v[226:227], off
	s_waitcnt vmcnt(8)
	s_waitcnt lgkmcnt(0)
	s_setprio 1
	s_barrier
	s_waitcnt lgkmcnt(0)
	v_mfma_f32_16x16x32_bf16 v[120:123], v[146:149], v[192:195], v[120:123]
	v_mfma_f32_16x16x32_bf16 v[112:115], v[158:161], v[192:195], v[112:115]
	v_mfma_f32_16x16x32_bf16 v[104:107], v[146:149], v[200:203], v[104:107]
	v_mfma_f32_16x16x32_bf16 v[96:99], v[158:161], v[200:203], v[96:99]
	v_mfma_f32_16x16x32_bf16 v[88:91], v[146:149], v[208:211], v[88:91]
	v_mfma_f32_16x16x32_bf16 v[80:83], v[158:161], v[208:211], v[80:83]
	v_mfma_f32_16x16x32_bf16 v[72:75], v[146:149], v[216:219], v[72:75]
	v_mfma_f32_16x16x32_bf16 v[64:67], v[158:161], v[216:219], v[64:67]
	v_mfma_f32_16x16x32_bf16 v[120:123], v[154:157], v[196:199], v[120:123]
	v_mfma_f32_16x16x32_bf16 v[112:115], v[162:165], v[196:199], v[112:115]
	v_mfma_f32_16x16x32_bf16 v[104:107], v[154:157], v[204:207], v[104:107]
	v_mfma_f32_16x16x32_bf16 v[96:99], v[162:165], v[204:207], v[96:99]
	v_mfma_f32_16x16x32_bf16 v[88:91], v[154:157], v[212:215], v[88:91]
	v_mfma_f32_16x16x32_bf16 v[80:83], v[162:165], v[212:215], v[80:83]
	v_mfma_f32_16x16x32_bf16 v[72:75], v[154:157], v[240:243], v[72:75]
	v_mfma_f32_16x16x32_bf16 v[64:67], v[162:165], v[240:243], v[64:67]
	s_setprio 0
	s_setprio 1
	v_mfma_f32_16x16x32_bf16 v[124:127], v[176:179], v[192:195], v[124:127]
	v_mfma_f32_16x16x32_bf16 v[116:119], v[184:187], v[192:195], v[116:119]
	v_mfma_f32_16x16x32_bf16 v[108:111], v[176:179], v[200:203], v[108:111]
	v_mfma_f32_16x16x32_bf16 v[100:103], v[184:187], v[200:203], v[100:103]
	v_mfma_f32_16x16x32_bf16 v[92:95], v[176:179], v[208:211], v[92:95]
	v_mfma_f32_16x16x32_bf16 v[84:87], v[184:187], v[208:211], v[84:87]
	v_mfma_f32_16x16x32_bf16 v[76:79], v[176:179], v[216:219], v[76:79]
	v_mfma_f32_16x16x32_bf16 v[68:71], v[184:187], v[216:219], v[68:71]
	v_mfma_f32_16x16x32_bf16 v[124:127], v[180:183], v[196:199], v[124:127]
	v_mfma_f32_16x16x32_bf16 v[116:119], v[188:191], v[196:199], v[116:119]
	v_mfma_f32_16x16x32_bf16 v[108:111], v[180:183], v[204:207], v[108:111]
	v_mfma_f32_16x16x32_bf16 v[100:103], v[188:191], v[204:207], v[100:103]
	v_mfma_f32_16x16x32_bf16 v[92:95], v[180:183], v[212:215], v[92:95]
	v_mfma_f32_16x16x32_bf16 v[84:87], v[188:191], v[212:215], v[84:87]
	v_mfma_f32_16x16x32_bf16 v[76:79], v[180:183], v[240:243], v[76:79]
	v_mfma_f32_16x16x32_bf16 v[68:71], v[188:191], v[240:243], v[68:71]
	s_setprio 0
	s_barrier
; #define PG8_STAGE(bufoff, gbase, voff) do { _Pragma("unroll") for (int _i = 0; _i < 2; ++_i) \
;         __builtin_amdgcn_global_load_lds((const unsigned*)((const char*)(gbase) + (voff)[_i]), (LAS unsigned*)(lds + (bufoff) + ldsw + _i * 8192), 16, 0, 0); } while (0)
; #define PG8_LDA(dst, b, h) do { _Pragma("unroll") for (int m = 0; m < 4; ++m) _Pragma("unroll") for (int k = 0; k < 2; ++k) dst[m][k] = *(const LAS bf16x8*)(lds + PG8_SA(b, h) + aoff + m * 2048 + k * 1024); } while (0)
; #define PG8_LDB(dst, b, h) do { _Pragma("unroll") for (int n = 0; n < 2; ++n) _Pragma("unroll") for (int k = 0; k < 2; ++k) dst[n][k] = *(const LAS bf16x8*)(lds + PG8_SB(b, h) + boff + n * 2048 + k * 1024); } while (0)
; #define PG8_MMA(ai, bj, At, Bt) do { __builtin_amdgcn_s_setprio(1); _Pragma("unroll") for (int k = 0; k < 2; ++k) _Pragma("unroll") for (int m = 0; m < 4; ++m) _Pragma("unroll") for (int n = 0; n < 2; ++n) \
;         acc[ai][bj][m][n] = __builtin_amdgcn_mfma_f32_16x16x32_bf16(Bt[n][k], At[m][k], acc[ai][bj][m][n], 0, 0, 0); __builtin_amdgcn_s_setprio(0); } while (0)
; #define PG8_WAIT_V(n) asm volatile("s_waitcnt vmcnt(" #n ")" ::: "memory")
; #define PG8_WAIT_L(n) asm volatile("s_waitcnt lgkmcnt(" #n ")" ::: "memory")
; #define PG8_BAR __builtin_amdgcn_s_barrier()
; #define PG8_SCHED __builtin_amdgcn_sched_barrier(0)
; template <class Epi, bool ALIGN_EPI>
; __device__ __forceinline__ void gemm_phase(LAS unsigned char* lds, const Gemm g, const StaticOrder& S, const Epi& E, const int tid) {
;     ...
;             PG8_LDA(At, 0, 1); PG8_STAGE(PG8_SB(0, 0), b2, voffB); PG8_STAGE(PG8_SB(0, 1), b2 + hB, voffB); PG8_STAGE(PG8_SA(0, 0), a2, voffA);
;             PG8_WAIT_V(8); PG8_WAIT_L(0); PG8_BAR; PG8_MMA(1, 0, At, B0); PG8_MMA(1, 1, At, B1); PG8_BAR; PG8_SCHED;
;             PG8_LDB(B0, 1, 0); PG8_LDB(B1, 1, 1); PG8_SCHED; PG8_LDA(At, 1, 0); PG8_STAGE(PG8_SA(0, 1), a2 + hA, voffA);
;             PG8_WAIT_V(8); PG8_WAIT_L(0); PG8_BAR; PG8_MMA(0, 0, At, B0); PG8_MMA(0, 1, At, B1); PG8_BAR; PG8_SCHED;
	s_add_i32 s65, s33, s45
	v_lshl_add_u64 v[226:227], v[220:221], 0, v[168:169]
	s_mov_b32 m0, s65
	ds_read_b128 v[192:195], v153 offset:16384
	ds_read_b128 v[196:199], v153 offset:17408
	ds_read_b128 v[200:203], v153 offset:18432
	ds_read_b128 v[204:207], v153 offset:19456
	ds_read_b128 v[208:211], v153 offset:20480
	ds_read_b128 v[212:215], v153 offset:21504
	ds_read_b128 v[216:219], v153 offset:22528
	ds_read_b128 v[240:243], v153 offset:23552
	global_load_lds_dwordx4 v[226:227], off
	v_lshl_add_u64 v[244:245], v[220:221], 0, v[128:129]
	s_add_i32 m0, s65, 0x2000
	v_lshl_add_u64 v[220:221], v[220:221], 0, s[12:13]
	s_add_i32 s10, s10, s45
	global_load_lds_dwordx4 v[244:245], off
	v_lshl_add_u64 v[246:247], v[220:221], 0, v[168:169]
	s_mov_b32 m0, s10
	v_lshl_add_u64 v[220:221], v[220:221], 0, v[128:129]
	global_load_lds_dwordx4 v[246:247], off
	s_add_i32 m0, s10, 0x2000
	v_lshl_add_u64 v[248:249], v[166:167], 0, v[132:133]
	global_load_lds_dwordx4 v[220:221], off
	s_mov_b32 m0, s51
	v_lshl_add_u64 v[250:251], v[166:167], 0, v[130:131]
	global_load_lds_dwordx4 v[248:249], off
	s_mov_b32 m0, s52
	s_nop 0
	global_load_lds_dwordx4 v[250:251], off
	s_waitcnt vmcnt(8)
	s_waitcnt lgkmcnt(0)
	s_setprio 1
	s_barrier
	s_waitcnt lgkmcnt(0)
	v_mfma_f32_16x16x32_bf16 v[56:59], v[146:149], v[192:195], v[56:59]
	v_mfma_f32_16x16x32_bf16 v[48:51], v[158:161], v[192:195], v[48:51]
	v_mfma_f32_16x16x32_bf16 v[40:43], v[146:149], v[200:203], v[40:43]
	v_mfma_f32_16x16x32_bf16 v[32:35], v[158:161], v[200:203], v[32:35]
	v_mfma_f32_16x16x32_bf16 v[24:27], v[146:149], v[208:211], v[24:27]
	v_mfma_f32_16x16x32_bf16 v[16:19], v[158:161], v[208:211], v[16:19]
	v_mfma_f32_16x16x32_bf16 v[8:11], v[146:149], v[216:219], v[8:11]
	v_mfma_f32_16x16x32_bf16 v[4:7], v[158:161], v[216:219], v[4:7]
	v_mfma_f32_16x16x32_bf16 v[56:59], v[154:157], v[196:199], v[56:59]
	v_mfma_f32_16x16x32_bf16 v[48:51], v[162:165], v[196:199], v[48:51]
	v_mfma_f32_16x16x32_bf16 v[40:43], v[154:157], v[204:207], v[40:43]
	v_mfma_f32_16x16x32_bf16 v[32:35], v[162:165], v[204:207], v[32:35]
	v_mfma_f32_16x16x32_bf16 v[24:27], v[154:157], v[212:215], v[24:27]
	v_mfma_f32_16x16x32_bf16 v[16:19], v[162:165], v[212:215], v[16:19]
	v_mfma_f32_16x16x32_bf16 v[8:11], v[154:157], v[240:243], v[8:11]
	v_mfma_f32_16x16x32_bf16 v[4:7], v[162:165], v[240:243], v[4:7]
	s_setprio 0
	s_setprio 1
	v_mfma_f32_16x16x32_bf16 v[60:63], v[176:179], v[192:195], v[60:63]
	v_mfma_f32_16x16x32_bf16 v[52:55], v[184:187], v[192:195], v[52:55]
	v_mfma_f32_16x16x32_bf16 v[44:47], v[176:179], v[200:203], v[44:47]
	v_mfma_f32_16x16x32_bf16 v[36:39], v[184:187], v[200:203], v[36:39]
	v_mfma_f32_16x16x32_bf16 v[28:31], v[176:179], v[208:211], v[28:31]
	v_mfma_f32_16x16x32_bf16 v[20:23], v[184:187], v[208:211], v[20:23]
	v_mfma_f32_16x16x32_bf16 v[12:15], v[176:179], v[216:219], v[12:15]
	v_mfma_f32_16x16x32_bf16 v[0:3], v[184:187], v[216:219], v[0:3]
	v_mfma_f32_16x16x32_bf16 v[60:63], v[180:183], v[196:199], v[60:63]
	v_mfma_f32_16x16x32_bf16 v[52:55], v[188:191], v[196:199], v[52:55]
	v_mfma_f32_16x16x32_bf16 v[44:47], v[180:183], v[204:207], v[44:47]
	v_mfma_f32_16x16x32_bf16 v[36:39], v[188:191], v[204:207], v[36:39]
	v_mfma_f32_16x16x32_bf16 v[28:31], v[180:183], v[212:215], v[28:31]
	v_mfma_f32_16x16x32_bf16 v[20:23], v[188:191], v[212:215], v[20:23]
	v_mfma_f32_16x16x32_bf16 v[12:15], v[180:183], v[240:243], v[12:15]
	v_mfma_f32_16x16x32_bf16 v[0:3], v[188:191], v[240:243], v[0:3]
	s_setprio 0
	s_barrier
	s_add_i32 s10, 0, 0x18000
	v_add_u32_e32 v150, s10, v151
	s_add_i32 s65, 0, 0x1c000
	ds_read_b128 v[146:149], v150
	ds_read_b128 v[154:157], v150 offset:1024
	ds_read_b128 v[158:161], v150 offset:2048
	ds_read_b128 v[162:165], v150 offset:3072
	v_add_u32_e32 v150, s65, v151
	ds_read_b128 v[176:179], v150
	ds_read_b128 v[180:183], v150 offset:1024
	ds_read_b128 v[184:187], v150 offset:2048
	ds_read_b128 v[188:191], v150 offset:3072
	v_lshl_add_u64 v[166:167], v[166:167], 0, s[94:95]
	s_mov_b32 m0, s53
	v_lshl_add_u64 v[252:253], v[166:167], 0, v[132:133]
	ds_read_b128 v[192:195], v153 offset:32768
	ds_read_b128 v[196:199], v153 offset:33792
	ds_read_b128 v[200:203], v153 offset:34816
	ds_read_b128 v[204:207], v153 offset:35840
	ds_read_b128 v[208:211], v153 offset:36864
	ds_read_b128 v[212:215], v153 offset:37888
	ds_read_b128 v[216:219], v153 offset:38912
	ds_read_b128 v[240:243], v153 offset:39936
	global_load_lds_dwordx4 v[252:253], off
	v_lshl_add_u64 v[166:167], v[166:167], 0, v[130:131]
	s_mov_b32 m0, s54
	s_nop 0
	global_load_lds_dwordx4 v[166:167], off
	s_waitcnt vmcnt(8)
	s_waitcnt lgkmcnt(0)
	s_setprio 1
	s_barrier
; __device__ __forceinline__ unsigned cvt_pk_bf16(float lo, float hi) { unsigned r; asm volatile("v_cvt_pk_bf16_f32 %0, %1, %2" : "=v"(r) : "v"(lo), "v"(hi)); return r; }
; __device__ __forceinline__ float siluf_(float x) { return x * sigmoidf_(x); }
; #define PG8_STAGE(bufoff, gbase, voff) do { _Pragma("unroll") for (int _i = 0; _i < 2; ++_i) \
;         __builtin_amdgcn_global_load_lds((const unsigned*)((const char*)(gbase) + (voff)[_i]), (LAS unsigned*)(lds + (bufoff) + ldsw + _i * 8192), 16, 0, 0); } while (0)
; #define PG8_LDA(dst, b, h) do { _Pragma("unroll") for (int m = 0; m < 4; ++m) _Pragma("unroll") for (int k = 0; k < 2; ++k) dst[m][k] = *(const LAS bf16x8*)(lds + PG8_SA(b, h) + aoff + m * 2048 + k * 1024); } while (0)
; #define PG8_WAIT_V(n) asm volatile("s_waitcnt vmcnt(" #n ")" ::: "memory")
; #define PG8_WAIT_L(n) asm volatile("s_waitcnt lgkmcnt(" #n ")" ::: "memory")
; #define PG8_BAR __builtin_amdgcn_s_barrier()
; #define PG8_SCHED __builtin_amdgcn_sched_barrier(0)
;     __device__ __forceinline__ void operator()(const f32x4 (&acc)[2][2][4][2], const Unit& u, int wr, int wc, int fr, int fq) const {
;         const int row0 = u.pm * BM + wr * 64 + fr, col0 = u.pn * HALF + wc * 32 + 8 * fq;
;         float rsv[2][4]; load_rstd(rsv, ssq, row0);
; #pragma unroll
;         for (int ai = 0; ai < 2; ++ai)
; #pragma unroll
;             for (int m = 0; m < 4; ++m) { const int row = row0 + ai * HALF + m * 16; bf16_t* rowp = O + (size_t)row * ldc + col0; const float rs = rsv[ai][m];
;                 f32x4 v0, v1;
; #pragma unroll
;                 for (int j = 0; j < 4; ++j) { v0[j] = siluf_(acc[ai][0][m][0][j] * rs) * (acc[ai][1][m][0][j] * rs); v1[j] = siluf_(acc[ai][0][m][1][j] * rs) * (acc[ai][1][m][1][j] * rs); }
;                 u32x4 w; w.x = cvt_pk_bf16(v0[0], v0[1]); w.y = cvt_pk_bf16(v0[2], v0[3]); w.z = cvt_pk_bf16(v1[0], v1[1]); w.w = cvt_pk_bf16(v1[2], v1[3]);
;                 *(u32x4*)rowp = w; }
; template <class Epi, bool ALIGN_EPI>
; __device__ __forceinline__ void gemm_phase(LAS unsigned char* lds, const Gemm g, const StaticOrder& S, const Epi& E, const int tid) {
;     ...
;             PG8_LDA(At, 1, 1); PG8_STAGE(PG8_SB(1, 0), b3, voffB); PG8_STAGE(PG8_SB(1, 1), b3 + hB, voffB); PG8_STAGE(PG8_SA(1, 0), a3, voffA);
;             PG8_WAIT_V(8); PG8_WAIT_L(0); PG8_BAR; PG8_MMA(1, 0, At, B0); PG8_MMA(1, 1, At, B1); PG8_BAR; PG8_SCHED;
	s_waitcnt lgkmcnt(0)
	v_mfma_f32_16x16x32_bf16 v[120:123], v[146:149], v[192:195], v[120:123]
	v_mfma_f32_16x16x32_bf16 v[112:115], v[158:161], v[192:195], v[112:115]
	v_mfma_f32_16x16x32_bf16 v[104:107], v[146:149], v[200:203], v[104:107]
	v_mfma_f32_16x16x32_bf16 v[96:99], v[158:161], v[200:203], v[96:99]
	v_mfma_f32_16x16x32_bf16 v[88:91], v[146:149], v[208:211], v[88:91]
	v_mfma_f32_16x16x32_bf16 v[80:83], v[158:161], v[208:211], v[80:83]
	v_mfma_f32_16x16x32_bf16 v[72:75], v[146:149], v[216:219], v[72:75]
	v_mfma_f32_16x16x32_bf16 v[64:67], v[158:161], v[216:219], v[64:67]
	v_mfma_f32_16x16x32_bf16 v[120:123], v[154:157], v[196:199], v[120:123]
	v_mfma_f32_16x16x32_bf16 v[112:115], v[162:165], v[196:199], v[112:115]
	v_mfma_f32_16x16x32_bf16 v[104:107], v[154:157], v[204:207], v[104:107]
	v_mfma_f32_16x16x32_bf16 v[96:99], v[162:165], v[204:207], v[96:99]
	v_mfma_f32_16x16x32_bf16 v[88:91], v[154:157], v[212:215], v[88:91]
	v_mfma_f32_16x16x32_bf16 v[80:83], v[162:165], v[212:215], v[80:83]
	v_mfma_f32_16x16x32_bf16 v[72:75], v[154:157], v[240:243], v[72:75]
	v_mfma_f32_16x16x32_bf16 v[64:67], v[162:165], v[240:243], v[64:67]
	s_setprio 0
	s_setprio 1
	v_mfma_f32_16x16x32_bf16 v[124:127], v[176:179], v[192:195], v[124:127]
	v_mfma_f32_16x16x32_bf16 v[116:119], v[184:187], v[192:195], v[116:119]
	v_mfma_f32_16x16x32_bf16 v[108:111], v[176:179], v[200:203], v[108:111]
	v_mfma_f32_16x16x32_bf16 v[100:103], v[184:187], v[200:203], v[100:103]
	v_mfma_f32_16x16x32_bf16 v[92:95], v[176:179], v[208:211], v[92:95]
	v_mfma_f32_16x16x32_bf16 v[84:87], v[184:187], v[208:211], v[84:87]
	v_mfma_f32_16x16x32_bf16 v[76:79], v[176:179], v[216:219], v[76:79]
	v_mfma_f32_16x16x32_bf16 v[68:71], v[184:187], v[216:219], v[68:71]
	v_mfma_f32_16x16x32_bf16 v[124:127], v[180:183], v[196:199], v[124:127]
	v_mfma_f32_16x16x32_bf16 v[116:119], v[188:191], v[196:199], v[116:119]
	v_mfma_f32_16x16x32_bf16 v[108:111], v[180:183], v[204:207], v[108:111]
	v_mfma_f32_16x16x32_bf16 v[100:103], v[188:191], v[204:207], v[100:103]
	v_mfma_f32_16x16x32_bf16 v[92:95], v[180:183], v[212:215], v[92:95]
	v_mfma_f32_16x16x32_bf16 v[84:87], v[188:191], v[212:215], v[84:87]
	v_mfma_f32_16x16x32_bf16 v[76:79], v[180:183], v[240:243], v[76:79]
	v_mfma_f32_16x16x32_bf16 v[68:71], v[188:191], v[240:243], v[68:71]
	s_setprio 0
	s_barrier
	s_add_i32 s10, s10, s45
	v_lshl_add_u64 v[166:167], v[226:227], 0, s[92:93]
	s_mov_b32 m0, s10
	ds_read_b128 v[192:195], v153 offset:49152
	ds_read_b128 v[196:199], v153 offset:50176
	ds_read_b128 v[200:203], v153 offset:51200
	ds_read_b128 v[204:207], v153 offset:52224
	ds_read_b128 v[208:211], v153 offset:53248
	ds_read_b128 v[212:215], v153 offset:54272
	ds_read_b128 v[216:219], v153 offset:55296
	ds_read_b128 v[240:243], v153 offset:56320
	global_load_lds_dwordx4 v[166:167], off
	v_lshl_add_u64 v[166:167], v[244:245], 0, s[92:93]
	s_add_i32 m0, s10, 0x2000
	s_add_i32 s10, s65, s45
	global_load_lds_dwordx4 v[166:167], off
	v_lshl_add_u64 v[166:167], v[246:247], 0, s[92:93]
	s_mov_b32 m0, s10
	s_nop 0
	global_load_lds_dwordx4 v[166:167], off
	v_lshl_add_u64 v[166:167], v[220:221], 0, s[92:93]
	s_add_i32 m0, s10, 0x2000
	s_nop 0
	global_load_lds_dwordx4 v[166:167], off
	v_lshl_add_u64 v[166:167], v[248:249], 0, s[92:93]
	s_mov_b32 m0, s56
	s_nop 0
	global_load_lds_dwordx4 v[166:167], off
	v_lshl_add_u64 v[166:167], v[250:251], 0, s[92:93]
	s_mov_b32 m0, s57
	s_nop 0
	global_load_lds_dwordx4 v[166:167], off
	s_waitcnt vmcnt(8)
	s_waitcnt lgkmcnt(0)
	s_setprio 1
	s_barrier
	s_waitcnt lgkmcnt(0)
	v_mfma_f32_16x16x32_bf16 v[56:59], v[146:149], v[192:195], v[56:59]
	v_lshrrev_b32_e32 v171, 8, v170
	v_and_b32_e32 v234, 15, v170
	v_lshl_add_u32 v171, v171, 6, v234
	s_lshl_b32 s98, s64, 8
	v_add_u32_e32 v171, s98, v171
	v_mul_lo_u32 v171, v171, s28
	v_bfe_u32 v234, v170, 6, 2
	v_bfe_u32 v224, v170, 4, 2
	v_lshlrev_b32_e32 v234, 5, v234
	v_lshl_or_b32 v234, v224, 3, v234
	v_mfma_f32_16x16x32_bf16 v[48:51], v[158:161], v[192:195], v[48:51]
	s_lshl_b32 s98, s63, 7
	v_add_u32_e32 v234, s98, v234
	v_add_lshl_u32 v232, v171, v234, 1
	v_mov_b32_e32 v233, 0
	v_lshl_add_u64 v[232:233], v[232:233], 0, s[30:31]
	s_lshl_b32 s98, s28, 5
	s_mov_b32 s99, 0
	s_mov_b32 s100, 0xbfb8aa3b
	s_mov_b32 s101, 0xbfb8aa3b
	v_mul_f32_e32 v120, v172, v120
	v_mfma_f32_16x16x32_bf16 v[40:43], v[146:149], v[200:203], v[40:43]
	v_mul_f32_e32 v121, v172, v121
	v_mul_f32_e32 v122, v172, v122
	v_mul_f32_e32 v123, v172, v123
	v_mul_f32_e32 v124, v172, v124
	v_mul_f32_e32 v125, v172, v125
	v_mul_f32_e32 v126, v172, v126
	v_mul_f32_e32 v127, v172, v127
	v_mul_f32_e32 v224, s100, v120
	v_mul_f32_e32 v225, s101, v121
	v_mul_f32_e32 v228, s100, v122
	v_mfma_f32_16x16x32_bf16 v[32:35], v[158:161], v[200:203], v[32:35]
	v_mul_f32_e32 v229, s101, v123
	v_exp_f32_e32 v224, v224
	v_exp_f32_e32 v225, v225
	v_exp_f32_e32 v228, v228
	v_exp_f32_e32 v229, v229
	v_add_f32_e32 v224, 1.0, v224
	v_add_f32_e32 v225, 1.0, v225
	v_add_f32_e32 v228, 1.0, v228
	v_add_f32_e32 v229, 1.0, v229
	v_rcp_f32_e32 v224, v224
	v_mfma_f32_16x16x32_bf16 v[24:27], v[146:149], v[208:211], v[24:27]
	v_rcp_f32_e32 v225, v225
	v_rcp_f32_e32 v228, v228
	v_rcp_f32_e32 v229, v229
	v_nop
	v_mul_f32_e32 v120, v224, v120
	v_mul_f32_e32 v121, v225, v121
	v_mul_f32_e32 v122, v228, v122
	v_mul_f32_e32 v123, v229, v123
	v_mul_f32_e32 v120, v124, v120
	v_mul_f32_e32 v121, v125, v121
	v_mfma_f32_16x16x32_bf16 v[16:19], v[158:161], v[208:211], v[16:19]
	v_mul_f32_e32 v122, v126, v122
	v_mul_f32_e32 v123, v127, v123
	v_mul_f32_e32 v112, v172, v112
	v_mul_f32_e32 v113, v172, v113
	v_mul_f32_e32 v114, v172, v114
	v_mul_f32_e32 v115, v172, v115
; __device__ __forceinline__ unsigned cvt_pk_bf16(float lo, float hi) { unsigned r; asm volatile("v_cvt_pk_bf16_f32 %0, %1, %2" : "=v"(r) : "v"(lo), "v"(hi)); return r; }
; __device__ __forceinline__ float siluf_(float x) { return x * sigmoidf_(x); }
; #define PG8_MMA(ai, bj, At, Bt) do { __builtin_amdgcn_s_setprio(1); _Pragma("unroll") for (int k = 0; k < 2; ++k) _Pragma("unroll") for (int m = 0; m < 4; ++m) _Pragma("unroll") for (int n = 0; n < 2; ++n) \
;         acc[ai][bj][m][n] = __builtin_amdgcn_mfma_f32_16x16x32_bf16(Bt[n][k], At[m][k], acc[ai][bj][m][n], 0, 0, 0); __builtin_amdgcn_s_setprio(0); } while (0)
; #define PG8_WAIT_V(n) asm volatile("s_waitcnt vmcnt(" #n ")" ::: "memory")
; #define PG8_WAIT_L(n) asm volatile("s_waitcnt lgkmcnt(" #n ")" ::: "memory")
; #define PG8_BAR __builtin_amdgcn_s_barrier()
; #define PG8_SCHED __builtin_amdgcn_sched_barrier(0)
;     __device__ __forceinline__ void operator()(const f32x4 (&acc)[2][2][4][2], const Unit& u, int wr, int wc, int fr, int fq) const {
;     ...
;         for (int ai = 0; ai < 2; ++ai)
; #pragma unroll
;             for (int m = 0; m < 4; ++m) { const int row = row0 + ai * HALF + m * 16; bf16_t* rowp = O + (size_t)row * ldc + col0; const float rs = rsv[ai][m];
;                 f32x4 v0, v1;
; #pragma unroll
;                 for (int j = 0; j < 4; ++j) { v0[j] = siluf_(acc[ai][0][m][0][j] * rs) * (acc[ai][1][m][0][j] * rs); v1[j] = siluf_(acc[ai][0][m][1][j] * rs) * (acc[ai][1][m][1][j] * rs); }
;                 u32x4 w; w.x = cvt_pk_bf16(v0[0], v0[1]); w.y = cvt_pk_bf16(v0[2], v0[3]); w.z = cvt_pk_bf16(v1[0], v1[1]); w.w = cvt_pk_bf16(v1[2], v1[3]);
;                 *(u32x4*)rowp = w; }
; template <class Epi, bool ALIGN_EPI>
; __device__ __forceinline__ void gemm_phase(LAS unsigned char* lds, const Gemm g, const StaticOrder& S, const Epi& E, const int tid) {
;     ...
;             PG8_WAIT_V(8); PG8_WAIT_L(0); PG8_BAR; PG8_MMA(1, 0, At, B0); PG8_MMA(1, 1, At, B1); PG8_BAR; PG8_SCHED;
	v_mul_f32_e32 v116, v172, v116
	v_mul_f32_e32 v117, v172, v117
	v_mul_f32_e32 v118, v172, v118
	v_mul_f32_e32 v119, v172, v119
	v_mfma_f32_16x16x32_bf16 v[8:11], v[146:149], v[216:219], v[8:11]
	v_mul_f32_e32 v224, s100, v112
	v_mul_f32_e32 v225, s101, v113
	v_mul_f32_e32 v228, s100, v114
	v_mul_f32_e32 v229, s101, v115
	v_exp_f32_e32 v224, v224
	v_exp_f32_e32 v225, v225
	v_exp_f32_e32 v228, v228
	v_exp_f32_e32 v229, v229
	v_add_f32_e32 v224, 1.0, v224
	v_add_f32_e32 v225, 1.0, v225
	v_mfma_f32_16x16x32_bf16 v[4:7], v[158:161], v[216:219], v[4:7]
	v_add_f32_e32 v228, 1.0, v228
	v_add_f32_e32 v229, 1.0, v229
	v_rcp_f32_e32 v224, v224
	v_rcp_f32_e32 v225, v225
	v_rcp_f32_e32 v228, v228
	v_rcp_f32_e32 v229, v229
	v_nop
	v_mul_f32_e32 v112, v224, v112
	v_mul_f32_e32 v113, v225, v113
	v_mul_f32_e32 v114, v228, v114
	v_mfma_f32_16x16x32_bf16 v[56:59], v[154:157], v[196:199], v[56:59]
	v_mul_f32_e32 v115, v229, v115
	v_mul_f32_e32 v112, v116, v112
	v_mul_f32_e32 v113, v117, v113
	v_mul_f32_e32 v114, v118, v114
	v_mul_f32_e32 v115, v119, v115
	v_cvt_pk_bf16_f32 v120, v120, v121
	v_cvt_pk_bf16_f32 v121, v122, v123
	v_cvt_pk_bf16_f32 v122, v112, v113
	v_cvt_pk_bf16_f32 v123, v114, v115
	global_store_dwordx4 v[232:233], v[120:123], off
	v_mfma_f32_16x16x32_bf16 v[48:51], v[162:165], v[196:199], v[48:51]
	v_lshl_add_u64 v[232:233], v[232:233], 0, s[98:99]
	v_mul_f32_e32 v104, v173, v104
	v_mul_f32_e32 v105, v173, v105
	v_mul_f32_e32 v106, v173, v106
	v_mul_f32_e32 v107, v173, v107
	v_mul_f32_e32 v108, v173, v108
	v_mul_f32_e32 v109, v173, v109
	v_mul_f32_e32 v110, v173, v110
	v_mul_f32_e32 v111, v173, v111
	v_mul_f32_e32 v224, s100, v104
	v_mfma_f32_16x16x32_bf16 v[40:43], v[154:157], v[204:207], v[40:43]
	v_mul_f32_e32 v225, s101, v105
	v_mul_f32_e32 v228, s100, v106
	v_mul_f32_e32 v229, s101, v107
	v_exp_f32_e32 v224, v224
	v_exp_f32_e32 v225, v225
	v_exp_f32_e32 v228, v228
	v_exp_f32_e32 v229, v229
	v_add_f32_e32 v224, 1.0, v224
	v_add_f32_e32 v225, 1.0, v225
	v_add_f32_e32 v228, 1.0, v228
	v_mfma_f32_16x16x32_bf16 v[32:35], v[162:165], v[204:207], v[32:35]
	v_add_f32_e32 v229, 1.0, v229
	v_rcp_f32_e32 v224, v224
	v_rcp_f32_e32 v225, v225
	v_rcp_f32_e32 v228, v228
	v_rcp_f32_e32 v229, v229
	v_nop
	v_mul_f32_e32 v104, v224, v104
	v_mul_f32_e32 v105, v225, v105
	v_mul_f32_e32 v106, v228, v106
	v_mul_f32_e32 v107, v229, v107
	v_mfma_f32_16x16x32_bf16 v[24:27], v[154:157], v[212:215], v[24:27]
	v_mul_f32_e32 v104, v108, v104
	v_mul_f32_e32 v105, v109, v105
	v_mul_f32_e32 v106, v110, v106
	v_mul_f32_e32 v107, v111, v107
	v_mul_f32_e32 v96, v173, v96
	v_mul_f32_e32 v97, v173, v97
	v_mul_f32_e32 v98, v173, v98
	v_mul_f32_e32 v99, v173, v99
	v_mul_f32_e32 v100, v173, v100
	v_mul_f32_e32 v101, v173, v101
	v_mfma_f32_16x16x32_bf16 v[16:19], v[162:165], v[212:215], v[16:19]
	v_mul_f32_e32 v102, v173, v102
	v_mul_f32_e32 v103, v173, v103
	v_mul_f32_e32 v224, s100, v96
	v_mul_f32_e32 v225, s101, v97
	v_mul_f32_e32 v228, s100, v98
	v_mul_f32_e32 v229, s101, v99
	v_exp_f32_e32 v224, v224
	v_exp_f32_e32 v225, v225
	v_exp_f32_e32 v228, v228
	v_exp_f32_e32 v229, v229
	v_mfma_f32_16x16x32_bf16 v[8:11], v[154:157], v[240:243], v[8:11]
	v_add_f32_e32 v224, 1.0, v224
	v_add_f32_e32 v225, 1.0, v225
	v_add_f32_e32 v228, 1.0, v228
	v_add_f32_e32 v229, 1.0, v229
	v_rcp_f32_e32 v224, v224
	v_rcp_f32_e32 v225, v225
	v_rcp_f32_e32 v228, v228
	v_rcp_f32_e32 v229, v229
	v_nop
	v_mul_f32_e32 v96, v224, v96
	v_mfma_f32_16x16x32_bf16 v[4:7], v[162:165], v[240:243], v[4:7]
	v_mul_f32_e32 v97, v225, v97
	v_mul_f32_e32 v98, v228, v98
	v_mul_f32_e32 v99, v229, v99
	v_mul_f32_e32 v96, v100, v96
	v_mul_f32_e32 v97, v101, v97
	v_mul_f32_e32 v98, v102, v98
	v_mul_f32_e32 v99, v103, v99
	v_cvt_pk_bf16_f32 v104, v104, v105
	v_cvt_pk_bf16_f32 v105, v106, v107
	v_cvt_pk_bf16_f32 v106, v96, v97
	s_setprio 0
	s_setprio 1
	v_mfma_f32_16x16x32_bf16 v[60:63], v[176:179], v[192:195], v[60:63]
	v_cvt_pk_bf16_f32 v107, v98, v99
	global_store_dwordx4 v[232:233], v[104:107], off
	v_lshl_add_u64 v[232:233], v[232:233], 0, s[98:99]
	v_mul_f32_e32 v88, v236, v88
	v_mul_f32_e32 v89, v236, v89
	v_mul_f32_e32 v90, v236, v90
	v_mul_f32_e32 v91, v236, v91
	v_mul_f32_e32 v92, v236, v92
	v_mul_f32_e32 v93, v236, v93
	v_mul_f32_e32 v94, v236, v94
	v_mfma_f32_16x16x32_bf16 v[52:55], v[184:187], v[192:195], v[52:55]
	v_mul_f32_e32 v95, v236, v95
	v_mul_f32_e32 v224, s100, v88
	v_mul_f32_e32 v225, s101, v89
	v_mul_f32_e32 v228, s100, v90
	v_mul_f32_e32 v229, s101, v91
	v_exp_f32_e32 v224, v224
	v_exp_f32_e32 v225, v225
	v_exp_f32_e32 v228, v228
	v_exp_f32_e32 v229, v229
	v_add_f32_e32 v224, 1.0, v224
	v_mfma_f32_16x16x32_bf16 v[44:47], v[176:179], v[200:203], v[44:47]
	v_add_f32_e32 v225, 1.0, v225
	v_add_f32_e32 v228, 1.0, v228
	v_add_f32_e32 v229, 1.0, v229
	v_rcp_f32_e32 v224, v224
	v_rcp_f32_e32 v225, v225
	v_rcp_f32_e32 v228, v228
	v_rcp_f32_e32 v229, v229
	v_nop
	v_mul_f32_e32 v88, v224, v88
	v_mul_f32_e32 v89, v225, v89
; __device__ __forceinline__ unsigned cvt_pk_bf16(float lo, float hi) { unsigned r; asm volatile("v_cvt_pk_bf16_f32 %0, %1, %2" : "=v"(r) : "v"(lo), "v"(hi)); return r; }
; __device__ __forceinline__ float siluf_(float x) { return x * sigmoidf_(x); }
; #define PG8_MMA(ai, bj, At, Bt) do { __builtin_amdgcn_s_setprio(1); _Pragma("unroll") for (int k = 0; k < 2; ++k) _Pragma("unroll") for (int m = 0; m < 4; ++m) _Pragma("unroll") for (int n = 0; n < 2; ++n) \
;         acc[ai][bj][m][n] = __builtin_amdgcn_mfma_f32_16x16x32_bf16(Bt[n][k], At[m][k], acc[ai][bj][m][n], 0, 0, 0); __builtin_amdgcn_s_setprio(0); } while (0)
;     __device__ __forceinline__ void operator()(const f32x4 (&acc)[2][2][4][2], const Unit& u, int wr, int wc, int fr, int fq) const {
;     ...
;         for (int ai = 0; ai < 2; ++ai)
; #pragma unroll
;             for (int m = 0; m < 4; ++m) { const int row = row0 + ai * HALF + m * 16; bf16_t* rowp = O + (size_t)row * ldc + col0; const float rs = rsv[ai][m];
;                 f32x4 v0, v1;
; #pragma unroll
;                 for (int j = 0; j < 4; ++j) { v0[j] = siluf_(acc[ai][0][m][0][j] * rs) * (acc[ai][1][m][0][j] * rs); v1[j] = siluf_(acc[ai][0][m][1][j] * rs) * (acc[ai][1][m][1][j] * rs); }
;                 u32x4 w; w.x = cvt_pk_bf16(v0[0], v0[1]); w.y = cvt_pk_bf16(v0[2], v0[3]); w.z = cvt_pk_bf16(v1[0], v1[1]); w.w = cvt_pk_bf16(v1[2], v1[3]);
;                 *(u32x4*)rowp = w; }
; template <class Epi, bool ALIGN_EPI>
; __device__ __forceinline__ void gemm_phase(LAS unsigned char* lds, const Gemm g, const StaticOrder& S, const Epi& E, const int tid) {
;     ...
;             PG8_WAIT_V(8); PG8_WAIT_L(0); PG8_BAR; PG8_MMA(1, 0, At, B0); PG8_MMA(1, 1, At, B1); PG8_BAR; PG8_SCHED;
;         }
;         if constexpr (ALIGN_EPI) { if (wr == 0) PG8_BAR; }
;         { int t2 = tid; asm volatile("" : "+v"(t2)); const int l2 = t2 & 63, w2 = __builtin_amdgcn_readfirstlane(t2 >> 6); E(acc, cur, w2 >> 2, w2 & 3, l2 & 15, l2 >> 4); }
;         if (!has_next) break;
; #pragma unroll
;         for (int a = 0; a < 2; ++a)
; #pragma unroll
;             for (int b = 0; b < 2; ++b)
; #pragma unroll
;                 for (int m = 0; m < 4; ++m)
; #pragma unroll
;                     for (int n = 0; n < 2; ++n) acc[a][b][m][n] = (f32x4){0.f, 0.f, 0.f, 0.f};
;         cur = nxt; cA = nA; cB = nB; ++ui;
;         if constexpr (ALIGN_EPI) { if (wr == 1) PG8_BAR; }
;     }
	v_mfma_f32_16x16x32_bf16 v[36:39], v[184:187], v[200:203], v[36:39]
	v_mul_f32_e32 v90, v228, v90
	v_mul_f32_e32 v91, v229, v91
	v_mul_f32_e32 v88, v92, v88
	v_mul_f32_e32 v89, v93, v89
	v_mul_f32_e32 v90, v94, v90
	v_mul_f32_e32 v91, v95, v91
	v_mul_f32_e32 v80, v236, v80
	v_mul_f32_e32 v81, v236, v81
	v_mul_f32_e32 v82, v236, v82
	v_mul_f32_e32 v83, v236, v83
	v_mfma_f32_16x16x32_bf16 v[28:31], v[176:179], v[208:211], v[28:31]
	v_mul_f32_e32 v84, v236, v84
	v_mul_f32_e32 v85, v236, v85
	v_mul_f32_e32 v86, v236, v86
	v_mul_f32_e32 v87, v236, v87
	v_mul_f32_e32 v224, s100, v80
	v_mul_f32_e32 v225, s101, v81
	v_mul_f32_e32 v228, s100, v82
	v_mul_f32_e32 v229, s101, v83
	v_exp_f32_e32 v224, v224
	v_exp_f32_e32 v225, v225
	v_mfma_f32_16x16x32_bf16 v[20:23], v[184:187], v[208:211], v[20:23]
	v_exp_f32_e32 v228, v228
	v_exp_f32_e32 v229, v229
	v_add_f32_e32 v224, 1.0, v224
	v_add_f32_e32 v225, 1.0, v225
	v_add_f32_e32 v228, 1.0, v228
	v_add_f32_e32 v229, 1.0, v229
	v_rcp_f32_e32 v224, v224
	v_rcp_f32_e32 v225, v225
	v_rcp_f32_e32 v228, v228
	v_rcp_f32_e32 v229, v229
	v_mfma_f32_16x16x32_bf16 v[12:15], v[176:179], v[216:219], v[12:15]
	v_nop
	v_mul_f32_e32 v80, v224, v80
	v_mul_f32_e32 v81, v225, v81
	v_mul_f32_e32 v82, v228, v82
	v_mul_f32_e32 v83, v229, v83
	v_mul_f32_e32 v80, v84, v80
	v_mul_f32_e32 v81, v85, v81
	v_mul_f32_e32 v82, v86, v82
	v_mul_f32_e32 v83, v87, v83
	v_cvt_pk_bf16_f32 v88, v88, v89
	v_mfma_f32_16x16x32_bf16 v[0:3], v[184:187], v[216:219], v[0:3]
	v_cvt_pk_bf16_f32 v89, v90, v91
	v_cvt_pk_bf16_f32 v90, v80, v81
	v_cvt_pk_bf16_f32 v91, v82, v83
	global_store_dwordx4 v[232:233], v[88:91], off
	v_lshl_add_u64 v[232:233], v[232:233], 0, s[98:99]
	v_mul_f32_e32 v72, v237, v72
	v_mul_f32_e32 v73, v237, v73
	v_mul_f32_e32 v74, v237, v74
	v_mul_f32_e32 v75, v237, v75
	v_mul_f32_e32 v76, v237, v76
	v_mfma_f32_16x16x32_bf16 v[60:63], v[180:183], v[196:199], v[60:63]
	v_mul_f32_e32 v77, v237, v77
	v_mul_f32_e32 v78, v237, v78
	v_mul_f32_e32 v79, v237, v79
	v_mul_f32_e32 v224, s100, v72
	v_mul_f32_e32 v225, s101, v73
	v_mul_f32_e32 v228, s100, v74
	v_mul_f32_e32 v229, s101, v75
	v_exp_f32_e32 v224, v224
	v_exp_f32_e32 v225, v225
	v_exp_f32_e32 v228, v228
	v_mfma_f32_16x16x32_bf16 v[52:55], v[188:191], v[196:199], v[52:55]
	v_exp_f32_e32 v229, v229
	v_add_f32_e32 v224, 1.0, v224
	v_add_f32_e32 v225, 1.0, v225
	v_add_f32_e32 v228, 1.0, v228
	v_add_f32_e32 v229, 1.0, v229
	v_rcp_f32_e32 v224, v224
	v_rcp_f32_e32 v225, v225
	v_rcp_f32_e32 v228, v228
	v_rcp_f32_e32 v229, v229
	v_nop
	v_mfma_f32_16x16x32_bf16 v[44:47], v[180:183], v[204:207], v[44:47]
	v_mul_f32_e32 v72, v224, v72
	v_mul_f32_e32 v73, v225, v73
	v_mul_f32_e32 v74, v228, v74
	v_mul_f32_e32 v75, v229, v75
	v_mul_f32_e32 v72, v76, v72
	v_mul_f32_e32 v73, v77, v73
	v_mul_f32_e32 v74, v78, v74
	v_mul_f32_e32 v75, v79, v75
	v_mul_f32_e32 v64, v237, v64
	v_mul_f32_e32 v65, v237, v65
	v_mfma_f32_16x16x32_bf16 v[36:39], v[188:191], v[204:207], v[36:39]
	v_mul_f32_e32 v66, v237, v66
	v_mul_f32_e32 v67, v237, v67
	v_mul_f32_e32 v68, v237, v68
	v_mul_f32_e32 v69, v237, v69
	v_mul_f32_e32 v70, v237, v70
	v_mul_f32_e32 v71, v237, v71
	v_mul_f32_e32 v224, s100, v64
	v_mul_f32_e32 v225, s101, v65
	v_mul_f32_e32 v228, s100, v66
	v_mul_f32_e32 v229, s101, v67
	v_mfma_f32_16x16x32_bf16 v[28:31], v[180:183], v[212:215], v[28:31]
	v_exp_f32_e32 v224, v224
	v_exp_f32_e32 v225, v225
	v_exp_f32_e32 v228, v228
	v_exp_f32_e32 v229, v229
	v_add_f32_e32 v224, 1.0, v224
	v_add_f32_e32 v225, 1.0, v225
	v_add_f32_e32 v228, 1.0, v228
	v_add_f32_e32 v229, 1.0, v229
	v_rcp_f32_e32 v224, v224
	v_rcp_f32_e32 v225, v225
	v_mfma_f32_16x16x32_bf16 v[20:23], v[188:191], v[212:215], v[20:23]
	v_rcp_f32_e32 v228, v228
	v_rcp_f32_e32 v229, v229
	v_nop
	v_mul_f32_e32 v64, v224, v64
	v_mul_f32_e32 v65, v225, v65
	v_mul_f32_e32 v66, v228, v66
	v_mul_f32_e32 v67, v229, v67
	v_mul_f32_e32 v64, v68, v64
	v_mul_f32_e32 v65, v69, v65
	v_mul_f32_e32 v66, v70, v66
	v_mfma_f32_16x16x32_bf16 v[12:15], v[180:183], v[240:243], v[12:15]
	v_mul_f32_e32 v67, v71, v67
	v_cvt_pk_bf16_f32 v72, v72, v73
	v_cvt_pk_bf16_f32 v73, v74, v75
	v_cvt_pk_bf16_f32 v74, v64, v65
	v_cvt_pk_bf16_f32 v75, v66, v67
	global_store_dwordx4 v[232:233], v[72:75], off
	v_lshl_add_u64 v[232:233], v[232:233], 0, s[98:99]
	v_lshl_add_u64 v[232:233], v[232:233], 0, s[98:99]
	v_lshl_add_u64 v[232:233], v[232:233], 0, s[98:99]
	v_lshl_add_u64 v[232:233], v[232:233], 0, s[98:99]
	v_mfma_f32_16x16x32_bf16 v[0:3], v[188:191], v[240:243], v[0:3]
	v_lshl_add_u64 v[232:233], v[232:233], 0, s[98:99]
	s_setprio 0
	s_barrier
	v_lshl_add_u64 v[142:143], v[142:143], 0, s[80:81]
	v_lshl_add_u64 v[144:145], v[144:145], 0, s[80:81]
	s_and_b64 vcc, exec, s[8:9]
	s_cbranch_vccnz .Lgu_notdefer
	s_cmp_lg_u32 s62, s64
	s_cbranch_scc1 .Lgu_notdefer
	s_mov_b32 s101, 1
	s_mov_b32 s63, s61
	s_mov_b32 s64, s62
	v_mov_b64_e32 v[144:145], v[140:141]
	v_mov_b64_e32 v[142:143], v[138:139]
	s_branch .LBB0_300

; #define PG8_STAGE(bufoff, gbase, voff) do { _Pragma("unroll") for (int _i = 0; _i < 2; ++_i) \
;         __builtin_amdgcn_global_load_lds((const unsigned*)((const char*)(gbase) + (voff)[_i]), (LAS unsigned*)(lds + (bufoff) + ldsw + _i * 8192), 16, 0, 0); } while (0)
; #define PG8_LDA(dst, b, h) do { _Pragma("unroll") for (int m = 0; m < 4; ++m) _Pragma("unroll") for (int k = 0; k < 2; ++k) dst[m][k] = *(const LAS bf16x8*)(lds + PG8_SA(b, h) + aoff + m * 2048 + k * 1024); } while (0)
; #define PG8_LDB(dst, b, h) do { _Pragma("unroll") for (int n = 0; n < 2; ++n) _Pragma("unroll") for (int k = 0; k < 2; ++k) dst[n][k] = *(const LAS bf16x8*)(lds + PG8_SB(b, h) + boff + n * 2048 + k * 1024); } while (0)
; #define PG8_MMA(ai, bj, At, Bt) do { __builtin_amdgcn_s_setprio(1); _Pragma("unroll") for (int k = 0; k < 2; ++k) _Pragma("unroll") for (int m = 0; m < 4; ++m) _Pragma("unroll") for (int n = 0; n < 2; ++n) \
;         acc[ai][bj][m][n] = __builtin_amdgcn_mfma_f32_16x16x32_bf16(Bt[n][k], At[m][k], acc[ai][bj][m][n], 0, 0, 0); __builtin_amdgcn_s_setprio(0); } while (0)
; #define PG8_WAIT_V(n) asm volatile("s_waitcnt vmcnt(" #n ")" ::: "memory")
; #define PG8_WAIT_L(n) asm volatile("s_waitcnt lgkmcnt(" #n ")" ::: "memory")
; #define PG8_BAR __builtin_amdgcn_s_barrier()
; #define PG8_SCHED __builtin_amdgcn_sched_barrier(0)
; template <class Epi, bool ALIGN_EPI>
; __device__ __forceinline__ void gemm_phase(LAS unsigned char* lds, const Gemm g, const StaticOrder& S, const Epi& E, const int tid) {
;     ...
;         for (int t = 0; t < nt; t += 2) {
;             const bool last = (t == nt - 2);
;             const char* a1 = cA + (size_t)(t + 1) * kstep;
;             const char* a2 = last ? nA : cA + (size_t)(t + 2) * kstep; const char* b2 = last ? nB : cB + (size_t)(t + 2) * kstep;
;             const char* a3 = a2 + kstep; const char* b3 = b2 + kstep;
;             PG8_LDB(B0, 0, 0); PG8_LDB(B1, 0, 1); PG8_SCHED; PG8_LDA(At, 0, 0); PG8_STAGE(PG8_SA(1, 1), a1 + hA, voffA);
;             PG8_WAIT_V(8); PG8_WAIT_L(0); PG8_BAR; PG8_MMA(0, 0, At, B0); PG8_MMA(0, 1, At, B1); PG8_BAR; PG8_SCHED;
;             PG8_LDA(At, 0, 1); PG8_STAGE(PG8_SB(0, 0), b2, voffB); PG8_STAGE(PG8_SB(0, 1), b2 + hB, voffB); PG8_STAGE(PG8_SA(0, 0), a2, voffA);
;             PG8_WAIT_V(8); PG8_WAIT_L(0); PG8_BAR; PG8_MMA(1, 0, At, B0); PG8_MMA(1, 1, At, B1); PG8_BAR; PG8_SCHED;
.LBB0_329:
	s_andn2_b64 vcc, exec, s[36:37]
	s_cbranch_vccnz .LBB0_332
	v_lshl_add_u64 v[142:143], v[142:143], 0, s[92:93]
	v_lshl_add_u64 v[144:145], v[144:145], 0, s[80:81]
	s_mov_b32 s10, 0
	s_add_i32 s11, s10, 2
	s_cmp_eq_u32 s58, s10
	v_lshl_add_u64 v[146:147], v[142:143], 0, s[92:93]
	s_cselect_b64 vcc, -1, 0
	v_add_u32_e32 v152, s33, v153
	s_add_i32 s10, 0, 0x14000
	v_cndmask_b32_e32 v151, v147, v139, vcc
	v_cndmask_b32_e32 v150, v146, v138, vcc
	ds_read_b128 v[146:149], v152
	ds_read_b128 v[156:159], v152 offset:1024
	ds_read_b128 v[160:163], v152 offset:2048
	ds_read_b128 v[164:167], v152 offset:3072
	v_add_u32_e32 v152, s10, v153
	ds_read_b128 v[176:179], v152
	ds_read_b128 v[180:183], v152 offset:1024
	ds_read_b128 v[184:187], v152 offset:2048
	ds_read_b128 v[188:191], v152 offset:3072
	v_cndmask_b32_e32 v221, v145, v141, vcc
	v_cndmask_b32_e32 v220, v144, v140, vcc
	v_lshl_add_u64 v[226:227], v[142:143], 0, v[134:135]
	s_add_i32 m0, s51, 0xc000
	ds_read_b128 v[192:195], v155
	ds_read_b128 v[196:199], v155 offset:1024
	ds_read_b128 v[200:203], v155 offset:2048
	ds_read_b128 v[204:207], v155 offset:3072
	ds_read_b128 v[208:211], v155 offset:4096
	ds_read_b128 v[212:215], v155 offset:5120
	ds_read_b128 v[216:219], v155 offset:6144
	ds_read_b128 v[240:243], v155 offset:7168
	global_load_lds_dwordx4 v[226:227], off
	v_lshl_add_u64 v[226:227], v[142:143], 0, v[136:137]
	s_add_i32 m0, s51, 0xe000
	s_nop 0
	global_load_lds_dwordx4 v[226:227], off
	s_waitcnt vmcnt(8)
	s_waitcnt lgkmcnt(0)
	s_setprio 1
	s_barrier
	s_waitcnt lgkmcnt(0)
	v_mfma_f32_16x16x32_bf16 v[120:123], v[146:149], v[192:195], 0
	v_mfma_f32_16x16x32_bf16 v[124:127], v[160:163], v[192:195], 0
	v_mfma_f32_16x16x32_bf16 v[108:111], v[146:149], v[200:203], 0
	v_mfma_f32_16x16x32_bf16 v[104:107], v[160:163], v[200:203], 0
	v_mfma_f32_16x16x32_bf16 v[92:95], v[146:149], v[208:211], 0
	v_mfma_f32_16x16x32_bf16 v[88:91], v[160:163], v[208:211], 0
	v_mfma_f32_16x16x32_bf16 v[76:79], v[146:149], v[216:219], 0
	v_mfma_f32_16x16x32_bf16 v[72:75], v[160:163], v[216:219], 0
	v_mfma_f32_16x16x32_bf16 v[120:123], v[156:159], v[196:199], v[120:123]
	v_mfma_f32_16x16x32_bf16 v[124:127], v[164:167], v[196:199], v[124:127]
	v_mfma_f32_16x16x32_bf16 v[108:111], v[156:159], v[204:207], v[108:111]
	v_mfma_f32_16x16x32_bf16 v[104:107], v[164:167], v[204:207], v[104:107]
	v_mfma_f32_16x16x32_bf16 v[92:95], v[156:159], v[212:215], v[92:95]
	v_mfma_f32_16x16x32_bf16 v[88:91], v[164:167], v[212:215], v[88:91]
	v_mfma_f32_16x16x32_bf16 v[76:79], v[156:159], v[240:243], v[76:79]
	v_mfma_f32_16x16x32_bf16 v[72:75], v[164:167], v[240:243], v[72:75]
	s_setprio 0
	s_setprio 1
	v_mfma_f32_16x16x32_bf16 v[116:119], v[176:179], v[192:195], 0
	v_mfma_f32_16x16x32_bf16 v[112:115], v[184:187], v[192:195], 0
	v_mfma_f32_16x16x32_bf16 v[100:103], v[176:179], v[200:203], 0
	v_mfma_f32_16x16x32_bf16 v[96:99], v[184:187], v[200:203], 0
	v_mfma_f32_16x16x32_bf16 v[84:87], v[176:179], v[208:211], 0
	v_mfma_f32_16x16x32_bf16 v[80:83], v[184:187], v[208:211], 0
	v_mfma_f32_16x16x32_bf16 v[68:71], v[176:179], v[216:219], 0
	v_mfma_f32_16x16x32_bf16 v[64:67], v[184:187], v[216:219], 0
	v_mfma_f32_16x16x32_bf16 v[116:119], v[180:183], v[196:199], v[116:119]
	v_mfma_f32_16x16x32_bf16 v[112:115], v[188:191], v[196:199], v[112:115]
	v_mfma_f32_16x16x32_bf16 v[100:103], v[180:183], v[204:207], v[100:103]
	v_mfma_f32_16x16x32_bf16 v[96:99], v[188:191], v[204:207], v[96:99]
	v_mfma_f32_16x16x32_bf16 v[84:87], v[180:183], v[212:215], v[84:87]
	v_mfma_f32_16x16x32_bf16 v[80:83], v[188:191], v[212:215], v[80:83]
	v_mfma_f32_16x16x32_bf16 v[68:71], v[180:183], v[240:243], v[68:71]
	v_mfma_f32_16x16x32_bf16 v[64:67], v[188:191], v[240:243], v[64:67]
	s_setprio 0
	s_barrier
	s_add_i32 s65, s33, s45
	v_lshl_add_u64 v[226:227], v[220:221], 0, v[168:169]
	s_mov_b32 m0, s65
	ds_read_b128 v[192:195], v155 offset:16384
	ds_read_b128 v[196:199], v155 offset:17408
	ds_read_b128 v[200:203], v155 offset:18432
	ds_read_b128 v[204:207], v155 offset:19456
	ds_read_b128 v[208:211], v155 offset:20480
	ds_read_b128 v[212:215], v155 offset:21504
	ds_read_b128 v[216:219], v155 offset:22528
	ds_read_b128 v[240:243], v155 offset:23552
	global_load_lds_dwordx4 v[226:227], off
	v_lshl_add_u64 v[244:245], v[220:221], 0, v[128:129]
	s_add_i32 m0, s65, 0x2000
	v_lshl_add_u64 v[220:221], v[220:221], 0, s[12:13]
	s_add_i32 s10, s10, s45
	global_load_lds_dwordx4 v[244:245], off
	v_lshl_add_u64 v[246:247], v[220:221], 0, v[168:169]
	s_mov_b32 m0, s10
	v_lshl_add_u64 v[220:221], v[220:221], 0, v[128:129]
	global_load_lds_dwordx4 v[246:247], off
	s_add_i32 m0, s10, 0x2000
	v_lshl_add_u64 v[248:249], v[150:151], 0, v[132:133]
	global_load_lds_dwordx4 v[220:221], off
	s_mov_b32 m0, s51
	v_lshl_add_u64 v[250:251], v[150:151], 0, v[130:131]
	global_load_lds_dwordx4 v[248:249], off
	s_mov_b32 m0, s52
	s_nop 0
	global_load_lds_dwordx4 v[250:251], off
	s_waitcnt vmcnt(8)
	s_waitcnt lgkmcnt(0)
	s_setprio 1
	s_barrier
; #define PG8_STAGE(bufoff, gbase, voff) do { _Pragma("unroll") for (int _i = 0; _i < 2; ++_i) \
;         __builtin_amdgcn_global_load_lds((const unsigned*)((const char*)(gbase) + (voff)[_i]), (LAS unsigned*)(lds + (bufoff) + ldsw + _i * 8192), 16, 0, 0); } while (0)
; #define PG8_LDA(dst, b, h) do { _Pragma("unroll") for (int m = 0; m < 4; ++m) _Pragma("unroll") for (int k = 0; k < 2; ++k) dst[m][k] = *(const LAS bf16x8*)(lds + PG8_SA(b, h) + aoff + m * 2048 + k * 1024); } while (0)
; #define PG8_LDB(dst, b, h) do { _Pragma("unroll") for (int n = 0; n < 2; ++n) _Pragma("unroll") for (int k = 0; k < 2; ++k) dst[n][k] = *(const LAS bf16x8*)(lds + PG8_SB(b, h) + boff + n * 2048 + k * 1024); } while (0)
; #define PG8_MMA(ai, bj, At, Bt) do { __builtin_amdgcn_s_setprio(1); _Pragma("unroll") for (int k = 0; k < 2; ++k) _Pragma("unroll") for (int m = 0; m < 4; ++m) _Pragma("unroll") for (int n = 0; n < 2; ++n) \
;         acc[ai][bj][m][n] = __builtin_amdgcn_mfma_f32_16x16x32_bf16(Bt[n][k], At[m][k], acc[ai][bj][m][n], 0, 0, 0); __builtin_amdgcn_s_setprio(0); } while (0)
; #define PG8_WAIT_V(n) asm volatile("s_waitcnt vmcnt(" #n ")" ::: "memory")
; #define PG8_WAIT_L(n) asm volatile("s_waitcnt lgkmcnt(" #n ")" ::: "memory")
; #define PG8_BAR __builtin_amdgcn_s_barrier()
; #define PG8_SCHED __builtin_amdgcn_sched_barrier(0)
; template <class Epi, bool ALIGN_EPI>
; __device__ __forceinline__ void gemm_phase(LAS unsigned char* lds, const Gemm g, const StaticOrder& S, const Epi& E, const int tid) {
;     ...
;             PG8_WAIT_V(8); PG8_WAIT_L(0); PG8_BAR; PG8_MMA(1, 0, At, B0); PG8_MMA(1, 1, At, B1); PG8_BAR; PG8_SCHED;
;             PG8_LDB(B0, 1, 0); PG8_LDB(B1, 1, 1); PG8_SCHED; PG8_LDA(At, 1, 0); PG8_STAGE(PG8_SA(0, 1), a2 + hA, voffA);
;             PG8_WAIT_V(8); PG8_WAIT_L(0); PG8_BAR; PG8_MMA(0, 0, At, B0); PG8_MMA(0, 1, At, B1); PG8_BAR; PG8_SCHED;
	s_waitcnt lgkmcnt(0)
	v_mfma_f32_16x16x32_bf16 v[60:63], v[146:149], v[192:195], 0
	v_mfma_f32_16x16x32_bf16 v[56:59], v[160:163], v[192:195], 0
	v_mfma_f32_16x16x32_bf16 v[44:47], v[146:149], v[200:203], 0
	v_mfma_f32_16x16x32_bf16 v[40:43], v[160:163], v[200:203], 0
	v_mfma_f32_16x16x32_bf16 v[28:31], v[146:149], v[208:211], 0
	v_mfma_f32_16x16x32_bf16 v[24:27], v[160:163], v[208:211], 0
	v_mfma_f32_16x16x32_bf16 v[12:15], v[146:149], v[216:219], 0
	v_mfma_f32_16x16x32_bf16 v[8:11], v[160:163], v[216:219], 0
	v_mfma_f32_16x16x32_bf16 v[60:63], v[156:159], v[196:199], v[60:63]
	v_mfma_f32_16x16x32_bf16 v[56:59], v[164:167], v[196:199], v[56:59]
	v_mfma_f32_16x16x32_bf16 v[44:47], v[156:159], v[204:207], v[44:47]
	v_mfma_f32_16x16x32_bf16 v[40:43], v[164:167], v[204:207], v[40:43]
	v_mfma_f32_16x16x32_bf16 v[28:31], v[156:159], v[212:215], v[28:31]
	v_mfma_f32_16x16x32_bf16 v[24:27], v[164:167], v[212:215], v[24:27]
	v_mfma_f32_16x16x32_bf16 v[12:15], v[156:159], v[240:243], v[12:15]
	v_mfma_f32_16x16x32_bf16 v[8:11], v[164:167], v[240:243], v[8:11]
	s_setprio 0
	s_setprio 1
	v_mfma_f32_16x16x32_bf16 v[52:55], v[176:179], v[192:195], 0
	v_mfma_f32_16x16x32_bf16 v[48:51], v[184:187], v[192:195], 0
	v_mfma_f32_16x16x32_bf16 v[36:39], v[176:179], v[200:203], 0
	v_mfma_f32_16x16x32_bf16 v[32:35], v[184:187], v[200:203], 0
	v_mfma_f32_16x16x32_bf16 v[20:23], v[176:179], v[208:211], 0
	v_mfma_f32_16x16x32_bf16 v[16:19], v[184:187], v[208:211], 0
	v_mfma_f32_16x16x32_bf16 v[4:7], v[176:179], v[216:219], 0
	v_mfma_f32_16x16x32_bf16 v[0:3], v[184:187], v[216:219], 0
	v_mfma_f32_16x16x32_bf16 v[52:55], v[180:183], v[196:199], v[52:55]
	v_mfma_f32_16x16x32_bf16 v[48:51], v[188:191], v[196:199], v[48:51]
	v_mfma_f32_16x16x32_bf16 v[36:39], v[180:183], v[204:207], v[36:39]
	v_mfma_f32_16x16x32_bf16 v[32:35], v[188:191], v[204:207], v[32:35]
	v_mfma_f32_16x16x32_bf16 v[20:23], v[180:183], v[212:215], v[20:23]
	v_mfma_f32_16x16x32_bf16 v[16:19], v[188:191], v[212:215], v[16:19]
	v_mfma_f32_16x16x32_bf16 v[4:7], v[180:183], v[240:243], v[4:7]
	v_mfma_f32_16x16x32_bf16 v[0:3], v[188:191], v[240:243], v[0:3]
	s_setprio 0
	s_barrier
	s_add_i32 s10, 0, 0x18000
	v_add_u32_e32 v152, s10, v153
	s_add_i32 s65, 0, 0x1c000
	ds_read_b128 v[146:149], v152
	ds_read_b128 v[156:159], v152 offset:1024
	ds_read_b128 v[160:163], v152 offset:2048
	ds_read_b128 v[164:167], v152 offset:3072
	v_add_u32_e32 v152, s65, v153
	ds_read_b128 v[176:179], v152
	ds_read_b128 v[180:183], v152 offset:1024
	ds_read_b128 v[184:187], v152 offset:2048
	ds_read_b128 v[188:191], v152 offset:3072
	v_lshl_add_u64 v[150:151], v[150:151], 0, s[94:95]
	s_mov_b32 m0, s53
	v_lshl_add_u64 v[252:253], v[150:151], 0, v[132:133]
	ds_read_b128 v[192:195], v155 offset:32768
	ds_read_b128 v[196:199], v155 offset:33792
	ds_read_b128 v[200:203], v155 offset:34816
	ds_read_b128 v[204:207], v155 offset:35840
	ds_read_b128 v[208:211], v155 offset:36864
	ds_read_b128 v[212:215], v155 offset:37888
	ds_read_b128 v[216:219], v155 offset:38912
	ds_read_b128 v[240:243], v155 offset:39936
	global_load_lds_dwordx4 v[252:253], off
	v_lshl_add_u64 v[150:151], v[150:151], 0, v[130:131]
	s_mov_b32 m0, s54
	s_nop 0
	global_load_lds_dwordx4 v[150:151], off
	s_waitcnt vmcnt(8)
	s_waitcnt lgkmcnt(0)
	s_setprio 1
	s_barrier
	s_waitcnt lgkmcnt(0)
	v_mfma_f32_16x16x32_bf16 v[120:123], v[146:149], v[192:195], v[120:123]
	v_mfma_f32_16x16x32_bf16 v[124:127], v[160:163], v[192:195], v[124:127]
	v_mfma_f32_16x16x32_bf16 v[108:111], v[146:149], v[200:203], v[108:111]
	v_mfma_f32_16x16x32_bf16 v[104:107], v[160:163], v[200:203], v[104:107]
	v_mfma_f32_16x16x32_bf16 v[92:95], v[146:149], v[208:211], v[92:95]
	v_mfma_f32_16x16x32_bf16 v[88:91], v[160:163], v[208:211], v[88:91]
	v_mfma_f32_16x16x32_bf16 v[76:79], v[146:149], v[216:219], v[76:79]
	v_mfma_f32_16x16x32_bf16 v[72:75], v[160:163], v[216:219], v[72:75]
	v_mfma_f32_16x16x32_bf16 v[120:123], v[156:159], v[196:199], v[120:123]
	v_mfma_f32_16x16x32_bf16 v[124:127], v[164:167], v[196:199], v[124:127]
	v_mfma_f32_16x16x32_bf16 v[108:111], v[156:159], v[204:207], v[108:111]
	v_mfma_f32_16x16x32_bf16 v[104:107], v[164:167], v[204:207], v[104:107]
	v_mfma_f32_16x16x32_bf16 v[92:95], v[156:159], v[212:215], v[92:95]
	v_mfma_f32_16x16x32_bf16 v[88:91], v[164:167], v[212:215], v[88:91]
	v_mfma_f32_16x16x32_bf16 v[76:79], v[156:159], v[240:243], v[76:79]
	v_mfma_f32_16x16x32_bf16 v[72:75], v[164:167], v[240:243], v[72:75]
	s_setprio 0
	s_setprio 1
	v_mfma_f32_16x16x32_bf16 v[116:119], v[176:179], v[192:195], v[116:119]
	v_mfma_f32_16x16x32_bf16 v[112:115], v[184:187], v[192:195], v[112:115]
	v_mfma_f32_16x16x32_bf16 v[100:103], v[176:179], v[200:203], v[100:103]
	v_mfma_f32_16x16x32_bf16 v[96:99], v[184:187], v[200:203], v[96:99]
	v_mfma_f32_16x16x32_bf16 v[84:87], v[176:179], v[208:211], v[84:87]
	v_mfma_f32_16x16x32_bf16 v[80:83], v[184:187], v[208:211], v[80:83]
	v_mfma_f32_16x16x32_bf16 v[68:71], v[176:179], v[216:219], v[68:71]
	v_mfma_f32_16x16x32_bf16 v[64:67], v[184:187], v[216:219], v[64:67]
	v_mfma_f32_16x16x32_bf16 v[116:119], v[180:183], v[196:199], v[116:119]
	v_mfma_f32_16x16x32_bf16 v[112:115], v[188:191], v[196:199], v[112:115]
	v_mfma_f32_16x16x32_bf16 v[100:103], v[180:183], v[204:207], v[100:103]
	v_mfma_f32_16x16x32_bf16 v[96:99], v[188:191], v[204:207], v[96:99]
	v_mfma_f32_16x16x32_bf16 v[84:87], v[180:183], v[212:215], v[84:87]
	v_mfma_f32_16x16x32_bf16 v[80:83], v[188:191], v[212:215], v[80:83]
	v_mfma_f32_16x16x32_bf16 v[68:71], v[180:183], v[240:243], v[68:71]
	v_mfma_f32_16x16x32_bf16 v[64:67], v[188:191], v[240:243], v[64:67]
	s_setprio 0
	s_barrier
; #define PG8_STAGE(bufoff, gbase, voff) do { _Pragma("unroll") for (int _i = 0; _i < 2; ++_i) \
;         __builtin_amdgcn_global_load_lds((const unsigned*)((const char*)(gbase) + (voff)[_i]), (LAS unsigned*)(lds + (bufoff) + ldsw + _i * 8192), 16, 0, 0); } while (0)
; #define PG8_LDA(dst, b, h) do { _Pragma("unroll") for (int m = 0; m < 4; ++m) _Pragma("unroll") for (int k = 0; k < 2; ++k) dst[m][k] = *(const LAS bf16x8*)(lds + PG8_SA(b, h) + aoff + m * 2048 + k * 1024); } while (0)
; #define PG8_LDB(dst, b, h) do { _Pragma("unroll") for (int n = 0; n < 2; ++n) _Pragma("unroll") for (int k = 0; k < 2; ++k) dst[n][k] = *(const LAS bf16x8*)(lds + PG8_SB(b, h) + boff + n * 2048 + k * 1024); } while (0)
; #define PG8_MMA(ai, bj, At, Bt) do { __builtin_amdgcn_s_setprio(1); _Pragma("unroll") for (int k = 0; k < 2; ++k) _Pragma("unroll") for (int m = 0; m < 4; ++m) _Pragma("unroll") for (int n = 0; n < 2; ++n) \
;         acc[ai][bj][m][n] = __builtin_amdgcn_mfma_f32_16x16x32_bf16(Bt[n][k], At[m][k], acc[ai][bj][m][n], 0, 0, 0); __builtin_amdgcn_s_setprio(0); } while (0)
; #define PG8_WAIT_V(n) asm volatile("s_waitcnt vmcnt(" #n ")" ::: "memory")
; #define PG8_BAR __builtin_amdgcn_s_barrier()
; template <class Epi, bool ALIGN_EPI>
; __device__ __forceinline__ void gemm_phase(LAS unsigned char* lds, const Gemm g, const StaticOrder& S, const Epi& E, const int tid) {
;     ...
;             PG8_LDB(B0, 0, 0); PG8_LDB(B1, 0, 1); PG8_SCHED; PG8_LDA(At, 0, 0); PG8_STAGE(PG8_SA(1, 1), a1 + hA, voffA);
;             PG8_WAIT_V(8); PG8_WAIT_L(0); PG8_BAR; PG8_MMA(0, 0, At, B0); PG8_MMA(0, 1, At, B1); PG8_BAR; PG8_SCHED;
;             PG8_LDA(At, 0, 1); PG8_STAGE(PG8_SB(0, 0), b2, voffB); PG8_STAGE(PG8_SB(0, 1), b2 + hB, voffB); PG8_STAGE(PG8_SA(0, 0), a2, voffA);
;             PG8_WAIT_V(8); PG8_WAIT_L(0); PG8_BAR; PG8_MMA(1, 0, At, B0); PG8_MMA(1, 1, At, B1); PG8_BAR; PG8_SCHED;
;             PG8_LDB(B0, 1, 0); PG8_LDB(B1, 1, 1); PG8_SCHED; PG8_LDA(At, 1, 0); PG8_STAGE(PG8_SA(0, 1), a2 + hA, voffA);
;             PG8_WAIT_V(8); PG8_WAIT_L(0); PG8_BAR; PG8_MMA(0, 0, At, B0); PG8_MMA(0, 1, At, B1); PG8_BAR; PG8_SCHED;
;             PG8_LDA(At, 1, 1); PG8_STAGE(PG8_SB(1, 0), b3, voffB); PG8_STAGE(PG8_SB(1, 1), b3 + hB, voffB); PG8_STAGE(PG8_SA(1, 0), a3, voffA);
;             PG8_WAIT_V(8); PG8_WAIT_L(0); PG8_BAR; PG8_MMA(1, 0, At, B0); PG8_MMA(1, 1, At, B1); PG8_BAR; PG8_SCHED;
	s_add_i32 s10, s10, s45
	v_lshl_add_u64 v[150:151], v[226:227], 0, s[92:93]
	s_mov_b32 m0, s10
	ds_read_b128 v[192:195], v155 offset:49152
	ds_read_b128 v[196:199], v155 offset:50176
	ds_read_b128 v[200:203], v155 offset:51200
	ds_read_b128 v[204:207], v155 offset:52224
	ds_read_b128 v[208:211], v155 offset:53248
	ds_read_b128 v[212:215], v155 offset:54272
	ds_read_b128 v[216:219], v155 offset:55296
	ds_read_b128 v[240:243], v155 offset:56320
	global_load_lds_dwordx4 v[150:151], off
	v_lshl_add_u64 v[150:151], v[244:245], 0, s[92:93]
	s_add_i32 m0, s10, 0x2000
	s_add_i32 s10, s65, s45
	global_load_lds_dwordx4 v[150:151], off
	v_lshl_add_u64 v[150:151], v[246:247], 0, s[92:93]
	s_mov_b32 m0, s10
	s_nop 0
	global_load_lds_dwordx4 v[150:151], off
	v_lshl_add_u64 v[150:151], v[220:221], 0, s[92:93]
	s_add_i32 m0, s10, 0x2000
	s_nop 0
	global_load_lds_dwordx4 v[150:151], off
	v_lshl_add_u64 v[150:151], v[248:249], 0, s[92:93]
	s_mov_b32 m0, s56
	s_nop 0
	global_load_lds_dwordx4 v[150:151], off
	v_lshl_add_u64 v[150:151], v[250:251], 0, s[92:93]
	s_mov_b32 m0, s57
	s_nop 0
	global_load_lds_dwordx4 v[150:151], off
	s_waitcnt vmcnt(8)
	s_waitcnt lgkmcnt(0)
	s_setprio 1
	s_barrier
	s_waitcnt lgkmcnt(0)
	v_mfma_f32_16x16x32_bf16 v[60:63], v[146:149], v[192:195], v[60:63]
	v_mfma_f32_16x16x32_bf16 v[56:59], v[160:163], v[192:195], v[56:59]
	v_mfma_f32_16x16x32_bf16 v[44:47], v[146:149], v[200:203], v[44:47]
	v_mfma_f32_16x16x32_bf16 v[40:43], v[160:163], v[200:203], v[40:43]
	v_mfma_f32_16x16x32_bf16 v[28:31], v[146:149], v[208:211], v[28:31]
	v_mfma_f32_16x16x32_bf16 v[24:27], v[160:163], v[208:211], v[24:27]
	v_mfma_f32_16x16x32_bf16 v[12:15], v[146:149], v[216:219], v[12:15]
	v_mfma_f32_16x16x32_bf16 v[8:11], v[160:163], v[216:219], v[8:11]
	v_mfma_f32_16x16x32_bf16 v[60:63], v[156:159], v[196:199], v[60:63]
	v_mfma_f32_16x16x32_bf16 v[56:59], v[164:167], v[196:199], v[56:59]
	v_mfma_f32_16x16x32_bf16 v[44:47], v[156:159], v[204:207], v[44:47]
	v_mfma_f32_16x16x32_bf16 v[40:43], v[164:167], v[204:207], v[40:43]
	v_mfma_f32_16x16x32_bf16 v[28:31], v[156:159], v[212:215], v[28:31]
	v_mfma_f32_16x16x32_bf16 v[24:27], v[164:167], v[212:215], v[24:27]
	v_mfma_f32_16x16x32_bf16 v[12:15], v[156:159], v[240:243], v[12:15]
	v_mfma_f32_16x16x32_bf16 v[8:11], v[164:167], v[240:243], v[8:11]
	s_setprio 0
	s_setprio 1
	v_mfma_f32_16x16x32_bf16 v[52:55], v[176:179], v[192:195], v[52:55]
	v_mfma_f32_16x16x32_bf16 v[48:51], v[184:187], v[192:195], v[48:51]
	v_mfma_f32_16x16x32_bf16 v[36:39], v[176:179], v[200:203], v[36:39]
	v_mfma_f32_16x16x32_bf16 v[32:35], v[184:187], v[200:203], v[32:35]
	v_mfma_f32_16x16x32_bf16 v[20:23], v[176:179], v[208:211], v[20:23]
	v_mfma_f32_16x16x32_bf16 v[16:19], v[184:187], v[208:211], v[16:19]
	v_mfma_f32_16x16x32_bf16 v[4:7], v[176:179], v[216:219], v[4:7]
	v_mfma_f32_16x16x32_bf16 v[0:3], v[184:187], v[216:219], v[0:3]
	v_mfma_f32_16x16x32_bf16 v[52:55], v[180:183], v[196:199], v[52:55]
	v_mfma_f32_16x16x32_bf16 v[48:51], v[188:191], v[196:199], v[48:51]
	v_mfma_f32_16x16x32_bf16 v[36:39], v[180:183], v[204:207], v[36:39]
	v_mfma_f32_16x16x32_bf16 v[32:35], v[188:191], v[204:207], v[32:35]
	v_mfma_f32_16x16x32_bf16 v[20:23], v[180:183], v[212:215], v[20:23]
	v_mfma_f32_16x16x32_bf16 v[16:19], v[188:191], v[212:215], v[16:19]
	v_mfma_f32_16x16x32_bf16 v[4:7], v[180:183], v[240:243], v[4:7]
	v_mfma_f32_16x16x32_bf16 v[0:3], v[188:191], v[240:243], v[0:3]
	s_setprio 0
	s_barrier
	v_lshl_add_u64 v[142:143], v[142:143], 0, s[80:81]
	v_lshl_add_u64 v[144:145], v[144:145], 0, s[80:81]
	s_cmp_ge_u32 s11, s55
	s_mov_b32 s10, s11
	s_cbranch_scc1 .Lpl4_after
.LBB0_331:
	s_add_i32 s11, s10, 2
	s_cmp_eq_u32 s58, s10
	v_lshl_add_u64 v[146:147], v[142:143], 0, s[92:93]
	s_cselect_b64 vcc, -1, 0
	v_add_u32_e32 v152, s33, v153
	s_add_i32 s10, 0, 0x14000
	v_cndmask_b32_e32 v151, v147, v139, vcc
	v_cndmask_b32_e32 v150, v146, v138, vcc
	ds_read_b128 v[146:149], v152
	ds_read_b128 v[156:159], v152 offset:1024
	ds_read_b128 v[160:163], v152 offset:2048
	ds_read_b128 v[164:167], v152 offset:3072
	v_add_u32_e32 v152, s10, v153
	ds_read_b128 v[176:179], v152
	ds_read_b128 v[180:183], v152 offset:1024
	ds_read_b128 v[184:187], v152 offset:2048
	ds_read_b128 v[188:191], v152 offset:3072
	v_cndmask_b32_e32 v221, v145, v141, vcc
	v_cndmask_b32_e32 v220, v144, v140, vcc
	v_lshl_add_u64 v[226:227], v[142:143], 0, v[134:135]
	s_add_i32 m0, s51, 0xc000
	ds_read_b128 v[192:195], v155
	ds_read_b128 v[196:199], v155 offset:1024
	ds_read_b128 v[200:203], v155 offset:2048
	ds_read_b128 v[204:207], v155 offset:3072
	ds_read_b128 v[208:211], v155 offset:4096
	ds_read_b128 v[212:215], v155 offset:5120
	ds_read_b128 v[216:219], v155 offset:6144
	ds_read_b128 v[240:243], v155 offset:7168
	global_load_lds_dwordx4 v[226:227], off
	v_lshl_add_u64 v[226:227], v[142:143], 0, v[136:137]
	s_add_i32 m0, s51, 0xe000
	s_nop 0
	global_load_lds_dwordx4 v[226:227], off
	s_waitcnt vmcnt(8)
	s_waitcnt lgkmcnt(0)
	s_setprio 1
	s_barrier
; #define PG8_STAGE(bufoff, gbase, voff) do { _Pragma("unroll") for (int _i = 0; _i < 2; ++_i) \
;         __builtin_amdgcn_global_load_lds((const unsigned*)((const char*)(gbase) + (voff)[_i]), (LAS unsigned*)(lds + (bufoff) + ldsw + _i * 8192), 16, 0, 0); } while (0)
; #define PG8_LDA(dst, b, h) do { _Pragma("unroll") for (int m = 0; m < 4; ++m) _Pragma("unroll") for (int k = 0; k < 2; ++k) dst[m][k] = *(const LAS bf16x8*)(lds + PG8_SA(b, h) + aoff + m * 2048 + k * 1024); } while (0)
; #define PG8_MMA(ai, bj, At, Bt) do { __builtin_amdgcn_s_setprio(1); _Pragma("unroll") for (int k = 0; k < 2; ++k) _Pragma("unroll") for (int m = 0; m < 4; ++m) _Pragma("unroll") for (int n = 0; n < 2; ++n) \
;         acc[ai][bj][m][n] = __builtin_amdgcn_mfma_f32_16x16x32_bf16(Bt[n][k], At[m][k], acc[ai][bj][m][n], 0, 0, 0); __builtin_amdgcn_s_setprio(0); } while (0)
; #define PG8_WAIT_V(n) asm volatile("s_waitcnt vmcnt(" #n ")" ::: "memory")
; #define PG8_WAIT_L(n) asm volatile("s_waitcnt lgkmcnt(" #n ")" ::: "memory")
; #define PG8_BAR __builtin_amdgcn_s_barrier()
; #define PG8_SCHED __builtin_amdgcn_sched_barrier(0)
; template <class Epi, bool ALIGN_EPI>
; __device__ __forceinline__ void gemm_phase(LAS unsigned char* lds, const Gemm g, const StaticOrder& S, const Epi& E, const int tid) {
;     ...
;             PG8_WAIT_V(8); PG8_WAIT_L(0); PG8_BAR; PG8_MMA(0, 0, At, B0); PG8_MMA(0, 1, At, B1); PG8_BAR; PG8_SCHED;
;             PG8_LDA(At, 0, 1); PG8_STAGE(PG8_SB(0, 0), b2, voffB); PG8_STAGE(PG8_SB(0, 1), b2 + hB, voffB); PG8_STAGE(PG8_SA(0, 0), a2, voffA);
;             PG8_WAIT_V(8); PG8_WAIT_L(0); PG8_BAR; PG8_MMA(1, 0, At, B0); PG8_MMA(1, 1, At, B1); PG8_BAR; PG8_SCHED;
	s_waitcnt lgkmcnt(0)
	v_mfma_f32_16x16x32_bf16 v[120:123], v[146:149], v[192:195], v[120:123]
	v_mfma_f32_16x16x32_bf16 v[124:127], v[160:163], v[192:195], v[124:127]
	v_mfma_f32_16x16x32_bf16 v[108:111], v[146:149], v[200:203], v[108:111]
	v_mfma_f32_16x16x32_bf16 v[104:107], v[160:163], v[200:203], v[104:107]
	v_mfma_f32_16x16x32_bf16 v[92:95], v[146:149], v[208:211], v[92:95]
	v_mfma_f32_16x16x32_bf16 v[88:91], v[160:163], v[208:211], v[88:91]
	v_mfma_f32_16x16x32_bf16 v[76:79], v[146:149], v[216:219], v[76:79]
	v_mfma_f32_16x16x32_bf16 v[72:75], v[160:163], v[216:219], v[72:75]
	v_mfma_f32_16x16x32_bf16 v[120:123], v[156:159], v[196:199], v[120:123]
	v_mfma_f32_16x16x32_bf16 v[124:127], v[164:167], v[196:199], v[124:127]
	v_mfma_f32_16x16x32_bf16 v[108:111], v[156:159], v[204:207], v[108:111]
	v_mfma_f32_16x16x32_bf16 v[104:107], v[164:167], v[204:207], v[104:107]
	v_mfma_f32_16x16x32_bf16 v[92:95], v[156:159], v[212:215], v[92:95]
	v_mfma_f32_16x16x32_bf16 v[88:91], v[164:167], v[212:215], v[88:91]
	v_mfma_f32_16x16x32_bf16 v[76:79], v[156:159], v[240:243], v[76:79]
	v_mfma_f32_16x16x32_bf16 v[72:75], v[164:167], v[240:243], v[72:75]
	s_setprio 0
	s_setprio 1
	v_mfma_f32_16x16x32_bf16 v[116:119], v[176:179], v[192:195], v[116:119]
	v_mfma_f32_16x16x32_bf16 v[112:115], v[184:187], v[192:195], v[112:115]
	v_mfma_f32_16x16x32_bf16 v[100:103], v[176:179], v[200:203], v[100:103]
	v_mfma_f32_16x16x32_bf16 v[96:99], v[184:187], v[200:203], v[96:99]
	v_mfma_f32_16x16x32_bf16 v[84:87], v[176:179], v[208:211], v[84:87]
	v_mfma_f32_16x16x32_bf16 v[80:83], v[184:187], v[208:211], v[80:83]
	v_mfma_f32_16x16x32_bf16 v[68:71], v[176:179], v[216:219], v[68:71]
	v_mfma_f32_16x16x32_bf16 v[64:67], v[184:187], v[216:219], v[64:67]
	v_mfma_f32_16x16x32_bf16 v[116:119], v[180:183], v[196:199], v[116:119]
	v_mfma_f32_16x16x32_bf16 v[112:115], v[188:191], v[196:199], v[112:115]
	v_mfma_f32_16x16x32_bf16 v[100:103], v[180:183], v[204:207], v[100:103]
	v_mfma_f32_16x16x32_bf16 v[96:99], v[188:191], v[204:207], v[96:99]
	v_mfma_f32_16x16x32_bf16 v[84:87], v[180:183], v[212:215], v[84:87]
	v_mfma_f32_16x16x32_bf16 v[80:83], v[188:191], v[212:215], v[80:83]
	v_mfma_f32_16x16x32_bf16 v[68:71], v[180:183], v[240:243], v[68:71]
	v_mfma_f32_16x16x32_bf16 v[64:67], v[188:191], v[240:243], v[64:67]
	s_setprio 0
	s_barrier
	s_add_i32 s65, s33, s45
	v_lshl_add_u64 v[226:227], v[220:221], 0, v[168:169]
	s_mov_b32 m0, s65
	ds_read_b128 v[192:195], v155 offset:16384
	ds_read_b128 v[196:199], v155 offset:17408
	ds_read_b128 v[200:203], v155 offset:18432
	ds_read_b128 v[204:207], v155 offset:19456
	ds_read_b128 v[208:211], v155 offset:20480
	ds_read_b128 v[212:215], v155 offset:21504
	ds_read_b128 v[216:219], v155 offset:22528
	ds_read_b128 v[240:243], v155 offset:23552
	global_load_lds_dwordx4 v[226:227], off
	v_lshl_add_u64 v[244:245], v[220:221], 0, v[128:129]
	s_add_i32 m0, s65, 0x2000
	v_lshl_add_u64 v[220:221], v[220:221], 0, s[12:13]
	s_add_i32 s10, s10, s45
	global_load_lds_dwordx4 v[244:245], off
	v_lshl_add_u64 v[246:247], v[220:221], 0, v[168:169]
	s_mov_b32 m0, s10
	v_lshl_add_u64 v[220:221], v[220:221], 0, v[128:129]
	global_load_lds_dwordx4 v[246:247], off
	s_add_i32 m0, s10, 0x2000
	v_lshl_add_u64 v[248:249], v[150:151], 0, v[132:133]
	global_load_lds_dwordx4 v[220:221], off
	s_mov_b32 m0, s51
	v_lshl_add_u64 v[250:251], v[150:151], 0, v[130:131]
	global_load_lds_dwordx4 v[248:249], off
	s_mov_b32 m0, s52
	s_nop 0
	global_load_lds_dwordx4 v[250:251], off
	s_waitcnt vmcnt(8)
	s_waitcnt lgkmcnt(0)
	s_setprio 1
	s_barrier
	s_waitcnt lgkmcnt(0)
	v_mfma_f32_16x16x32_bf16 v[60:63], v[146:149], v[192:195], v[60:63]
	v_mfma_f32_16x16x32_bf16 v[56:59], v[160:163], v[192:195], v[56:59]
	v_mfma_f32_16x16x32_bf16 v[44:47], v[146:149], v[200:203], v[44:47]
	v_mfma_f32_16x16x32_bf16 v[40:43], v[160:163], v[200:203], v[40:43]
	v_mfma_f32_16x16x32_bf16 v[28:31], v[146:149], v[208:211], v[28:31]
	v_mfma_f32_16x16x32_bf16 v[24:27], v[160:163], v[208:211], v[24:27]
	v_mfma_f32_16x16x32_bf16 v[12:15], v[146:149], v[216:219], v[12:15]
	v_mfma_f32_16x16x32_bf16 v[8:11], v[160:163], v[216:219], v[8:11]
	v_mfma_f32_16x16x32_bf16 v[60:63], v[156:159], v[196:199], v[60:63]
	v_mfma_f32_16x16x32_bf16 v[56:59], v[164:167], v[196:199], v[56:59]
	v_mfma_f32_16x16x32_bf16 v[44:47], v[156:159], v[204:207], v[44:47]
	v_mfma_f32_16x16x32_bf16 v[40:43], v[164:167], v[204:207], v[40:43]
	v_mfma_f32_16x16x32_bf16 v[28:31], v[156:159], v[212:215], v[28:31]
	v_mfma_f32_16x16x32_bf16 v[24:27], v[164:167], v[212:215], v[24:27]
	v_mfma_f32_16x16x32_bf16 v[12:15], v[156:159], v[240:243], v[12:15]
	v_mfma_f32_16x16x32_bf16 v[8:11], v[164:167], v[240:243], v[8:11]
	s_setprio 0
	s_setprio 1
	v_mfma_f32_16x16x32_bf16 v[52:55], v[176:179], v[192:195], v[52:55]
	v_mfma_f32_16x16x32_bf16 v[48:51], v[184:187], v[192:195], v[48:51]
	v_mfma_f32_16x16x32_bf16 v[36:39], v[176:179], v[200:203], v[36:39]
	v_mfma_f32_16x16x32_bf16 v[32:35], v[184:187], v[200:203], v[32:35]
	v_mfma_f32_16x16x32_bf16 v[20:23], v[176:179], v[208:211], v[20:23]
	v_mfma_f32_16x16x32_bf16 v[16:19], v[184:187], v[208:211], v[16:19]
	v_mfma_f32_16x16x32_bf16 v[4:7], v[176:179], v[216:219], v[4:7]
	v_mfma_f32_16x16x32_bf16 v[0:3], v[184:187], v[216:219], v[0:3]
	v_mfma_f32_16x16x32_bf16 v[52:55], v[180:183], v[196:199], v[52:55]
	v_mfma_f32_16x16x32_bf16 v[48:51], v[188:191], v[196:199], v[48:51]
	v_mfma_f32_16x16x32_bf16 v[36:39], v[180:183], v[204:207], v[36:39]
	v_mfma_f32_16x16x32_bf16 v[32:35], v[188:191], v[204:207], v[32:35]
	v_mfma_f32_16x16x32_bf16 v[20:23], v[180:183], v[212:215], v[20:23]
	v_mfma_f32_16x16x32_bf16 v[16:19], v[188:191], v[212:215], v[16:19]
	v_mfma_f32_16x16x32_bf16 v[4:7], v[180:183], v[240:243], v[4:7]
	v_mfma_f32_16x16x32_bf16 v[0:3], v[188:191], v[240:243], v[0:3]
	s_setprio 0
	s_barrier
; #define PG8_STAGE(bufoff, gbase, voff) do { _Pragma("unroll") for (int _i = 0; _i < 2; ++_i) \
;         __builtin_amdgcn_global_load_lds((const unsigned*)((const char*)(gbase) + (voff)[_i]), (LAS unsigned*)(lds + (bufoff) + ldsw + _i * 8192), 16, 0, 0); } while (0)
; #define PG8_LDA(dst, b, h) do { _Pragma("unroll") for (int m = 0; m < 4; ++m) _Pragma("unroll") for (int k = 0; k < 2; ++k) dst[m][k] = *(const LAS bf16x8*)(lds + PG8_SA(b, h) + aoff + m * 2048 + k * 1024); } while (0)
; #define PG8_LDB(dst, b, h) do { _Pragma("unroll") for (int n = 0; n < 2; ++n) _Pragma("unroll") for (int k = 0; k < 2; ++k) dst[n][k] = *(const LAS bf16x8*)(lds + PG8_SB(b, h) + boff + n * 2048 + k * 1024); } while (0)
; #define PG8_MMA(ai, bj, At, Bt) do { __builtin_amdgcn_s_setprio(1); _Pragma("unroll") for (int k = 0; k < 2; ++k) _Pragma("unroll") for (int m = 0; m < 4; ++m) _Pragma("unroll") for (int n = 0; n < 2; ++n) \
;         acc[ai][bj][m][n] = __builtin_amdgcn_mfma_f32_16x16x32_bf16(Bt[n][k], At[m][k], acc[ai][bj][m][n], 0, 0, 0); __builtin_amdgcn_s_setprio(0); } while (0)
; #define PG8_WAIT_V(n) asm volatile("s_waitcnt vmcnt(" #n ")" ::: "memory")
; #define PG8_WAIT_L(n) asm volatile("s_waitcnt lgkmcnt(" #n ")" ::: "memory")
; #define PG8_BAR __builtin_amdgcn_s_barrier()
; #define PG8_SCHED __builtin_amdgcn_sched_barrier(0)
; template <class Epi, bool ALIGN_EPI>
; __device__ __forceinline__ void gemm_phase(LAS unsigned char* lds, const Gemm g, const StaticOrder& S, const Epi& E, const int tid) {
;     ...
;             PG8_LDB(B0, 1, 0); PG8_LDB(B1, 1, 1); PG8_SCHED; PG8_LDA(At, 1, 0); PG8_STAGE(PG8_SA(0, 1), a2 + hA, voffA);
;             PG8_WAIT_V(8); PG8_WAIT_L(0); PG8_BAR; PG8_MMA(0, 0, At, B0); PG8_MMA(0, 1, At, B1); PG8_BAR; PG8_SCHED;
	s_add_i32 s10, 0, 0x18000
	v_add_u32_e32 v152, s10, v153
	s_add_i32 s65, 0, 0x1c000
	ds_read_b128 v[146:149], v152
	ds_read_b128 v[156:159], v152 offset:1024
	ds_read_b128 v[160:163], v152 offset:2048
	ds_read_b128 v[164:167], v152 offset:3072
	v_add_u32_e32 v152, s65, v153
	ds_read_b128 v[176:179], v152
	ds_read_b128 v[180:183], v152 offset:1024
	ds_read_b128 v[184:187], v152 offset:2048
	ds_read_b128 v[188:191], v152 offset:3072
	v_lshl_add_u64 v[150:151], v[150:151], 0, s[94:95]
	s_mov_b32 m0, s53
	v_lshl_add_u64 v[252:253], v[150:151], 0, v[132:133]
	ds_read_b128 v[192:195], v155 offset:32768
	ds_read_b128 v[196:199], v155 offset:33792
	ds_read_b128 v[200:203], v155 offset:34816
	ds_read_b128 v[204:207], v155 offset:35840
	ds_read_b128 v[208:211], v155 offset:36864
	ds_read_b128 v[212:215], v155 offset:37888
	ds_read_b128 v[216:219], v155 offset:38912
	ds_read_b128 v[240:243], v155 offset:39936
	global_load_lds_dwordx4 v[252:253], off
	v_lshl_add_u64 v[150:151], v[150:151], 0, v[130:131]
	s_mov_b32 m0, s54
	s_nop 0
	global_load_lds_dwordx4 v[150:151], off
	s_waitcnt vmcnt(8)
	s_waitcnt lgkmcnt(0)
	s_setprio 1
	s_barrier
	s_waitcnt lgkmcnt(0)
	v_mfma_f32_16x16x32_bf16 v[120:123], v[146:149], v[192:195], v[120:123]
	v_mfma_f32_16x16x32_bf16 v[124:127], v[160:163], v[192:195], v[124:127]
	v_mfma_f32_16x16x32_bf16 v[108:111], v[146:149], v[200:203], v[108:111]
	v_mfma_f32_16x16x32_bf16 v[104:107], v[160:163], v[200:203], v[104:107]
	v_mfma_f32_16x16x32_bf16 v[92:95], v[146:149], v[208:211], v[92:95]
	v_mfma_f32_16x16x32_bf16 v[88:91], v[160:163], v[208:211], v[88:91]
	v_mfma_f32_16x16x32_bf16 v[76:79], v[146:149], v[216:219], v[76:79]
	v_mfma_f32_16x16x32_bf16 v[72:75], v[160:163], v[216:219], v[72:75]
	v_mfma_f32_16x16x32_bf16 v[120:123], v[156:159], v[196:199], v[120:123]
	v_mfma_f32_16x16x32_bf16 v[124:127], v[164:167], v[196:199], v[124:127]
	v_mfma_f32_16x16x32_bf16 v[108:111], v[156:159], v[204:207], v[108:111]
	v_mfma_f32_16x16x32_bf16 v[104:107], v[164:167], v[204:207], v[104:107]
	v_mfma_f32_16x16x32_bf16 v[92:95], v[156:159], v[212:215], v[92:95]
	v_mfma_f32_16x16x32_bf16 v[88:91], v[164:167], v[212:215], v[88:91]
	v_mfma_f32_16x16x32_bf16 v[76:79], v[156:159], v[240:243], v[76:79]
	v_mfma_f32_16x16x32_bf16 v[72:75], v[164:167], v[240:243], v[72:75]
	s_setprio 0
	s_setprio 1
	v_mfma_f32_16x16x32_bf16 v[116:119], v[176:179], v[192:195], v[116:119]
	v_mfma_f32_16x16x32_bf16 v[112:115], v[184:187], v[192:195], v[112:115]
	v_mfma_f32_16x16x32_bf16 v[100:103], v[176:179], v[200:203], v[100:103]
	v_mfma_f32_16x16x32_bf16 v[96:99], v[184:187], v[200:203], v[96:99]
	v_mfma_f32_16x16x32_bf16 v[84:87], v[176:179], v[208:211], v[84:87]
	v_mfma_f32_16x16x32_bf16 v[80:83], v[184:187], v[208:211], v[80:83]
	v_mfma_f32_16x16x32_bf16 v[68:71], v[176:179], v[216:219], v[68:71]
	v_mfma_f32_16x16x32_bf16 v[64:67], v[184:187], v[216:219], v[64:67]
	v_mfma_f32_16x16x32_bf16 v[116:119], v[180:183], v[196:199], v[116:119]
	v_mfma_f32_16x16x32_bf16 v[112:115], v[188:191], v[196:199], v[112:115]
	v_mfma_f32_16x16x32_bf16 v[100:103], v[180:183], v[204:207], v[100:103]
	v_mfma_f32_16x16x32_bf16 v[96:99], v[188:191], v[204:207], v[96:99]
	v_mfma_f32_16x16x32_bf16 v[84:87], v[180:183], v[212:215], v[84:87]
	v_mfma_f32_16x16x32_bf16 v[80:83], v[188:191], v[212:215], v[80:83]
	v_mfma_f32_16x16x32_bf16 v[68:71], v[180:183], v[240:243], v[68:71]
	v_mfma_f32_16x16x32_bf16 v[64:67], v[188:191], v[240:243], v[64:67]
	s_setprio 0
	s_barrier
; #define PG8_STAGE(bufoff, gbase, voff) do { _Pragma("unroll") for (int _i = 0; _i < 2; ++_i) \
;         __builtin_amdgcn_global_load_lds((const unsigned*)((const char*)(gbase) + (voff)[_i]), (LAS unsigned*)(lds + (bufoff) + ldsw + _i * 8192), 16, 0, 0); } while (0)
; #define PG8_LDA(dst, b, h) do { _Pragma("unroll") for (int m = 0; m < 4; ++m) _Pragma("unroll") for (int k = 0; k < 2; ++k) dst[m][k] = *(const LAS bf16x8*)(lds + PG8_SA(b, h) + aoff + m * 2048 + k * 1024); } while (0)
; #define PG8_MMA(ai, bj, At, Bt) do { __builtin_amdgcn_s_setprio(1); _Pragma("unroll") for (int k = 0; k < 2; ++k) _Pragma("unroll") for (int m = 0; m < 4; ++m) _Pragma("unroll") for (int n = 0; n < 2; ++n) \
;         acc[ai][bj][m][n] = __builtin_amdgcn_mfma_f32_16x16x32_bf16(Bt[n][k], At[m][k], acc[ai][bj][m][n], 0, 0, 0); __builtin_amdgcn_s_setprio(0); } while (0)
; #define PG8_WAIT_V(n) asm volatile("s_waitcnt vmcnt(" #n ")" ::: "memory")
; #define PG8_WAIT_L(n) asm volatile("s_waitcnt lgkmcnt(" #n ")" ::: "memory")
; #define PG8_BAR __builtin_amdgcn_s_barrier()
; #define PG8_SCHED __builtin_amdgcn_sched_barrier(0)
; template <class Epi, bool ALIGN_EPI>
; __device__ __forceinline__ void gemm_phase(LAS unsigned char* lds, const Gemm g, const StaticOrder& S, const Epi& E, const int tid) {
;     ...
;             PG8_LDA(At, 1, 1); PG8_STAGE(PG8_SB(1, 0), b3, voffB); PG8_STAGE(PG8_SB(1, 1), b3 + hB, voffB); PG8_STAGE(PG8_SA(1, 0), a3, voffA);
;             PG8_WAIT_V(8); PG8_WAIT_L(0); PG8_BAR; PG8_MMA(1, 0, At, B0); PG8_MMA(1, 1, At, B1); PG8_BAR; PG8_SCHED;
;         }
	s_add_i32 s10, s10, s45
	v_lshl_add_u64 v[150:151], v[226:227], 0, s[92:93]
	s_mov_b32 m0, s10
	ds_read_b128 v[192:195], v155 offset:49152
	ds_read_b128 v[196:199], v155 offset:50176
	ds_read_b128 v[200:203], v155 offset:51200
	ds_read_b128 v[204:207], v155 offset:52224
	ds_read_b128 v[208:211], v155 offset:53248
	ds_read_b128 v[212:215], v155 offset:54272
	ds_read_b128 v[216:219], v155 offset:55296
	ds_read_b128 v[240:243], v155 offset:56320
	global_load_lds_dwordx4 v[150:151], off
	v_lshl_add_u64 v[150:151], v[244:245], 0, s[92:93]
	s_add_i32 m0, s10, 0x2000
	s_add_i32 s10, s65, s45
	global_load_lds_dwordx4 v[150:151], off
	v_lshl_add_u64 v[150:151], v[246:247], 0, s[92:93]
	s_mov_b32 m0, s10
	s_nop 0
	global_load_lds_dwordx4 v[150:151], off
	v_lshl_add_u64 v[150:151], v[220:221], 0, s[92:93]
	s_add_i32 m0, s10, 0x2000
	s_nop 0
	global_load_lds_dwordx4 v[150:151], off
	v_lshl_add_u64 v[150:151], v[248:249], 0, s[92:93]
	s_mov_b32 m0, s56
	s_nop 0
	global_load_lds_dwordx4 v[150:151], off
	v_lshl_add_u64 v[150:151], v[250:251], 0, s[92:93]
	s_mov_b32 m0, s57
	s_nop 0
	global_load_lds_dwordx4 v[150:151], off
	s_waitcnt vmcnt(8)
	s_waitcnt lgkmcnt(0)
	s_setprio 1
	s_barrier
	s_waitcnt lgkmcnt(0)
	v_mfma_f32_16x16x32_bf16 v[60:63], v[146:149], v[192:195], v[60:63]
	v_mfma_f32_16x16x32_bf16 v[56:59], v[160:163], v[192:195], v[56:59]
	v_mfma_f32_16x16x32_bf16 v[44:47], v[146:149], v[200:203], v[44:47]
	v_mfma_f32_16x16x32_bf16 v[40:43], v[160:163], v[200:203], v[40:43]
	v_mfma_f32_16x16x32_bf16 v[28:31], v[146:149], v[208:211], v[28:31]
	v_mfma_f32_16x16x32_bf16 v[24:27], v[160:163], v[208:211], v[24:27]
	v_mfma_f32_16x16x32_bf16 v[12:15], v[146:149], v[216:219], v[12:15]
	v_mfma_f32_16x16x32_bf16 v[8:11], v[160:163], v[216:219], v[8:11]
	v_mfma_f32_16x16x32_bf16 v[60:63], v[156:159], v[196:199], v[60:63]
	v_mfma_f32_16x16x32_bf16 v[56:59], v[164:167], v[196:199], v[56:59]
	v_mfma_f32_16x16x32_bf16 v[44:47], v[156:159], v[204:207], v[44:47]
	v_mfma_f32_16x16x32_bf16 v[40:43], v[164:167], v[204:207], v[40:43]
	v_mfma_f32_16x16x32_bf16 v[28:31], v[156:159], v[212:215], v[28:31]
	v_mfma_f32_16x16x32_bf16 v[24:27], v[164:167], v[212:215], v[24:27]
	v_mfma_f32_16x16x32_bf16 v[12:15], v[156:159], v[240:243], v[12:15]
	v_mfma_f32_16x16x32_bf16 v[8:11], v[164:167], v[240:243], v[8:11]
	s_setprio 0
	s_setprio 1
	v_mfma_f32_16x16x32_bf16 v[52:55], v[176:179], v[192:195], v[52:55]
	v_mfma_f32_16x16x32_bf16 v[48:51], v[184:187], v[192:195], v[48:51]
	v_mfma_f32_16x16x32_bf16 v[36:39], v[176:179], v[200:203], v[36:39]
	v_mfma_f32_16x16x32_bf16 v[32:35], v[184:187], v[200:203], v[32:35]
	v_mfma_f32_16x16x32_bf16 v[20:23], v[176:179], v[208:211], v[20:23]
	v_mfma_f32_16x16x32_bf16 v[16:19], v[184:187], v[208:211], v[16:19]
	v_mfma_f32_16x16x32_bf16 v[4:7], v[176:179], v[216:219], v[4:7]
	v_mfma_f32_16x16x32_bf16 v[0:3], v[184:187], v[216:219], v[0:3]
	v_mfma_f32_16x16x32_bf16 v[52:55], v[180:183], v[196:199], v[52:55]
	v_mfma_f32_16x16x32_bf16 v[48:51], v[188:191], v[196:199], v[48:51]
	v_mfma_f32_16x16x32_bf16 v[36:39], v[180:183], v[204:207], v[36:39]
	v_mfma_f32_16x16x32_bf16 v[32:35], v[188:191], v[204:207], v[32:35]
	v_mfma_f32_16x16x32_bf16 v[20:23], v[180:183], v[212:215], v[20:23]
	v_mfma_f32_16x16x32_bf16 v[16:19], v[188:191], v[212:215], v[16:19]
	v_mfma_f32_16x16x32_bf16 v[4:7], v[180:183], v[240:243], v[4:7]
	v_mfma_f32_16x16x32_bf16 v[0:3], v[188:191], v[240:243], v[0:3]
	s_setprio 0
	s_barrier
	v_lshl_add_u64 v[142:143], v[142:143], 0, s[80:81]
	v_lshl_add_u64 v[144:145], v[144:145], 0, s[80:81]
	s_cmp_ge_u32 s11, s55
	s_mov_b32 s10, s11
	s_cbranch_scc0 .LBB0_331

;     __device__ __forceinline__ void operator()(const f32x4 (&acc)[2][2][4][2], const Unit& u, int wr, int wc, int fr, int fq) const {
;     ...
;             for (int m = 0; m < 4; ++m) { const int row = row0 + ai * HALF + m * 16; bf16_t* rowp = O + (size_t)row * ldc + col0; const float rs = rsv[ai][m];
; #pragma unroll
;                 for (int bj = 0; bj < 2; ++bj) { f32x4 v0 = acc[ai][bj][m][0] * rs, v1 = acc[ai][bj][m][1] * rs;
;                     if (ACT == 1) {
; #pragma unroll
;                         for (int j = 0; j < 4; ++j) { v0[j] = gelu_tanh(v0[j]); v1[j] = gelu_tanh(v1[j]); } }
;                     u32x4 w; w.x = cvt_pk_bf16(v0[0], v0[1]); w.y = cvt_pk_bf16(v0[2], v0[3]); w.z = cvt_pk_bf16(v1[0], v1[1]); w.w = cvt_pk_bf16(v1[2], v1[3]);
;                     *(u32x4*)(rowp + bj * HALF) = w; } }
; template <class Epi, bool ALIGN_EPI>
; __device__ __forceinline__ void gemm_phase(LAS unsigned char* lds, const Gemm g, const StaticOrder& S, const Epi& E, const int tid) {
;     ...
;         for (int t = 0; t < nt; t += 2) {
;             const bool last = (t == nt - 2);
;             const char* a1 = cA + (size_t)(t + 1) * kstep;
;             const char* a2 = last ? nA : cA + (size_t)(t + 2) * kstep; const char* b2 = last ? nB : cB + (size_t)(t + 2) * kstep;
;             const char* a3 = a2 + kstep; const char* b3 = b2 + kstep;
;             PG8_LDB(B0, 0, 0); PG8_LDB(B1, 0, 1); PG8_SCHED; PG8_LDA(At, 0, 0); PG8_STAGE(PG8_SA(1, 1), a1 + hA, voffA);
;             PG8_WAIT_V(8); PG8_WAIT_L(0); PG8_BAR; PG8_MMA(0, 0, At, B0); PG8_MMA(0, 1, At, B1); PG8_BAR; PG8_SCHED;
;             PG8_LDA(At, 0, 1); PG8_STAGE(PG8_SB(0, 0), b2, voffB); PG8_STAGE(PG8_SB(0, 1), b2 + hB, voffB); PG8_STAGE(PG8_SA(0, 0), a2, voffA);
;             PG8_WAIT_V(8); PG8_WAIT_L(0); PG8_BAR; PG8_MMA(1, 0, At, B0); PG8_MMA(1, 1, At, B1); PG8_BAR; PG8_SCHED;
;             PG8_LDB(B0, 1, 0); PG8_LDB(B1, 1, 1); PG8_SCHED; PG8_LDA(At, 1, 0); PG8_STAGE(PG8_SA(0, 1), a2 + hA, voffA);
;             PG8_WAIT_V(8); PG8_WAIT_L(0); PG8_BAR; PG8_MMA(0, 0, At, B0); PG8_MMA(0, 1, At, B1); PG8_BAR; PG8_SCHED;
;             PG8_LDA(At, 1, 1); PG8_STAGE(PG8_SB(1, 0), b3, voffB); PG8_STAGE(PG8_SB(1, 1), b3 + hB, voffB); PG8_STAGE(PG8_SA(1, 0), a3, voffA);
;             PG8_WAIT_V(8); PG8_WAIT_L(0); PG8_BAR; PG8_MMA(1, 0, At, B0); PG8_MMA(1, 1, At, B1); PG8_BAR; PG8_SCHED;
.Lq5_first_epi:
	s_add_i32 s11, s10, 2
	s_cmp_eq_u32 s55, s10
	s_cselect_b64 vcc, -1, 0
	v_add_u32_e32 v148, s33, v149
	s_add_i32 s10, 0, 0x14000
	ds_read_b128 v[152:155], v148
	ds_read_b128 v[156:159], v148 offset:1024
	ds_read_b128 v[160:163], v148 offset:2048
	ds_read_b128 v[164:167], v148 offset:3072
	v_add_u32_e32 v148, s10, v149
	ds_read_b128 v[176:179], v148
	ds_read_b128 v[180:183], v148 offset:1024
	ds_read_b128 v[184:187], v148 offset:2048
	ds_read_b128 v[188:191], v148 offset:3072
	v_lshl_add_u64 v[146:147], v[142:143], 0, s[92:93]
	v_cndmask_b32_e32 v147, v147, v139, vcc
	v_cndmask_b32_e32 v146, v146, v138, vcc
	v_cndmask_b32_e32 v221, v145, v141, vcc
	v_cndmask_b32_e32 v220, v144, v140, vcc
	v_lshl_add_u64 v[244:245], v[142:143], 0, v[134:135]
	s_add_i32 m0, s25, 0xc000
	ds_read_b128 v[192:195], v151
	ds_read_b128 v[196:199], v151 offset:1024
	ds_read_b128 v[200:203], v151 offset:2048
	ds_read_b128 v[204:207], v151 offset:3072
	ds_read_b128 v[208:211], v151 offset:4096
	ds_read_b128 v[212:215], v151 offset:5120
	ds_read_b128 v[216:219], v151 offset:6144
	ds_read_b128 v[240:243], v151 offset:7168
	global_load_lds_dwordx4 v[244:245], off
	v_lshl_add_u64 v[244:245], v[142:143], 0, v[136:137]
	s_add_i32 m0, s25, 0xe000
	s_nop 0
	global_load_lds_dwordx4 v[244:245], off
	s_waitcnt vmcnt(16)
	s_waitcnt lgkmcnt(0)
	s_setprio 1
	s_barrier
	s_waitcnt lgkmcnt(0)
	v_mfma_f32_16x16x32_bf16 v[124:127], v[152:155], v[192:195], 0
	s_lshl_b32 s98, s28, 5
	s_mov_b32 s99, 0
	v_mul_f32_e32 v60, v238, v60
	v_mul_f32_e32 v61, v238, v61
	v_mfma_f32_16x16x32_bf16 v[120:123], v[160:163], v[192:195], 0
	v_mul_f32_e32 v62, v238, v62
	v_mul_f32_e32 v63, v238, v63
	v_mul_f32_e32 v56, v238, v56
	v_mul_f32_e32 v57, v238, v57
	v_mfma_f32_16x16x32_bf16 v[108:111], v[152:155], v[200:203], 0
	v_mul_f32_e32 v58, v238, v58
	v_mul_f32_e32 v59, v238, v59
	v_cvt_pk_bf16_f32 v60, v60, v61
	v_cvt_pk_bf16_f32 v61, v62, v63
	v_mfma_f32_16x16x32_bf16 v[104:107], v[160:163], v[200:203], 0
	v_cvt_pk_bf16_f32 v62, v56, v57
	v_cvt_pk_bf16_f32 v63, v58, v59
	global_store_dwordx4 v[232:233], v[60:63], off
	v_mul_f32_e32 v52, v238, v52
	v_mfma_f32_16x16x32_bf16 v[92:95], v[152:155], v[208:211], 0
	v_mul_f32_e32 v53, v238, v53
	v_mul_f32_e32 v54, v238, v54
	v_mul_f32_e32 v55, v238, v55
	v_mul_f32_e32 v48, v238, v48
	v_mfma_f32_16x16x32_bf16 v[88:91], v[160:163], v[208:211], 0
	v_mul_f32_e32 v49, v238, v49
	v_mul_f32_e32 v50, v238, v50
	v_mul_f32_e32 v51, v238, v51
	v_cvt_pk_bf16_f32 v52, v52, v53
	v_mfma_f32_16x16x32_bf16 v[76:79], v[152:155], v[216:219], 0
	v_cvt_pk_bf16_f32 v53, v54, v55
	v_cvt_pk_bf16_f32 v54, v48, v49
	v_cvt_pk_bf16_f32 v55, v50, v51
	global_store_dwordx4 v[232:233], v[52:55], off offset:256
	v_mfma_f32_16x16x32_bf16 v[72:75], v[160:163], v[216:219], 0
	v_lshl_add_u64 v[232:233], v[232:233], 0, s[98:99]
	v_mul_f32_e32 v44, v239, v44
	v_mul_f32_e32 v45, v239, v45
	v_mul_f32_e32 v46, v239, v46
	v_mfma_f32_16x16x32_bf16 v[124:127], v[156:159], v[196:199], v[124:127]
	v_mul_f32_e32 v47, v239, v47
	v_mul_f32_e32 v40, v239, v40
	v_mul_f32_e32 v41, v239, v41
	v_mul_f32_e32 v42, v239, v42
	v_mfma_f32_16x16x32_bf16 v[120:123], v[164:167], v[196:199], v[120:123]
	v_mul_f32_e32 v43, v239, v43
	v_cvt_pk_bf16_f32 v44, v44, v45
	v_cvt_pk_bf16_f32 v45, v46, v47
	v_cvt_pk_bf16_f32 v46, v40, v41
	v_mfma_f32_16x16x32_bf16 v[108:111], v[156:159], v[204:207], v[108:111]
	v_cvt_pk_bf16_f32 v47, v42, v43
	global_store_dwordx4 v[232:233], v[44:47], off
	v_mul_f32_e32 v36, v239, v36
	v_mul_f32_e32 v37, v239, v37
	v_mfma_f32_16x16x32_bf16 v[104:107], v[164:167], v[204:207], v[104:107]
	v_mul_f32_e32 v38, v239, v38
	v_mul_f32_e32 v39, v239, v39
	v_mul_f32_e32 v32, v239, v32
	v_mul_f32_e32 v33, v239, v33
	v_mfma_f32_16x16x32_bf16 v[92:95], v[156:159], v[212:215], v[92:95]
	v_mul_f32_e32 v34, v239, v34
	v_mul_f32_e32 v35, v239, v35
	v_cvt_pk_bf16_f32 v36, v36, v37
	v_cvt_pk_bf16_f32 v37, v38, v39
	v_mfma_f32_16x16x32_bf16 v[88:91], v[164:167], v[212:215], v[88:91]
	v_cvt_pk_bf16_f32 v38, v32, v33
	v_cvt_pk_bf16_f32 v39, v34, v35
	global_store_dwordx4 v[232:233], v[36:39], off offset:256
	v_lshl_add_u64 v[232:233], v[232:233], 0, s[98:99]
	v_mfma_f32_16x16x32_bf16 v[76:79], v[156:159], v[240:243], v[76:79]
	v_mul_f32_e32 v28, v230, v28
	v_mul_f32_e32 v29, v230, v29
	v_mul_f32_e32 v30, v230, v30
	v_mul_f32_e32 v31, v230, v31
	v_mfma_f32_16x16x32_bf16 v[72:75], v[164:167], v[240:243], v[72:75]
	v_mul_f32_e32 v24, v230, v24
	v_mul_f32_e32 v25, v230, v25
	v_mul_f32_e32 v26, v230, v26
	v_mul_f32_e32 v27, v230, v27
	s_setprio 0
	s_setprio 1
	v_mfma_f32_16x16x32_bf16 v[116:119], v[176:179], v[192:195], 0
	v_cvt_pk_bf16_f32 v28, v28, v29
	v_cvt_pk_bf16_f32 v29, v30, v31
	v_cvt_pk_bf16_f32 v30, v24, v25
	v_cvt_pk_bf16_f32 v31, v26, v27
	v_mfma_f32_16x16x32_bf16 v[112:115], v[184:187], v[192:195], 0
	global_store_dwordx4 v[232:233], v[28:31], off
	v_mul_f32_e32 v20, v230, v20
	v_mul_f32_e32 v21, v230, v21
	v_mul_f32_e32 v22, v230, v22
	v_mfma_f32_16x16x32_bf16 v[100:103], v[176:179], v[200:203], 0
	v_mul_f32_e32 v23, v230, v23
	v_mul_f32_e32 v16, v230, v16
	v_mul_f32_e32 v17, v230, v17
	v_mul_f32_e32 v18, v230, v18
	v_mfma_f32_16x16x32_bf16 v[96:99], v[184:187], v[200:203], 0
	v_mul_f32_e32 v19, v230, v19
	v_cvt_pk_bf16_f32 v20, v20, v21
	v_cvt_pk_bf16_f32 v21, v22, v23
	v_cvt_pk_bf16_f32 v22, v16, v17
	v_mfma_f32_16x16x32_bf16 v[84:87], v[176:179], v[208:211], 0
	v_cvt_pk_bf16_f32 v23, v18, v19
	global_store_dwordx4 v[232:233], v[20:23], off offset:256
	v_lshl_add_u64 v[232:233], v[232:233], 0, s[98:99]
	v_mul_f32_e32 v12, v231, v12
	v_mfma_f32_16x16x32_bf16 v[80:83], v[184:187], v[208:211], 0
; __device__ __forceinline__ unsigned cvt_pk_bf16(float lo, float hi) { unsigned r; asm volatile("v_cvt_pk_bf16_f32 %0, %1, %2" : "=v"(r) : "v"(lo), "v"(hi)); return r; }
; __device__ __forceinline__ float gelu_tanh(float x) { const float u = 0.7978845608028654f * (x + 0.044715f * x * x * x); return x * fast_rcp(1.0f + fast_exp2(-2.0f * LOG2E * u)); }
; #define PG8_STAGE(bufoff, gbase, voff) do { _Pragma("unroll") for (int _i = 0; _i < 2; ++_i) \
;         __builtin_amdgcn_global_load_lds((const unsigned*)((const char*)(gbase) + (voff)[_i]), (LAS unsigned*)(lds + (bufoff) + ldsw + _i * 8192), 16, 0, 0); } while (0)
; #define PG8_WAIT_V(n) asm volatile("s_waitcnt vmcnt(" #n ")" ::: "memory")
; #define PG8_WAIT_L(n) asm volatile("s_waitcnt lgkmcnt(" #n ")" ::: "memory")
;     __device__ __forceinline__ void operator()(const f32x4 (&acc)[2][2][4][2], const Unit& u, int wr, int wc, int fr, int fq) const {
;     ...
;             for (int m = 0; m < 4; ++m) { const int row = row0 + ai * HALF + m * 16; bf16_t* rowp = O + (size_t)row * ldc + col0; const float rs = rsv[ai][m];
; #pragma unroll
;                 for (int bj = 0; bj < 2; ++bj) { f32x4 v0 = acc[ai][bj][m][0] * rs, v1 = acc[ai][bj][m][1] * rs;
;                     if (ACT == 1) {
; #pragma unroll
;                         for (int j = 0; j < 4; ++j) { v0[j] = gelu_tanh(v0[j]); v1[j] = gelu_tanh(v1[j]); } }
;                     u32x4 w; w.x = cvt_pk_bf16(v0[0], v0[1]); w.y = cvt_pk_bf16(v0[2], v0[3]); w.z = cvt_pk_bf16(v1[0], v1[1]); w.w = cvt_pk_bf16(v1[2], v1[3]);
;                     *(u32x4*)(rowp + bj * HALF) = w; } }
; template <class Epi, bool ALIGN_EPI>
; __device__ __forceinline__ void gemm_phase(LAS unsigned char* lds, const Gemm g, const StaticOrder& S, const Epi& E, const int tid) {
;     ...
;             PG8_WAIT_V(8); PG8_WAIT_L(0); PG8_BAR; PG8_MMA(0, 0, At, B0); PG8_MMA(0, 1, At, B1); PG8_BAR; PG8_SCHED;
;             PG8_LDA(At, 0, 1); PG8_STAGE(PG8_SB(0, 0), b2, voffB); PG8_STAGE(PG8_SB(0, 1), b2 + hB, voffB); PG8_STAGE(PG8_SA(0, 0), a2, voffA);
;             PG8_WAIT_V(8); PG8_WAIT_L(0); PG8_BAR; PG8_MMA(1, 0, At, B0); PG8_MMA(1, 1, At, B1); PG8_BAR; PG8_SCHED;
;             PG8_LDB(B0, 1, 0); PG8_LDB(B1, 1, 1); PG8_SCHED; PG8_LDA(At, 1, 0); PG8_STAGE(PG8_SA(0, 1), a2 + hA, voffA);
;             PG8_WAIT_V(8); PG8_WAIT_L(0); PG8_BAR; PG8_MMA(0, 0, At, B0); PG8_MMA(0, 1, At, B1); PG8_BAR; PG8_SCHED;
	v_mul_f32_e32 v13, v231, v13
	v_mul_f32_e32 v14, v231, v14
	v_mul_f32_e32 v15, v231, v15
	v_mul_f32_e32 v8, v231, v8
	v_mfma_f32_16x16x32_bf16 v[68:71], v[176:179], v[216:219], 0
	v_mul_f32_e32 v9, v231, v9
	v_mul_f32_e32 v10, v231, v10
	v_mul_f32_e32 v11, v231, v11
	v_cvt_pk_bf16_f32 v12, v12, v13
	v_mfma_f32_16x16x32_bf16 v[64:67], v[184:187], v[216:219], 0
	v_cvt_pk_bf16_f32 v13, v14, v15
	v_cvt_pk_bf16_f32 v14, v8, v9
	v_cvt_pk_bf16_f32 v15, v10, v11
	global_store_dwordx4 v[232:233], v[12:15], off
	v_mfma_f32_16x16x32_bf16 v[116:119], v[180:183], v[196:199], v[116:119]
	v_mul_f32_e32 v4, v231, v4
	v_mul_f32_e32 v5, v231, v5
	v_mul_f32_e32 v6, v231, v6
	v_mul_f32_e32 v7, v231, v7
	v_mfma_f32_16x16x32_bf16 v[112:115], v[188:191], v[196:199], v[112:115]
	v_mul_f32_e32 v0, v231, v0
	v_mul_f32_e32 v1, v231, v1
	v_mul_f32_e32 v2, v231, v2
	v_mul_f32_e32 v3, v231, v3
	v_mfma_f32_16x16x32_bf16 v[100:103], v[180:183], v[204:207], v[100:103]
	v_cvt_pk_bf16_f32 v4, v4, v5
	v_cvt_pk_bf16_f32 v5, v6, v7
	v_cvt_pk_bf16_f32 v6, v0, v1
	v_cvt_pk_bf16_f32 v7, v2, v3
	v_mfma_f32_16x16x32_bf16 v[96:99], v[188:191], v[204:207], v[96:99]
	global_store_dwordx4 v[232:233], v[4:7], off offset:256
	v_mfma_f32_16x16x32_bf16 v[84:87], v[180:183], v[212:215], v[84:87]
	v_mfma_f32_16x16x32_bf16 v[80:83], v[188:191], v[212:215], v[80:83]
	v_mfma_f32_16x16x32_bf16 v[68:71], v[180:183], v[240:243], v[68:71]
	v_mfma_f32_16x16x32_bf16 v[64:67], v[188:191], v[240:243], v[64:67]
	s_setprio 0
	s_barrier
	s_add_i32 s62, s33, s45
	v_lshl_add_u64 v[244:245], v[220:221], 0, v[168:169]
	s_mov_b32 m0, s62
	ds_read_b128 v[192:195], v151 offset:16384
	ds_read_b128 v[196:199], v151 offset:17408
	ds_read_b128 v[200:203], v151 offset:18432
	ds_read_b128 v[204:207], v151 offset:19456
	ds_read_b128 v[208:211], v151 offset:20480
	ds_read_b128 v[212:215], v151 offset:21504
	ds_read_b128 v[216:219], v151 offset:22528
	ds_read_b128 v[240:243], v151 offset:23552
	global_load_lds_dwordx4 v[244:245], off
	v_lshl_add_u64 v[246:247], v[220:221], 0, v[128:129]
	s_add_i32 m0, s62, 0x2000
	v_lshl_add_u64 v[220:221], v[220:221], 0, s[12:13]
	s_add_i32 s10, s10, s45
	global_load_lds_dwordx4 v[246:247], off
	v_lshl_add_u64 v[248:249], v[220:221], 0, v[168:169]
	s_mov_b32 m0, s10
	v_lshl_add_u64 v[220:221], v[220:221], 0, v[128:129]
	global_load_lds_dwordx4 v[248:249], off
	s_add_i32 m0, s10, 0x2000
	v_lshl_add_u64 v[250:251], v[146:147], 0, v[132:133]
	global_load_lds_dwordx4 v[220:221], off
	s_mov_b32 m0, s25
	v_lshl_add_u64 v[252:253], v[146:147], 0, v[130:131]
	global_load_lds_dwordx4 v[250:251], off
	s_mov_b32 m0, s50
	s_nop 0
	global_load_lds_dwordx4 v[252:253], off
	s_waitcnt vmcnt(24)
	s_waitcnt lgkmcnt(0)
	s_setprio 1
	s_barrier
	s_waitcnt lgkmcnt(0)
	v_mfma_f32_16x16x32_bf16 v[60:63], v[152:155], v[192:195], 0
	v_mfma_f32_16x16x32_bf16 v[56:59], v[160:163], v[192:195], 0
	v_mfma_f32_16x16x32_bf16 v[44:47], v[152:155], v[200:203], 0
	v_mfma_f32_16x16x32_bf16 v[40:43], v[160:163], v[200:203], 0
	v_mfma_f32_16x16x32_bf16 v[28:31], v[152:155], v[208:211], 0
	v_mfma_f32_16x16x32_bf16 v[24:27], v[160:163], v[208:211], 0
	v_mfma_f32_16x16x32_bf16 v[12:15], v[152:155], v[216:219], 0
	v_mfma_f32_16x16x32_bf16 v[8:11], v[160:163], v[216:219], 0
	v_mfma_f32_16x16x32_bf16 v[60:63], v[156:159], v[196:199], v[60:63]
	v_mfma_f32_16x16x32_bf16 v[56:59], v[164:167], v[196:199], v[56:59]
	v_mfma_f32_16x16x32_bf16 v[44:47], v[156:159], v[204:207], v[44:47]
	v_mfma_f32_16x16x32_bf16 v[40:43], v[164:167], v[204:207], v[40:43]
	v_mfma_f32_16x16x32_bf16 v[28:31], v[156:159], v[212:215], v[28:31]
	v_mfma_f32_16x16x32_bf16 v[24:27], v[164:167], v[212:215], v[24:27]
	v_mfma_f32_16x16x32_bf16 v[12:15], v[156:159], v[240:243], v[12:15]
	v_mfma_f32_16x16x32_bf16 v[8:11], v[164:167], v[240:243], v[8:11]
	s_setprio 0
	s_setprio 1
	v_mfma_f32_16x16x32_bf16 v[52:55], v[176:179], v[192:195], 0
	v_mfma_f32_16x16x32_bf16 v[48:51], v[184:187], v[192:195], 0
	v_mfma_f32_16x16x32_bf16 v[36:39], v[176:179], v[200:203], 0
	v_mfma_f32_16x16x32_bf16 v[32:35], v[184:187], v[200:203], 0
	v_mfma_f32_16x16x32_bf16 v[20:23], v[176:179], v[208:211], 0
	v_mfma_f32_16x16x32_bf16 v[16:19], v[184:187], v[208:211], 0
	v_mfma_f32_16x16x32_bf16 v[4:7], v[176:179], v[216:219], 0
	v_mfma_f32_16x16x32_bf16 v[0:3], v[184:187], v[216:219], 0
	v_mfma_f32_16x16x32_bf16 v[52:55], v[180:183], v[196:199], v[52:55]
	v_mfma_f32_16x16x32_bf16 v[48:51], v[188:191], v[196:199], v[48:51]
	v_mfma_f32_16x16x32_bf16 v[36:39], v[180:183], v[204:207], v[36:39]
	v_mfma_f32_16x16x32_bf16 v[32:35], v[188:191], v[204:207], v[32:35]
	v_mfma_f32_16x16x32_bf16 v[20:23], v[180:183], v[212:215], v[20:23]
	v_mfma_f32_16x16x32_bf16 v[16:19], v[188:191], v[212:215], v[16:19]
	v_mfma_f32_16x16x32_bf16 v[4:7], v[180:183], v[240:243], v[4:7]
	v_mfma_f32_16x16x32_bf16 v[0:3], v[188:191], v[240:243], v[0:3]
	s_setprio 0
	s_barrier
	s_add_i32 s10, 0, 0x18000
	v_add_u32_e32 v148, s10, v149
	s_add_i32 s62, 0, 0x1c000
	ds_read_b128 v[152:155], v148
	ds_read_b128 v[156:159], v148 offset:1024
	ds_read_b128 v[160:163], v148 offset:2048
	ds_read_b128 v[164:167], v148 offset:3072
	v_add_u32_e32 v148, s62, v149
	ds_read_b128 v[176:179], v148
	ds_read_b128 v[180:183], v148 offset:1024
	ds_read_b128 v[184:187], v148 offset:2048
	ds_read_b128 v[188:191], v148 offset:3072
	v_lshl_add_u64 v[146:147], v[146:147], 0, s[94:95]
	s_mov_b32 m0, s51
	v_lshl_add_u64 v[226:227], v[146:147], 0, v[132:133]
	ds_read_b128 v[192:195], v151 offset:32768
	ds_read_b128 v[196:199], v151 offset:33792
	ds_read_b128 v[200:203], v151 offset:34816
	ds_read_b128 v[204:207], v151 offset:35840
	ds_read_b128 v[208:211], v151 offset:36864
	ds_read_b128 v[212:215], v151 offset:37888
	ds_read_b128 v[216:219], v151 offset:38912
	ds_read_b128 v[240:243], v151 offset:39936
	global_load_lds_dwordx4 v[226:227], off
	v_lshl_add_u64 v[146:147], v[146:147], 0, v[130:131]
	s_mov_b32 m0, s52
	s_nop 0
	global_load_lds_dwordx4 v[146:147], off
	s_waitcnt vmcnt(16)
	s_waitcnt lgkmcnt(0)
	s_setprio 1
	s_barrier
; #define PG8_STAGE(bufoff, gbase, voff) do { _Pragma("unroll") for (int _i = 0; _i < 2; ++_i) \
;         __builtin_amdgcn_global_load_lds((const unsigned*)((const char*)(gbase) + (voff)[_i]), (LAS unsigned*)(lds + (bufoff) + ldsw + _i * 8192), 16, 0, 0); } while (0)
; #define PG8_LDA(dst, b, h) do { _Pragma("unroll") for (int m = 0; m < 4; ++m) _Pragma("unroll") for (int k = 0; k < 2; ++k) dst[m][k] = *(const LAS bf16x8*)(lds + PG8_SA(b, h) + aoff + m * 2048 + k * 1024); } while (0)
; #define PG8_MMA(ai, bj, At, Bt) do { __builtin_amdgcn_s_setprio(1); _Pragma("unroll") for (int k = 0; k < 2; ++k) _Pragma("unroll") for (int m = 0; m < 4; ++m) _Pragma("unroll") for (int n = 0; n < 2; ++n) \
;         acc[ai][bj][m][n] = __builtin_amdgcn_mfma_f32_16x16x32_bf16(Bt[n][k], At[m][k], acc[ai][bj][m][n], 0, 0, 0); __builtin_amdgcn_s_setprio(0); } while (0)
; #define PG8_WAIT_V(n) asm volatile("s_waitcnt vmcnt(" #n ")" ::: "memory")
; #define PG8_WAIT_L(n) asm volatile("s_waitcnt lgkmcnt(" #n ")" ::: "memory")
; #define PG8_BAR __builtin_amdgcn_s_barrier()
; #define PG8_SCHED __builtin_amdgcn_sched_barrier(0)
; template <class Epi, bool ALIGN_EPI>
; __device__ __forceinline__ void gemm_phase(LAS unsigned char* lds, const Gemm g, const StaticOrder& S, const Epi& E, const int tid) {
;     ...
;             PG8_WAIT_V(8); PG8_WAIT_L(0); PG8_BAR; PG8_MMA(0, 0, At, B0); PG8_MMA(0, 1, At, B1); PG8_BAR; PG8_SCHED;
;             PG8_LDA(At, 1, 1); PG8_STAGE(PG8_SB(1, 0), b3, voffB); PG8_STAGE(PG8_SB(1, 1), b3 + hB, voffB); PG8_STAGE(PG8_SA(1, 0), a3, voffA);
;             PG8_WAIT_V(8); PG8_WAIT_L(0); PG8_BAR; PG8_MMA(1, 0, At, B0); PG8_MMA(1, 1, At, B1); PG8_BAR; PG8_SCHED;
;         }
	s_waitcnt lgkmcnt(0)
	v_mfma_f32_16x16x32_bf16 v[124:127], v[152:155], v[192:195], v[124:127]
	v_mfma_f32_16x16x32_bf16 v[120:123], v[160:163], v[192:195], v[120:123]
	v_mfma_f32_16x16x32_bf16 v[108:111], v[152:155], v[200:203], v[108:111]
	v_mfma_f32_16x16x32_bf16 v[104:107], v[160:163], v[200:203], v[104:107]
	v_mfma_f32_16x16x32_bf16 v[92:95], v[152:155], v[208:211], v[92:95]
	v_mfma_f32_16x16x32_bf16 v[88:91], v[160:163], v[208:211], v[88:91]
	v_mfma_f32_16x16x32_bf16 v[76:79], v[152:155], v[216:219], v[76:79]
	v_mfma_f32_16x16x32_bf16 v[72:75], v[160:163], v[216:219], v[72:75]
	v_mfma_f32_16x16x32_bf16 v[124:127], v[156:159], v[196:199], v[124:127]
	v_mfma_f32_16x16x32_bf16 v[120:123], v[164:167], v[196:199], v[120:123]
	v_mfma_f32_16x16x32_bf16 v[108:111], v[156:159], v[204:207], v[108:111]
	v_mfma_f32_16x16x32_bf16 v[104:107], v[164:167], v[204:207], v[104:107]
	v_mfma_f32_16x16x32_bf16 v[92:95], v[156:159], v[212:215], v[92:95]
	v_mfma_f32_16x16x32_bf16 v[88:91], v[164:167], v[212:215], v[88:91]
	v_mfma_f32_16x16x32_bf16 v[76:79], v[156:159], v[240:243], v[76:79]
	v_mfma_f32_16x16x32_bf16 v[72:75], v[164:167], v[240:243], v[72:75]
	s_setprio 0
	s_setprio 1
	v_mfma_f32_16x16x32_bf16 v[116:119], v[176:179], v[192:195], v[116:119]
	v_mfma_f32_16x16x32_bf16 v[112:115], v[184:187], v[192:195], v[112:115]
	v_mfma_f32_16x16x32_bf16 v[100:103], v[176:179], v[200:203], v[100:103]
	v_mfma_f32_16x16x32_bf16 v[96:99], v[184:187], v[200:203], v[96:99]
	v_mfma_f32_16x16x32_bf16 v[84:87], v[176:179], v[208:211], v[84:87]
	v_mfma_f32_16x16x32_bf16 v[80:83], v[184:187], v[208:211], v[80:83]
	v_mfma_f32_16x16x32_bf16 v[68:71], v[176:179], v[216:219], v[68:71]
	v_mfma_f32_16x16x32_bf16 v[64:67], v[184:187], v[216:219], v[64:67]
	v_mfma_f32_16x16x32_bf16 v[116:119], v[180:183], v[196:199], v[116:119]
	v_mfma_f32_16x16x32_bf16 v[112:115], v[188:191], v[196:199], v[112:115]
	v_mfma_f32_16x16x32_bf16 v[100:103], v[180:183], v[204:207], v[100:103]
	v_mfma_f32_16x16x32_bf16 v[96:99], v[188:191], v[204:207], v[96:99]
	v_mfma_f32_16x16x32_bf16 v[84:87], v[180:183], v[212:215], v[84:87]
	v_mfma_f32_16x16x32_bf16 v[80:83], v[188:191], v[212:215], v[80:83]
	v_mfma_f32_16x16x32_bf16 v[68:71], v[180:183], v[240:243], v[68:71]
	v_mfma_f32_16x16x32_bf16 v[64:67], v[188:191], v[240:243], v[64:67]
	s_setprio 0
	s_barrier
	s_add_i32 s10, s10, s45
	v_lshl_add_u64 v[146:147], v[244:245], 0, s[92:93]
	s_mov_b32 m0, s10
	ds_read_b128 v[192:195], v151 offset:49152
	ds_read_b128 v[196:199], v151 offset:50176
	ds_read_b128 v[200:203], v151 offset:51200
	ds_read_b128 v[204:207], v151 offset:52224
	ds_read_b128 v[208:211], v151 offset:53248
	ds_read_b128 v[212:215], v151 offset:54272
	ds_read_b128 v[216:219], v151 offset:55296
	ds_read_b128 v[240:243], v151 offset:56320
	global_load_lds_dwordx4 v[146:147], off
	v_lshl_add_u64 v[146:147], v[246:247], 0, s[92:93]
	s_add_i32 m0, s10, 0x2000
	s_add_i32 s10, s62, s45
	global_load_lds_dwordx4 v[146:147], off
	v_lshl_add_u64 v[146:147], v[248:249], 0, s[92:93]
	s_mov_b32 m0, s10
	s_nop 0
	global_load_lds_dwordx4 v[146:147], off
	v_lshl_add_u64 v[146:147], v[220:221], 0, s[92:93]
	s_add_i32 m0, s10, 0x2000
	s_nop 0
	global_load_lds_dwordx4 v[146:147], off
	v_lshl_add_u64 v[146:147], v[250:251], 0, s[92:93]
	s_mov_b32 m0, s53
	s_nop 0
	global_load_lds_dwordx4 v[146:147], off
	v_lshl_add_u64 v[146:147], v[252:253], 0, s[92:93]
	s_mov_b32 m0, s54
	s_nop 0
	global_load_lds_dwordx4 v[146:147], off
	s_waitcnt vmcnt(8)
	s_waitcnt lgkmcnt(0)
	s_setprio 1
	s_barrier
	s_waitcnt lgkmcnt(0)
	v_mfma_f32_16x16x32_bf16 v[60:63], v[152:155], v[192:195], v[60:63]
	v_mfma_f32_16x16x32_bf16 v[56:59], v[160:163], v[192:195], v[56:59]
	v_mfma_f32_16x16x32_bf16 v[44:47], v[152:155], v[200:203], v[44:47]
	v_mfma_f32_16x16x32_bf16 v[40:43], v[160:163], v[200:203], v[40:43]
	v_mfma_f32_16x16x32_bf16 v[28:31], v[152:155], v[208:211], v[28:31]
	v_mfma_f32_16x16x32_bf16 v[24:27], v[160:163], v[208:211], v[24:27]
	v_mfma_f32_16x16x32_bf16 v[12:15], v[152:155], v[216:219], v[12:15]
	v_mfma_f32_16x16x32_bf16 v[8:11], v[160:163], v[216:219], v[8:11]
	v_mfma_f32_16x16x32_bf16 v[60:63], v[156:159], v[196:199], v[60:63]
	v_mfma_f32_16x16x32_bf16 v[56:59], v[164:167], v[196:199], v[56:59]
	v_mfma_f32_16x16x32_bf16 v[44:47], v[156:159], v[204:207], v[44:47]
	v_mfma_f32_16x16x32_bf16 v[40:43], v[164:167], v[204:207], v[40:43]
	v_mfma_f32_16x16x32_bf16 v[28:31], v[156:159], v[212:215], v[28:31]
	v_mfma_f32_16x16x32_bf16 v[24:27], v[164:167], v[212:215], v[24:27]
	v_mfma_f32_16x16x32_bf16 v[12:15], v[156:159], v[240:243], v[12:15]
	v_mfma_f32_16x16x32_bf16 v[8:11], v[164:167], v[240:243], v[8:11]
	s_setprio 0
	s_setprio 1
	v_mfma_f32_16x16x32_bf16 v[52:55], v[176:179], v[192:195], v[52:55]
	v_mfma_f32_16x16x32_bf16 v[48:51], v[184:187], v[192:195], v[48:51]
	v_mfma_f32_16x16x32_bf16 v[36:39], v[176:179], v[200:203], v[36:39]
	v_mfma_f32_16x16x32_bf16 v[32:35], v[184:187], v[200:203], v[32:35]
	v_mfma_f32_16x16x32_bf16 v[20:23], v[176:179], v[208:211], v[20:23]
	v_mfma_f32_16x16x32_bf16 v[16:19], v[184:187], v[208:211], v[16:19]
	v_mfma_f32_16x16x32_bf16 v[4:7], v[176:179], v[216:219], v[4:7]
	v_mfma_f32_16x16x32_bf16 v[0:3], v[184:187], v[216:219], v[0:3]
	v_mfma_f32_16x16x32_bf16 v[52:55], v[180:183], v[196:199], v[52:55]
	v_mfma_f32_16x16x32_bf16 v[48:51], v[188:191], v[196:199], v[48:51]
	v_mfma_f32_16x16x32_bf16 v[36:39], v[180:183], v[204:207], v[36:39]
	v_mfma_f32_16x16x32_bf16 v[32:35], v[188:191], v[204:207], v[32:35]
	v_mfma_f32_16x16x32_bf16 v[20:23], v[180:183], v[212:215], v[20:23]
	v_mfma_f32_16x16x32_bf16 v[16:19], v[188:191], v[212:215], v[16:19]
	v_mfma_f32_16x16x32_bf16 v[4:7], v[180:183], v[240:243], v[4:7]
	v_mfma_f32_16x16x32_bf16 v[0:3], v[188:191], v[240:243], v[0:3]
	s_setprio 0
	s_barrier
	v_lshl_add_u64 v[142:143], v[142:143], 0, s[80:81]
	v_lshl_add_u64 v[144:145], v[144:145], 0, s[80:81]
	s_mov_b32 s10, s11
	s_cmp_eq_u32 s10, s55
	s_cbranch_scc1 .Lq5_last
	s_branch .LBB0_354
; #define PG8_STAGE(bufoff, gbase, voff) do { _Pragma("unroll") for (int _i = 0; _i < 2; ++_i) \
;         __builtin_amdgcn_global_load_lds((const unsigned*)((const char*)(gbase) + (voff)[_i]), (LAS unsigned*)(lds + (bufoff) + ldsw + _i * 8192), 16, 0, 0); } while (0)
; #define PG8_LDA(dst, b, h) do { _Pragma("unroll") for (int m = 0; m < 4; ++m) _Pragma("unroll") for (int k = 0; k < 2; ++k) dst[m][k] = *(const LAS bf16x8*)(lds + PG8_SA(b, h) + aoff + m * 2048 + k * 1024); } while (0)
; #define PG8_LDB(dst, b, h) do { _Pragma("unroll") for (int n = 0; n < 2; ++n) _Pragma("unroll") for (int k = 0; k < 2; ++k) dst[n][k] = *(const LAS bf16x8*)(lds + PG8_SB(b, h) + boff + n * 2048 + k * 1024); } while (0)
; #define PG8_MMA(ai, bj, At, Bt) do { __builtin_amdgcn_s_setprio(1); _Pragma("unroll") for (int k = 0; k < 2; ++k) _Pragma("unroll") for (int m = 0; m < 4; ++m) _Pragma("unroll") for (int n = 0; n < 2; ++n) \
;         acc[ai][bj][m][n] = __builtin_amdgcn_mfma_f32_16x16x32_bf16(Bt[n][k], At[m][k], acc[ai][bj][m][n], 0, 0, 0); __builtin_amdgcn_s_setprio(0); } while (0)
; #define PG8_WAIT_V(n) asm volatile("s_waitcnt vmcnt(" #n ")" ::: "memory")
; #define PG8_WAIT_L(n) asm volatile("s_waitcnt lgkmcnt(" #n ")" ::: "memory")
; #define PG8_BAR __builtin_amdgcn_s_barrier()
; #define PG8_SCHED __builtin_amdgcn_sched_barrier(0)
; template <class Epi, bool ALIGN_EPI>
; __device__ __forceinline__ void gemm_phase(LAS unsigned char* lds, const Gemm g, const StaticOrder& S, const Epi& E, const int tid) {
;     ...
;         for (int t = 0; t < nt; t += 2) {
;             const bool last = (t == nt - 2);
;             const char* a1 = cA + (size_t)(t + 1) * kstep;
;             const char* a2 = last ? nA : cA + (size_t)(t + 2) * kstep; const char* b2 = last ? nB : cB + (size_t)(t + 2) * kstep;
;             const char* a3 = a2 + kstep; const char* b3 = b2 + kstep;
;             PG8_LDB(B0, 0, 0); PG8_LDB(B1, 0, 1); PG8_SCHED; PG8_LDA(At, 0, 0); PG8_STAGE(PG8_SA(1, 1), a1 + hA, voffA);
;             PG8_WAIT_V(8); PG8_WAIT_L(0); PG8_BAR; PG8_MMA(0, 0, At, B0); PG8_MMA(0, 1, At, B1); PG8_BAR; PG8_SCHED;
;             PG8_LDA(At, 0, 1); PG8_STAGE(PG8_SB(0, 0), b2, voffB); PG8_STAGE(PG8_SB(0, 1), b2 + hB, voffB); PG8_STAGE(PG8_SA(0, 0), a2, voffA);
;             PG8_WAIT_V(8); PG8_WAIT_L(0); PG8_BAR; PG8_MMA(1, 0, At, B0); PG8_MMA(1, 1, At, B1); PG8_BAR; PG8_SCHED;
.Lq5_first:
	s_add_i32 s11, s10, 2
	s_cmp_eq_u32 s55, s10
	s_cselect_b64 vcc, -1, 0
	v_add_u32_e32 v148, s33, v149
	s_add_i32 s10, 0, 0x14000
	ds_read_b128 v[152:155], v148
	ds_read_b128 v[156:159], v148 offset:1024
	ds_read_b128 v[160:163], v148 offset:2048
	ds_read_b128 v[164:167], v148 offset:3072
	v_add_u32_e32 v148, s10, v149
	ds_read_b128 v[176:179], v148
	ds_read_b128 v[180:183], v148 offset:1024
	ds_read_b128 v[184:187], v148 offset:2048
	ds_read_b128 v[188:191], v148 offset:3072
	v_lshl_add_u64 v[146:147], v[142:143], 0, s[92:93]
	v_cndmask_b32_e32 v147, v147, v139, vcc
	v_cndmask_b32_e32 v146, v146, v138, vcc
	v_cndmask_b32_e32 v221, v145, v141, vcc
	v_cndmask_b32_e32 v220, v144, v140, vcc
	v_lshl_add_u64 v[244:245], v[142:143], 0, v[134:135]
	s_add_i32 m0, s25, 0xc000
	ds_read_b128 v[192:195], v151
	ds_read_b128 v[196:199], v151 offset:1024
	ds_read_b128 v[200:203], v151 offset:2048
	ds_read_b128 v[204:207], v151 offset:3072
	ds_read_b128 v[208:211], v151 offset:4096
	ds_read_b128 v[212:215], v151 offset:5120
	ds_read_b128 v[216:219], v151 offset:6144
	ds_read_b128 v[240:243], v151 offset:7168
	global_load_lds_dwordx4 v[244:245], off
	v_lshl_add_u64 v[244:245], v[142:143], 0, v[136:137]
	s_add_i32 m0, s25, 0xe000
	s_nop 0
	global_load_lds_dwordx4 v[244:245], off
	s_waitcnt vmcnt(8)
	s_waitcnt lgkmcnt(0)
	s_setprio 1
	s_barrier
	s_waitcnt lgkmcnt(0)
	v_mfma_f32_16x16x32_bf16 v[124:127], v[152:155], v[192:195], 0
	v_mfma_f32_16x16x32_bf16 v[120:123], v[160:163], v[192:195], 0
	v_mfma_f32_16x16x32_bf16 v[108:111], v[152:155], v[200:203], 0
	v_mfma_f32_16x16x32_bf16 v[104:107], v[160:163], v[200:203], 0
	v_mfma_f32_16x16x32_bf16 v[92:95], v[152:155], v[208:211], 0
	v_mfma_f32_16x16x32_bf16 v[88:91], v[160:163], v[208:211], 0
	v_mfma_f32_16x16x32_bf16 v[76:79], v[152:155], v[216:219], 0
	v_mfma_f32_16x16x32_bf16 v[72:75], v[160:163], v[216:219], 0
	v_mfma_f32_16x16x32_bf16 v[124:127], v[156:159], v[196:199], v[124:127]
	v_mfma_f32_16x16x32_bf16 v[120:123], v[164:167], v[196:199], v[120:123]
	v_mfma_f32_16x16x32_bf16 v[108:111], v[156:159], v[204:207], v[108:111]
	v_mfma_f32_16x16x32_bf16 v[104:107], v[164:167], v[204:207], v[104:107]
	v_mfma_f32_16x16x32_bf16 v[92:95], v[156:159], v[212:215], v[92:95]
	v_mfma_f32_16x16x32_bf16 v[88:91], v[164:167], v[212:215], v[88:91]
	v_mfma_f32_16x16x32_bf16 v[76:79], v[156:159], v[240:243], v[76:79]
	v_mfma_f32_16x16x32_bf16 v[72:75], v[164:167], v[240:243], v[72:75]
	s_setprio 0
	s_setprio 1
	v_mfma_f32_16x16x32_bf16 v[116:119], v[176:179], v[192:195], 0
	v_mfma_f32_16x16x32_bf16 v[112:115], v[184:187], v[192:195], 0
	v_mfma_f32_16x16x32_bf16 v[100:103], v[176:179], v[200:203], 0
	v_mfma_f32_16x16x32_bf16 v[96:99], v[184:187], v[200:203], 0
	v_mfma_f32_16x16x32_bf16 v[84:87], v[176:179], v[208:211], 0
	v_mfma_f32_16x16x32_bf16 v[80:83], v[184:187], v[208:211], 0
	v_mfma_f32_16x16x32_bf16 v[68:71], v[176:179], v[216:219], 0
	v_mfma_f32_16x16x32_bf16 v[64:67], v[184:187], v[216:219], 0
	v_mfma_f32_16x16x32_bf16 v[116:119], v[180:183], v[196:199], v[116:119]
	v_mfma_f32_16x16x32_bf16 v[112:115], v[188:191], v[196:199], v[112:115]
	v_mfma_f32_16x16x32_bf16 v[100:103], v[180:183], v[204:207], v[100:103]
	v_mfma_f32_16x16x32_bf16 v[96:99], v[188:191], v[204:207], v[96:99]
	v_mfma_f32_16x16x32_bf16 v[84:87], v[180:183], v[212:215], v[84:87]
	v_mfma_f32_16x16x32_bf16 v[80:83], v[188:191], v[212:215], v[80:83]
	v_mfma_f32_16x16x32_bf16 v[68:71], v[180:183], v[240:243], v[68:71]
	v_mfma_f32_16x16x32_bf16 v[64:67], v[188:191], v[240:243], v[64:67]
	s_setprio 0
	s_barrier
	s_add_i32 s62, s33, s45
	v_lshl_add_u64 v[244:245], v[220:221], 0, v[168:169]
	s_mov_b32 m0, s62
	ds_read_b128 v[192:195], v151 offset:16384
	ds_read_b128 v[196:199], v151 offset:17408
	ds_read_b128 v[200:203], v151 offset:18432
	ds_read_b128 v[204:207], v151 offset:19456
	ds_read_b128 v[208:211], v151 offset:20480
	ds_read_b128 v[212:215], v151 offset:21504
	ds_read_b128 v[216:219], v151 offset:22528
	ds_read_b128 v[240:243], v151 offset:23552
	global_load_lds_dwordx4 v[244:245], off
	v_lshl_add_u64 v[246:247], v[220:221], 0, v[128:129]
	s_add_i32 m0, s62, 0x2000
	v_lshl_add_u64 v[220:221], v[220:221], 0, s[12:13]
	s_add_i32 s10, s10, s45
	global_load_lds_dwordx4 v[246:247], off
	v_lshl_add_u64 v[248:249], v[220:221], 0, v[168:169]
	s_mov_b32 m0, s10
	v_lshl_add_u64 v[220:221], v[220:221], 0, v[128:129]
	global_load_lds_dwordx4 v[248:249], off
	s_add_i32 m0, s10, 0x2000
	v_lshl_add_u64 v[250:251], v[146:147], 0, v[132:133]
	global_load_lds_dwordx4 v[220:221], off
	s_mov_b32 m0, s25
	v_lshl_add_u64 v[252:253], v[146:147], 0, v[130:131]
	global_load_lds_dwordx4 v[250:251], off
	s_mov_b32 m0, s50
	s_nop 0
	global_load_lds_dwordx4 v[252:253], off
	s_waitcnt vmcnt(8)
	s_waitcnt lgkmcnt(0)
	s_setprio 1
	s_barrier
; #define PG8_STAGE(bufoff, gbase, voff) do { _Pragma("unroll") for (int _i = 0; _i < 2; ++_i) \
;         __builtin_amdgcn_global_load_lds((const unsigned*)((const char*)(gbase) + (voff)[_i]), (LAS unsigned*)(lds + (bufoff) + ldsw + _i * 8192), 16, 0, 0); } while (0)
; #define PG8_LDA(dst, b, h) do { _Pragma("unroll") for (int m = 0; m < 4; ++m) _Pragma("unroll") for (int k = 0; k < 2; ++k) dst[m][k] = *(const LAS bf16x8*)(lds + PG8_SA(b, h) + aoff + m * 2048 + k * 1024); } while (0)
; #define PG8_LDB(dst, b, h) do { _Pragma("unroll") for (int n = 0; n < 2; ++n) _Pragma("unroll") for (int k = 0; k < 2; ++k) dst[n][k] = *(const LAS bf16x8*)(lds + PG8_SB(b, h) + boff + n * 2048 + k * 1024); } while (0)
; #define PG8_MMA(ai, bj, At, Bt) do { __builtin_amdgcn_s_setprio(1); _Pragma("unroll") for (int k = 0; k < 2; ++k) _Pragma("unroll") for (int m = 0; m < 4; ++m) _Pragma("unroll") for (int n = 0; n < 2; ++n) \
;         acc[ai][bj][m][n] = __builtin_amdgcn_mfma_f32_16x16x32_bf16(Bt[n][k], At[m][k], acc[ai][bj][m][n], 0, 0, 0); __builtin_amdgcn_s_setprio(0); } while (0)
; #define PG8_WAIT_V(n) asm volatile("s_waitcnt vmcnt(" #n ")" ::: "memory")
; #define PG8_WAIT_L(n) asm volatile("s_waitcnt lgkmcnt(" #n ")" ::: "memory")
; #define PG8_BAR __builtin_amdgcn_s_barrier()
; #define PG8_SCHED __builtin_amdgcn_sched_barrier(0)
; template <class Epi, bool ALIGN_EPI>
; __device__ __forceinline__ void gemm_phase(LAS unsigned char* lds, const Gemm g, const StaticOrder& S, const Epi& E, const int tid) {
;     ...
;             PG8_WAIT_V(8); PG8_WAIT_L(0); PG8_BAR; PG8_MMA(1, 0, At, B0); PG8_MMA(1, 1, At, B1); PG8_BAR; PG8_SCHED;
;             PG8_LDB(B0, 1, 0); PG8_LDB(B1, 1, 1); PG8_SCHED; PG8_LDA(At, 1, 0); PG8_STAGE(PG8_SA(0, 1), a2 + hA, voffA);
;             PG8_WAIT_V(8); PG8_WAIT_L(0); PG8_BAR; PG8_MMA(0, 0, At, B0); PG8_MMA(0, 1, At, B1); PG8_BAR; PG8_SCHED;
;             PG8_LDA(At, 1, 1); PG8_STAGE(PG8_SB(1, 0), b3, voffB); PG8_STAGE(PG8_SB(1, 1), b3 + hB, voffB); PG8_STAGE(PG8_SA(1, 0), a3, voffA);
	s_waitcnt lgkmcnt(0)
	v_mfma_f32_16x16x32_bf16 v[60:63], v[152:155], v[192:195], 0
	v_mfma_f32_16x16x32_bf16 v[56:59], v[160:163], v[192:195], 0
	v_mfma_f32_16x16x32_bf16 v[44:47], v[152:155], v[200:203], 0
	v_mfma_f32_16x16x32_bf16 v[40:43], v[160:163], v[200:203], 0
	v_mfma_f32_16x16x32_bf16 v[28:31], v[152:155], v[208:211], 0
	v_mfma_f32_16x16x32_bf16 v[24:27], v[160:163], v[208:211], 0
	v_mfma_f32_16x16x32_bf16 v[12:15], v[152:155], v[216:219], 0
	v_mfma_f32_16x16x32_bf16 v[8:11], v[160:163], v[216:219], 0
	v_mfma_f32_16x16x32_bf16 v[60:63], v[156:159], v[196:199], v[60:63]
	v_mfma_f32_16x16x32_bf16 v[56:59], v[164:167], v[196:199], v[56:59]
	v_mfma_f32_16x16x32_bf16 v[44:47], v[156:159], v[204:207], v[44:47]
	v_mfma_f32_16x16x32_bf16 v[40:43], v[164:167], v[204:207], v[40:43]
	v_mfma_f32_16x16x32_bf16 v[28:31], v[156:159], v[212:215], v[28:31]
	v_mfma_f32_16x16x32_bf16 v[24:27], v[164:167], v[212:215], v[24:27]
	v_mfma_f32_16x16x32_bf16 v[12:15], v[156:159], v[240:243], v[12:15]
	v_mfma_f32_16x16x32_bf16 v[8:11], v[164:167], v[240:243], v[8:11]
	s_setprio 0
	s_setprio 1
	v_mfma_f32_16x16x32_bf16 v[52:55], v[176:179], v[192:195], 0
	v_mfma_f32_16x16x32_bf16 v[48:51], v[184:187], v[192:195], 0
	v_mfma_f32_16x16x32_bf16 v[36:39], v[176:179], v[200:203], 0
	v_mfma_f32_16x16x32_bf16 v[32:35], v[184:187], v[200:203], 0
	v_mfma_f32_16x16x32_bf16 v[20:23], v[176:179], v[208:211], 0
	v_mfma_f32_16x16x32_bf16 v[16:19], v[184:187], v[208:211], 0
	v_mfma_f32_16x16x32_bf16 v[4:7], v[176:179], v[216:219], 0
	v_mfma_f32_16x16x32_bf16 v[0:3], v[184:187], v[216:219], 0
	v_mfma_f32_16x16x32_bf16 v[52:55], v[180:183], v[196:199], v[52:55]
	v_mfma_f32_16x16x32_bf16 v[48:51], v[188:191], v[196:199], v[48:51]
	v_mfma_f32_16x16x32_bf16 v[36:39], v[180:183], v[204:207], v[36:39]
	v_mfma_f32_16x16x32_bf16 v[32:35], v[188:191], v[204:207], v[32:35]
	v_mfma_f32_16x16x32_bf16 v[20:23], v[180:183], v[212:215], v[20:23]
	v_mfma_f32_16x16x32_bf16 v[16:19], v[188:191], v[212:215], v[16:19]
	v_mfma_f32_16x16x32_bf16 v[4:7], v[180:183], v[240:243], v[4:7]
	v_mfma_f32_16x16x32_bf16 v[0:3], v[188:191], v[240:243], v[0:3]
	s_setprio 0
	s_barrier
	s_add_i32 s10, 0, 0x18000
	v_add_u32_e32 v148, s10, v149
	s_add_i32 s62, 0, 0x1c000
	ds_read_b128 v[152:155], v148
	ds_read_b128 v[156:159], v148 offset:1024
	ds_read_b128 v[160:163], v148 offset:2048
	ds_read_b128 v[164:167], v148 offset:3072
	v_add_u32_e32 v148, s62, v149
	ds_read_b128 v[176:179], v148
	ds_read_b128 v[180:183], v148 offset:1024
	ds_read_b128 v[184:187], v148 offset:2048
	ds_read_b128 v[188:191], v148 offset:3072
	v_lshl_add_u64 v[146:147], v[146:147], 0, s[94:95]
	s_mov_b32 m0, s51
	v_lshl_add_u64 v[226:227], v[146:147], 0, v[132:133]
	ds_read_b128 v[192:195], v151 offset:32768
	ds_read_b128 v[196:199], v151 offset:33792
	ds_read_b128 v[200:203], v151 offset:34816
	ds_read_b128 v[204:207], v151 offset:35840
	ds_read_b128 v[208:211], v151 offset:36864
	ds_read_b128 v[212:215], v151 offset:37888
	ds_read_b128 v[216:219], v151 offset:38912
	ds_read_b128 v[240:243], v151 offset:39936
	global_load_lds_dwordx4 v[226:227], off
	v_lshl_add_u64 v[146:147], v[146:147], 0, v[130:131]
	s_mov_b32 m0, s52
	s_nop 0
	global_load_lds_dwordx4 v[146:147], off
	s_waitcnt vmcnt(8)
	s_waitcnt lgkmcnt(0)
	s_setprio 1
	s_barrier
	s_waitcnt lgkmcnt(0)
	v_mfma_f32_16x16x32_bf16 v[124:127], v[152:155], v[192:195], v[124:127]
	v_mfma_f32_16x16x32_bf16 v[120:123], v[160:163], v[192:195], v[120:123]
	v_mfma_f32_16x16x32_bf16 v[108:111], v[152:155], v[200:203], v[108:111]
	v_mfma_f32_16x16x32_bf16 v[104:107], v[160:163], v[200:203], v[104:107]
	v_mfma_f32_16x16x32_bf16 v[92:95], v[152:155], v[208:211], v[92:95]
	v_mfma_f32_16x16x32_bf16 v[88:91], v[160:163], v[208:211], v[88:91]
	v_mfma_f32_16x16x32_bf16 v[76:79], v[152:155], v[216:219], v[76:79]
	v_mfma_f32_16x16x32_bf16 v[72:75], v[160:163], v[216:219], v[72:75]
	v_mfma_f32_16x16x32_bf16 v[124:127], v[156:159], v[196:199], v[124:127]
	v_mfma_f32_16x16x32_bf16 v[120:123], v[164:167], v[196:199], v[120:123]
	v_mfma_f32_16x16x32_bf16 v[108:111], v[156:159], v[204:207], v[108:111]
	v_mfma_f32_16x16x32_bf16 v[104:107], v[164:167], v[204:207], v[104:107]
	v_mfma_f32_16x16x32_bf16 v[92:95], v[156:159], v[212:215], v[92:95]
	v_mfma_f32_16x16x32_bf16 v[88:91], v[164:167], v[212:215], v[88:91]
	v_mfma_f32_16x16x32_bf16 v[76:79], v[156:159], v[240:243], v[76:79]
	v_mfma_f32_16x16x32_bf16 v[72:75], v[164:167], v[240:243], v[72:75]
	s_setprio 0
	s_setprio 1
	v_mfma_f32_16x16x32_bf16 v[116:119], v[176:179], v[192:195], v[116:119]
	v_mfma_f32_16x16x32_bf16 v[112:115], v[184:187], v[192:195], v[112:115]
	v_mfma_f32_16x16x32_bf16 v[100:103], v[176:179], v[200:203], v[100:103]
	v_mfma_f32_16x16x32_bf16 v[96:99], v[184:187], v[200:203], v[96:99]
	v_mfma_f32_16x16x32_bf16 v[84:87], v[176:179], v[208:211], v[84:87]
	v_mfma_f32_16x16x32_bf16 v[80:83], v[184:187], v[208:211], v[80:83]
	v_mfma_f32_16x16x32_bf16 v[68:71], v[176:179], v[216:219], v[68:71]
	v_mfma_f32_16x16x32_bf16 v[64:67], v[184:187], v[216:219], v[64:67]
	v_mfma_f32_16x16x32_bf16 v[116:119], v[180:183], v[196:199], v[116:119]
	v_mfma_f32_16x16x32_bf16 v[112:115], v[188:191], v[196:199], v[112:115]
	v_mfma_f32_16x16x32_bf16 v[100:103], v[180:183], v[204:207], v[100:103]
	v_mfma_f32_16x16x32_bf16 v[96:99], v[188:191], v[204:207], v[96:99]
	v_mfma_f32_16x16x32_bf16 v[84:87], v[180:183], v[212:215], v[84:87]
	v_mfma_f32_16x16x32_bf16 v[80:83], v[188:191], v[212:215], v[80:83]
	v_mfma_f32_16x16x32_bf16 v[68:71], v[180:183], v[240:243], v[68:71]
	v_mfma_f32_16x16x32_bf16 v[64:67], v[188:191], v[240:243], v[64:67]
	s_setprio 0
	s_barrier
; #define PG8_STAGE(bufoff, gbase, voff) do { _Pragma("unroll") for (int _i = 0; _i < 2; ++_i) \
;         __builtin_amdgcn_global_load_lds((const unsigned*)((const char*)(gbase) + (voff)[_i]), (LAS unsigned*)(lds + (bufoff) + ldsw + _i * 8192), 16, 0, 0); } while (0)
; #define PG8_LDA(dst, b, h) do { _Pragma("unroll") for (int m = 0; m < 4; ++m) _Pragma("unroll") for (int k = 0; k < 2; ++k) dst[m][k] = *(const LAS bf16x8*)(lds + PG8_SA(b, h) + aoff + m * 2048 + k * 1024); } while (0)
; #define PG8_LDB(dst, b, h) do { _Pragma("unroll") for (int n = 0; n < 2; ++n) _Pragma("unroll") for (int k = 0; k < 2; ++k) dst[n][k] = *(const LAS bf16x8*)(lds + PG8_SB(b, h) + boff + n * 2048 + k * 1024); } while (0)
; #define PG8_MMA(ai, bj, At, Bt) do { __builtin_amdgcn_s_setprio(1); _Pragma("unroll") for (int k = 0; k < 2; ++k) _Pragma("unroll") for (int m = 0; m < 4; ++m) _Pragma("unroll") for (int n = 0; n < 2; ++n) \
;         acc[ai][bj][m][n] = __builtin_amdgcn_mfma_f32_16x16x32_bf16(Bt[n][k], At[m][k], acc[ai][bj][m][n], 0, 0, 0); __builtin_amdgcn_s_setprio(0); } while (0)
; #define PG8_WAIT_V(n) asm volatile("s_waitcnt vmcnt(" #n ")" ::: "memory")
; #define PG8_WAIT_L(n) asm volatile("s_waitcnt lgkmcnt(" #n ")" ::: "memory")
; #define PG8_BAR __builtin_amdgcn_s_barrier()
; #define PG8_SCHED __builtin_amdgcn_sched_barrier(0)
; template <class Epi, bool ALIGN_EPI>
; __device__ __forceinline__ void gemm_phase(LAS unsigned char* lds, const Gemm g, const StaticOrder& S, const Epi& E, const int tid) {
;     ...
;             PG8_LDB(B0, 0, 0); PG8_LDB(B1, 0, 1); PG8_SCHED; PG8_LDA(At, 0, 0); PG8_STAGE(PG8_SA(1, 1), a1 + hA, voffA);
;             PG8_WAIT_V(8); PG8_WAIT_L(0); PG8_BAR; PG8_MMA(0, 0, At, B0); PG8_MMA(0, 1, At, B1); PG8_BAR; PG8_SCHED;
;     ...
;             PG8_LDA(At, 1, 1); PG8_STAGE(PG8_SB(1, 0), b3, voffB); PG8_STAGE(PG8_SB(1, 1), b3 + hB, voffB); PG8_STAGE(PG8_SA(1, 0), a3, voffA);
;             PG8_WAIT_V(8); PG8_WAIT_L(0); PG8_BAR; PG8_MMA(1, 0, At, B0); PG8_MMA(1, 1, At, B1); PG8_BAR; PG8_SCHED;
	s_add_i32 s10, s10, s45
	v_lshl_add_u64 v[146:147], v[244:245], 0, s[92:93]
	s_mov_b32 m0, s10
	ds_read_b128 v[192:195], v151 offset:49152
	ds_read_b128 v[196:199], v151 offset:50176
	ds_read_b128 v[200:203], v151 offset:51200
	ds_read_b128 v[204:207], v151 offset:52224
	ds_read_b128 v[208:211], v151 offset:53248
	ds_read_b128 v[212:215], v151 offset:54272
	ds_read_b128 v[216:219], v151 offset:55296
	ds_read_b128 v[240:243], v151 offset:56320
	global_load_lds_dwordx4 v[146:147], off
	v_lshl_add_u64 v[146:147], v[246:247], 0, s[92:93]
	s_add_i32 m0, s10, 0x2000
	s_add_i32 s10, s62, s45
	global_load_lds_dwordx4 v[146:147], off
	v_lshl_add_u64 v[146:147], v[248:249], 0, s[92:93]
	s_mov_b32 m0, s10
	s_nop 0
	global_load_lds_dwordx4 v[146:147], off
	v_lshl_add_u64 v[146:147], v[220:221], 0, s[92:93]
	s_add_i32 m0, s10, 0x2000
	s_nop 0
	global_load_lds_dwordx4 v[146:147], off
	v_lshl_add_u64 v[146:147], v[250:251], 0, s[92:93]
	s_mov_b32 m0, s53
	s_nop 0
	global_load_lds_dwordx4 v[146:147], off
	v_lshl_add_u64 v[146:147], v[252:253], 0, s[92:93]
	s_mov_b32 m0, s54
	s_nop 0
	global_load_lds_dwordx4 v[146:147], off
	s_waitcnt vmcnt(8)
	s_waitcnt lgkmcnt(0)
	s_setprio 1
	s_barrier
	s_waitcnt lgkmcnt(0)
	v_mfma_f32_16x16x32_bf16 v[60:63], v[152:155], v[192:195], v[60:63]
	v_mfma_f32_16x16x32_bf16 v[56:59], v[160:163], v[192:195], v[56:59]
	v_mfma_f32_16x16x32_bf16 v[44:47], v[152:155], v[200:203], v[44:47]
	v_mfma_f32_16x16x32_bf16 v[40:43], v[160:163], v[200:203], v[40:43]
	v_mfma_f32_16x16x32_bf16 v[28:31], v[152:155], v[208:211], v[28:31]
	v_mfma_f32_16x16x32_bf16 v[24:27], v[160:163], v[208:211], v[24:27]
	v_mfma_f32_16x16x32_bf16 v[12:15], v[152:155], v[216:219], v[12:15]
	v_mfma_f32_16x16x32_bf16 v[8:11], v[160:163], v[216:219], v[8:11]
	v_mfma_f32_16x16x32_bf16 v[60:63], v[156:159], v[196:199], v[60:63]
	v_mfma_f32_16x16x32_bf16 v[56:59], v[164:167], v[196:199], v[56:59]
	v_mfma_f32_16x16x32_bf16 v[44:47], v[156:159], v[204:207], v[44:47]
	v_mfma_f32_16x16x32_bf16 v[40:43], v[164:167], v[204:207], v[40:43]
	v_mfma_f32_16x16x32_bf16 v[28:31], v[156:159], v[212:215], v[28:31]
	v_mfma_f32_16x16x32_bf16 v[24:27], v[164:167], v[212:215], v[24:27]
	v_mfma_f32_16x16x32_bf16 v[12:15], v[156:159], v[240:243], v[12:15]
	v_mfma_f32_16x16x32_bf16 v[8:11], v[164:167], v[240:243], v[8:11]
	s_setprio 0
	s_setprio 1
	v_mfma_f32_16x16x32_bf16 v[52:55], v[176:179], v[192:195], v[52:55]
	v_mfma_f32_16x16x32_bf16 v[48:51], v[184:187], v[192:195], v[48:51]
	v_mfma_f32_16x16x32_bf16 v[36:39], v[176:179], v[200:203], v[36:39]
	v_mfma_f32_16x16x32_bf16 v[32:35], v[184:187], v[200:203], v[32:35]
	v_mfma_f32_16x16x32_bf16 v[20:23], v[176:179], v[208:211], v[20:23]
	v_mfma_f32_16x16x32_bf16 v[16:19], v[184:187], v[208:211], v[16:19]
	v_mfma_f32_16x16x32_bf16 v[4:7], v[176:179], v[216:219], v[4:7]
	v_mfma_f32_16x16x32_bf16 v[0:3], v[184:187], v[216:219], v[0:3]
	v_mfma_f32_16x16x32_bf16 v[52:55], v[180:183], v[196:199], v[52:55]
	v_mfma_f32_16x16x32_bf16 v[48:51], v[188:191], v[196:199], v[48:51]
	v_mfma_f32_16x16x32_bf16 v[36:39], v[180:183], v[204:207], v[36:39]
	v_mfma_f32_16x16x32_bf16 v[32:35], v[188:191], v[204:207], v[32:35]
	v_mfma_f32_16x16x32_bf16 v[20:23], v[180:183], v[212:215], v[20:23]
	v_mfma_f32_16x16x32_bf16 v[16:19], v[188:191], v[212:215], v[16:19]
	v_mfma_f32_16x16x32_bf16 v[4:7], v[180:183], v[240:243], v[4:7]
	v_mfma_f32_16x16x32_bf16 v[0:3], v[188:191], v[240:243], v[0:3]
	s_setprio 0
	s_barrier
	v_lshl_add_u64 v[142:143], v[142:143], 0, s[80:81]
	v_lshl_add_u64 v[144:145], v[144:145], 0, s[80:81]
	s_mov_b32 s10, s11
	s_cmp_eq_u32 s10, s55
	s_cbranch_scc1 .Lq5_last
.LBB0_354:
	s_add_i32 s11, s10, 2
	s_cmp_eq_u32 s55, s10
	s_cselect_b64 vcc, -1, 0
	v_add_u32_e32 v148, s33, v149
	s_add_i32 s10, 0, 0x14000
	ds_read_b128 v[152:155], v148
	ds_read_b128 v[156:159], v148 offset:1024
	ds_read_b128 v[160:163], v148 offset:2048
	ds_read_b128 v[164:167], v148 offset:3072
	v_add_u32_e32 v148, s10, v149
	ds_read_b128 v[176:179], v148
	ds_read_b128 v[180:183], v148 offset:1024
	ds_read_b128 v[184:187], v148 offset:2048
	ds_read_b128 v[188:191], v148 offset:3072
	v_lshl_add_u64 v[146:147], v[142:143], 0, s[92:93]
	v_cndmask_b32_e32 v147, v147, v139, vcc
	v_cndmask_b32_e32 v146, v146, v138, vcc
	v_cndmask_b32_e32 v221, v145, v141, vcc
	v_cndmask_b32_e32 v220, v144, v140, vcc
	v_lshl_add_u64 v[244:245], v[142:143], 0, v[134:135]
	s_add_i32 m0, s25, 0xc000
	ds_read_b128 v[192:195], v151
	ds_read_b128 v[196:199], v151 offset:1024
	ds_read_b128 v[200:203], v151 offset:2048
	ds_read_b128 v[204:207], v151 offset:3072
	ds_read_b128 v[208:211], v151 offset:4096
	ds_read_b128 v[212:215], v151 offset:5120
	ds_read_b128 v[216:219], v151 offset:6144
	ds_read_b128 v[240:243], v151 offset:7168
	global_load_lds_dwordx4 v[244:245], off
	v_lshl_add_u64 v[244:245], v[142:143], 0, v[136:137]
	s_add_i32 m0, s25, 0xe000
	s_nop 0
	global_load_lds_dwordx4 v[244:245], off
	s_waitcnt vmcnt(8)
	s_waitcnt lgkmcnt(0)
	s_setprio 1
	s_barrier
; #define PG8_STAGE(bufoff, gbase, voff) do { _Pragma("unroll") for (int _i = 0; _i < 2; ++_i) \
;         __builtin_amdgcn_global_load_lds((const unsigned*)((const char*)(gbase) + (voff)[_i]), (LAS unsigned*)(lds + (bufoff) + ldsw + _i * 8192), 16, 0, 0); } while (0)
; #define PG8_LDA(dst, b, h) do { _Pragma("unroll") for (int m = 0; m < 4; ++m) _Pragma("unroll") for (int k = 0; k < 2; ++k) dst[m][k] = *(const LAS bf16x8*)(lds + PG8_SA(b, h) + aoff + m * 2048 + k * 1024); } while (0)
; #define PG8_LDB(dst, b, h) do { _Pragma("unroll") for (int n = 0; n < 2; ++n) _Pragma("unroll") for (int k = 0; k < 2; ++k) dst[n][k] = *(const LAS bf16x8*)(lds + PG8_SB(b, h) + boff + n * 2048 + k * 1024); } while (0)
; #define PG8_MMA(ai, bj, At, Bt) do { __builtin_amdgcn_s_setprio(1); _Pragma("unroll") for (int k = 0; k < 2; ++k) _Pragma("unroll") for (int m = 0; m < 4; ++m) _Pragma("unroll") for (int n = 0; n < 2; ++n) \
;         acc[ai][bj][m][n] = __builtin_amdgcn_mfma_f32_16x16x32_bf16(Bt[n][k], At[m][k], acc[ai][bj][m][n], 0, 0, 0); __builtin_amdgcn_s_setprio(0); } while (0)
; #define PG8_WAIT_V(n) asm volatile("s_waitcnt vmcnt(" #n ")" ::: "memory")
; #define PG8_WAIT_L(n) asm volatile("s_waitcnt lgkmcnt(" #n ")" ::: "memory")
; #define PG8_BAR __builtin_amdgcn_s_barrier()
; #define PG8_SCHED __builtin_amdgcn_sched_barrier(0)
; template <class Epi, bool ALIGN_EPI>
; __device__ __forceinline__ void gemm_phase(LAS unsigned char* lds, const Gemm g, const StaticOrder& S, const Epi& E, const int tid) {
;     ...
;             PG8_WAIT_V(8); PG8_WAIT_L(0); PG8_BAR; PG8_MMA(0, 0, At, B0); PG8_MMA(0, 1, At, B1); PG8_BAR; PG8_SCHED;
;             PG8_LDA(At, 0, 1); PG8_STAGE(PG8_SB(0, 0), b2, voffB); PG8_STAGE(PG8_SB(0, 1), b2 + hB, voffB); PG8_STAGE(PG8_SA(0, 0), a2, voffA);
;             PG8_WAIT_V(8); PG8_WAIT_L(0); PG8_BAR; PG8_MMA(1, 0, At, B0); PG8_MMA(1, 1, At, B1); PG8_BAR; PG8_SCHED;
;             PG8_LDB(B0, 1, 0); PG8_LDB(B1, 1, 1); PG8_SCHED; PG8_LDA(At, 1, 0); PG8_STAGE(PG8_SA(0, 1), a2 + hA, voffA);
;             PG8_WAIT_V(8); PG8_WAIT_L(0); PG8_BAR; PG8_MMA(0, 0, At, B0); PG8_MMA(0, 1, At, B1); PG8_BAR; PG8_SCHED;
	s_waitcnt lgkmcnt(0)
	v_mfma_f32_16x16x32_bf16 v[124:127], v[152:155], v[192:195], v[124:127]
	v_mfma_f32_16x16x32_bf16 v[120:123], v[160:163], v[192:195], v[120:123]
	v_mfma_f32_16x16x32_bf16 v[108:111], v[152:155], v[200:203], v[108:111]
	v_mfma_f32_16x16x32_bf16 v[104:107], v[160:163], v[200:203], v[104:107]
	v_mfma_f32_16x16x32_bf16 v[92:95], v[152:155], v[208:211], v[92:95]
	v_mfma_f32_16x16x32_bf16 v[88:91], v[160:163], v[208:211], v[88:91]
	v_mfma_f32_16x16x32_bf16 v[76:79], v[152:155], v[216:219], v[76:79]
	v_mfma_f32_16x16x32_bf16 v[72:75], v[160:163], v[216:219], v[72:75]
	v_mfma_f32_16x16x32_bf16 v[124:127], v[156:159], v[196:199], v[124:127]
	v_mfma_f32_16x16x32_bf16 v[120:123], v[164:167], v[196:199], v[120:123]
	v_mfma_f32_16x16x32_bf16 v[108:111], v[156:159], v[204:207], v[108:111]
	v_mfma_f32_16x16x32_bf16 v[104:107], v[164:167], v[204:207], v[104:107]
	v_mfma_f32_16x16x32_bf16 v[92:95], v[156:159], v[212:215], v[92:95]
	v_mfma_f32_16x16x32_bf16 v[88:91], v[164:167], v[212:215], v[88:91]
	v_mfma_f32_16x16x32_bf16 v[76:79], v[156:159], v[240:243], v[76:79]
	v_mfma_f32_16x16x32_bf16 v[72:75], v[164:167], v[240:243], v[72:75]
	s_setprio 0
	s_setprio 1
	v_mfma_f32_16x16x32_bf16 v[116:119], v[176:179], v[192:195], v[116:119]
	v_mfma_f32_16x16x32_bf16 v[112:115], v[184:187], v[192:195], v[112:115]
	v_mfma_f32_16x16x32_bf16 v[100:103], v[176:179], v[200:203], v[100:103]
	v_mfma_f32_16x16x32_bf16 v[96:99], v[184:187], v[200:203], v[96:99]
	v_mfma_f32_16x16x32_bf16 v[84:87], v[176:179], v[208:211], v[84:87]
	v_mfma_f32_16x16x32_bf16 v[80:83], v[184:187], v[208:211], v[80:83]
	v_mfma_f32_16x16x32_bf16 v[68:71], v[176:179], v[216:219], v[68:71]
	v_mfma_f32_16x16x32_bf16 v[64:67], v[184:187], v[216:219], v[64:67]
	v_mfma_f32_16x16x32_bf16 v[116:119], v[180:183], v[196:199], v[116:119]
	v_mfma_f32_16x16x32_bf16 v[112:115], v[188:191], v[196:199], v[112:115]
	v_mfma_f32_16x16x32_bf16 v[100:103], v[180:183], v[204:207], v[100:103]
	v_mfma_f32_16x16x32_bf16 v[96:99], v[188:191], v[204:207], v[96:99]
	v_mfma_f32_16x16x32_bf16 v[84:87], v[180:183], v[212:215], v[84:87]
	v_mfma_f32_16x16x32_bf16 v[80:83], v[188:191], v[212:215], v[80:83]
	v_mfma_f32_16x16x32_bf16 v[68:71], v[180:183], v[240:243], v[68:71]
	v_mfma_f32_16x16x32_bf16 v[64:67], v[188:191], v[240:243], v[64:67]
	s_setprio 0
	s_barrier
	s_add_i32 s62, s33, s45
	v_lshl_add_u64 v[244:245], v[220:221], 0, v[168:169]
	s_mov_b32 m0, s62
	ds_read_b128 v[192:195], v151 offset:16384
	ds_read_b128 v[196:199], v151 offset:17408
	ds_read_b128 v[200:203], v151 offset:18432
	ds_read_b128 v[204:207], v151 offset:19456
	ds_read_b128 v[208:211], v151 offset:20480
	ds_read_b128 v[212:215], v151 offset:21504
	ds_read_b128 v[216:219], v151 offset:22528
	ds_read_b128 v[240:243], v151 offset:23552
	global_load_lds_dwordx4 v[244:245], off
	v_lshl_add_u64 v[246:247], v[220:221], 0, v[128:129]
	s_add_i32 m0, s62, 0x2000
	v_lshl_add_u64 v[220:221], v[220:221], 0, s[12:13]
	s_add_i32 s10, s10, s45
	global_load_lds_dwordx4 v[246:247], off
	v_lshl_add_u64 v[248:249], v[220:221], 0, v[168:169]
	s_mov_b32 m0, s10
	v_lshl_add_u64 v[220:221], v[220:221], 0, v[128:129]
	global_load_lds_dwordx4 v[248:249], off
	s_add_i32 m0, s10, 0x2000
	v_lshl_add_u64 v[250:251], v[146:147], 0, v[132:133]
	global_load_lds_dwordx4 v[220:221], off
	s_mov_b32 m0, s25
	v_lshl_add_u64 v[252:253], v[146:147], 0, v[130:131]
	global_load_lds_dwordx4 v[250:251], off
	s_mov_b32 m0, s50
	s_nop 0
	global_load_lds_dwordx4 v[252:253], off
	s_waitcnt vmcnt(8)
	s_waitcnt lgkmcnt(0)
	s_setprio 1
	s_barrier
	s_waitcnt lgkmcnt(0)
	v_mfma_f32_16x16x32_bf16 v[60:63], v[152:155], v[192:195], v[60:63]
	v_mfma_f32_16x16x32_bf16 v[56:59], v[160:163], v[192:195], v[56:59]
	v_mfma_f32_16x16x32_bf16 v[44:47], v[152:155], v[200:203], v[44:47]
	v_mfma_f32_16x16x32_bf16 v[40:43], v[160:163], v[200:203], v[40:43]
	v_mfma_f32_16x16x32_bf16 v[28:31], v[152:155], v[208:211], v[28:31]
	v_mfma_f32_16x16x32_bf16 v[24:27], v[160:163], v[208:211], v[24:27]
	v_mfma_f32_16x16x32_bf16 v[12:15], v[152:155], v[216:219], v[12:15]
	v_mfma_f32_16x16x32_bf16 v[8:11], v[160:163], v[216:219], v[8:11]
	v_mfma_f32_16x16x32_bf16 v[60:63], v[156:159], v[196:199], v[60:63]
	v_mfma_f32_16x16x32_bf16 v[56:59], v[164:167], v[196:199], v[56:59]
	v_mfma_f32_16x16x32_bf16 v[44:47], v[156:159], v[204:207], v[44:47]
	v_mfma_f32_16x16x32_bf16 v[40:43], v[164:167], v[204:207], v[40:43]
	v_mfma_f32_16x16x32_bf16 v[28:31], v[156:159], v[212:215], v[28:31]
	v_mfma_f32_16x16x32_bf16 v[24:27], v[164:167], v[212:215], v[24:27]
	v_mfma_f32_16x16x32_bf16 v[12:15], v[156:159], v[240:243], v[12:15]
	v_mfma_f32_16x16x32_bf16 v[8:11], v[164:167], v[240:243], v[8:11]
	s_setprio 0
	s_setprio 1
	v_mfma_f32_16x16x32_bf16 v[52:55], v[176:179], v[192:195], v[52:55]
	v_mfma_f32_16x16x32_bf16 v[48:51], v[184:187], v[192:195], v[48:51]
	v_mfma_f32_16x16x32_bf16 v[36:39], v[176:179], v[200:203], v[36:39]
	v_mfma_f32_16x16x32_bf16 v[32:35], v[184:187], v[200:203], v[32:35]
	v_mfma_f32_16x16x32_bf16 v[20:23], v[176:179], v[208:211], v[20:23]
	v_mfma_f32_16x16x32_bf16 v[16:19], v[184:187], v[208:211], v[16:19]
	v_mfma_f32_16x16x32_bf16 v[4:7], v[176:179], v[216:219], v[4:7]
	v_mfma_f32_16x16x32_bf16 v[0:3], v[184:187], v[216:219], v[0:3]
	v_mfma_f32_16x16x32_bf16 v[52:55], v[180:183], v[196:199], v[52:55]
	v_mfma_f32_16x16x32_bf16 v[48:51], v[188:191], v[196:199], v[48:51]
	v_mfma_f32_16x16x32_bf16 v[36:39], v[180:183], v[204:207], v[36:39]
	v_mfma_f32_16x16x32_bf16 v[32:35], v[188:191], v[204:207], v[32:35]
	v_mfma_f32_16x16x32_bf16 v[20:23], v[180:183], v[212:215], v[20:23]
	v_mfma_f32_16x16x32_bf16 v[16:19], v[188:191], v[212:215], v[16:19]
	v_mfma_f32_16x16x32_bf16 v[4:7], v[180:183], v[240:243], v[4:7]
	v_mfma_f32_16x16x32_bf16 v[0:3], v[188:191], v[240:243], v[0:3]
	s_setprio 0
	s_barrier
; #define PG8_STAGE(bufoff, gbase, voff) do { _Pragma("unroll") for (int _i = 0; _i < 2; ++_i) \
;         __builtin_amdgcn_global_load_lds((const unsigned*)((const char*)(gbase) + (voff)[_i]), (LAS unsigned*)(lds + (bufoff) + ldsw + _i * 8192), 16, 0, 0); } while (0)
; #define PG8_LDA(dst, b, h) do { _Pragma("unroll") for (int m = 0; m < 4; ++m) _Pragma("unroll") for (int k = 0; k < 2; ++k) dst[m][k] = *(const LAS bf16x8*)(lds + PG8_SA(b, h) + aoff + m * 2048 + k * 1024); } while (0)
; #define PG8_LDB(dst, b, h) do { _Pragma("unroll") for (int n = 0; n < 2; ++n) _Pragma("unroll") for (int k = 0; k < 2; ++k) dst[n][k] = *(const LAS bf16x8*)(lds + PG8_SB(b, h) + boff + n * 2048 + k * 1024); } while (0)
; #define PG8_MMA(ai, bj, At, Bt) do { __builtin_amdgcn_s_setprio(1); _Pragma("unroll") for (int k = 0; k < 2; ++k) _Pragma("unroll") for (int m = 0; m < 4; ++m) _Pragma("unroll") for (int n = 0; n < 2; ++n) \
;         acc[ai][bj][m][n] = __builtin_amdgcn_mfma_f32_16x16x32_bf16(Bt[n][k], At[m][k], acc[ai][bj][m][n], 0, 0, 0); __builtin_amdgcn_s_setprio(0); } while (0)
; #define PG8_WAIT_V(n) asm volatile("s_waitcnt vmcnt(" #n ")" ::: "memory")
; #define PG8_WAIT_L(n) asm volatile("s_waitcnt lgkmcnt(" #n ")" ::: "memory")
; #define PG8_BAR __builtin_amdgcn_s_barrier()
; #define PG8_SCHED __builtin_amdgcn_sched_barrier(0)
; template <class Epi, bool ALIGN_EPI>
; __device__ __forceinline__ void gemm_phase(LAS unsigned char* lds, const Gemm g, const StaticOrder& S, const Epi& E, const int tid) {
;     ...
;             PG8_LDB(B0, 1, 0); PG8_LDB(B1, 1, 1); PG8_SCHED; PG8_LDA(At, 1, 0); PG8_STAGE(PG8_SA(0, 1), a2 + hA, voffA);
;             PG8_WAIT_V(8); PG8_WAIT_L(0); PG8_BAR; PG8_MMA(0, 0, At, B0); PG8_MMA(0, 1, At, B1); PG8_BAR; PG8_SCHED;
;             PG8_LDA(At, 1, 1); PG8_STAGE(PG8_SB(1, 0), b3, voffB); PG8_STAGE(PG8_SB(1, 1), b3 + hB, voffB); PG8_STAGE(PG8_SA(1, 0), a3, voffA);
;             PG8_WAIT_V(8); PG8_WAIT_L(0); PG8_BAR; PG8_MMA(1, 0, At, B0); PG8_MMA(1, 1, At, B1); PG8_BAR; PG8_SCHED;
	s_add_i32 s10, 0, 0x18000
	v_add_u32_e32 v148, s10, v149
	s_add_i32 s62, 0, 0x1c000
	ds_read_b128 v[152:155], v148
	ds_read_b128 v[156:159], v148 offset:1024
	ds_read_b128 v[160:163], v148 offset:2048
	ds_read_b128 v[164:167], v148 offset:3072
	v_add_u32_e32 v148, s62, v149
	ds_read_b128 v[176:179], v148
	ds_read_b128 v[180:183], v148 offset:1024
	ds_read_b128 v[184:187], v148 offset:2048
	ds_read_b128 v[188:191], v148 offset:3072
	v_lshl_add_u64 v[146:147], v[146:147], 0, s[94:95]
	s_mov_b32 m0, s51
	v_lshl_add_u64 v[226:227], v[146:147], 0, v[132:133]
	ds_read_b128 v[192:195], v151 offset:32768
	ds_read_b128 v[196:199], v151 offset:33792
	ds_read_b128 v[200:203], v151 offset:34816
	ds_read_b128 v[204:207], v151 offset:35840
	ds_read_b128 v[208:211], v151 offset:36864
	ds_read_b128 v[212:215], v151 offset:37888
	ds_read_b128 v[216:219], v151 offset:38912
	ds_read_b128 v[240:243], v151 offset:39936
	global_load_lds_dwordx4 v[226:227], off
	v_lshl_add_u64 v[146:147], v[146:147], 0, v[130:131]
	s_mov_b32 m0, s52
	s_nop 0
	global_load_lds_dwordx4 v[146:147], off
	s_waitcnt vmcnt(8)
	s_waitcnt lgkmcnt(0)
	s_setprio 1
	s_barrier
	s_waitcnt lgkmcnt(0)
	v_mfma_f32_16x16x32_bf16 v[124:127], v[152:155], v[192:195], v[124:127]
	v_mfma_f32_16x16x32_bf16 v[120:123], v[160:163], v[192:195], v[120:123]
	v_mfma_f32_16x16x32_bf16 v[108:111], v[152:155], v[200:203], v[108:111]
	v_mfma_f32_16x16x32_bf16 v[104:107], v[160:163], v[200:203], v[104:107]
	v_mfma_f32_16x16x32_bf16 v[92:95], v[152:155], v[208:211], v[92:95]
	v_mfma_f32_16x16x32_bf16 v[88:91], v[160:163], v[208:211], v[88:91]
	v_mfma_f32_16x16x32_bf16 v[76:79], v[152:155], v[216:219], v[76:79]
	v_mfma_f32_16x16x32_bf16 v[72:75], v[160:163], v[216:219], v[72:75]
	v_mfma_f32_16x16x32_bf16 v[124:127], v[156:159], v[196:199], v[124:127]
	v_mfma_f32_16x16x32_bf16 v[120:123], v[164:167], v[196:199], v[120:123]
	v_mfma_f32_16x16x32_bf16 v[108:111], v[156:159], v[204:207], v[108:111]
	v_mfma_f32_16x16x32_bf16 v[104:107], v[164:167], v[204:207], v[104:107]
	v_mfma_f32_16x16x32_bf16 v[92:95], v[156:159], v[212:215], v[92:95]
	v_mfma_f32_16x16x32_bf16 v[88:91], v[164:167], v[212:215], v[88:91]
	v_mfma_f32_16x16x32_bf16 v[76:79], v[156:159], v[240:243], v[76:79]
	v_mfma_f32_16x16x32_bf16 v[72:75], v[164:167], v[240:243], v[72:75]
	s_setprio 0
	s_setprio 1
	v_mfma_f32_16x16x32_bf16 v[116:119], v[176:179], v[192:195], v[116:119]
	v_mfma_f32_16x16x32_bf16 v[112:115], v[184:187], v[192:195], v[112:115]
	v_mfma_f32_16x16x32_bf16 v[100:103], v[176:179], v[200:203], v[100:103]
	v_mfma_f32_16x16x32_bf16 v[96:99], v[184:187], v[200:203], v[96:99]
	v_mfma_f32_16x16x32_bf16 v[84:87], v[176:179], v[208:211], v[84:87]
	v_mfma_f32_16x16x32_bf16 v[80:83], v[184:187], v[208:211], v[80:83]
	v_mfma_f32_16x16x32_bf16 v[68:71], v[176:179], v[216:219], v[68:71]
	v_mfma_f32_16x16x32_bf16 v[64:67], v[184:187], v[216:219], v[64:67]
	v_mfma_f32_16x16x32_bf16 v[116:119], v[180:183], v[196:199], v[116:119]
	v_mfma_f32_16x16x32_bf16 v[112:115], v[188:191], v[196:199], v[112:115]
	v_mfma_f32_16x16x32_bf16 v[100:103], v[180:183], v[204:207], v[100:103]
	v_mfma_f32_16x16x32_bf16 v[96:99], v[188:191], v[204:207], v[96:99]
	v_mfma_f32_16x16x32_bf16 v[84:87], v[180:183], v[212:215], v[84:87]
	v_mfma_f32_16x16x32_bf16 v[80:83], v[188:191], v[212:215], v[80:83]
	v_mfma_f32_16x16x32_bf16 v[68:71], v[180:183], v[240:243], v[68:71]
	v_mfma_f32_16x16x32_bf16 v[64:67], v[188:191], v[240:243], v[64:67]
	s_setprio 0
	s_barrier
	s_add_i32 s10, s10, s45
	v_lshl_add_u64 v[146:147], v[244:245], 0, s[92:93]
	s_mov_b32 m0, s10
	ds_read_b128 v[192:195], v151 offset:49152
	ds_read_b128 v[196:199], v151 offset:50176
	ds_read_b128 v[200:203], v151 offset:51200
	ds_read_b128 v[204:207], v151 offset:52224
	ds_read_b128 v[208:211], v151 offset:53248
	ds_read_b128 v[212:215], v151 offset:54272
	ds_read_b128 v[216:219], v151 offset:55296
	ds_read_b128 v[240:243], v151 offset:56320
	global_load_lds_dwordx4 v[146:147], off
	v_lshl_add_u64 v[146:147], v[246:247], 0, s[92:93]
	s_add_i32 m0, s10, 0x2000
	s_add_i32 s10, s62, s45
	global_load_lds_dwordx4 v[146:147], off
	v_lshl_add_u64 v[146:147], v[248:249], 0, s[92:93]
	s_mov_b32 m0, s10
	s_nop 0
	global_load_lds_dwordx4 v[146:147], off
	v_lshl_add_u64 v[146:147], v[220:221], 0, s[92:93]
	s_add_i32 m0, s10, 0x2000
	s_nop 0
	global_load_lds_dwordx4 v[146:147], off
	v_lshl_add_u64 v[146:147], v[250:251], 0, s[92:93]
	s_mov_b32 m0, s53
	s_nop 0
	global_load_lds_dwordx4 v[146:147], off
	v_lshl_add_u64 v[146:147], v[252:253], 0, s[92:93]
	s_mov_b32 m0, s54
	s_nop 0
	global_load_lds_dwordx4 v[146:147], off
	s_waitcnt vmcnt(8)
	s_waitcnt lgkmcnt(0)
	s_setprio 1
	s_barrier
; #define PG8_STAGE(bufoff, gbase, voff) do { _Pragma("unroll") for (int _i = 0; _i < 2; ++_i) \
;         __builtin_amdgcn_global_load_lds((const unsigned*)((const char*)(gbase) + (voff)[_i]), (LAS unsigned*)(lds + (bufoff) + ldsw + _i * 8192), 16, 0, 0); } while (0)
; #define PG8_LDA(dst, b, h) do { _Pragma("unroll") for (int m = 0; m < 4; ++m) _Pragma("unroll") for (int k = 0; k < 2; ++k) dst[m][k] = *(const LAS bf16x8*)(lds + PG8_SA(b, h) + aoff + m * 2048 + k * 1024); } while (0)
; #define PG8_LDB(dst, b, h) do { _Pragma("unroll") for (int n = 0; n < 2; ++n) _Pragma("unroll") for (int k = 0; k < 2; ++k) dst[n][k] = *(const LAS bf16x8*)(lds + PG8_SB(b, h) + boff + n * 2048 + k * 1024); } while (0)
; #define PG8_MMA(ai, bj, At, Bt) do { __builtin_amdgcn_s_setprio(1); _Pragma("unroll") for (int k = 0; k < 2; ++k) _Pragma("unroll") for (int m = 0; m < 4; ++m) _Pragma("unroll") for (int n = 0; n < 2; ++n) \
;         acc[ai][bj][m][n] = __builtin_amdgcn_mfma_f32_16x16x32_bf16(Bt[n][k], At[m][k], acc[ai][bj][m][n], 0, 0, 0); __builtin_amdgcn_s_setprio(0); } while (0)
; template <class Epi, bool ALIGN_EPI>
; __device__ __forceinline__ void gemm_phase(LAS unsigned char* lds, const Gemm g, const StaticOrder& S, const Epi& E, const int tid) {
;     ...
;         for (int t = 0; t < nt; t += 2) {
;             const bool last = (t == nt - 2);
;             const char* a1 = cA + (size_t)(t + 1) * kstep;
;             const char* a2 = last ? nA : cA + (size_t)(t + 2) * kstep; const char* b2 = last ? nB : cB + (size_t)(t + 2) * kstep;
;             const char* a3 = a2 + kstep; const char* b3 = b2 + kstep;
;             PG8_LDB(B0, 0, 0); PG8_LDB(B1, 0, 1); PG8_SCHED; PG8_LDA(At, 0, 0); PG8_STAGE(PG8_SA(1, 1), a1 + hA, voffA);
;             PG8_WAIT_V(8); PG8_WAIT_L(0); PG8_BAR; PG8_MMA(0, 0, At, B0); PG8_MMA(0, 1, At, B1); PG8_BAR; PG8_SCHED;
;             PG8_LDA(At, 0, 1); PG8_STAGE(PG8_SB(0, 0), b2, voffB); PG8_STAGE(PG8_SB(0, 1), b2 + hB, voffB); PG8_STAGE(PG8_SA(0, 0), a2, voffA);
;             PG8_WAIT_V(8); PG8_WAIT_L(0); PG8_BAR; PG8_MMA(1, 0, At, B0); PG8_MMA(1, 1, At, B1); PG8_BAR; PG8_SCHED;
;     ...
;             PG8_LDA(At, 1, 1); PG8_STAGE(PG8_SB(1, 0), b3, voffB); PG8_STAGE(PG8_SB(1, 1), b3 + hB, voffB); PG8_STAGE(PG8_SA(1, 0), a3, voffA);
;             PG8_WAIT_V(8); PG8_WAIT_L(0); PG8_BAR; PG8_MMA(1, 0, At, B0); PG8_MMA(1, 1, At, B1); PG8_BAR; PG8_SCHED;
;         }
	s_waitcnt lgkmcnt(0)
	v_mfma_f32_16x16x32_bf16 v[60:63], v[152:155], v[192:195], v[60:63]
	v_mfma_f32_16x16x32_bf16 v[56:59], v[160:163], v[192:195], v[56:59]
	v_mfma_f32_16x16x32_bf16 v[44:47], v[152:155], v[200:203], v[44:47]
	v_mfma_f32_16x16x32_bf16 v[40:43], v[160:163], v[200:203], v[40:43]
	v_mfma_f32_16x16x32_bf16 v[28:31], v[152:155], v[208:211], v[28:31]
	v_mfma_f32_16x16x32_bf16 v[24:27], v[160:163], v[208:211], v[24:27]
	v_mfma_f32_16x16x32_bf16 v[12:15], v[152:155], v[216:219], v[12:15]
	v_mfma_f32_16x16x32_bf16 v[8:11], v[160:163], v[216:219], v[8:11]
	v_mfma_f32_16x16x32_bf16 v[60:63], v[156:159], v[196:199], v[60:63]
	v_mfma_f32_16x16x32_bf16 v[56:59], v[164:167], v[196:199], v[56:59]
	v_mfma_f32_16x16x32_bf16 v[44:47], v[156:159], v[204:207], v[44:47]
	v_mfma_f32_16x16x32_bf16 v[40:43], v[164:167], v[204:207], v[40:43]
	v_mfma_f32_16x16x32_bf16 v[28:31], v[156:159], v[212:215], v[28:31]
	v_mfma_f32_16x16x32_bf16 v[24:27], v[164:167], v[212:215], v[24:27]
	v_mfma_f32_16x16x32_bf16 v[12:15], v[156:159], v[240:243], v[12:15]
	v_mfma_f32_16x16x32_bf16 v[8:11], v[164:167], v[240:243], v[8:11]
	s_setprio 0
	s_setprio 1
	v_mfma_f32_16x16x32_bf16 v[52:55], v[176:179], v[192:195], v[52:55]
	v_mfma_f32_16x16x32_bf16 v[48:51], v[184:187], v[192:195], v[48:51]
	v_mfma_f32_16x16x32_bf16 v[36:39], v[176:179], v[200:203], v[36:39]
	v_mfma_f32_16x16x32_bf16 v[32:35], v[184:187], v[200:203], v[32:35]
	v_mfma_f32_16x16x32_bf16 v[20:23], v[176:179], v[208:211], v[20:23]
	v_mfma_f32_16x16x32_bf16 v[16:19], v[184:187], v[208:211], v[16:19]
	v_mfma_f32_16x16x32_bf16 v[4:7], v[176:179], v[216:219], v[4:7]
	v_mfma_f32_16x16x32_bf16 v[0:3], v[184:187], v[216:219], v[0:3]
	v_mfma_f32_16x16x32_bf16 v[52:55], v[180:183], v[196:199], v[52:55]
	v_mfma_f32_16x16x32_bf16 v[48:51], v[188:191], v[196:199], v[48:51]
	v_mfma_f32_16x16x32_bf16 v[36:39], v[180:183], v[204:207], v[36:39]
	v_mfma_f32_16x16x32_bf16 v[32:35], v[188:191], v[204:207], v[32:35]
	v_mfma_f32_16x16x32_bf16 v[20:23], v[180:183], v[212:215], v[20:23]
	v_mfma_f32_16x16x32_bf16 v[16:19], v[188:191], v[212:215], v[16:19]
	v_mfma_f32_16x16x32_bf16 v[4:7], v[180:183], v[240:243], v[4:7]
	v_mfma_f32_16x16x32_bf16 v[0:3], v[188:191], v[240:243], v[0:3]
	s_setprio 0
	s_barrier
	v_lshl_add_u64 v[142:143], v[142:143], 0, s[80:81]
	v_lshl_add_u64 v[144:145], v[144:145], 0, s[80:81]
	s_mov_b32 s10, s11
	s_cmp_lg_u32 s10, s55
	s_cbranch_scc1 .LBB0_354
.Lq5_last:
	s_add_i32 s11, s10, 2
	s_cmp_eq_u32 s55, s10
	s_cselect_b64 vcc, -1, 0
	v_add_u32_e32 v148, s33, v149
	s_add_i32 s10, 0, 0x14000
	ds_read_b128 v[152:155], v148
	ds_read_b128 v[156:159], v148 offset:1024
	ds_read_b128 v[160:163], v148 offset:2048
	ds_read_b128 v[164:167], v148 offset:3072
	v_add_u32_e32 v148, s10, v149
	ds_read_b128 v[176:179], v148
	ds_read_b128 v[180:183], v148 offset:1024
	ds_read_b128 v[184:187], v148 offset:2048
	ds_read_b128 v[188:191], v148 offset:3072
	v_lshl_add_u64 v[146:147], v[142:143], 0, s[92:93]
	v_cndmask_b32_e32 v147, v147, v139, vcc
	v_cndmask_b32_e32 v146, v146, v138, vcc
	v_cndmask_b32_e32 v221, v145, v141, vcc
	v_cndmask_b32_e32 v220, v144, v140, vcc
	v_lshl_add_u64 v[244:245], v[142:143], 0, v[134:135]
	s_add_i32 m0, s25, 0xc000
	ds_read_b128 v[192:195], v151
	ds_read_b128 v[196:199], v151 offset:1024
	ds_read_b128 v[200:203], v151 offset:2048
	ds_read_b128 v[204:207], v151 offset:3072
	ds_read_b128 v[208:211], v151 offset:4096
	ds_read_b128 v[212:215], v151 offset:5120
	ds_read_b128 v[216:219], v151 offset:6144
	ds_read_b128 v[240:243], v151 offset:7168
	global_load_lds_dwordx4 v[244:245], off
	v_lshl_add_u64 v[244:245], v[142:143], 0, v[136:137]
	s_add_i32 m0, s25, 0xe000
	s_nop 0
	global_load_lds_dwordx4 v[244:245], off
	s_waitcnt vmcnt(8)
	s_waitcnt lgkmcnt(0)
	s_setprio 1
	s_barrier
	s_waitcnt lgkmcnt(0)
	v_mfma_f32_16x16x32_bf16 v[124:127], v[152:155], v[192:195], v[124:127]
	v_mfma_f32_16x16x32_bf16 v[120:123], v[160:163], v[192:195], v[120:123]
	v_mfma_f32_16x16x32_bf16 v[108:111], v[152:155], v[200:203], v[108:111]
	v_mfma_f32_16x16x32_bf16 v[104:107], v[160:163], v[200:203], v[104:107]
	v_mfma_f32_16x16x32_bf16 v[92:95], v[152:155], v[208:211], v[92:95]
	v_mfma_f32_16x16x32_bf16 v[88:91], v[160:163], v[208:211], v[88:91]
	v_mfma_f32_16x16x32_bf16 v[76:79], v[152:155], v[216:219], v[76:79]
	v_mfma_f32_16x16x32_bf16 v[72:75], v[160:163], v[216:219], v[72:75]
	v_mfma_f32_16x16x32_bf16 v[124:127], v[156:159], v[196:199], v[124:127]
	v_mfma_f32_16x16x32_bf16 v[120:123], v[164:167], v[196:199], v[120:123]
	v_mfma_f32_16x16x32_bf16 v[108:111], v[156:159], v[204:207], v[108:111]
	v_mfma_f32_16x16x32_bf16 v[104:107], v[164:167], v[204:207], v[104:107]
	v_mfma_f32_16x16x32_bf16 v[92:95], v[156:159], v[212:215], v[92:95]
	v_mfma_f32_16x16x32_bf16 v[88:91], v[164:167], v[212:215], v[88:91]
	v_mfma_f32_16x16x32_bf16 v[76:79], v[156:159], v[240:243], v[76:79]
	v_mfma_f32_16x16x32_bf16 v[72:75], v[164:167], v[240:243], v[72:75]
	s_setprio 0
	s_setprio 1
	v_mfma_f32_16x16x32_bf16 v[116:119], v[176:179], v[192:195], v[116:119]
	v_mfma_f32_16x16x32_bf16 v[112:115], v[184:187], v[192:195], v[112:115]
	v_mfma_f32_16x16x32_bf16 v[100:103], v[176:179], v[200:203], v[100:103]
	v_mfma_f32_16x16x32_bf16 v[96:99], v[184:187], v[200:203], v[96:99]
	v_mfma_f32_16x16x32_bf16 v[84:87], v[176:179], v[208:211], v[84:87]
	v_mfma_f32_16x16x32_bf16 v[80:83], v[184:187], v[208:211], v[80:83]
	v_mfma_f32_16x16x32_bf16 v[68:71], v[176:179], v[216:219], v[68:71]
	v_mfma_f32_16x16x32_bf16 v[64:67], v[184:187], v[216:219], v[64:67]
	v_mfma_f32_16x16x32_bf16 v[116:119], v[180:183], v[196:199], v[116:119]
	v_mfma_f32_16x16x32_bf16 v[112:115], v[188:191], v[196:199], v[112:115]
	v_mfma_f32_16x16x32_bf16 v[100:103], v[180:183], v[204:207], v[100:103]
	v_mfma_f32_16x16x32_bf16 v[96:99], v[188:191], v[204:207], v[96:99]
	v_mfma_f32_16x16x32_bf16 v[84:87], v[180:183], v[212:215], v[84:87]
	v_mfma_f32_16x16x32_bf16 v[80:83], v[188:191], v[212:215], v[80:83]
	v_mfma_f32_16x16x32_bf16 v[68:71], v[180:183], v[240:243], v[68:71]
	v_mfma_f32_16x16x32_bf16 v[64:67], v[188:191], v[240:243], v[64:67]
	s_setprio 0
	s_barrier
; #define PG8_STAGE(bufoff, gbase, voff) do { _Pragma("unroll") for (int _i = 0; _i < 2; ++_i) \
;         __builtin_amdgcn_global_load_lds((const unsigned*)((const char*)(gbase) + (voff)[_i]), (LAS unsigned*)(lds + (bufoff) + ldsw + _i * 8192), 16, 0, 0); } while (0)
; #define PG8_LDA(dst, b, h) do { _Pragma("unroll") for (int m = 0; m < 4; ++m) _Pragma("unroll") for (int k = 0; k < 2; ++k) dst[m][k] = *(const LAS bf16x8*)(lds + PG8_SA(b, h) + aoff + m * 2048 + k * 1024); } while (0)
; #define PG8_LDB(dst, b, h) do { _Pragma("unroll") for (int n = 0; n < 2; ++n) _Pragma("unroll") for (int k = 0; k < 2; ++k) dst[n][k] = *(const LAS bf16x8*)(lds + PG8_SB(b, h) + boff + n * 2048 + k * 1024); } while (0)
; #define PG8_MMA(ai, bj, At, Bt) do { __builtin_amdgcn_s_setprio(1); _Pragma("unroll") for (int k = 0; k < 2; ++k) _Pragma("unroll") for (int m = 0; m < 4; ++m) _Pragma("unroll") for (int n = 0; n < 2; ++n) \
;         acc[ai][bj][m][n] = __builtin_amdgcn_mfma_f32_16x16x32_bf16(Bt[n][k], At[m][k], acc[ai][bj][m][n], 0, 0, 0); __builtin_amdgcn_s_setprio(0); } while (0)
; #define PG8_WAIT_V(n) asm volatile("s_waitcnt vmcnt(" #n ")" ::: "memory")
; #define PG8_WAIT_L(n) asm volatile("s_waitcnt lgkmcnt(" #n ")" ::: "memory")
; #define PG8_BAR __builtin_amdgcn_s_barrier()
; #define PG8_SCHED __builtin_amdgcn_sched_barrier(0)
; template <class Epi, bool ALIGN_EPI>
; __device__ __forceinline__ void gemm_phase(LAS unsigned char* lds, const Gemm g, const StaticOrder& S, const Epi& E, const int tid) {
;     ...
;             PG8_LDA(At, 0, 1); PG8_STAGE(PG8_SB(0, 0), b2, voffB); PG8_STAGE(PG8_SB(0, 1), b2 + hB, voffB); PG8_STAGE(PG8_SA(0, 0), a2, voffA);
;             PG8_WAIT_V(8); PG8_WAIT_L(0); PG8_BAR; PG8_MMA(1, 0, At, B0); PG8_MMA(1, 1, At, B1); PG8_BAR; PG8_SCHED;
;             PG8_LDB(B0, 1, 0); PG8_LDB(B1, 1, 1); PG8_SCHED; PG8_LDA(At, 1, 0); PG8_STAGE(PG8_SA(0, 1), a2 + hA, voffA);
;             PG8_WAIT_V(8); PG8_WAIT_L(0); PG8_BAR; PG8_MMA(0, 0, At, B0); PG8_MMA(0, 1, At, B1); PG8_BAR; PG8_SCHED;
;             PG8_LDA(At, 1, 1); PG8_STAGE(PG8_SB(1, 0), b3, voffB); PG8_STAGE(PG8_SB(1, 1), b3 + hB, voffB); PG8_STAGE(PG8_SA(1, 0), a3, voffA);
	s_add_i32 s62, s33, s45
	v_lshl_add_u64 v[244:245], v[220:221], 0, v[168:169]
	s_mov_b32 m0, s62
	ds_read_b128 v[192:195], v151 offset:16384
	ds_read_b128 v[196:199], v151 offset:17408
	ds_read_b128 v[200:203], v151 offset:18432
	ds_read_b128 v[204:207], v151 offset:19456
	ds_read_b128 v[208:211], v151 offset:20480
	ds_read_b128 v[212:215], v151 offset:21504
	ds_read_b128 v[216:219], v151 offset:22528
	ds_read_b128 v[240:243], v151 offset:23552
	global_load_lds_dwordx4 v[244:245], off
	v_lshl_add_u64 v[246:247], v[220:221], 0, v[128:129]
	s_add_i32 m0, s62, 0x2000
	v_lshl_add_u64 v[220:221], v[220:221], 0, s[12:13]
	s_add_i32 s10, s10, s45
	global_load_lds_dwordx4 v[246:247], off
	v_lshl_add_u64 v[248:249], v[220:221], 0, v[168:169]
	s_mov_b32 m0, s10
	v_lshl_add_u64 v[220:221], v[220:221], 0, v[128:129]
	global_load_lds_dwordx4 v[248:249], off
	s_add_i32 m0, s10, 0x2000
	v_lshl_add_u64 v[250:251], v[146:147], 0, v[132:133]
	global_load_lds_dwordx4 v[220:221], off
	s_mov_b32 m0, s25
	v_lshl_add_u64 v[252:253], v[146:147], 0, v[130:131]
	global_load_lds_dwordx4 v[250:251], off
	s_mov_b32 m0, s50
	s_nop 0
	global_load_lds_dwordx4 v[252:253], off
	s_waitcnt vmcnt(8)
	s_waitcnt lgkmcnt(0)
	s_setprio 1
	s_barrier
	s_waitcnt lgkmcnt(0)
	v_mfma_f32_16x16x32_bf16 v[60:63], v[152:155], v[192:195], v[60:63]
	v_mfma_f32_16x16x32_bf16 v[56:59], v[160:163], v[192:195], v[56:59]
	v_mfma_f32_16x16x32_bf16 v[44:47], v[152:155], v[200:203], v[44:47]
	v_mfma_f32_16x16x32_bf16 v[40:43], v[160:163], v[200:203], v[40:43]
	v_mfma_f32_16x16x32_bf16 v[28:31], v[152:155], v[208:211], v[28:31]
	v_mfma_f32_16x16x32_bf16 v[24:27], v[160:163], v[208:211], v[24:27]
	v_mfma_f32_16x16x32_bf16 v[12:15], v[152:155], v[216:219], v[12:15]
	v_mfma_f32_16x16x32_bf16 v[8:11], v[160:163], v[216:219], v[8:11]
	v_mfma_f32_16x16x32_bf16 v[60:63], v[156:159], v[196:199], v[60:63]
	v_mfma_f32_16x16x32_bf16 v[56:59], v[164:167], v[196:199], v[56:59]
	v_mfma_f32_16x16x32_bf16 v[44:47], v[156:159], v[204:207], v[44:47]
	v_mfma_f32_16x16x32_bf16 v[40:43], v[164:167], v[204:207], v[40:43]
	v_mfma_f32_16x16x32_bf16 v[28:31], v[156:159], v[212:215], v[28:31]
	v_mfma_f32_16x16x32_bf16 v[24:27], v[164:167], v[212:215], v[24:27]
	v_mfma_f32_16x16x32_bf16 v[12:15], v[156:159], v[240:243], v[12:15]
	v_mfma_f32_16x16x32_bf16 v[8:11], v[164:167], v[240:243], v[8:11]
	s_setprio 0
	s_setprio 1
	v_mfma_f32_16x16x32_bf16 v[52:55], v[176:179], v[192:195], v[52:55]
	v_mfma_f32_16x16x32_bf16 v[48:51], v[184:187], v[192:195], v[48:51]
	v_mfma_f32_16x16x32_bf16 v[36:39], v[176:179], v[200:203], v[36:39]
	v_mfma_f32_16x16x32_bf16 v[32:35], v[184:187], v[200:203], v[32:35]
	v_mfma_f32_16x16x32_bf16 v[20:23], v[176:179], v[208:211], v[20:23]
	v_mfma_f32_16x16x32_bf16 v[16:19], v[184:187], v[208:211], v[16:19]
	v_mfma_f32_16x16x32_bf16 v[4:7], v[176:179], v[216:219], v[4:7]
	v_mfma_f32_16x16x32_bf16 v[0:3], v[184:187], v[216:219], v[0:3]
	v_mfma_f32_16x16x32_bf16 v[52:55], v[180:183], v[196:199], v[52:55]
	v_mfma_f32_16x16x32_bf16 v[48:51], v[188:191], v[196:199], v[48:51]
	v_mfma_f32_16x16x32_bf16 v[36:39], v[180:183], v[204:207], v[36:39]
	v_mfma_f32_16x16x32_bf16 v[32:35], v[188:191], v[204:207], v[32:35]
	v_mfma_f32_16x16x32_bf16 v[20:23], v[180:183], v[212:215], v[20:23]
	v_mfma_f32_16x16x32_bf16 v[16:19], v[188:191], v[212:215], v[16:19]
	v_mfma_f32_16x16x32_bf16 v[4:7], v[180:183], v[240:243], v[4:7]
	v_mfma_f32_16x16x32_bf16 v[0:3], v[188:191], v[240:243], v[0:3]
	s_setprio 0
	s_barrier
	s_add_i32 s10, 0, 0x18000
	v_add_u32_e32 v148, s10, v149
	s_add_i32 s62, 0, 0x1c000
	ds_read_b128 v[152:155], v148
	ds_read_b128 v[156:159], v148 offset:1024
	ds_read_b128 v[160:163], v148 offset:2048
	ds_read_b128 v[164:167], v148 offset:3072
	v_add_u32_e32 v148, s62, v149
	ds_read_b128 v[176:179], v148
	ds_read_b128 v[180:183], v148 offset:1024
	ds_read_b128 v[184:187], v148 offset:2048
	ds_read_b128 v[188:191], v148 offset:3072
	v_lshl_add_u64 v[146:147], v[146:147], 0, s[94:95]
	s_mov_b32 m0, s51
	v_lshl_add_u64 v[226:227], v[146:147], 0, v[132:133]
	ds_read_b128 v[192:195], v151 offset:32768
	ds_read_b128 v[196:199], v151 offset:33792
	ds_read_b128 v[200:203], v151 offset:34816
	ds_read_b128 v[204:207], v151 offset:35840
	ds_read_b128 v[208:211], v151 offset:36864
	ds_read_b128 v[212:215], v151 offset:37888
	ds_read_b128 v[216:219], v151 offset:38912
	ds_read_b128 v[240:243], v151 offset:39936
	global_load_lds_dwordx4 v[226:227], off
	v_lshl_add_u64 v[146:147], v[146:147], 0, v[130:131]
	s_mov_b32 m0, s52
	s_nop 0
	global_load_lds_dwordx4 v[146:147], off
	s_waitcnt vmcnt(8)
	s_waitcnt lgkmcnt(0)
	s_setprio 1
	s_barrier
; __device__ __forceinline__ unsigned cvt_pk_bf16(float lo, float hi) { unsigned r; asm volatile("v_cvt_pk_bf16_f32 %0, %1, %2" : "=v"(r) : "v"(lo), "v"(hi)); return r; }
; __device__ __forceinline__ float gelu_tanh(float x) { const float u = 0.7978845608028654f * (x + 0.044715f * x * x * x); return x * fast_rcp(1.0f + fast_exp2(-2.0f * LOG2E * u)); }
; #define PG8_STAGE(bufoff, gbase, voff) do { _Pragma("unroll") for (int _i = 0; _i < 2; ++_i) \
;         __builtin_amdgcn_global_load_lds((const unsigned*)((const char*)(gbase) + (voff)[_i]), (LAS unsigned*)(lds + (bufoff) + ldsw + _i * 8192), 16, 0, 0); } while (0)
; #define PG8_WAIT_V(n) asm volatile("s_waitcnt vmcnt(" #n ")" ::: "memory")
; #define PG8_WAIT_L(n) asm volatile("s_waitcnt lgkmcnt(" #n ")" ::: "memory")
;     __device__ __forceinline__ void operator()(const f32x4 (&acc)[2][2][4][2], const Unit& u, int wr, int wc, int fr, int fq) const {
;         const int row0 = u.pm * BM + wr * 64 + fr, col0 = u.pn * BM + wc * 32 + 8 * fq;
;         float rsv[2][4]; load_rstd(rsv, ssq, row0);
; #pragma unroll
;         for (int ai = 0; ai < 2; ++ai)
; #pragma unroll
;             for (int m = 0; m < 4; ++m) { const int row = row0 + ai * HALF + m * 16; bf16_t* rowp = O + (size_t)row * ldc + col0; const float rs = rsv[ai][m];
; #pragma unroll
;                 for (int bj = 0; bj < 2; ++bj) { f32x4 v0 = acc[ai][bj][m][0] * rs, v1 = acc[ai][bj][m][1] * rs;
;                     if (ACT == 1) {
; #pragma unroll
;                         for (int j = 0; j < 4; ++j) { v0[j] = gelu_tanh(v0[j]); v1[j] = gelu_tanh(v1[j]); } }
;                     u32x4 w; w.x = cvt_pk_bf16(v0[0], v0[1]); w.y = cvt_pk_bf16(v0[2], v0[3]); w.z = cvt_pk_bf16(v1[0], v1[1]); w.w = cvt_pk_bf16(v1[2], v1[3]);
;                     *(u32x4*)(rowp + bj * HALF) = w; } }
; template <class Epi, bool ALIGN_EPI>
; __device__ __forceinline__ void gemm_phase(LAS unsigned char* lds, const Gemm g, const StaticOrder& S, const Epi& E, const int tid) {
;     ...
;             PG8_WAIT_V(8); PG8_WAIT_L(0); PG8_BAR; PG8_MMA(0, 0, At, B0); PG8_MMA(0, 1, At, B1); PG8_BAR; PG8_SCHED;
;             PG8_LDA(At, 1, 1); PG8_STAGE(PG8_SB(1, 0), b3, voffB); PG8_STAGE(PG8_SB(1, 1), b3 + hB, voffB); PG8_STAGE(PG8_SA(1, 0), a3, voffA);
;             PG8_WAIT_V(8); PG8_WAIT_L(0); PG8_BAR; PG8_MMA(1, 0, At, B0); PG8_MMA(1, 1, At, B1); PG8_BAR; PG8_SCHED;
	s_waitcnt lgkmcnt(0)
	v_mfma_f32_16x16x32_bf16 v[124:127], v[152:155], v[192:195], v[124:127]
	v_mfma_f32_16x16x32_bf16 v[120:123], v[160:163], v[192:195], v[120:123]
	v_mfma_f32_16x16x32_bf16 v[108:111], v[152:155], v[200:203], v[108:111]
	v_mfma_f32_16x16x32_bf16 v[104:107], v[160:163], v[200:203], v[104:107]
	v_mfma_f32_16x16x32_bf16 v[92:95], v[152:155], v[208:211], v[92:95]
	v_mfma_f32_16x16x32_bf16 v[88:91], v[160:163], v[208:211], v[88:91]
	v_mfma_f32_16x16x32_bf16 v[76:79], v[152:155], v[216:219], v[76:79]
	v_mfma_f32_16x16x32_bf16 v[72:75], v[160:163], v[216:219], v[72:75]
	v_mfma_f32_16x16x32_bf16 v[124:127], v[156:159], v[196:199], v[124:127]
	v_mfma_f32_16x16x32_bf16 v[120:123], v[164:167], v[196:199], v[120:123]
	v_mfma_f32_16x16x32_bf16 v[108:111], v[156:159], v[204:207], v[108:111]
	v_mfma_f32_16x16x32_bf16 v[104:107], v[164:167], v[204:207], v[104:107]
	v_mfma_f32_16x16x32_bf16 v[92:95], v[156:159], v[212:215], v[92:95]
	v_mfma_f32_16x16x32_bf16 v[88:91], v[164:167], v[212:215], v[88:91]
	v_mfma_f32_16x16x32_bf16 v[76:79], v[156:159], v[240:243], v[76:79]
	v_mfma_f32_16x16x32_bf16 v[72:75], v[164:167], v[240:243], v[72:75]
	s_setprio 0
	s_setprio 1
	v_mfma_f32_16x16x32_bf16 v[116:119], v[176:179], v[192:195], v[116:119]
	v_mfma_f32_16x16x32_bf16 v[112:115], v[184:187], v[192:195], v[112:115]
	v_mfma_f32_16x16x32_bf16 v[100:103], v[176:179], v[200:203], v[100:103]
	v_mfma_f32_16x16x32_bf16 v[96:99], v[184:187], v[200:203], v[96:99]
	v_mfma_f32_16x16x32_bf16 v[84:87], v[176:179], v[208:211], v[84:87]
	v_mfma_f32_16x16x32_bf16 v[80:83], v[184:187], v[208:211], v[80:83]
	v_mfma_f32_16x16x32_bf16 v[68:71], v[176:179], v[216:219], v[68:71]
	v_mfma_f32_16x16x32_bf16 v[64:67], v[184:187], v[216:219], v[64:67]
	v_mfma_f32_16x16x32_bf16 v[116:119], v[180:183], v[196:199], v[116:119]
	v_mfma_f32_16x16x32_bf16 v[112:115], v[188:191], v[196:199], v[112:115]
	v_mfma_f32_16x16x32_bf16 v[100:103], v[180:183], v[204:207], v[100:103]
	v_mfma_f32_16x16x32_bf16 v[96:99], v[188:191], v[204:207], v[96:99]
	v_mfma_f32_16x16x32_bf16 v[84:87], v[180:183], v[212:215], v[84:87]
	v_mfma_f32_16x16x32_bf16 v[80:83], v[188:191], v[212:215], v[80:83]
	v_mfma_f32_16x16x32_bf16 v[68:71], v[180:183], v[240:243], v[68:71]
	v_mfma_f32_16x16x32_bf16 v[64:67], v[188:191], v[240:243], v[64:67]
	s_setprio 0
	s_barrier
	s_add_i32 s10, s10, s45
	v_lshl_add_u64 v[146:147], v[244:245], 0, s[92:93]
	s_mov_b32 m0, s10
	ds_read_b128 v[192:195], v151 offset:49152
	ds_read_b128 v[196:199], v151 offset:50176
	ds_read_b128 v[200:203], v151 offset:51200
	ds_read_b128 v[204:207], v151 offset:52224
	ds_read_b128 v[208:211], v151 offset:53248
	ds_read_b128 v[212:215], v151 offset:54272
	ds_read_b128 v[216:219], v151 offset:55296
	ds_read_b128 v[240:243], v151 offset:56320
	global_load_lds_dwordx4 v[146:147], off
	v_lshl_add_u64 v[146:147], v[246:247], 0, s[92:93]
	s_add_i32 m0, s10, 0x2000
	s_add_i32 s10, s62, s45
	global_load_lds_dwordx4 v[146:147], off
	v_lshl_add_u64 v[146:147], v[248:249], 0, s[92:93]
	s_mov_b32 m0, s10
	s_nop 0
	global_load_lds_dwordx4 v[146:147], off
	v_lshl_add_u64 v[146:147], v[220:221], 0, s[92:93]
	s_add_i32 m0, s10, 0x2000
	s_nop 0
	global_load_lds_dwordx4 v[146:147], off
	v_lshl_add_u64 v[146:147], v[250:251], 0, s[92:93]
	s_mov_b32 m0, s53
	s_nop 0
	global_load_lds_dwordx4 v[146:147], off
	v_lshl_add_u64 v[146:147], v[252:253], 0, s[92:93]
	s_mov_b32 m0, s54
	s_nop 0
	global_load_lds_dwordx4 v[146:147], off
	s_waitcnt vmcnt(8)
	s_waitcnt lgkmcnt(0)
	s_setprio 1
	s_barrier
	s_waitcnt lgkmcnt(0)
	v_mfma_f32_16x16x32_bf16 v[60:63], v[152:155], v[192:195], v[60:63]
	v_lshrrev_b32_e32 v171, 8, v170
	v_and_b32_e32 v234, 15, v170
	v_lshl_add_u32 v171, v171, 6, v234
	s_lshl_b32 s98, s61, 8
	v_add_u32_e32 v171, s98, v171
	v_mfma_f32_16x16x32_bf16 v[56:59], v[160:163], v[192:195], v[56:59]
	v_mul_lo_u32 v171, v171, s28
	v_bfe_u32 v234, v170, 6, 2
	v_bfe_u32 v224, v170, 4, 2
	v_lshlrev_b32_e32 v234, 5, v234
	v_lshl_or_b32 v234, v224, 3, v234
	v_mfma_f32_16x16x32_bf16 v[44:47], v[152:155], v[200:203], v[44:47]
	s_lshl_b32 s98, s60, 8
	v_add_u32_e32 v234, s98, v234
	v_add_lshl_u32 v232, v171, v234, 1
	v_mov_b32_e32 v233, 0
	v_lshl_add_u64 v[232:233], v[232:233], 0, s[30:31]
	v_mfma_f32_16x16x32_bf16 v[40:43], v[160:163], v[200:203], v[40:43]
	s_lshl_b32 s98, s28, 5
	s_mov_b32 s99, 0
	v_mul_f32_e32 v124, v172, v124
	v_mul_f32_e32 v125, v172, v125
	v_mul_f32_e32 v126, v172, v126
	v_mfma_f32_16x16x32_bf16 v[28:31], v[152:155], v[208:211], v[28:31]
	v_mul_f32_e32 v127, v172, v127
	v_mul_f32_e32 v120, v172, v120
	v_mul_f32_e32 v121, v172, v121
	v_mul_f32_e32 v122, v172, v122
	v_mul_f32_e32 v123, v172, v123
	v_mfma_f32_16x16x32_bf16 v[24:27], v[160:163], v[208:211], v[24:27]
	v_cvt_pk_bf16_f32 v124, v124, v125
	v_cvt_pk_bf16_f32 v125, v126, v127
	v_cvt_pk_bf16_f32 v126, v120, v121
	v_cvt_pk_bf16_f32 v127, v122, v123
	global_store_dwordx4 v[232:233], v[124:127], off
	v_mfma_f32_16x16x32_bf16 v[12:15], v[152:155], v[216:219], v[12:15]
	v_mul_f32_e32 v116, v172, v116
	v_mul_f32_e32 v117, v172, v117
	v_mul_f32_e32 v118, v172, v118
	v_mul_f32_e32 v119, v172, v119
	v_mul_f32_e32 v112, v172, v112
	v_mfma_f32_16x16x32_bf16 v[8:11], v[160:163], v[216:219], v[8:11]
	v_mul_f32_e32 v113, v172, v113
	v_mul_f32_e32 v114, v172, v114
; __device__ __forceinline__ unsigned cvt_pk_bf16(float lo, float hi) { unsigned r; asm volatile("v_cvt_pk_bf16_f32 %0, %1, %2" : "=v"(r) : "v"(lo), "v"(hi)); return r; }
; __device__ __forceinline__ float gelu_tanh(float x) { const float u = 0.7978845608028654f * (x + 0.044715f * x * x * x); return x * fast_rcp(1.0f + fast_exp2(-2.0f * LOG2E * u)); }
; #define PG8_BAR __builtin_amdgcn_s_barrier()
;     __device__ __forceinline__ void operator()(const f32x4 (&acc)[2][2][4][2], const Unit& u, int wr, int wc, int fr, int fq) const {
;     ...
;             for (int m = 0; m < 4; ++m) { const int row = row0 + ai * HALF + m * 16; bf16_t* rowp = O + (size_t)row * ldc + col0; const float rs = rsv[ai][m];
; #pragma unroll
;                 for (int bj = 0; bj < 2; ++bj) { f32x4 v0 = acc[ai][bj][m][0] * rs, v1 = acc[ai][bj][m][1] * rs;
;                     if (ACT == 1) {
; #pragma unroll
;                         for (int j = 0; j < 4; ++j) { v0[j] = gelu_tanh(v0[j]); v1[j] = gelu_tanh(v1[j]); } }
;                     u32x4 w; w.x = cvt_pk_bf16(v0[0], v0[1]); w.y = cvt_pk_bf16(v0[2], v0[3]); w.z = cvt_pk_bf16(v1[0], v1[1]); w.w = cvt_pk_bf16(v1[2], v1[3]);
;                     *(u32x4*)(rowp + bj * HALF) = w; } }
; template <class Epi, bool ALIGN_EPI>
; __device__ __forceinline__ void gemm_phase(LAS unsigned char* lds, const Gemm g, const StaticOrder& S, const Epi& E, const int tid) {
;     ...
;         if constexpr (ALIGN_EPI) { if (wr == 0) PG8_BAR; }
;         { int t2 = tid; asm volatile("" : "+v"(t2)); const int l2 = t2 & 63, w2 = __builtin_amdgcn_readfirstlane(t2 >> 6); E(acc, cur, w2 >> 2, w2 & 3, l2 & 15, l2 >> 4); }
;         if (!has_next) break;
; #pragma unroll
;         for (int a = 0; a < 2; ++a)
; #pragma unroll
;             for (int b = 0; b < 2; ++b)
; #pragma unroll
;                 for (int m = 0; m < 4; ++m)
; #pragma unroll
;                     for (int n = 0; n < 2; ++n) acc[a][b][m][n] = (f32x4){0.f, 0.f, 0.f, 0.f};
;         cur = nxt; cA = nA; cB = nB; ++ui;
	v_mul_f32_e32 v115, v172, v115
	v_cvt_pk_bf16_f32 v116, v116, v117
	v_cvt_pk_bf16_f32 v117, v118, v119
	v_mfma_f32_16x16x32_bf16 v[60:63], v[156:159], v[196:199], v[60:63]
	v_cvt_pk_bf16_f32 v118, v112, v113
	v_cvt_pk_bf16_f32 v119, v114, v115
	global_store_dwordx4 v[232:233], v[116:119], off offset:256
	v_lshl_add_u64 v[232:233], v[232:233], 0, s[98:99]
	v_mul_f32_e32 v108, v173, v108
	v_mfma_f32_16x16x32_bf16 v[56:59], v[164:167], v[196:199], v[56:59]
	v_mul_f32_e32 v109, v173, v109
	v_mul_f32_e32 v110, v173, v110
	v_mul_f32_e32 v111, v173, v111
	v_mul_f32_e32 v104, v173, v104
	v_mul_f32_e32 v105, v173, v105
	v_mfma_f32_16x16x32_bf16 v[44:47], v[156:159], v[204:207], v[44:47]
	v_mul_f32_e32 v106, v173, v106
	v_mul_f32_e32 v107, v173, v107
	v_cvt_pk_bf16_f32 v108, v108, v109
	v_cvt_pk_bf16_f32 v109, v110, v111
	v_cvt_pk_bf16_f32 v110, v104, v105
	v_mfma_f32_16x16x32_bf16 v[40:43], v[164:167], v[204:207], v[40:43]
	v_cvt_pk_bf16_f32 v111, v106, v107
	global_store_dwordx4 v[232:233], v[108:111], off
	v_mul_f32_e32 v100, v173, v100
	v_mul_f32_e32 v101, v173, v101
	v_mul_f32_e32 v102, v173, v102
	v_mfma_f32_16x16x32_bf16 v[28:31], v[156:159], v[212:215], v[28:31]
	v_mul_f32_e32 v103, v173, v103
	v_mul_f32_e32 v96, v173, v96
	v_mul_f32_e32 v97, v173, v97
	v_mul_f32_e32 v98, v173, v98
	v_mul_f32_e32 v99, v173, v99
	v_mfma_f32_16x16x32_bf16 v[24:27], v[164:167], v[212:215], v[24:27]
	v_cvt_pk_bf16_f32 v100, v100, v101
	v_cvt_pk_bf16_f32 v101, v102, v103
	v_cvt_pk_bf16_f32 v102, v96, v97
	v_cvt_pk_bf16_f32 v103, v98, v99
	global_store_dwordx4 v[232:233], v[100:103], off offset:256
	v_mfma_f32_16x16x32_bf16 v[12:15], v[156:159], v[240:243], v[12:15]
	v_lshl_add_u64 v[232:233], v[232:233], 0, s[98:99]
	v_mul_f32_e32 v92, v236, v92
	v_mul_f32_e32 v93, v236, v93
	v_mul_f32_e32 v94, v236, v94
	v_mul_f32_e32 v95, v236, v95
	v_mfma_f32_16x16x32_bf16 v[8:11], v[164:167], v[240:243], v[8:11]
	v_mul_f32_e32 v88, v236, v88
	v_mul_f32_e32 v89, v236, v89
	v_mul_f32_e32 v90, v236, v90
	v_mul_f32_e32 v91, v236, v91
	v_cvt_pk_bf16_f32 v92, v92, v93
	s_setprio 0
	s_setprio 1
	v_mfma_f32_16x16x32_bf16 v[52:55], v[176:179], v[192:195], v[52:55]
	v_cvt_pk_bf16_f32 v93, v94, v95
	v_cvt_pk_bf16_f32 v94, v88, v89
	v_cvt_pk_bf16_f32 v95, v90, v91
	global_store_dwordx4 v[232:233], v[92:95], off
	v_mul_f32_e32 v84, v236, v84
	v_mfma_f32_16x16x32_bf16 v[48:51], v[184:187], v[192:195], v[48:51]
	v_mul_f32_e32 v85, v236, v85
	v_mul_f32_e32 v86, v236, v86
	v_mul_f32_e32 v87, v236, v87
	v_mul_f32_e32 v80, v236, v80
	v_mul_f32_e32 v81, v236, v81
	v_mfma_f32_16x16x32_bf16 v[36:39], v[176:179], v[200:203], v[36:39]
	v_mul_f32_e32 v82, v236, v82
	v_mul_f32_e32 v83, v236, v83
	v_cvt_pk_bf16_f32 v84, v84, v85
	v_cvt_pk_bf16_f32 v85, v86, v87
	v_cvt_pk_bf16_f32 v86, v80, v81
	v_mfma_f32_16x16x32_bf16 v[32:35], v[184:187], v[200:203], v[32:35]
	v_cvt_pk_bf16_f32 v87, v82, v83
	global_store_dwordx4 v[232:233], v[84:87], off offset:256
	v_lshl_add_u64 v[232:233], v[232:233], 0, s[98:99]
	v_mul_f32_e32 v76, v237, v76
	v_mul_f32_e32 v77, v237, v77
	v_mfma_f32_16x16x32_bf16 v[20:23], v[176:179], v[208:211], v[20:23]
	v_mul_f32_e32 v78, v237, v78
	v_mul_f32_e32 v79, v237, v79
	v_mul_f32_e32 v72, v237, v72
	v_mul_f32_e32 v73, v237, v73
	v_mul_f32_e32 v74, v237, v74
	v_mfma_f32_16x16x32_bf16 v[16:19], v[184:187], v[208:211], v[16:19]
	v_mul_f32_e32 v75, v237, v75
	v_cvt_pk_bf16_f32 v76, v76, v77
	v_cvt_pk_bf16_f32 v77, v78, v79
	v_cvt_pk_bf16_f32 v78, v72, v73
	v_cvt_pk_bf16_f32 v79, v74, v75
	v_mfma_f32_16x16x32_bf16 v[4:7], v[176:179], v[216:219], v[4:7]
	global_store_dwordx4 v[232:233], v[76:79], off
	v_mul_f32_e32 v68, v237, v68
	v_mul_f32_e32 v69, v237, v69
	v_mul_f32_e32 v70, v237, v70
	v_mul_f32_e32 v71, v237, v71
	v_mfma_f32_16x16x32_bf16 v[0:3], v[184:187], v[216:219], v[0:3]
	v_mul_f32_e32 v64, v237, v64
	v_mul_f32_e32 v65, v237, v65
	v_mul_f32_e32 v66, v237, v66
	v_mul_f32_e32 v67, v237, v67
	v_cvt_pk_bf16_f32 v68, v68, v69
	v_mfma_f32_16x16x32_bf16 v[52:55], v[180:183], v[196:199], v[52:55]
	v_cvt_pk_bf16_f32 v69, v70, v71
	v_cvt_pk_bf16_f32 v70, v64, v65
	v_cvt_pk_bf16_f32 v71, v66, v67
	global_store_dwordx4 v[232:233], v[68:71], off offset:256
	v_lshl_add_u64 v[232:233], v[232:233], 0, s[98:99]
	v_mfma_f32_16x16x32_bf16 v[48:51], v[188:191], v[196:199], v[48:51]
	v_lshl_add_u64 v[232:233], v[232:233], 0, s[98:99]
	v_lshl_add_u64 v[232:233], v[232:233], 0, s[98:99]
	v_lshl_add_u64 v[232:233], v[232:233], 0, s[98:99]
	v_lshl_add_u64 v[232:233], v[232:233], 0, s[98:99]
	v_mfma_f32_16x16x32_bf16 v[36:39], v[180:183], v[204:207], v[36:39]
	v_mfma_f32_16x16x32_bf16 v[32:35], v[188:191], v[204:207], v[32:35]
	v_mfma_f32_16x16x32_bf16 v[20:23], v[180:183], v[212:215], v[20:23]
	v_mfma_f32_16x16x32_bf16 v[16:19], v[188:191], v[212:215], v[16:19]
	v_mfma_f32_16x16x32_bf16 v[4:7], v[180:183], v[240:243], v[4:7]
	v_mfma_f32_16x16x32_bf16 v[0:3], v[188:191], v[240:243], v[0:3]
	s_setprio 0
	s_barrier
	v_lshl_add_u64 v[142:143], v[142:143], 0, s[80:81]
	v_lshl_add_u64 v[144:145], v[144:145], 0, s[80:81]
	s_and_b64 vcc, exec, s[8:9]
	s_cbranch_vccnz .Lq5_notdefer
	s_cmp_lg_u32 s59, s61
	s_cbranch_scc1 .Lq5_notdefer
	s_mov_b32 s101, 1
	s_mov_b32 s60, s58
	s_mov_b32 s61, s59
	v_mov_b64_e32 v[144:145], v[140:141]
	v_mov_b64_e32 v[142:143], v[138:139]
	s_branch .LBB0_346

; #define PG8_STAGE(bufoff, gbase, voff) do { _Pragma("unroll") for (int _i = 0; _i < 2; ++_i) \
;         __builtin_amdgcn_global_load_lds((const unsigned*)((const char*)(gbase) + (voff)[_i]), (LAS unsigned*)(lds + (bufoff) + ldsw + _i * 8192), 16, 0, 0); } while (0)
; #define PG8_LDA(dst, b, h) do { _Pragma("unroll") for (int m = 0; m < 4; ++m) _Pragma("unroll") for (int k = 0; k < 2; ++k) dst[m][k] = *(const LAS bf16x8*)(lds + PG8_SA(b, h) + aoff + m * 2048 + k * 1024); } while (0)
; #define PG8_LDB(dst, b, h) do { _Pragma("unroll") for (int n = 0; n < 2; ++n) _Pragma("unroll") for (int k = 0; k < 2; ++k) dst[n][k] = *(const LAS bf16x8*)(lds + PG8_SB(b, h) + boff + n * 2048 + k * 1024); } while (0)
; #define PG8_MMA(ai, bj, At, Bt) do { __builtin_amdgcn_s_setprio(1); _Pragma("unroll") for (int k = 0; k < 2; ++k) _Pragma("unroll") for (int m = 0; m < 4; ++m) _Pragma("unroll") for (int n = 0; n < 2; ++n) \
;         acc[ai][bj][m][n] = __builtin_amdgcn_mfma_f32_16x16x32_bf16(Bt[n][k], At[m][k], acc[ai][bj][m][n], 0, 0, 0); __builtin_amdgcn_s_setprio(0); } while (0)
; template <class Epi, bool ALIGN_EPI>
; __device__ __forceinline__ void gemm_phase(LAS unsigned char* lds, const Gemm g, const StaticOrder& S, const Epi& E, const int tid) {
;     ...
;         const bool has_next = S.next(ui + 1, nxt);
;         const char* nA = has_next ? (const char*)g.A + (size_t)nxt.pm * tA + (size_t)nxt.pn * g.apn * 2 : cA; const char* nB = has_next ? (const char*)g.Bt + (size_t)nxt.pn * tB : cB;
;         for (int t = 0; t < nt; t += 2) {
;             const bool last = (t == nt - 2);
;             const char* a1 = cA + (size_t)(t + 1) * kstep;
;             const char* a2 = last ? nA : cA + (size_t)(t + 2) * kstep; const char* b2 = last ? nB : cB + (size_t)(t + 2) * kstep;
;             const char* a3 = a2 + kstep; const char* b3 = b2 + kstep;
;             PG8_LDB(B0, 0, 0); PG8_LDB(B1, 0, 1); PG8_SCHED; PG8_LDA(At, 0, 0); PG8_STAGE(PG8_SA(1, 1), a1 + hA, voffA);
;             PG8_WAIT_V(8); PG8_WAIT_L(0); PG8_BAR; PG8_MMA(0, 0, At, B0); PG8_MMA(0, 1, At, B1); PG8_BAR; PG8_SCHED;
;             PG8_LDA(At, 0, 1); PG8_STAGE(PG8_SB(0, 0), b2, voffB); PG8_STAGE(PG8_SB(0, 1), b2 + hB, voffB); PG8_STAGE(PG8_SA(0, 0), a2, voffA);
;             PG8_WAIT_V(8); PG8_WAIT_L(0); PG8_BAR; PG8_MMA(1, 0, At, B0); PG8_MMA(1, 1, At, B1); PG8_BAR; PG8_SCHED;
.LBB0_378:
	s_ashr_i32 s17, s16, 31
	s_lshl_b64 s[22:23], s[16:17], 17
	s_add_u32 s22, s4, s22
	s_addc_u32 s23, s5, s23
	s_and_b64 s[26:27], s[8:9], exec
	s_cselect_b32 s17, s23, s35
	s_cselect_b32 s59, s22, s34
	s_ashr_i32 s15, s14, 31
	s_lshl_b64 s[26:27], s[14:15], 17
	s_add_u32 s26, s7, s26
	s_addc_u32 s27, s25, s27
	s_and_b64 s[36:37], s[8:9], exec
	s_cselect_b32 s15, s27, s31
	s_cselect_b32 s60, s26, s30
	s_mov_b32 s40, 0
	s_mov_b64 s[36:37], -1
	s_mov_b64 s[38:39], 0
	s_add_u32 s41, s34, s40
	s_addc_u32 s46, s35, 0
	s_add_u32 s44, s41, 0x100
	s_addc_u32 s45, s46, 0
	s_and_b64 s[42:43], s[38:39], exec
	s_cselect_b32 s43, s17, s45
	s_cselect_b32 s42, s59, s44
	s_add_u32 s40, s30, s40
	s_addc_u32 s44, s31, 0
	s_add_u32 s40, s40, 0x100
	s_addc_u32 s44, s44, 0
	s_and_b64 s[38:39], s[38:39], exec
	s_cselect_b32 s45, s15, s44
	s_cselect_b32 s44, s60, s40
	s_add_i32 s39, 0, 0x14000
	s_add_u32 s48, s41, 0x10080
	s_addc_u32 s49, s46, 0
	s_add_i32 s68, s33, s50
	s_add_i32 m0, s51, 0xc000
	s_add_i32 s71, s51, 0xe000
	s_add_i32 s65, s68, 0x2000
	v_add_u32_e32 v138, s33, v141
	s_add_u32 s46, s44, 0x10000
	ds_read_b128 v[134:137], v138
	ds_read_b128 v[146:149], v138 offset:1024
	ds_read_b128 v[150:153], v138 offset:2048
	ds_read_b128 v[154:157], v138 offset:3072
	v_add_u32_e32 v138, s39, v141
	s_addc_u32 s47, s45, 0
	s_add_i32 s67, s39, s50
	ds_read_b128 v[158:161], v138
	ds_read_b128 v[162:165], v138 offset:1024
	ds_read_b128 v[174:177], v138 offset:2048
	ds_read_b128 v[178:181], v138 offset:3072
	s_add_i32 s66, s67, 0x2000
	s_add_i32 s64, 0, 0x18000
	s_add_i32 s63, 0, 0x1c000
	s_add_u32 s40, s42, 0x10000
	s_addc_u32 s41, s43, 0
	s_add_i32 s62, s64, s50
	s_add_i32 s61, s62, 0x2000
	s_add_u32 s38, s44, 0x10080
	s_addc_u32 s39, s45, 0
	s_add_i32 s70, s63, s50
	s_add_i32 s69, s70, 0x2000
	v_lshl_add_u64 v[138:139], s[48:49], 0, v[128:129]
	ds_read_b128 v[182:185], v145
	ds_read_b128 v[186:189], v145 offset:1024
	ds_read_b128 v[190:193], v145 offset:2048
	ds_read_b128 v[194:197], v145 offset:3072
	ds_read_b128 v[198:201], v145 offset:4096
	ds_read_b128 v[202:205], v145 offset:5120
	ds_read_b128 v[206:209], v145 offset:6144
	ds_read_b128 v[210:213], v145 offset:7168
	global_load_lds_dwordx4 v[138:139], off
	v_lshl_add_u64 v[138:139], s[48:49], 0, v[130:131]
	s_mov_b32 m0, s71
	s_nop 0
	global_load_lds_dwordx4 v[138:139], off
	s_waitcnt vmcnt(8)
	s_waitcnt lgkmcnt(0)
	s_setprio 1
	s_barrier
	s_waitcnt lgkmcnt(0)
	v_mfma_f32_16x16x32_bf16 v[124:127], v[134:137], v[182:185], 0
	v_mfma_f32_16x16x32_bf16 v[120:123], v[150:153], v[182:185], 0
	v_mfma_f32_16x16x32_bf16 v[108:111], v[134:137], v[190:193], 0
	v_mfma_f32_16x16x32_bf16 v[104:107], v[150:153], v[190:193], 0
	v_mfma_f32_16x16x32_bf16 v[92:95], v[134:137], v[198:201], 0
	v_mfma_f32_16x16x32_bf16 v[88:91], v[150:153], v[198:201], 0
	v_mfma_f32_16x16x32_bf16 v[76:79], v[134:137], v[206:209], 0
	v_mfma_f32_16x16x32_bf16 v[72:75], v[150:153], v[206:209], 0
	v_mfma_f32_16x16x32_bf16 v[124:127], v[146:149], v[186:189], v[124:127]
	v_mfma_f32_16x16x32_bf16 v[120:123], v[154:157], v[186:189], v[120:123]
	v_mfma_f32_16x16x32_bf16 v[108:111], v[146:149], v[194:197], v[108:111]
	v_mfma_f32_16x16x32_bf16 v[104:107], v[154:157], v[194:197], v[104:107]
	v_mfma_f32_16x16x32_bf16 v[92:95], v[146:149], v[202:205], v[92:95]
	v_mfma_f32_16x16x32_bf16 v[88:91], v[154:157], v[202:205], v[88:91]
	v_mfma_f32_16x16x32_bf16 v[76:79], v[146:149], v[210:213], v[76:79]
	v_mfma_f32_16x16x32_bf16 v[72:75], v[154:157], v[210:213], v[72:75]
	s_setprio 0
	s_setprio 1
	v_mfma_f32_16x16x32_bf16 v[116:119], v[158:161], v[182:185], 0
	v_mfma_f32_16x16x32_bf16 v[112:115], v[174:177], v[182:185], 0
	v_mfma_f32_16x16x32_bf16 v[100:103], v[158:161], v[190:193], 0
	v_mfma_f32_16x16x32_bf16 v[96:99], v[174:177], v[190:193], 0
	v_mfma_f32_16x16x32_bf16 v[84:87], v[158:161], v[198:201], 0
	v_mfma_f32_16x16x32_bf16 v[80:83], v[174:177], v[198:201], 0
	v_mfma_f32_16x16x32_bf16 v[68:71], v[158:161], v[206:209], 0
	v_mfma_f32_16x16x32_bf16 v[64:67], v[174:177], v[206:209], 0
	v_mfma_f32_16x16x32_bf16 v[116:119], v[162:165], v[186:189], v[116:119]
	v_mfma_f32_16x16x32_bf16 v[112:115], v[178:181], v[186:189], v[112:115]
	v_mfma_f32_16x16x32_bf16 v[100:103], v[162:165], v[194:197], v[100:103]
	v_mfma_f32_16x16x32_bf16 v[96:99], v[178:181], v[194:197], v[96:99]
	v_mfma_f32_16x16x32_bf16 v[84:87], v[162:165], v[202:205], v[84:87]
	v_mfma_f32_16x16x32_bf16 v[80:83], v[178:181], v[202:205], v[80:83]
	v_mfma_f32_16x16x32_bf16 v[68:71], v[162:165], v[210:213], v[68:71]
	v_mfma_f32_16x16x32_bf16 v[64:67], v[178:181], v[210:213], v[64:67]
	s_setprio 0
	s_barrier
	s_mov_b32 m0, s68
	v_lshl_add_u64 v[138:139], s[44:45], 0, v[168:169]
	ds_read_b128 v[182:185], v145 offset:16384
	ds_read_b128 v[186:189], v145 offset:17408
	ds_read_b128 v[190:193], v145 offset:18432
	ds_read_b128 v[194:197], v145 offset:19456
	ds_read_b128 v[198:201], v145 offset:20480
	ds_read_b128 v[202:205], v145 offset:21504
	ds_read_b128 v[206:209], v145 offset:22528
	ds_read_b128 v[210:213], v145 offset:23552
	global_load_lds_dwordx4 v[138:139], off
	v_lshl_add_u64 v[142:143], s[44:45], 0, v[132:133]
	s_mov_b32 m0, s65
	v_lshl_add_u64 v[166:167], s[46:47], 0, v[168:169]
	global_load_lds_dwordx4 v[142:143], off
	s_mov_b32 m0, s67
	v_lshl_add_u64 v[214:215], s[42:43], 0, v[130:131]
	global_load_lds_dwordx4 v[166:167], off
	v_lshl_add_u64 v[166:167], s[46:47], 0, v[132:133]
	s_mov_b32 m0, s66
	s_nop 0
	global_load_lds_dwordx4 v[166:167], off
	v_lshl_add_u64 v[166:167], s[42:43], 0, v[128:129]
	s_mov_b32 m0, s51
	s_nop 0
	global_load_lds_dwordx4 v[166:167], off
	s_mov_b32 m0, s52
	s_nop 0
	global_load_lds_dwordx4 v[214:215], off
	s_waitcnt vmcnt(8)
	s_waitcnt lgkmcnt(0)
	s_setprio 1
	s_barrier
; #define PG8_STAGE(bufoff, gbase, voff) do { _Pragma("unroll") for (int _i = 0; _i < 2; ++_i) \
;         __builtin_amdgcn_global_load_lds((const unsigned*)((const char*)(gbase) + (voff)[_i]), (LAS unsigned*)(lds + (bufoff) + ldsw + _i * 8192), 16, 0, 0); } while (0)
; #define PG8_LDA(dst, b, h) do { _Pragma("unroll") for (int m = 0; m < 4; ++m) _Pragma("unroll") for (int k = 0; k < 2; ++k) dst[m][k] = *(const LAS bf16x8*)(lds + PG8_SA(b, h) + aoff + m * 2048 + k * 1024); } while (0)
; #define PG8_LDB(dst, b, h) do { _Pragma("unroll") for (int n = 0; n < 2; ++n) _Pragma("unroll") for (int k = 0; k < 2; ++k) dst[n][k] = *(const LAS bf16x8*)(lds + PG8_SB(b, h) + boff + n * 2048 + k * 1024); } while (0)
; #define PG8_MMA(ai, bj, At, Bt) do { __builtin_amdgcn_s_setprio(1); _Pragma("unroll") for (int k = 0; k < 2; ++k) _Pragma("unroll") for (int m = 0; m < 4; ++m) _Pragma("unroll") for (int n = 0; n < 2; ++n) \
;         acc[ai][bj][m][n] = __builtin_amdgcn_mfma_f32_16x16x32_bf16(Bt[n][k], At[m][k], acc[ai][bj][m][n], 0, 0, 0); __builtin_amdgcn_s_setprio(0); } while (0)
; #define PG8_WAIT_V(n) asm volatile("s_waitcnt vmcnt(" #n ")" ::: "memory")
; #define PG8_WAIT_L(n) asm volatile("s_waitcnt lgkmcnt(" #n ")" ::: "memory")
; #define PG8_BAR __builtin_amdgcn_s_barrier()
; #define PG8_SCHED __builtin_amdgcn_sched_barrier(0)
; template <class Epi, bool ALIGN_EPI>
; __device__ __forceinline__ void gemm_phase(LAS unsigned char* lds, const Gemm g, const StaticOrder& S, const Epi& E, const int tid) {
;     ...
;             PG8_WAIT_V(8); PG8_WAIT_L(0); PG8_BAR; PG8_MMA(1, 0, At, B0); PG8_MMA(1, 1, At, B1); PG8_BAR; PG8_SCHED;
;             PG8_LDB(B0, 1, 0); PG8_LDB(B1, 1, 1); PG8_SCHED; PG8_LDA(At, 1, 0); PG8_STAGE(PG8_SA(0, 1), a2 + hA, voffA);
;             PG8_WAIT_V(8); PG8_WAIT_L(0); PG8_BAR; PG8_MMA(0, 0, At, B0); PG8_MMA(0, 1, At, B1); PG8_BAR; PG8_SCHED;
;             PG8_LDA(At, 1, 1); PG8_STAGE(PG8_SB(1, 0), b3, voffB); PG8_STAGE(PG8_SB(1, 1), b3 + hB, voffB); PG8_STAGE(PG8_SA(1, 0), a3, voffA);
	s_waitcnt lgkmcnt(0)
	v_mfma_f32_16x16x32_bf16 v[60:63], v[134:137], v[182:185], 0
	v_mfma_f32_16x16x32_bf16 v[56:59], v[150:153], v[182:185], 0
	v_mfma_f32_16x16x32_bf16 v[48:51], v[134:137], v[190:193], 0
	v_mfma_f32_16x16x32_bf16 v[40:43], v[150:153], v[190:193], 0
	v_mfma_f32_16x16x32_bf16 v[32:35], v[134:137], v[198:201], 0
	v_mfma_f32_16x16x32_bf16 v[24:27], v[150:153], v[198:201], 0
	v_mfma_f32_16x16x32_bf16 v[16:19], v[134:137], v[206:209], 0
	v_mfma_f32_16x16x32_bf16 v[8:11], v[150:153], v[206:209], 0
	v_mfma_f32_16x16x32_bf16 v[60:63], v[146:149], v[186:189], v[60:63]
	v_mfma_f32_16x16x32_bf16 v[56:59], v[154:157], v[186:189], v[56:59]
	v_mfma_f32_16x16x32_bf16 v[48:51], v[146:149], v[194:197], v[48:51]
	v_mfma_f32_16x16x32_bf16 v[40:43], v[154:157], v[194:197], v[40:43]
	v_mfma_f32_16x16x32_bf16 v[32:35], v[146:149], v[202:205], v[32:35]
	v_mfma_f32_16x16x32_bf16 v[24:27], v[154:157], v[202:205], v[24:27]
	v_mfma_f32_16x16x32_bf16 v[16:19], v[146:149], v[210:213], v[16:19]
	v_mfma_f32_16x16x32_bf16 v[8:11], v[154:157], v[210:213], v[8:11]
	s_setprio 0
	s_setprio 1
	v_mfma_f32_16x16x32_bf16 v[52:55], v[158:161], v[182:185], 0
	v_mfma_f32_16x16x32_bf16 v[44:47], v[174:177], v[182:185], 0
	v_mfma_f32_16x16x32_bf16 v[36:39], v[158:161], v[190:193], 0
	v_mfma_f32_16x16x32_bf16 v[28:31], v[174:177], v[190:193], 0
	v_mfma_f32_16x16x32_bf16 v[20:23], v[158:161], v[198:201], 0
	v_mfma_f32_16x16x32_bf16 v[12:15], v[174:177], v[198:201], 0
	v_mfma_f32_16x16x32_bf16 v[4:7], v[158:161], v[206:209], 0
	v_mfma_f32_16x16x32_bf16 v[0:3], v[174:177], v[206:209], 0
	v_mfma_f32_16x16x32_bf16 v[52:55], v[162:165], v[186:189], v[52:55]
	v_mfma_f32_16x16x32_bf16 v[44:47], v[178:181], v[186:189], v[44:47]
	v_mfma_f32_16x16x32_bf16 v[36:39], v[162:165], v[194:197], v[36:39]
	v_mfma_f32_16x16x32_bf16 v[28:31], v[178:181], v[194:197], v[28:31]
	v_mfma_f32_16x16x32_bf16 v[20:23], v[162:165], v[202:205], v[20:23]
	v_mfma_f32_16x16x32_bf16 v[12:15], v[178:181], v[202:205], v[12:15]
	v_mfma_f32_16x16x32_bf16 v[4:7], v[162:165], v[210:213], v[4:7]
	v_mfma_f32_16x16x32_bf16 v[0:3], v[178:181], v[210:213], v[0:3]
	s_setprio 0
	s_barrier
	v_add_u32_e32 v140, s64, v141
	ds_read_b128 v[134:137], v140
	ds_read_b128 v[146:149], v140 offset:1024
	ds_read_b128 v[150:153], v140 offset:2048
	ds_read_b128 v[154:157], v140 offset:3072
	v_add_u32_e32 v140, s63, v141
	ds_read_b128 v[158:161], v140
	ds_read_b128 v[162:165], v140 offset:1024
	ds_read_b128 v[174:177], v140 offset:2048
	ds_read_b128 v[178:181], v140 offset:3072
	s_mov_b32 m0, s53
	v_lshl_add_u64 v[216:217], s[40:41], 0, v[128:129]
	ds_read_b128 v[182:185], v145 offset:32768
	ds_read_b128 v[186:189], v145 offset:33792
	ds_read_b128 v[190:193], v145 offset:34816
	ds_read_b128 v[194:197], v145 offset:35840
	ds_read_b128 v[198:201], v145 offset:36864
	ds_read_b128 v[202:205], v145 offset:37888
	ds_read_b128 v[206:209], v145 offset:38912
	ds_read_b128 v[210:213], v145 offset:39936
	global_load_lds_dwordx4 v[216:217], off
	v_lshl_add_u64 v[216:217], s[40:41], 0, v[130:131]
	s_mov_b32 m0, s54
	s_nop 0
	global_load_lds_dwordx4 v[216:217], off
	s_waitcnt vmcnt(8)
	s_waitcnt lgkmcnt(0)
	s_setprio 1
	s_barrier
	s_waitcnt lgkmcnt(0)
	v_mfma_f32_16x16x32_bf16 v[124:127], v[134:137], v[182:185], v[124:127]
	v_mfma_f32_16x16x32_bf16 v[120:123], v[150:153], v[182:185], v[120:123]
	v_mfma_f32_16x16x32_bf16 v[108:111], v[134:137], v[190:193], v[108:111]
	v_mfma_f32_16x16x32_bf16 v[104:107], v[150:153], v[190:193], v[104:107]
	v_mfma_f32_16x16x32_bf16 v[92:95], v[134:137], v[198:201], v[92:95]
	v_mfma_f32_16x16x32_bf16 v[88:91], v[150:153], v[198:201], v[88:91]
	v_mfma_f32_16x16x32_bf16 v[76:79], v[134:137], v[206:209], v[76:79]
	v_mfma_f32_16x16x32_bf16 v[72:75], v[150:153], v[206:209], v[72:75]
	v_mfma_f32_16x16x32_bf16 v[124:127], v[146:149], v[186:189], v[124:127]
	v_mfma_f32_16x16x32_bf16 v[120:123], v[154:157], v[186:189], v[120:123]
	v_mfma_f32_16x16x32_bf16 v[108:111], v[146:149], v[194:197], v[108:111]
	v_mfma_f32_16x16x32_bf16 v[104:107], v[154:157], v[194:197], v[104:107]
	v_mfma_f32_16x16x32_bf16 v[92:95], v[146:149], v[202:205], v[92:95]
	v_mfma_f32_16x16x32_bf16 v[88:91], v[154:157], v[202:205], v[88:91]
	v_mfma_f32_16x16x32_bf16 v[76:79], v[146:149], v[210:213], v[76:79]
	v_mfma_f32_16x16x32_bf16 v[72:75], v[154:157], v[210:213], v[72:75]
	s_setprio 0
	s_setprio 1
	v_mfma_f32_16x16x32_bf16 v[116:119], v[158:161], v[182:185], v[116:119]
	v_mfma_f32_16x16x32_bf16 v[112:115], v[174:177], v[182:185], v[112:115]
	v_mfma_f32_16x16x32_bf16 v[100:103], v[158:161], v[190:193], v[100:103]
	v_mfma_f32_16x16x32_bf16 v[96:99], v[174:177], v[190:193], v[96:99]
	v_mfma_f32_16x16x32_bf16 v[84:87], v[158:161], v[198:201], v[84:87]
	v_mfma_f32_16x16x32_bf16 v[80:83], v[174:177], v[198:201], v[80:83]
	v_mfma_f32_16x16x32_bf16 v[68:71], v[158:161], v[206:209], v[68:71]
	v_mfma_f32_16x16x32_bf16 v[64:67], v[174:177], v[206:209], v[64:67]
	v_mfma_f32_16x16x32_bf16 v[116:119], v[162:165], v[186:189], v[116:119]
	v_mfma_f32_16x16x32_bf16 v[112:115], v[178:181], v[186:189], v[112:115]
	v_mfma_f32_16x16x32_bf16 v[100:103], v[162:165], v[194:197], v[100:103]
	v_mfma_f32_16x16x32_bf16 v[96:99], v[178:181], v[194:197], v[96:99]
	v_mfma_f32_16x16x32_bf16 v[84:87], v[162:165], v[202:205], v[84:87]
	v_mfma_f32_16x16x32_bf16 v[80:83], v[178:181], v[202:205], v[80:83]
	v_mfma_f32_16x16x32_bf16 v[68:71], v[162:165], v[210:213], v[68:71]
	v_mfma_f32_16x16x32_bf16 v[64:67], v[178:181], v[210:213], v[64:67]
	s_setprio 0
	s_barrier
; #define PG8_STAGE(bufoff, gbase, voff) do { _Pragma("unroll") for (int _i = 0; _i < 2; ++_i) \
;         __builtin_amdgcn_global_load_lds((const unsigned*)((const char*)(gbase) + (voff)[_i]), (LAS unsigned*)(lds + (bufoff) + ldsw + _i * 8192), 16, 0, 0); } while (0)
; #define PG8_LDA(dst, b, h) do { _Pragma("unroll") for (int m = 0; m < 4; ++m) _Pragma("unroll") for (int k = 0; k < 2; ++k) dst[m][k] = *(const LAS bf16x8*)(lds + PG8_SA(b, h) + aoff + m * 2048 + k * 1024); } while (0)
; #define PG8_LDB(dst, b, h) do { _Pragma("unroll") for (int n = 0; n < 2; ++n) _Pragma("unroll") for (int k = 0; k < 2; ++k) dst[n][k] = *(const LAS bf16x8*)(lds + PG8_SB(b, h) + boff + n * 2048 + k * 1024); } while (0)
; #define PG8_MMA(ai, bj, At, Bt) do { __builtin_amdgcn_s_setprio(1); _Pragma("unroll") for (int k = 0; k < 2; ++k) _Pragma("unroll") for (int m = 0; m < 4; ++m) _Pragma("unroll") for (int n = 0; n < 2; ++n) \
;         acc[ai][bj][m][n] = __builtin_amdgcn_mfma_f32_16x16x32_bf16(Bt[n][k], At[m][k], acc[ai][bj][m][n], 0, 0, 0); __builtin_amdgcn_s_setprio(0); } while (0)
; #define PG8_WAIT_V(n) asm volatile("s_waitcnt vmcnt(" #n ")" ::: "memory")
; #define PG8_WAIT_L(n) asm volatile("s_waitcnt lgkmcnt(" #n ")" ::: "memory")
; #define PG8_BAR __builtin_amdgcn_s_barrier()
; #define PG8_SCHED __builtin_amdgcn_sched_barrier(0)
; template <class Epi, bool ALIGN_EPI>
; __device__ __forceinline__ void gemm_phase(LAS unsigned char* lds, const Gemm g, const StaticOrder& S, const Epi& E, const int tid) {
;     ...
;         for (int t = 0; t < nt; t += 2) {
;             const bool last = (t == nt - 2);
;             const char* a1 = cA + (size_t)(t + 1) * kstep;
;             const char* a2 = last ? nA : cA + (size_t)(t + 2) * kstep; const char* b2 = last ? nB : cB + (size_t)(t + 2) * kstep;
;             const char* a3 = a2 + kstep; const char* b3 = b2 + kstep;
;             PG8_LDB(B0, 0, 0); PG8_LDB(B1, 0, 1); PG8_SCHED; PG8_LDA(At, 0, 0); PG8_STAGE(PG8_SA(1, 1), a1 + hA, voffA);
;             PG8_WAIT_V(8); PG8_WAIT_L(0); PG8_BAR; PG8_MMA(0, 0, At, B0); PG8_MMA(0, 1, At, B1); PG8_BAR; PG8_SCHED;
;     ...
;             PG8_LDA(At, 1, 1); PG8_STAGE(PG8_SB(1, 0), b3, voffB); PG8_STAGE(PG8_SB(1, 1), b3 + hB, voffB); PG8_STAGE(PG8_SA(1, 0), a3, voffA);
;             PG8_WAIT_V(8); PG8_WAIT_L(0); PG8_BAR; PG8_MMA(1, 0, At, B0); PG8_MMA(1, 1, At, B1); PG8_BAR; PG8_SCHED;
	s_mov_b32 m0, s62
	v_lshl_add_u64 v[138:139], v[138:139], 0, s[92:93]
	ds_read_b128 v[182:185], v145 offset:49152
	ds_read_b128 v[186:189], v145 offset:50176
	ds_read_b128 v[190:193], v145 offset:51200
	ds_read_b128 v[194:197], v145 offset:52224
	ds_read_b128 v[198:201], v145 offset:53248
	ds_read_b128 v[202:205], v145 offset:54272
	ds_read_b128 v[206:209], v145 offset:55296
	ds_read_b128 v[210:213], v145 offset:56320
	global_load_lds_dwordx4 v[138:139], off
	v_lshl_add_u64 v[138:139], v[142:143], 0, s[92:93]
	s_mov_b32 m0, s61
	s_nop 0
	global_load_lds_dwordx4 v[138:139], off
	v_lshl_add_u64 v[138:139], s[38:39], 0, v[168:169]
	s_mov_b32 m0, s70
	s_nop 0
	global_load_lds_dwordx4 v[138:139], off
	v_lshl_add_u64 v[138:139], s[38:39], 0, v[132:133]
	s_mov_b32 m0, s69
	s_nop 0
	global_load_lds_dwordx4 v[138:139], off
	v_lshl_add_u64 v[138:139], v[166:167], 0, s[92:93]
	s_mov_b32 m0, s55
	s_nop 0
	global_load_lds_dwordx4 v[138:139], off
	v_lshl_add_u64 v[138:139], v[214:215], 0, s[92:93]
	s_mov_b32 m0, s56
	s_nop 0
	global_load_lds_dwordx4 v[138:139], off
	s_waitcnt vmcnt(8)
	s_waitcnt lgkmcnt(0)
	s_setprio 1
	s_barrier
	s_waitcnt lgkmcnt(0)
	v_mfma_f32_16x16x32_bf16 v[60:63], v[134:137], v[182:185], v[60:63]
	v_mfma_f32_16x16x32_bf16 v[56:59], v[150:153], v[182:185], v[56:59]
	v_mfma_f32_16x16x32_bf16 v[48:51], v[134:137], v[190:193], v[48:51]
	v_mfma_f32_16x16x32_bf16 v[40:43], v[150:153], v[190:193], v[40:43]
	v_mfma_f32_16x16x32_bf16 v[32:35], v[134:137], v[198:201], v[32:35]
	v_mfma_f32_16x16x32_bf16 v[24:27], v[150:153], v[198:201], v[24:27]
	v_mfma_f32_16x16x32_bf16 v[16:19], v[134:137], v[206:209], v[16:19]
	v_mfma_f32_16x16x32_bf16 v[8:11], v[150:153], v[206:209], v[8:11]
	v_mfma_f32_16x16x32_bf16 v[60:63], v[146:149], v[186:189], v[60:63]
	v_mfma_f32_16x16x32_bf16 v[56:59], v[154:157], v[186:189], v[56:59]
	v_mfma_f32_16x16x32_bf16 v[48:51], v[146:149], v[194:197], v[48:51]
	v_mfma_f32_16x16x32_bf16 v[40:43], v[154:157], v[194:197], v[40:43]
	v_mfma_f32_16x16x32_bf16 v[32:35], v[146:149], v[202:205], v[32:35]
	v_mfma_f32_16x16x32_bf16 v[24:27], v[154:157], v[202:205], v[24:27]
	v_mfma_f32_16x16x32_bf16 v[16:19], v[146:149], v[210:213], v[16:19]
	v_mfma_f32_16x16x32_bf16 v[8:11], v[154:157], v[210:213], v[8:11]
	s_setprio 0
	s_setprio 1
	v_mfma_f32_16x16x32_bf16 v[52:55], v[158:161], v[182:185], v[52:55]
	v_mfma_f32_16x16x32_bf16 v[44:47], v[174:177], v[182:185], v[44:47]
	v_mfma_f32_16x16x32_bf16 v[36:39], v[158:161], v[190:193], v[36:39]
	v_mfma_f32_16x16x32_bf16 v[28:31], v[174:177], v[190:193], v[28:31]
	v_mfma_f32_16x16x32_bf16 v[20:23], v[158:161], v[198:201], v[20:23]
	v_mfma_f32_16x16x32_bf16 v[12:15], v[174:177], v[198:201], v[12:15]
	v_mfma_f32_16x16x32_bf16 v[4:7], v[158:161], v[206:209], v[4:7]
	v_mfma_f32_16x16x32_bf16 v[0:3], v[174:177], v[206:209], v[0:3]
	v_mfma_f32_16x16x32_bf16 v[52:55], v[162:165], v[186:189], v[52:55]
	v_mfma_f32_16x16x32_bf16 v[44:47], v[178:181], v[186:189], v[44:47]
	v_mfma_f32_16x16x32_bf16 v[36:39], v[162:165], v[194:197], v[36:39]
	v_mfma_f32_16x16x32_bf16 v[28:31], v[178:181], v[194:197], v[28:31]
	v_mfma_f32_16x16x32_bf16 v[20:23], v[162:165], v[202:205], v[20:23]
	v_mfma_f32_16x16x32_bf16 v[12:15], v[178:181], v[202:205], v[12:15]
	v_mfma_f32_16x16x32_bf16 v[4:7], v[162:165], v[210:213], v[4:7]
	v_mfma_f32_16x16x32_bf16 v[0:3], v[178:181], v[210:213], v[0:3]
	s_setprio 0
	s_barrier
	s_movk_i32 s40, 0x100
	s_andn2_b64 vcc, exec, s[36:37]
	s_mov_b64 s[38:39], -1
	s_mov_b64 s[36:37], 0
.LBB0_379:
	s_add_u32 s41, s34, s40
	s_addc_u32 s46, s35, 0
	s_add_u32 s44, s41, 0x100
	s_addc_u32 s45, s46, 0
	s_and_b64 s[42:43], s[38:39], exec
	s_cselect_b32 s43, s17, s45
	s_cselect_b32 s42, s59, s44
	s_add_u32 s40, s30, s40
	s_addc_u32 s44, s31, 0
	s_add_u32 s40, s40, 0x100
	s_addc_u32 s44, s44, 0
	s_and_b64 s[38:39], s[38:39], exec
	s_cselect_b32 s45, s15, s44
	s_cselect_b32 s44, s60, s40
	s_add_i32 s39, 0, 0x14000
	s_add_u32 s48, s41, 0x10080
	s_addc_u32 s49, s46, 0
	s_add_i32 s68, s33, s50
	s_add_i32 m0, s51, 0xc000
	s_add_i32 s71, s51, 0xe000
	s_add_i32 s65, s68, 0x2000
	v_add_u32_e32 v138, s33, v141
	s_add_u32 s46, s44, 0x10000
	ds_read_b128 v[134:137], v138
	ds_read_b128 v[146:149], v138 offset:1024
	ds_read_b128 v[150:153], v138 offset:2048
	ds_read_b128 v[154:157], v138 offset:3072
	v_add_u32_e32 v138, s39, v141
	s_addc_u32 s47, s45, 0
	s_add_i32 s67, s39, s50
	ds_read_b128 v[158:161], v138
	ds_read_b128 v[162:165], v138 offset:1024
	ds_read_b128 v[174:177], v138 offset:2048
	ds_read_b128 v[178:181], v138 offset:3072
	s_add_i32 s66, s67, 0x2000
	s_add_i32 s64, 0, 0x18000
	s_add_i32 s63, 0, 0x1c000
	s_add_u32 s40, s42, 0x10000
	s_addc_u32 s41, s43, 0
	s_add_i32 s62, s64, s50
	s_add_i32 s61, s62, 0x2000
	s_add_u32 s38, s44, 0x10080
	s_addc_u32 s39, s45, 0
	s_add_i32 s70, s63, s50
	s_add_i32 s69, s70, 0x2000
	v_lshl_add_u64 v[138:139], s[48:49], 0, v[128:129]
	ds_read_b128 v[182:185], v145
	ds_read_b128 v[186:189], v145 offset:1024
	ds_read_b128 v[190:193], v145 offset:2048
	ds_read_b128 v[194:197], v145 offset:3072
	ds_read_b128 v[198:201], v145 offset:4096
	ds_read_b128 v[202:205], v145 offset:5120
	ds_read_b128 v[206:209], v145 offset:6144
	ds_read_b128 v[210:213], v145 offset:7168
	global_load_lds_dwordx4 v[138:139], off
	v_lshl_add_u64 v[138:139], s[48:49], 0, v[130:131]
	s_mov_b32 m0, s71
	s_nop 0
	global_load_lds_dwordx4 v[138:139], off
	s_waitcnt vmcnt(8)
	s_waitcnt lgkmcnt(0)
	s_setprio 1
	s_barrier
; #define PG8_STAGE(bufoff, gbase, voff) do { _Pragma("unroll") for (int _i = 0; _i < 2; ++_i) \
;         __builtin_amdgcn_global_load_lds((const unsigned*)((const char*)(gbase) + (voff)[_i]), (LAS unsigned*)(lds + (bufoff) + ldsw + _i * 8192), 16, 0, 0); } while (0)
; #define PG8_LDA(dst, b, h) do { _Pragma("unroll") for (int m = 0; m < 4; ++m) _Pragma("unroll") for (int k = 0; k < 2; ++k) dst[m][k] = *(const LAS bf16x8*)(lds + PG8_SA(b, h) + aoff + m * 2048 + k * 1024); } while (0)
; #define PG8_LDB(dst, b, h) do { _Pragma("unroll") for (int n = 0; n < 2; ++n) _Pragma("unroll") for (int k = 0; k < 2; ++k) dst[n][k] = *(const LAS bf16x8*)(lds + PG8_SB(b, h) + boff + n * 2048 + k * 1024); } while (0)
; #define PG8_MMA(ai, bj, At, Bt) do { __builtin_amdgcn_s_setprio(1); _Pragma("unroll") for (int k = 0; k < 2; ++k) _Pragma("unroll") for (int m = 0; m < 4; ++m) _Pragma("unroll") for (int n = 0; n < 2; ++n) \
;         acc[ai][bj][m][n] = __builtin_amdgcn_mfma_f32_16x16x32_bf16(Bt[n][k], At[m][k], acc[ai][bj][m][n], 0, 0, 0); __builtin_amdgcn_s_setprio(0); } while (0)
; #define PG8_WAIT_V(n) asm volatile("s_waitcnt vmcnt(" #n ")" ::: "memory")
; #define PG8_WAIT_L(n) asm volatile("s_waitcnt lgkmcnt(" #n ")" ::: "memory")
; #define PG8_BAR __builtin_amdgcn_s_barrier()
; #define PG8_SCHED __builtin_amdgcn_sched_barrier(0)
; template <class Epi, bool ALIGN_EPI>
; __device__ __forceinline__ void gemm_phase(LAS unsigned char* lds, const Gemm g, const StaticOrder& S, const Epi& E, const int tid) {
;     ...
;             PG8_WAIT_V(8); PG8_WAIT_L(0); PG8_BAR; PG8_MMA(0, 0, At, B0); PG8_MMA(0, 1, At, B1); PG8_BAR; PG8_SCHED;
;             PG8_LDA(At, 0, 1); PG8_STAGE(PG8_SB(0, 0), b2, voffB); PG8_STAGE(PG8_SB(0, 1), b2 + hB, voffB); PG8_STAGE(PG8_SA(0, 0), a2, voffA);
;             PG8_WAIT_V(8); PG8_WAIT_L(0); PG8_BAR; PG8_MMA(1, 0, At, B0); PG8_MMA(1, 1, At, B1); PG8_BAR; PG8_SCHED;
;             PG8_LDB(B0, 1, 0); PG8_LDB(B1, 1, 1); PG8_SCHED; PG8_LDA(At, 1, 0); PG8_STAGE(PG8_SA(0, 1), a2 + hA, voffA);
;             PG8_WAIT_V(8); PG8_WAIT_L(0); PG8_BAR; PG8_MMA(0, 0, At, B0); PG8_MMA(0, 1, At, B1); PG8_BAR; PG8_SCHED;
	s_waitcnt lgkmcnt(0)
	v_mfma_f32_16x16x32_bf16 v[124:127], v[134:137], v[182:185], v[124:127]
	v_mfma_f32_16x16x32_bf16 v[120:123], v[150:153], v[182:185], v[120:123]
	v_mfma_f32_16x16x32_bf16 v[108:111], v[134:137], v[190:193], v[108:111]
	v_mfma_f32_16x16x32_bf16 v[104:107], v[150:153], v[190:193], v[104:107]
	v_mfma_f32_16x16x32_bf16 v[92:95], v[134:137], v[198:201], v[92:95]
	v_mfma_f32_16x16x32_bf16 v[88:91], v[150:153], v[198:201], v[88:91]
	v_mfma_f32_16x16x32_bf16 v[76:79], v[134:137], v[206:209], v[76:79]
	v_mfma_f32_16x16x32_bf16 v[72:75], v[150:153], v[206:209], v[72:75]
	v_mfma_f32_16x16x32_bf16 v[124:127], v[146:149], v[186:189], v[124:127]
	v_mfma_f32_16x16x32_bf16 v[120:123], v[154:157], v[186:189], v[120:123]
	v_mfma_f32_16x16x32_bf16 v[108:111], v[146:149], v[194:197], v[108:111]
	v_mfma_f32_16x16x32_bf16 v[104:107], v[154:157], v[194:197], v[104:107]
	v_mfma_f32_16x16x32_bf16 v[92:95], v[146:149], v[202:205], v[92:95]
	v_mfma_f32_16x16x32_bf16 v[88:91], v[154:157], v[202:205], v[88:91]
	v_mfma_f32_16x16x32_bf16 v[76:79], v[146:149], v[210:213], v[76:79]
	v_mfma_f32_16x16x32_bf16 v[72:75], v[154:157], v[210:213], v[72:75]
	s_setprio 0
	s_setprio 1
	v_mfma_f32_16x16x32_bf16 v[116:119], v[158:161], v[182:185], v[116:119]
	v_mfma_f32_16x16x32_bf16 v[112:115], v[174:177], v[182:185], v[112:115]
	v_mfma_f32_16x16x32_bf16 v[100:103], v[158:161], v[190:193], v[100:103]
	v_mfma_f32_16x16x32_bf16 v[96:99], v[174:177], v[190:193], v[96:99]
	v_mfma_f32_16x16x32_bf16 v[84:87], v[158:161], v[198:201], v[84:87]
	v_mfma_f32_16x16x32_bf16 v[80:83], v[174:177], v[198:201], v[80:83]
	v_mfma_f32_16x16x32_bf16 v[68:71], v[158:161], v[206:209], v[68:71]
	v_mfma_f32_16x16x32_bf16 v[64:67], v[174:177], v[206:209], v[64:67]
	v_mfma_f32_16x16x32_bf16 v[116:119], v[162:165], v[186:189], v[116:119]
	v_mfma_f32_16x16x32_bf16 v[112:115], v[178:181], v[186:189], v[112:115]
	v_mfma_f32_16x16x32_bf16 v[100:103], v[162:165], v[194:197], v[100:103]
	v_mfma_f32_16x16x32_bf16 v[96:99], v[178:181], v[194:197], v[96:99]
	v_mfma_f32_16x16x32_bf16 v[84:87], v[162:165], v[202:205], v[84:87]
	v_mfma_f32_16x16x32_bf16 v[80:83], v[178:181], v[202:205], v[80:83]
	v_mfma_f32_16x16x32_bf16 v[68:71], v[162:165], v[210:213], v[68:71]
	v_mfma_f32_16x16x32_bf16 v[64:67], v[178:181], v[210:213], v[64:67]
	s_setprio 0
	s_barrier
	s_mov_b32 m0, s68
	v_lshl_add_u64 v[138:139], s[44:45], 0, v[168:169]
	ds_read_b128 v[182:185], v145 offset:16384
	ds_read_b128 v[186:189], v145 offset:17408
	ds_read_b128 v[190:193], v145 offset:18432
	ds_read_b128 v[194:197], v145 offset:19456
	ds_read_b128 v[198:201], v145 offset:20480
	ds_read_b128 v[202:205], v145 offset:21504
	ds_read_b128 v[206:209], v145 offset:22528
	ds_read_b128 v[210:213], v145 offset:23552
	global_load_lds_dwordx4 v[138:139], off
	v_lshl_add_u64 v[142:143], s[44:45], 0, v[132:133]
	s_mov_b32 m0, s65
	v_lshl_add_u64 v[166:167], s[46:47], 0, v[168:169]
	global_load_lds_dwordx4 v[142:143], off
	s_mov_b32 m0, s67
	v_lshl_add_u64 v[214:215], s[42:43], 0, v[130:131]
	global_load_lds_dwordx4 v[166:167], off
	v_lshl_add_u64 v[166:167], s[46:47], 0, v[132:133]
	s_mov_b32 m0, s66
	s_nop 0
	global_load_lds_dwordx4 v[166:167], off
	v_lshl_add_u64 v[166:167], s[42:43], 0, v[128:129]
	s_mov_b32 m0, s51
	s_nop 0
	global_load_lds_dwordx4 v[166:167], off
	s_mov_b32 m0, s52
	s_nop 0
	global_load_lds_dwordx4 v[214:215], off
	s_waitcnt vmcnt(8)
	s_waitcnt lgkmcnt(0)
	s_setprio 1
	s_barrier
	s_waitcnt lgkmcnt(0)
	v_mfma_f32_16x16x32_bf16 v[60:63], v[134:137], v[182:185], v[60:63]
	v_mfma_f32_16x16x32_bf16 v[56:59], v[150:153], v[182:185], v[56:59]
	v_mfma_f32_16x16x32_bf16 v[48:51], v[134:137], v[190:193], v[48:51]
	v_mfma_f32_16x16x32_bf16 v[40:43], v[150:153], v[190:193], v[40:43]
	v_mfma_f32_16x16x32_bf16 v[32:35], v[134:137], v[198:201], v[32:35]
	v_mfma_f32_16x16x32_bf16 v[24:27], v[150:153], v[198:201], v[24:27]
	v_mfma_f32_16x16x32_bf16 v[16:19], v[134:137], v[206:209], v[16:19]
	v_mfma_f32_16x16x32_bf16 v[8:11], v[150:153], v[206:209], v[8:11]
	v_mfma_f32_16x16x32_bf16 v[60:63], v[146:149], v[186:189], v[60:63]
	v_mfma_f32_16x16x32_bf16 v[56:59], v[154:157], v[186:189], v[56:59]
	v_mfma_f32_16x16x32_bf16 v[48:51], v[146:149], v[194:197], v[48:51]
	v_mfma_f32_16x16x32_bf16 v[40:43], v[154:157], v[194:197], v[40:43]
	v_mfma_f32_16x16x32_bf16 v[32:35], v[146:149], v[202:205], v[32:35]
	v_mfma_f32_16x16x32_bf16 v[24:27], v[154:157], v[202:205], v[24:27]
	v_mfma_f32_16x16x32_bf16 v[16:19], v[146:149], v[210:213], v[16:19]
	v_mfma_f32_16x16x32_bf16 v[8:11], v[154:157], v[210:213], v[8:11]
	s_setprio 0
	s_setprio 1
	v_mfma_f32_16x16x32_bf16 v[52:55], v[158:161], v[182:185], v[52:55]
	v_mfma_f32_16x16x32_bf16 v[44:47], v[174:177], v[182:185], v[44:47]
	v_mfma_f32_16x16x32_bf16 v[36:39], v[158:161], v[190:193], v[36:39]
	v_mfma_f32_16x16x32_bf16 v[28:31], v[174:177], v[190:193], v[28:31]
	v_mfma_f32_16x16x32_bf16 v[20:23], v[158:161], v[198:201], v[20:23]
	v_mfma_f32_16x16x32_bf16 v[12:15], v[174:177], v[198:201], v[12:15]
	v_mfma_f32_16x16x32_bf16 v[4:7], v[158:161], v[206:209], v[4:7]
	v_mfma_f32_16x16x32_bf16 v[0:3], v[174:177], v[206:209], v[0:3]
	v_mfma_f32_16x16x32_bf16 v[52:55], v[162:165], v[186:189], v[52:55]
	v_mfma_f32_16x16x32_bf16 v[44:47], v[178:181], v[186:189], v[44:47]
	v_mfma_f32_16x16x32_bf16 v[36:39], v[162:165], v[194:197], v[36:39]
	v_mfma_f32_16x16x32_bf16 v[28:31], v[178:181], v[194:197], v[28:31]
	v_mfma_f32_16x16x32_bf16 v[20:23], v[162:165], v[202:205], v[20:23]
	v_mfma_f32_16x16x32_bf16 v[12:15], v[178:181], v[202:205], v[12:15]
	v_mfma_f32_16x16x32_bf16 v[4:7], v[162:165], v[210:213], v[4:7]
	v_mfma_f32_16x16x32_bf16 v[0:3], v[178:181], v[210:213], v[0:3]
	s_setprio 0
	s_barrier
; #define PG8_STAGE(bufoff, gbase, voff) do { _Pragma("unroll") for (int _i = 0; _i < 2; ++_i) \
;         __builtin_amdgcn_global_load_lds((const unsigned*)((const char*)(gbase) + (voff)[_i]), (LAS unsigned*)(lds + (bufoff) + ldsw + _i * 8192), 16, 0, 0); } while (0)
; #define PG8_LDA(dst, b, h) do { _Pragma("unroll") for (int m = 0; m < 4; ++m) _Pragma("unroll") for (int k = 0; k < 2; ++k) dst[m][k] = *(const LAS bf16x8*)(lds + PG8_SA(b, h) + aoff + m * 2048 + k * 1024); } while (0)
; #define PG8_LDB(dst, b, h) do { _Pragma("unroll") for (int n = 0; n < 2; ++n) _Pragma("unroll") for (int k = 0; k < 2; ++k) dst[n][k] = *(const LAS bf16x8*)(lds + PG8_SB(b, h) + boff + n * 2048 + k * 1024); } while (0)
; #define PG8_MMA(ai, bj, At, Bt) do { __builtin_amdgcn_s_setprio(1); _Pragma("unroll") for (int k = 0; k < 2; ++k) _Pragma("unroll") for (int m = 0; m < 4; ++m) _Pragma("unroll") for (int n = 0; n < 2; ++n) \
;         acc[ai][bj][m][n] = __builtin_amdgcn_mfma_f32_16x16x32_bf16(Bt[n][k], At[m][k], acc[ai][bj][m][n], 0, 0, 0); __builtin_amdgcn_s_setprio(0); } while (0)
; #define PG8_WAIT_V(n) asm volatile("s_waitcnt vmcnt(" #n ")" ::: "memory")
; #define PG8_WAIT_L(n) asm volatile("s_waitcnt lgkmcnt(" #n ")" ::: "memory")
; #define PG8_BAR __builtin_amdgcn_s_barrier()
; #define PG8_SCHED __builtin_amdgcn_sched_barrier(0)
; template <class Epi, bool ALIGN_EPI>
; __device__ __forceinline__ void gemm_phase(LAS unsigned char* lds, const Gemm g, const StaticOrder& S, const Epi& E, const int tid) {
;     ...
;             PG8_LDB(B0, 1, 0); PG8_LDB(B1, 1, 1); PG8_SCHED; PG8_LDA(At, 1, 0); PG8_STAGE(PG8_SA(0, 1), a2 + hA, voffA);
;             PG8_WAIT_V(8); PG8_WAIT_L(0); PG8_BAR; PG8_MMA(0, 0, At, B0); PG8_MMA(0, 1, At, B1); PG8_BAR; PG8_SCHED;
;             PG8_LDA(At, 1, 1); PG8_STAGE(PG8_SB(1, 0), b3, voffB); PG8_STAGE(PG8_SB(1, 1), b3 + hB, voffB); PG8_STAGE(PG8_SA(1, 0), a3, voffA);
;             PG8_WAIT_V(8); PG8_WAIT_L(0); PG8_BAR; PG8_MMA(1, 0, At, B0); PG8_MMA(1, 1, At, B1); PG8_BAR; PG8_SCHED;
;         }
;         if constexpr (ALIGN_EPI) { if (wr == 0) PG8_BAR; }
;         { int t2 = tid; asm volatile("" : "+v"(t2)); const int l2 = t2 & 63, w2 = __builtin_amdgcn_readfirstlane(t2 >> 6); E(acc, cur, w2 >> 2, w2 & 3, l2 & 15, l2 >> 4); }
	v_add_u32_e32 v140, s64, v141
	ds_read_b128 v[134:137], v140
	ds_read_b128 v[146:149], v140 offset:1024
	ds_read_b128 v[150:153], v140 offset:2048
	ds_read_b128 v[154:157], v140 offset:3072
	v_add_u32_e32 v140, s63, v141
	ds_read_b128 v[158:161], v140
	ds_read_b128 v[162:165], v140 offset:1024
	ds_read_b128 v[174:177], v140 offset:2048
	ds_read_b128 v[178:181], v140 offset:3072
	s_mov_b32 m0, s53
	v_lshl_add_u64 v[216:217], s[40:41], 0, v[128:129]
	ds_read_b128 v[182:185], v145 offset:32768
	ds_read_b128 v[186:189], v145 offset:33792
	ds_read_b128 v[190:193], v145 offset:34816
	ds_read_b128 v[194:197], v145 offset:35840
	ds_read_b128 v[198:201], v145 offset:36864
	ds_read_b128 v[202:205], v145 offset:37888
	ds_read_b128 v[206:209], v145 offset:38912
	ds_read_b128 v[210:213], v145 offset:39936
	global_load_lds_dwordx4 v[216:217], off
	v_lshl_add_u64 v[216:217], s[40:41], 0, v[130:131]
	s_mov_b32 m0, s54
	s_nop 0
	global_load_lds_dwordx4 v[216:217], off
	s_waitcnt vmcnt(8)
	s_waitcnt lgkmcnt(0)
	s_setprio 1
	s_barrier
	s_waitcnt lgkmcnt(0)
	v_mfma_f32_16x16x32_bf16 v[124:127], v[134:137], v[182:185], v[124:127]
	v_mfma_f32_16x16x32_bf16 v[120:123], v[150:153], v[182:185], v[120:123]
	v_mfma_f32_16x16x32_bf16 v[108:111], v[134:137], v[190:193], v[108:111]
	v_mfma_f32_16x16x32_bf16 v[104:107], v[150:153], v[190:193], v[104:107]
	v_mfma_f32_16x16x32_bf16 v[92:95], v[134:137], v[198:201], v[92:95]
	v_mfma_f32_16x16x32_bf16 v[88:91], v[150:153], v[198:201], v[88:91]
	v_mfma_f32_16x16x32_bf16 v[76:79], v[134:137], v[206:209], v[76:79]
	v_mfma_f32_16x16x32_bf16 v[72:75], v[150:153], v[206:209], v[72:75]
	v_mfma_f32_16x16x32_bf16 v[124:127], v[146:149], v[186:189], v[124:127]
	v_mfma_f32_16x16x32_bf16 v[120:123], v[154:157], v[186:189], v[120:123]
	v_mfma_f32_16x16x32_bf16 v[108:111], v[146:149], v[194:197], v[108:111]
	v_mfma_f32_16x16x32_bf16 v[104:107], v[154:157], v[194:197], v[104:107]
	v_mfma_f32_16x16x32_bf16 v[92:95], v[146:149], v[202:205], v[92:95]
	v_mfma_f32_16x16x32_bf16 v[88:91], v[154:157], v[202:205], v[88:91]
	v_mfma_f32_16x16x32_bf16 v[76:79], v[146:149], v[210:213], v[76:79]
	v_mfma_f32_16x16x32_bf16 v[72:75], v[154:157], v[210:213], v[72:75]
	s_setprio 0
	s_setprio 1
	v_mfma_f32_16x16x32_bf16 v[116:119], v[158:161], v[182:185], v[116:119]
	v_mfma_f32_16x16x32_bf16 v[112:115], v[174:177], v[182:185], v[112:115]
	v_mfma_f32_16x16x32_bf16 v[100:103], v[158:161], v[190:193], v[100:103]
	v_mfma_f32_16x16x32_bf16 v[96:99], v[174:177], v[190:193], v[96:99]
	v_mfma_f32_16x16x32_bf16 v[84:87], v[158:161], v[198:201], v[84:87]
	v_mfma_f32_16x16x32_bf16 v[80:83], v[174:177], v[198:201], v[80:83]
	v_mfma_f32_16x16x32_bf16 v[68:71], v[158:161], v[206:209], v[68:71]
	v_mfma_f32_16x16x32_bf16 v[64:67], v[174:177], v[206:209], v[64:67]
	v_mfma_f32_16x16x32_bf16 v[116:119], v[162:165], v[186:189], v[116:119]
	v_mfma_f32_16x16x32_bf16 v[112:115], v[178:181], v[186:189], v[112:115]
	v_mfma_f32_16x16x32_bf16 v[100:103], v[162:165], v[194:197], v[100:103]
	v_mfma_f32_16x16x32_bf16 v[96:99], v[178:181], v[194:197], v[96:99]
	v_mfma_f32_16x16x32_bf16 v[84:87], v[162:165], v[202:205], v[84:87]
	v_mfma_f32_16x16x32_bf16 v[80:83], v[178:181], v[202:205], v[80:83]
	v_mfma_f32_16x16x32_bf16 v[68:71], v[162:165], v[210:213], v[68:71]
	v_mfma_f32_16x16x32_bf16 v[64:67], v[178:181], v[210:213], v[64:67]
	s_setprio 0
	s_barrier
	s_mov_b32 m0, s62
	v_lshl_add_u64 v[138:139], v[138:139], 0, s[92:93]
	ds_read_b128 v[182:185], v145 offset:49152
	ds_read_b128 v[186:189], v145 offset:50176
	ds_read_b128 v[190:193], v145 offset:51200
	ds_read_b128 v[194:197], v145 offset:52224
	ds_read_b128 v[198:201], v145 offset:53248
	ds_read_b128 v[202:205], v145 offset:54272
	ds_read_b128 v[206:209], v145 offset:55296
	ds_read_b128 v[210:213], v145 offset:56320
	global_load_lds_dwordx4 v[138:139], off
	v_lshl_add_u64 v[138:139], v[142:143], 0, s[92:93]
	s_mov_b32 m0, s61
	s_nop 0
	global_load_lds_dwordx4 v[138:139], off
	v_lshl_add_u64 v[138:139], s[38:39], 0, v[168:169]
	s_mov_b32 m0, s70
	s_nop 0
	global_load_lds_dwordx4 v[138:139], off
	v_lshl_add_u64 v[138:139], s[38:39], 0, v[132:133]
	s_mov_b32 m0, s69
	s_nop 0
	global_load_lds_dwordx4 v[138:139], off
	v_lshl_add_u64 v[138:139], v[166:167], 0, s[92:93]
	s_mov_b32 m0, s55
	s_nop 0
	global_load_lds_dwordx4 v[138:139], off
	v_lshl_add_u64 v[138:139], v[214:215], 0, s[92:93]
	s_mov_b32 m0, s56
	s_nop 0
	global_load_lds_dwordx4 v[138:139], off
	s_waitcnt vmcnt(8)
	s_waitcnt lgkmcnt(0)
	s_setprio 1
	s_barrier
	s_waitcnt lgkmcnt(0)
	v_mfma_f32_16x16x32_bf16 v[60:63], v[134:137], v[182:185], v[60:63]
	v_mfma_f32_16x16x32_bf16 v[56:59], v[150:153], v[182:185], v[56:59]
	v_mfma_f32_16x16x32_bf16 v[48:51], v[134:137], v[190:193], v[48:51]
	v_mfma_f32_16x16x32_bf16 v[40:43], v[150:153], v[190:193], v[40:43]
	v_mfma_f32_16x16x32_bf16 v[32:35], v[134:137], v[198:201], v[32:35]
	v_mfma_f32_16x16x32_bf16 v[24:27], v[150:153], v[198:201], v[24:27]
	v_mfma_f32_16x16x32_bf16 v[16:19], v[134:137], v[206:209], v[16:19]
	v_mfma_f32_16x16x32_bf16 v[8:11], v[150:153], v[206:209], v[8:11]
	v_mfma_f32_16x16x32_bf16 v[60:63], v[146:149], v[186:189], v[60:63]
	v_mfma_f32_16x16x32_bf16 v[56:59], v[154:157], v[186:189], v[56:59]
	v_mfma_f32_16x16x32_bf16 v[48:51], v[146:149], v[194:197], v[48:51]
	v_mfma_f32_16x16x32_bf16 v[40:43], v[154:157], v[194:197], v[40:43]
	v_mfma_f32_16x16x32_bf16 v[32:35], v[146:149], v[202:205], v[32:35]
	v_mfma_f32_16x16x32_bf16 v[24:27], v[154:157], v[202:205], v[24:27]
	v_mfma_f32_16x16x32_bf16 v[16:19], v[146:149], v[210:213], v[16:19]
	v_mfma_f32_16x16x32_bf16 v[8:11], v[154:157], v[210:213], v[8:11]
	s_setprio 0
	s_setprio 1
	v_mfma_f32_16x16x32_bf16 v[52:55], v[158:161], v[182:185], v[52:55]
	v_mfma_f32_16x16x32_bf16 v[44:47], v[174:177], v[182:185], v[44:47]
	v_mfma_f32_16x16x32_bf16 v[36:39], v[158:161], v[190:193], v[36:39]
	v_mfma_f32_16x16x32_bf16 v[28:31], v[174:177], v[190:193], v[28:31]
	v_mfma_f32_16x16x32_bf16 v[20:23], v[158:161], v[198:201], v[20:23]
	v_mfma_f32_16x16x32_bf16 v[12:15], v[174:177], v[198:201], v[12:15]
	v_mfma_f32_16x16x32_bf16 v[4:7], v[158:161], v[206:209], v[4:7]
	v_mfma_f32_16x16x32_bf16 v[0:3], v[174:177], v[206:209], v[0:3]
	v_mfma_f32_16x16x32_bf16 v[52:55], v[162:165], v[186:189], v[52:55]
	v_mfma_f32_16x16x32_bf16 v[44:47], v[178:181], v[186:189], v[44:47]
	v_mfma_f32_16x16x32_bf16 v[36:39], v[162:165], v[194:197], v[36:39]
	v_mfma_f32_16x16x32_bf16 v[28:31], v[178:181], v[194:197], v[28:31]
	v_mfma_f32_16x16x32_bf16 v[20:23], v[162:165], v[202:205], v[20:23]
	v_mfma_f32_16x16x32_bf16 v[12:15], v[178:181], v[202:205], v[12:15]
	v_mfma_f32_16x16x32_bf16 v[4:7], v[162:165], v[210:213], v[4:7]
	v_mfma_f32_16x16x32_bf16 v[0:3], v[178:181], v[210:213], v[0:3]
	s_setprio 0
	s_barrier
	s_movk_i32 s40, 0x100
	s_andn2_b64 vcc, exec, s[36:37]
	s_mov_b64 s[38:39], -1
	s_mov_b64 s[36:37], 0
	s_cbranch_vccz .LBB0_379
	v_readlane_b32 s60, v255, 51
	s_and_b64 vcc, exec, s[12:13]
	v_readlane_b32 s61, v255, 52
	s_cbranch_vccz .LBB0_382
	s_barrier
